# v10 + GEMM K-loops split per half: one barrier per super-phase (lead: load,compute,BAR / trail: BAR,compute,load), trailing half higher MFMA priority
# baseline (speedup 1.0000x reference)
; #define PG8_STAGE(bufoff, gbase, voff) do { _Pragma("unroll") for (int _i = 0; _i < 2; ++_i) \
;         __builtin_amdgcn_global_load_lds((const unsigned*)((const char*)(gbase) + (voff)[_i]), (PG8_LAS unsigned*)(lds + (bufoff) + ldsw + _i * 8192), 16, 0, 0); } while (0)
; #define PG8_WAIT_V(n) asm volatile("s_waitcnt vmcnt(" #n ")" ::: "memory")
; #define PG8_BAR __builtin_amdgcn_s_barrier()
; template <class Epi, class Sched, bool ALIGN_EPI = false, bool SP2 = false>
; __device__ __forceinline__ void gemm_phase(PG8_LAS unsigned char* lds, const Gemm g, const Sched& S, const Epi& E) {
;     ...
;     for (int i = 0; i < 2; ++i) { int R, C; stage_rc(tid * 16 + i * 8192, R, C); const int Rb = Epi::PERM ? ((R & ~31) + perm32(R & 31)) : R;
;         voffA[i] = (unsigned)(R * K + C) * 2u; voffB[i] = (unsigned)(Rb * K + C) * 2u; }
;     const size_t kstep = (size_t)(BK * 2);
;     const size_t hstep = (size_t)HALF * K * 2;
;     const size_t tstep = 2 * hstep;
;     const unsigned ldsw = (unsigned)wid * 1024u;
;     const int aoff = lds_byte(wr * 64 + fr, fq * 8), boff = lds_byte(wc * 32 + fr, fq * 8);
;     ...
;     if constexpr (SP2) {
;         PG8_STAGE(PG8_SB(0, 0), cB, voffB); PG8_STAGE(PG8_SB(0, 1), cB + hstep, voffB); PG8_STAGE(PG8_SA(0, 0), cA, voffA); PG8_STAGE(PG8_SA(0, 1), cA + hstep, voffA);
;         if (wr == 1) PG8_BAR;
;         PG8_WAIT_V(2); PG8_BAR;
;         PG8_STAGE(PG8_SB(1, 0), cB + kstep, voffB); PG8_STAGE(PG8_SA(1, 0), cA + kstep, voffA); PG8_STAGE(PG8_SB(1, 1), cB + hstep + kstep, voffB);
;         PG8_WAIT_V(6); PG8_BAR;
.LBB0_131:
	s_or_b64 exec, exec, s[0:1]
	v_ashrrev_i32_e32 v3, 31, v146
	v_lshrrev_b32_e32 v3, 26, v3
	v_add_u32_e32 v3, v146, v3
	v_ashrrev_i32_e32 v10, 6, v3
	v_bfe_i32 v3, v146, 27, 1
	v_lshlrev_b32_e32 v2, 4, v146
	v_lshrrev_b32_e32 v3, 22, v3
	v_add_u32_e32 v3, v2, v3
	v_and_b32_e32 v3, 0xfffffc00, v3
	v_sub_u32_e32 v3, v2, v3
	v_lshrrev_b32_e32 v4, 4, v3
	s_add_u32 s49, s4, 0x1d800000
	s_mul_i32 s34, s86, 0x1500000
	v_bitop3_b32 v3, v4, v3, 32 bitop3:0x6c
	s_addc_u32 s50, s5, 0
	s_lshl_b64 s[0:1], s[34:35], 1
	v_ashrrev_i32_e32 v5, 31, v3
	s_add_u32 s34, s46, s0
	v_lshrrev_b32_e32 v5, 26, v5
	s_addc_u32 s51, s47, s1
	v_readlane_b32 s0, v252, 20
	v_add_u32_e32 v5, v3, v5
	v_readlane_b32 s1, v252, 21
	s_add_u32 s30, s49, s0
	v_lshlrev_b32_e32 v4, 3, v10
	v_ashrrev_i32_e32 v11, 6, v5
	v_and_b32_e32 v5, 0xc0, v5
	s_addc_u32 s31, s50, s1
	v_readlane_b32 s0, v254, 50
	v_and_b32_e32 v4, -16, v4
	v_sub_u32_e32 v3, v3, v5
	v_readlane_b32 s1, v254, 51
	s_add_u32 s36, s34, s0
	v_add_u32_e32 v4, v11, v4
	v_ashrrev_i16_sdwa v3, v194, sext(v3) dst_sel:DWORD dst_unused:UNUSED_PAD src0_sel:DWORD src1_sel:BYTE_0
	s_addc_u32 s37, s51, s1
	v_lshlrev_b32_e32 v6, 5, v10
	v_bfe_i32 v12, v3, 0, 16
	v_lshlrev_b32_e32 v3, 1, v4
	v_lshrrev_b32_e32 v5, 2, v4
	v_and_b32_e32 v7, 3, v11
	s_mov_b32 s1, 0xfffe0
	v_and_b32_e32 v6, 32, v6
	v_and_b32_e32 v3, 24, v3
	v_and_b32_e32 v5, 4, v5
	v_and_or_b32 v7, v4, s1, v7
	v_or3_b32 v3, v7, v5, v3
	v_add_lshl_u32 v5, v6, v12, 1
	v_add_u32_e32 v2, 0x2000, v2
	v_lshl_add_u32 v158, v3, 12, v5
	v_ashrrev_i32_e32 v3, 31, v2
	v_lshrrev_b32_e32 v3, 22, v3
	v_add_u32_e32 v3, v2, v3
	v_ashrrev_i32_e32 v13, 10, v3
	v_mul_i32_i24_e32 v3, 0x400, v13
	v_sub_u32_e32 v2, v2, v3
	v_lshrrev_b32_e32 v3, 4, v2
	v_bitop3_b32 v2, v3, v2, 32 bitop3:0x6c
	v_lshl_add_u32 v130, v4, 12, v5
	v_ashrrev_i32_e32 v4, 31, v2
	v_lshrrev_b32_e32 v4, 26, v4
	v_lshlrev_b32_e32 v3, 3, v13
	v_add_u32_e32 v4, v2, v4
	v_and_b32_e32 v3, -16, v3
	v_ashrrev_i32_e32 v14, 6, v4
	v_add_u32_e32 v3, v14, v3
	v_and_b32_e32 v4, 0xc0, v4
	v_and_b32_e32 v6, 3, v14
	v_sub_u32_e32 v2, v2, v4
	v_and_or_b32 v6, v3, s1, v6
	s_ashr_i32 s1, s16, 6
	v_ashrrev_i16_sdwa v2, v194, sext(v2) dst_sel:DWORD dst_unused:UNUSED_PAD src0_sel:DWORD src1_sel:BYTE_0
	s_lshl_b32 s52, s1, 10
	v_lshlrev_b32_e32 v5, 5, v13
	v_bfe_i32 v15, v2, 0, 16
	v_lshlrev_b32_e32 v2, 1, v3
	v_lshrrev_b32_e32 v4, 2, v3
	s_add_i32 s53, s52, 0
	v_and_b32_e32 v5, 32, v5
	v_and_b32_e32 v2, 24, v2
	v_and_b32_e32 v4, 4, v4
	s_add_i32 m0, s53, 0x10000
	s_ashr_i32 s0, s16, 8
	v_or3_b32 v2, v6, v4, v2
	v_add_lshl_u32 v4, v5, v15, 1
	global_load_lds_dwordx4 v158, s[36:37]
	s_add_i32 m0, s53, 0x12000
	v_lshl_add_u32 v134, v2, 12, v4
	s_add_u32 s14, s36, 0x80000
	global_load_lds_dwordx4 v134, s[36:37]
	s_addc_u32 s15, s37, 0
	s_add_i32 m0, s53, 0x14000
	s_add_i32 s54, s53, 0x2000
	global_load_lds_dwordx4 v158, s[14:15]
	s_add_i32 m0, s53, 0x16000
	v_lshl_add_u32 v132, v3, 12, v4
	global_load_lds_dwordx4 v134, s[14:15]
	s_mov_b32 m0, s53
	s_add_u32 s14, s30, 0x80000
	global_load_lds_dwordx4 v130, s[30:31]
	s_mov_b32 m0, s54
	s_addc_u32 s15, s31, 0
	s_add_i32 s55, s53, 0x4000
	global_load_lds_dwordx4 v132, s[30:31]
	s_mov_b32 m0, s55
	s_add_i32 s56, s53, 0x6000
	global_load_lds_dwordx4 v130, s[14:15]
	s_mov_b32 m0, s56
	v_mov_b32_e32 v135, v159
	global_load_lds_dwordx4 v132, s[14:15]
	v_mov_b32_e32 v131, v159
	v_mov_b32_e32 v133, v159
	s_cmp_eq_u32 s0, 1
	v_lshl_add_u64 v[8:9], s[36:37], 0, v[158:159]
	v_lshl_add_u64 v[6:7], s[36:37], 0, v[134:135]
	v_lshl_add_u64 v[2:3], s[30:31], 0, v[130:131]
	s_cselect_b64 s[14:15], -1, 0
	s_cmp_lg_u32 s0, 1
	v_lshl_add_u64 v[4:5], s[30:31], 0, v[132:133]
	s_cbranch_scc1 .LBB0_133
.LBB0_133:
	s_lshl_b32 s1, s1, 5
	s_and_b32 s1, s1, 0x60
	s_add_i32 m0, s53, 0x18000
	v_lshl_add_u64 v[8:9], v[8:9], 0, s[10:11]
	s_lshl_b32 s17, s0, 13
	s_lshl_b32 s24, s1, 7
	s_waitcnt vmcnt(2)
	s_barrier
	global_load_lds_dwordx4 v[8:9], off
	v_lshl_add_u64 v[6:7], v[6:7], 0, s[10:11]
	s_add_i32 m0, s53, 0x1a000
	s_add_i32 s57, s53, 0x8000
	s_add_i32 s58, s53, 0xa000
	global_load_lds_dwordx4 v[6:7], off
	v_lshl_add_u64 v[2:3], v[2:3], 0, s[10:11]
	s_mov_b32 m0, s57
	s_add_u32 s22, s36, 0x80080
	global_load_lds_dwordx4 v[2:3], off
	v_lshl_add_u64 v[2:3], v[4:5], 0, s[10:11]
	s_mov_b32 m0, s58
	s_addc_u32 s23, s37, 0
	global_load_lds_dwordx4 v[2:3], off
	s_add_i32 m0, s53, 0x1c000
	v_lshl_add_u64 v[2:3], s[22:23], 0, v[158:159]
	global_load_lds_dwordx4 v[2:3], off
	v_lshl_add_u64 v[2:3], s[22:23], 0, v[134:135]
	s_add_i32 m0, s53, 0x1e000
	s_cmpk_lt_u32 s16, 0x100
	global_load_lds_dwordx4 v[2:3], off
	v_and_b32_e32 v3, 15, v146
	v_and_b32_e32 v2, 48, v146
	v_lshl_or_b32 v147, s0, 6, v3
	v_lshl_or_b32 v4, v3, 6, v2
	v_lshlrev_b32_e32 v3, 2, v3
	v_and_b32_e32 v5, 32, v3
	v_bitop3_b32 v6, v4, s17, v5 bitop3:0xde
	s_cselect_b64 s[16:17], -1, 0
	s_lshl_b32 s0, s0, 8
	s_add_i32 s22, 0, 0x20000
	s_add_i32 s0, s22, s0
	s_ashr_i32 s59, s48, 31
	v_add_u32_e32 v149, s0, v3
	s_lshl_b32 s0, s1, 1
	s_add_u32 s0, s4, s0
	s_addc_u32 s1, s5, 0
	v_mov_b32_e32 v3, v159
	v_lshl_add_u64 v[2:3], s[0:1], 0, v[2:3]
	s_mov_b64 s[0:1], 0x25800000
	v_lshl_add_u64 v[136:137], v[2:3], 0, s[0:1]
	v_lshlrev_b32_e32 v2, 15, v10
	v_and_b32_e32 v2, 0xffff0000, v2
	v_lshl_add_u32 v2, v11, 12, v2
	v_and_b32_e32 v3, 1, v10
	v_lshl_or_b32 v2, v3, 6, v2
	v_lshl_add_u32 v138, v12, 1, v2
	v_lshlrev_b32_e32 v2, 15, v13
	v_and_b32_e32 v2, 0xffff0000, v2
	s_waitcnt vmcnt(6)
	v_lshl_add_u32 v2, v14, 12, v2
	v_and_b32_e32 v3, 1, v13
	v_lshl_or_b32 v2, v3, 6, v2
	v_readlane_b32 s0, v252, 18
	v_bitop3_b32 v148, v4, s24, v5 bitop3:0xde
	v_lshl_add_u32 v150, v146, 2, s22
	v_mov_b32_e32 v139, v159
	v_lshl_add_u32 v140, v15, 1, v2
	v_mov_b32_e32 v141, v159
	s_mov_b32 s60, 0
	v_add_u32_e32 v151, 0, v6
	v_readlane_b32 s63, v254, 49
	s_mov_b32 s44, s0
	s_mov_b32 s62, s0
	s_mov_b32 s61, 0
	s_barrier
	v_readlane_b32 s1, v252, 19
	s_branch .LBB0_136

; #define PG8_STAGE(bufoff, gbase, voff) do { _Pragma("unroll") for (int _i = 0; _i < 2; ++_i) \
;         __builtin_amdgcn_global_load_lds((const unsigned*)((const char*)(gbase) + (voff)[_i]), (PG8_LAS unsigned*)(lds + (bufoff) + ldsw + _i * 8192), 16, 0, 0); } while (0)
; #define PG8_LDA(dst, b, h) do { _Pragma("unroll") for (int m = 0; m < 4; ++m) _Pragma("unroll") for (int k = 0; k < 2; ++k) dst[m][k] = *(const PG8_LAS bf16x8*)(lds + PG8_SA(b, h) + aoff + m * 2048 + k * 1024); } while (0)
; #define PG8_LDB(dst, b, h) do { _Pragma("unroll") for (int n = 0; n < 2; ++n) _Pragma("unroll") for (int k = 0; k < 2; ++k) dst[n][k] = *(const PG8_LAS bf16x8*)(lds + PG8_SB(b, h) + boff + n * 2048 + k * 1024); } while (0)
; #define PG8_WAIT_V(n) asm volatile("s_waitcnt vmcnt(" #n ")" ::: "memory")
; #define PG8_WAIT_L(n) asm volatile("s_waitcnt lgkmcnt(" #n ")" ::: "memory")
; #define PG8_BAR __builtin_amdgcn_s_barrier()
; #define PG8_SCHED __builtin_amdgcn_sched_barrier(0)
; template <class Epi, class Sched, bool ALIGN_EPI = false, bool SP2 = false>
; __device__ __forceinline__ void gemm_phase(PG8_LAS unsigned char* lds, const Gemm g, const Sched& S, const Epi& E) {
;     ...
;         const char* nA = has_next ? (const char*)g.A + (size_t)nxt.pm * tstep : cA; const char* nB = has_next ? (const char*)g.Bt + (size_t)nxt.pn * tstep : cB;
;         for (int t = 0; t < nt; t += 2) {
;             const bool last = (t == nt - 2);
;             const char* a1 = cA + (size_t)(t + 1) * kstep;
;             const char* a2 = last ? nA : cA + (size_t)(t + 2) * kstep; const char* b2 = last ? nB : cB + (size_t)(t + 2) * kstep;
;             const char* a3 = a2 + kstep; const char* b3 = b2 + kstep;
;             if (last && has_next) S.a_ready(nxt);
;             if constexpr (SP2) {
;             PG8_LDB(B0, 0, 0); PG8_LDB(B1, 0, 1); PG8_SCHED; PG8_LDA(At, 0, 0); PG8_STAGE(PG8_SA(1, 1), a1 + hstep, voffA);
;             PG8_WAIT_V(8); PG8_WAIT_L(0); PG8_BAR; PG8_MMA(0, 0, At, B0); PG8_MMA(0, 1, At, B1); PG8_BAR; PG8_SCHED;
;     ...
;         for (int a = 0; a < 2; ++a)
; #pragma unroll
;             for (int b = 0; b < 2; ++b)
; #pragma unroll
;                 for (int m = 0; m < 4; ++m)
; #pragma unroll
;                     for (int n = 0; n < 2; ++n) acc[a][b][m][n] = (f32x4){0.f, 0.f, 0.f, 0.f};
.LBB0_138:
	s_ashr_i32 s25, s24, 31
	s_lshl_b64 s[0:1], s[24:25], 20
	s_add_u32 s0, s49, s0
	s_addc_u32 s1, s50, s1
	s_and_b64 s[28:29], s[42:43], exec
	s_cselect_b32 s25, s1, s31
	s_cselect_b32 s45, s0, s30
	s_ashr_i32 s23, s22, 31
	s_lshl_b64 s[28:29], s[22:23], 20
	s_add_u32 s28, s34, s28
	s_addc_u32 s29, s51, s29
	s_and_b64 s[38:39], s[42:43], exec
	s_cselect_b32 s23, s29, s37
	s_cselect_b32 s66, s28, s36
	s_add_u32 s30, s30, 0x80080
	s_addc_u32 s31, s31, 0
	s_add_u32 s67, s36, 0x100
	v_mov_b32_e32 v2, 0
	s_addc_u32 s68, s37, 0
	s_mov_b32 s69, -2
	v_mov_b32_e32 v3, v2
	v_mov_b32_e32 v4, v2
	v_mov_b32_e32 v5, v2
	v_mov_b32_e32 v6, v2
	v_mov_b32_e32 v7, v2
	v_mov_b32_e32 v8, v2
	v_mov_b32_e32 v9, v2
	v_mov_b32_e32 v18, v2
	v_mov_b32_e32 v19, v2
	v_mov_b32_e32 v20, v2
	v_mov_b32_e32 v21, v2
	v_mov_b32_e32 v22, v2
	v_mov_b32_e32 v23, v2
	v_mov_b32_e32 v24, v2
	v_mov_b32_e32 v25, v2
	v_mov_b32_e32 v34, v2
	v_mov_b32_e32 v35, v2
	v_mov_b32_e32 v36, v2
	v_mov_b32_e32 v37, v2
	v_mov_b32_e32 v38, v2
	v_mov_b32_e32 v39, v2
	v_mov_b32_e32 v40, v2
	v_mov_b32_e32 v41, v2
	v_mov_b32_e32 v50, v2
	v_mov_b32_e32 v51, v2
	v_mov_b32_e32 v52, v2
	v_mov_b32_e32 v53, v2
	v_mov_b32_e32 v54, v2
	v_mov_b32_e32 v55, v2
	v_mov_b32_e32 v56, v2
	v_mov_b32_e32 v57, v2
	v_mov_b32_e32 v10, v2
	v_mov_b32_e32 v11, v2
	v_mov_b32_e32 v12, v2
	v_mov_b32_e32 v13, v2
	v_mov_b32_e32 v14, v2
	v_mov_b32_e32 v15, v2
	v_mov_b32_e32 v16, v2
	v_mov_b32_e32 v17, v2
	v_mov_b32_e32 v26, v2
	v_mov_b32_e32 v27, v2
	v_mov_b32_e32 v28, v2
	v_mov_b32_e32 v29, v2
	v_mov_b32_e32 v30, v2
	v_mov_b32_e32 v31, v2
	v_mov_b32_e32 v32, v2
	v_mov_b32_e32 v33, v2
	v_mov_b32_e32 v42, v2
	v_mov_b32_e32 v43, v2
	v_mov_b32_e32 v44, v2
	v_mov_b32_e32 v45, v2
	v_mov_b32_e32 v46, v2
	v_mov_b32_e32 v47, v2
	v_mov_b32_e32 v48, v2
	v_mov_b32_e32 v49, v2
	v_mov_b32_e32 v58, v2
	v_mov_b32_e32 v59, v2
	v_mov_b32_e32 v60, v2
	v_mov_b32_e32 v61, v2
	v_mov_b32_e32 v62, v2
	v_mov_b32_e32 v63, v2
	v_mov_b32_e32 v64, v2
	v_mov_b32_e32 v65, v2
	v_mov_b32_e32 v66, v2
	v_mov_b32_e32 v67, v2
	v_mov_b32_e32 v68, v2
	v_mov_b32_e32 v69, v2
	v_mov_b32_e32 v70, v2
	v_mov_b32_e32 v71, v2
	v_mov_b32_e32 v72, v2
	v_mov_b32_e32 v73, v2
	v_mov_b32_e32 v82, v2
	v_mov_b32_e32 v83, v2
	v_mov_b32_e32 v84, v2
	v_mov_b32_e32 v85, v2
	v_mov_b32_e32 v86, v2
	v_mov_b32_e32 v87, v2
	v_mov_b32_e32 v88, v2
	v_mov_b32_e32 v89, v2
	v_mov_b32_e32 v98, v2
	v_mov_b32_e32 v99, v2
	v_mov_b32_e32 v100, v2
	v_mov_b32_e32 v101, v2
	v_mov_b32_e32 v102, v2
	v_mov_b32_e32 v103, v2
	v_mov_b32_e32 v104, v2
	v_mov_b32_e32 v105, v2
	v_mov_b32_e32 v114, v2
	v_mov_b32_e32 v115, v2
	v_mov_b32_e32 v116, v2
	v_mov_b32_e32 v117, v2
	v_mov_b32_e32 v118, v2
	v_mov_b32_e32 v119, v2
	v_mov_b32_e32 v120, v2
	v_mov_b32_e32 v121, v2
	v_mov_b32_e32 v74, v2
	v_mov_b32_e32 v75, v2
	v_mov_b32_e32 v76, v2
	v_mov_b32_e32 v77, v2
	v_mov_b32_e32 v78, v2
	v_mov_b32_e32 v79, v2
	v_mov_b32_e32 v80, v2
	v_mov_b32_e32 v81, v2
	v_mov_b32_e32 v90, v2
	v_mov_b32_e32 v91, v2
	v_mov_b32_e32 v92, v2
	v_mov_b32_e32 v93, v2
	v_mov_b32_e32 v94, v2
	v_mov_b32_e32 v95, v2
	v_mov_b32_e32 v96, v2
	v_mov_b32_e32 v97, v2
	v_mov_b32_e32 v106, v2
	v_mov_b32_e32 v107, v2
	v_mov_b32_e32 v108, v2
	v_mov_b32_e32 v109, v2
	v_mov_b32_e32 v110, v2
	v_mov_b32_e32 v111, v2
	v_mov_b32_e32 v112, v2
	v_mov_b32_e32 v113, v2
	v_mov_b32_e32 v122, v2
	v_mov_b32_e32 v123, v2
	v_mov_b32_e32 v124, v2
	v_mov_b32_e32 v125, v2
	v_mov_b32_e32 v126, v2
	v_mov_b32_e32 v127, v2
	v_mov_b32_e32 v128, v2
	v_mov_b32_e32 v129, v2
	s_and_b64 vcc, exec, s[14:15]
	s_cbranch_vccnz .Lhb_T_139
.LBB0_139:
	s_add_u32 s36, s30, 0xfff80080
	s_addc_u32 s37, s31, -1
	s_add_i32 s70, 0, 0x10000
	s_cmp_eq_u32 s69, 28
	s_cselect_b32 s39, s25, s37
	s_cselect_b32 s38, s45, s36
	v_add_u32_e32 v142, s70, v148
	s_cselect_b32 s37, s23, s68
	s_cselect_b32 s36, s66, s67
	s_add_i32 s75, 0, 0x14000
	ds_read_b128 v[152:155], v142
	ds_read_b128 v[166:169], v142 offset:1024
	ds_read_b128 v[170:173], v142 offset:2048
	ds_read_b128 v[174:177], v142 offset:3072
	v_add_u32_e32 v142, s75, v148
	ds_read_b128 v[178:181], v142
	ds_read_b128 v[182:185], v142 offset:1024
	ds_read_b128 v[186:189], v142 offset:2048
	ds_read_b128 v[190:193], v142 offset:3072
	s_add_u32 s98, s30, 0xfff80000
	s_addc_u32 s99, s31, -1
	v_lshl_add_u64 v[144:145], s[98:99], 0, v[138:139]
	s_mov_b32 m0, s57
	s_nop 0
	global_load_lds_dwordx4 v[144:145], off
	v_lshl_add_u64 v[144:145], s[98:99], 0, v[140:141]
	s_mov_b32 m0, s58
	s_nop 0
	global_load_lds_dwordx4 v[144:145], off
	v_lshl_add_u64 v[144:145], s[30:31], 0, v[138:139]
	s_add_i32 m0, s53, 0xc000
	ds_read_b128 v[200:203], v151
	ds_read_b128 v[204:207], v151 offset:1024
	ds_read_b128 v[208:211], v151 offset:2048
	ds_read_b128 v[212:215], v151 offset:3072
	ds_read_b128 v[216:219], v151 offset:4096
	ds_read_b128 v[220:223], v151 offset:5120
	ds_read_b128 v[224:227], v151 offset:6144
	ds_read_b128 v[228:231], v151 offset:7168
	global_load_lds_dwordx4 v[144:145], off
	v_lshl_add_u64 v[144:145], s[30:31], 0, v[140:141]
	s_add_i32 m0, s53, 0xe000
	s_nop 0
	global_load_lds_dwordx4 v[144:145], off
	s_waitcnt lgkmcnt(0)
	s_setprio 1
	s_waitcnt lgkmcnt(0)
; #define PG8_STAGE(bufoff, gbase, voff) do { _Pragma("unroll") for (int _i = 0; _i < 2; ++_i) \
;         __builtin_amdgcn_global_load_lds((const unsigned*)((const char*)(gbase) + (voff)[_i]), (PG8_LAS unsigned*)(lds + (bufoff) + ldsw + _i * 8192), 16, 0, 0); } while (0)
; #define PG8_LDA(dst, b, h) do { _Pragma("unroll") for (int m = 0; m < 4; ++m) _Pragma("unroll") for (int k = 0; k < 2; ++k) dst[m][k] = *(const PG8_LAS bf16x8*)(lds + PG8_SA(b, h) + aoff + m * 2048 + k * 1024); } while (0)
; #define PG8_MMA(ai, bj, At, Bt) do { __builtin_amdgcn_s_setprio(1); _Pragma("unroll") for (int m = 0; m < 4; ++m) _Pragma("unroll") for (int n = 0; n < 2; ++n) _Pragma("unroll") for (int k = 0; k < 2; ++k) \
;         acc[ai][bj][m][n] = __builtin_amdgcn_mfma_f32_16x16x32_bf16(Bt[n][k], At[m][k], acc[ai][bj][m][n], 0, 0, 0); __builtin_amdgcn_s_setprio(0); } while (0)
; #define PG8_WAIT_V(n) asm volatile("s_waitcnt vmcnt(" #n ")" ::: "memory")
; #define PG8_WAIT_L(n) asm volatile("s_waitcnt lgkmcnt(" #n ")" ::: "memory")
; #define PG8_BAR __builtin_amdgcn_s_barrier()
; #define PG8_SCHED __builtin_amdgcn_sched_barrier(0)
; template <class Epi, class Sched, bool ALIGN_EPI = false, bool SP2 = false>
; __device__ __forceinline__ void gemm_phase(PG8_LAS unsigned char* lds, const Gemm g, const Sched& S, const Epi& E) {
;     ...
;             PG8_WAIT_V(8); PG8_WAIT_L(0); PG8_BAR; PG8_MMA(0, 0, At, B0); PG8_MMA(0, 1, At, B1); PG8_BAR; PG8_SCHED;
;             PG8_LDA(At, 0, 1); PG8_STAGE(PG8_SB(0, 0), b2, voffB); PG8_STAGE(PG8_SB(0, 1), b2 + hstep, voffB); PG8_STAGE(PG8_SA(0, 0), a2, voffA);
;             PG8_WAIT_V(8); PG8_WAIT_L(0); PG8_BAR; PG8_MMA(1, 0, At, B0); PG8_MMA(1, 1, At, B1); PG8_BAR; PG8_SCHED;
	v_mfma_f32_16x16x32_bf16 v[126:129], v[152:155], v[200:203], v[126:129]
	v_mfma_f32_16x16x32_bf16 v[122:125], v[170:173], v[200:203], v[122:125]
	v_mfma_f32_16x16x32_bf16 v[110:113], v[152:155], v[208:211], v[110:113]
	v_mfma_f32_16x16x32_bf16 v[106:109], v[170:173], v[208:211], v[106:109]
	v_mfma_f32_16x16x32_bf16 v[94:97], v[152:155], v[216:219], v[94:97]
	v_mfma_f32_16x16x32_bf16 v[90:93], v[170:173], v[216:219], v[90:93]
	v_mfma_f32_16x16x32_bf16 v[78:81], v[152:155], v[224:227], v[78:81]
	v_mfma_f32_16x16x32_bf16 v[74:77], v[170:173], v[224:227], v[74:77]
	v_mfma_f32_16x16x32_bf16 v[126:129], v[166:169], v[204:207], v[126:129]
	v_mfma_f32_16x16x32_bf16 v[122:125], v[174:177], v[204:207], v[122:125]
	v_mfma_f32_16x16x32_bf16 v[110:113], v[166:169], v[212:215], v[110:113]
	v_mfma_f32_16x16x32_bf16 v[106:109], v[174:177], v[212:215], v[106:109]
	v_mfma_f32_16x16x32_bf16 v[94:97], v[166:169], v[220:223], v[94:97]
	v_mfma_f32_16x16x32_bf16 v[90:93], v[174:177], v[220:223], v[90:93]
	v_mfma_f32_16x16x32_bf16 v[78:81], v[166:169], v[228:231], v[78:81]
	v_mfma_f32_16x16x32_bf16 v[74:77], v[174:177], v[228:231], v[74:77]
	v_mfma_f32_16x16x32_bf16 v[118:121], v[178:181], v[200:203], v[118:121]
	v_mfma_f32_16x16x32_bf16 v[114:117], v[186:189], v[200:203], v[114:117]
	v_mfma_f32_16x16x32_bf16 v[102:105], v[178:181], v[208:211], v[102:105]
	v_mfma_f32_16x16x32_bf16 v[98:101], v[186:189], v[208:211], v[98:101]
	v_mfma_f32_16x16x32_bf16 v[86:89], v[178:181], v[216:219], v[86:89]
	v_mfma_f32_16x16x32_bf16 v[82:85], v[186:189], v[216:219], v[82:85]
	v_mfma_f32_16x16x32_bf16 v[70:73], v[178:181], v[224:227], v[70:73]
	v_mfma_f32_16x16x32_bf16 v[66:69], v[186:189], v[224:227], v[66:69]
	v_mfma_f32_16x16x32_bf16 v[118:121], v[182:185], v[204:207], v[118:121]
	v_mfma_f32_16x16x32_bf16 v[114:117], v[190:193], v[204:207], v[114:117]
	v_mfma_f32_16x16x32_bf16 v[102:105], v[182:185], v[212:215], v[102:105]
	v_mfma_f32_16x16x32_bf16 v[98:101], v[190:193], v[212:215], v[98:101]
	v_mfma_f32_16x16x32_bf16 v[86:89], v[182:185], v[220:223], v[86:89]
	v_mfma_f32_16x16x32_bf16 v[82:85], v[190:193], v[220:223], v[82:85]
	v_mfma_f32_16x16x32_bf16 v[70:73], v[182:185], v[228:231], v[70:73]
	v_mfma_f32_16x16x32_bf16 v[66:69], v[190:193], v[228:231], v[66:69]
	s_setprio 0
	s_waitcnt vmcnt(8)
	s_barrier
	s_add_i32 s70, s70, s52
	v_lshl_add_u64 v[144:145], s[36:37], 0, v[158:159]
	s_mov_b32 m0, s70
	ds_read_b128 v[200:203], v151 offset:16384
	ds_read_b128 v[204:207], v151 offset:17408
	ds_read_b128 v[208:211], v151 offset:18432
	ds_read_b128 v[212:215], v151 offset:19456
	ds_read_b128 v[216:219], v151 offset:20480
	ds_read_b128 v[220:223], v151 offset:21504
	ds_read_b128 v[224:227], v151 offset:22528
	ds_read_b128 v[228:231], v151 offset:23552
	global_load_lds_dwordx4 v[144:145], off
	s_add_i32 m0, s70, 0x2000
	s_add_u32 s70, s36, 0x80000
	v_lshl_add_u64 v[156:157], s[36:37], 0, v[134:135]
	s_addc_u32 s71, s37, 0
	s_add_i32 s75, s75, s52
	global_load_lds_dwordx4 v[156:157], off
	v_lshl_add_u64 v[162:163], s[70:71], 0, v[158:159]
	s_mov_b32 m0, s75
	v_lshl_add_u64 v[164:165], s[38:39], 0, v[132:133]
	global_load_lds_dwordx4 v[162:163], off
	v_lshl_add_u64 v[162:163], s[70:71], 0, v[134:135]
	s_add_i32 m0, s75, 0x2000
	s_nop 0
	global_load_lds_dwordx4 v[162:163], off
	v_lshl_add_u64 v[162:163], s[38:39], 0, v[130:131]
	s_waitcnt lgkmcnt(0)
	s_setprio 1
	s_waitcnt lgkmcnt(0)
	v_mfma_f32_16x16x32_bf16 v[62:65], v[152:155], v[200:203], v[62:65]
	v_mfma_f32_16x16x32_bf16 v[58:61], v[170:173], v[200:203], v[58:61]
	v_mfma_f32_16x16x32_bf16 v[46:49], v[152:155], v[208:211], v[46:49]
	v_mfma_f32_16x16x32_bf16 v[42:45], v[170:173], v[208:211], v[42:45]
	v_mfma_f32_16x16x32_bf16 v[30:33], v[152:155], v[216:219], v[30:33]
	v_mfma_f32_16x16x32_bf16 v[26:29], v[170:173], v[216:219], v[26:29]
	v_mfma_f32_16x16x32_bf16 v[14:17], v[152:155], v[224:227], v[14:17]
	v_mfma_f32_16x16x32_bf16 v[10:13], v[170:173], v[224:227], v[10:13]
	v_mfma_f32_16x16x32_bf16 v[62:65], v[166:169], v[204:207], v[62:65]
	v_mfma_f32_16x16x32_bf16 v[58:61], v[174:177], v[204:207], v[58:61]
	v_mfma_f32_16x16x32_bf16 v[46:49], v[166:169], v[212:215], v[46:49]
	v_mfma_f32_16x16x32_bf16 v[42:45], v[174:177], v[212:215], v[42:45]
	v_mfma_f32_16x16x32_bf16 v[30:33], v[166:169], v[220:223], v[30:33]
	v_mfma_f32_16x16x32_bf16 v[26:29], v[174:177], v[220:223], v[26:29]
	v_mfma_f32_16x16x32_bf16 v[14:17], v[166:169], v[228:231], v[14:17]
	v_mfma_f32_16x16x32_bf16 v[10:13], v[174:177], v[228:231], v[10:13]
	v_mfma_f32_16x16x32_bf16 v[54:57], v[178:181], v[200:203], v[54:57]
	v_mfma_f32_16x16x32_bf16 v[50:53], v[186:189], v[200:203], v[50:53]
	v_mfma_f32_16x16x32_bf16 v[38:41], v[178:181], v[208:211], v[38:41]
	v_mfma_f32_16x16x32_bf16 v[34:37], v[186:189], v[208:211], v[34:37]
	v_mfma_f32_16x16x32_bf16 v[22:25], v[178:181], v[216:219], v[22:25]
	v_mfma_f32_16x16x32_bf16 v[18:21], v[186:189], v[216:219], v[18:21]
	v_mfma_f32_16x16x32_bf16 v[6:9], v[178:181], v[224:227], v[6:9]
	v_mfma_f32_16x16x32_bf16 v[2:5], v[186:189], v[224:227], v[2:5]
	v_mfma_f32_16x16x32_bf16 v[54:57], v[182:185], v[204:207], v[54:57]
	v_mfma_f32_16x16x32_bf16 v[50:53], v[190:193], v[204:207], v[50:53]
	v_mfma_f32_16x16x32_bf16 v[38:41], v[182:185], v[212:215], v[38:41]
	v_mfma_f32_16x16x32_bf16 v[34:37], v[190:193], v[212:215], v[34:37]
	v_mfma_f32_16x16x32_bf16 v[22:25], v[182:185], v[220:223], v[22:25]
	v_mfma_f32_16x16x32_bf16 v[18:21], v[190:193], v[220:223], v[18:21]
	v_mfma_f32_16x16x32_bf16 v[6:9], v[182:185], v[228:231], v[6:9]
	v_mfma_f32_16x16x32_bf16 v[2:5], v[190:193], v[228:231], v[2:5]
	s_setprio 0
	s_waitcnt vmcnt(6)
	s_barrier
; #define PG8_STAGE(bufoff, gbase, voff) do { _Pragma("unroll") for (int _i = 0; _i < 2; ++_i) \
;         __builtin_amdgcn_global_load_lds((const unsigned*)((const char*)(gbase) + (voff)[_i]), (PG8_LAS unsigned*)(lds + (bufoff) + ldsw + _i * 8192), 16, 0, 0); } while (0)
; #define PG8_LDA(dst, b, h) do { _Pragma("unroll") for (int m = 0; m < 4; ++m) _Pragma("unroll") for (int k = 0; k < 2; ++k) dst[m][k] = *(const PG8_LAS bf16x8*)(lds + PG8_SA(b, h) + aoff + m * 2048 + k * 1024); } while (0)
; #define PG8_LDB(dst, b, h) do { _Pragma("unroll") for (int n = 0; n < 2; ++n) _Pragma("unroll") for (int k = 0; k < 2; ++k) dst[n][k] = *(const PG8_LAS bf16x8*)(lds + PG8_SB(b, h) + boff + n * 2048 + k * 1024); } while (0)
; #define PG8_MMA(ai, bj, At, Bt) do { __builtin_amdgcn_s_setprio(1); _Pragma("unroll") for (int m = 0; m < 4; ++m) _Pragma("unroll") for (int n = 0; n < 2; ++n) _Pragma("unroll") for (int k = 0; k < 2; ++k) \
;         acc[ai][bj][m][n] = __builtin_amdgcn_mfma_f32_16x16x32_bf16(Bt[n][k], At[m][k], acc[ai][bj][m][n], 0, 0, 0); __builtin_amdgcn_s_setprio(0); } while (0)
; #define PG8_WAIT_V(n) asm volatile("s_waitcnt vmcnt(" #n ")" ::: "memory")
; #define PG8_WAIT_L(n) asm volatile("s_waitcnt lgkmcnt(" #n ")" ::: "memory")
; #define PG8_BAR __builtin_amdgcn_s_barrier()
; #define PG8_SCHED __builtin_amdgcn_sched_barrier(0)
; template <class Epi, class Sched, bool ALIGN_EPI = false, bool SP2 = false>
; __device__ __forceinline__ void gemm_phase(PG8_LAS unsigned char* lds, const Gemm g, const Sched& S, const Epi& E) {
;     ...
;             PG8_LDB(B0, 1, 0); PG8_LDB(B1, 1, 1); PG8_SCHED; PG8_LDA(At, 1, 0); PG8_STAGE(PG8_SA(0, 1), a2 + hstep, voffA);
;             PG8_WAIT_V(8); PG8_WAIT_L(0); PG8_BAR; PG8_MMA(0, 0, At, B0); PG8_MMA(0, 1, At, B1); PG8_BAR; PG8_SCHED;
;             PG8_LDA(At, 1, 1); PG8_STAGE(PG8_SB(1, 0), b3, voffB); PG8_STAGE(PG8_SB(1, 1), b3 + hstep, voffB); PG8_STAGE(PG8_SA(1, 0), a3, voffA);
;             PG8_WAIT_V(8); PG8_WAIT_L(0); PG8_BAR; PG8_MMA(1, 0, At, B0); PG8_MMA(1, 1, At, B1); PG8_BAR; PG8_SCHED;
	s_add_i32 s70, 0, 0x18000
	v_add_u32_e32 v142, s70, v148
	s_add_i32 s71, 0, 0x1c000
	ds_read_b128 v[152:155], v142
	ds_read_b128 v[166:169], v142 offset:1024
	ds_read_b128 v[170:173], v142 offset:2048
	ds_read_b128 v[174:177], v142 offset:3072
	v_add_u32_e32 v142, s71, v148
	ds_read_b128 v[178:181], v142
	ds_read_b128 v[182:185], v142 offset:1024
	ds_read_b128 v[186:189], v142 offset:2048
	ds_read_b128 v[190:193], v142 offset:3072
	s_add_u32 s38, s38, 0x80000
	s_addc_u32 s39, s39, 0
	s_mov_b32 m0, s53
	s_nop 0
	global_load_lds_dwordx4 v[162:163], off
	s_mov_b32 m0, s54
	s_nop 0
	global_load_lds_dwordx4 v[164:165], off
	s_mov_b32 m0, s55
	v_lshl_add_u64 v[232:233], s[38:39], 0, v[130:131]
	ds_read_b128 v[200:203], v151 offset:32768
	ds_read_b128 v[204:207], v151 offset:33792
	ds_read_b128 v[208:211], v151 offset:34816
	ds_read_b128 v[212:215], v151 offset:35840
	ds_read_b128 v[216:219], v151 offset:36864
	ds_read_b128 v[220:223], v151 offset:37888
	ds_read_b128 v[224:227], v151 offset:38912
	ds_read_b128 v[228:231], v151 offset:39936
	global_load_lds_dwordx4 v[232:233], off
	v_lshl_add_u64 v[232:233], s[38:39], 0, v[132:133]
	s_mov_b32 m0, s56
	s_nop 0
	global_load_lds_dwordx4 v[232:233], off
	s_waitcnt lgkmcnt(0)
	s_setprio 1
	s_waitcnt lgkmcnt(0)
	v_mfma_f32_16x16x32_bf16 v[126:129], v[152:155], v[200:203], v[126:129]
	v_mfma_f32_16x16x32_bf16 v[122:125], v[170:173], v[200:203], v[122:125]
	v_mfma_f32_16x16x32_bf16 v[110:113], v[152:155], v[208:211], v[110:113]
	v_mfma_f32_16x16x32_bf16 v[106:109], v[170:173], v[208:211], v[106:109]
	v_mfma_f32_16x16x32_bf16 v[94:97], v[152:155], v[216:219], v[94:97]
	v_mfma_f32_16x16x32_bf16 v[90:93], v[170:173], v[216:219], v[90:93]
	v_mfma_f32_16x16x32_bf16 v[78:81], v[152:155], v[224:227], v[78:81]
	v_mfma_f32_16x16x32_bf16 v[74:77], v[170:173], v[224:227], v[74:77]
	v_mfma_f32_16x16x32_bf16 v[126:129], v[166:169], v[204:207], v[126:129]
	v_mfma_f32_16x16x32_bf16 v[122:125], v[174:177], v[204:207], v[122:125]
	v_mfma_f32_16x16x32_bf16 v[110:113], v[166:169], v[212:215], v[110:113]
	v_mfma_f32_16x16x32_bf16 v[106:109], v[174:177], v[212:215], v[106:109]
	v_mfma_f32_16x16x32_bf16 v[94:97], v[166:169], v[220:223], v[94:97]
	v_mfma_f32_16x16x32_bf16 v[90:93], v[174:177], v[220:223], v[90:93]
	v_mfma_f32_16x16x32_bf16 v[78:81], v[166:169], v[228:231], v[78:81]
	v_mfma_f32_16x16x32_bf16 v[74:77], v[174:177], v[228:231], v[74:77]
	v_mfma_f32_16x16x32_bf16 v[118:121], v[178:181], v[200:203], v[118:121]
	v_mfma_f32_16x16x32_bf16 v[114:117], v[186:189], v[200:203], v[114:117]
	v_mfma_f32_16x16x32_bf16 v[102:105], v[178:181], v[208:211], v[102:105]
	v_mfma_f32_16x16x32_bf16 v[98:101], v[186:189], v[208:211], v[98:101]
	v_mfma_f32_16x16x32_bf16 v[86:89], v[178:181], v[216:219], v[86:89]
	v_mfma_f32_16x16x32_bf16 v[82:85], v[186:189], v[216:219], v[82:85]
	v_mfma_f32_16x16x32_bf16 v[70:73], v[178:181], v[224:227], v[70:73]
	v_mfma_f32_16x16x32_bf16 v[66:69], v[186:189], v[224:227], v[66:69]
	v_mfma_f32_16x16x32_bf16 v[118:121], v[182:185], v[204:207], v[118:121]
	v_mfma_f32_16x16x32_bf16 v[114:117], v[190:193], v[204:207], v[114:117]
	v_mfma_f32_16x16x32_bf16 v[102:105], v[182:185], v[212:215], v[102:105]
	v_mfma_f32_16x16x32_bf16 v[98:101], v[190:193], v[212:215], v[98:101]
	v_mfma_f32_16x16x32_bf16 v[86:89], v[182:185], v[220:223], v[86:89]
	v_mfma_f32_16x16x32_bf16 v[82:85], v[190:193], v[220:223], v[82:85]
	v_mfma_f32_16x16x32_bf16 v[70:73], v[182:185], v[228:231], v[70:73]
	v_mfma_f32_16x16x32_bf16 v[66:69], v[190:193], v[228:231], v[66:69]
	s_setprio 0
	s_waitcnt vmcnt(8)
	s_barrier
	s_add_i32 s38, s70, s52
	v_lshl_add_u64 v[144:145], v[144:145], 0, s[10:11]
	s_mov_b32 m0, s38
	ds_read_b128 v[200:203], v151 offset:49152
	ds_read_b128 v[204:207], v151 offset:50176
	ds_read_b128 v[208:211], v151 offset:51200
	ds_read_b128 v[212:215], v151 offset:52224
	ds_read_b128 v[216:219], v151 offset:53248
	ds_read_b128 v[220:223], v151 offset:54272
	ds_read_b128 v[224:227], v151 offset:55296
	ds_read_b128 v[228:231], v151 offset:56320
	global_load_lds_dwordx4 v[144:145], off
	s_add_i32 m0, s38, 0x2000
	s_add_u32 s36, s36, 0x80080
	v_lshl_add_u64 v[144:145], v[156:157], 0, s[10:11]
	s_addc_u32 s37, s37, 0
	s_add_i32 s38, s71, s52
	global_load_lds_dwordx4 v[144:145], off
	v_lshl_add_u64 v[144:145], s[36:37], 0, v[158:159]
	s_mov_b32 m0, s38
	s_nop 0
	global_load_lds_dwordx4 v[144:145], off
	v_lshl_add_u64 v[144:145], s[36:37], 0, v[134:135]
	s_add_i32 m0, s38, 0x2000
	s_nop 0
	global_load_lds_dwordx4 v[144:145], off
	s_waitcnt lgkmcnt(0)
	s_setprio 1
	s_waitcnt lgkmcnt(0)
	v_mfma_f32_16x16x32_bf16 v[62:65], v[152:155], v[200:203], v[62:65]
	v_mfma_f32_16x16x32_bf16 v[58:61], v[170:173], v[200:203], v[58:61]
	v_mfma_f32_16x16x32_bf16 v[46:49], v[152:155], v[208:211], v[46:49]
	v_mfma_f32_16x16x32_bf16 v[42:45], v[170:173], v[208:211], v[42:45]
	v_mfma_f32_16x16x32_bf16 v[30:33], v[152:155], v[216:219], v[30:33]
	v_mfma_f32_16x16x32_bf16 v[26:29], v[170:173], v[216:219], v[26:29]
	v_mfma_f32_16x16x32_bf16 v[14:17], v[152:155], v[224:227], v[14:17]
	v_mfma_f32_16x16x32_bf16 v[10:13], v[170:173], v[224:227], v[10:13]
	v_mfma_f32_16x16x32_bf16 v[62:65], v[166:169], v[204:207], v[62:65]
	v_mfma_f32_16x16x32_bf16 v[58:61], v[174:177], v[204:207], v[58:61]
	v_mfma_f32_16x16x32_bf16 v[46:49], v[166:169], v[212:215], v[46:49]
	v_mfma_f32_16x16x32_bf16 v[42:45], v[174:177], v[212:215], v[42:45]
	v_mfma_f32_16x16x32_bf16 v[30:33], v[166:169], v[220:223], v[30:33]
	v_mfma_f32_16x16x32_bf16 v[26:29], v[174:177], v[220:223], v[26:29]
	v_mfma_f32_16x16x32_bf16 v[14:17], v[166:169], v[228:231], v[14:17]
	v_mfma_f32_16x16x32_bf16 v[10:13], v[174:177], v[228:231], v[10:13]
	v_mfma_f32_16x16x32_bf16 v[54:57], v[178:181], v[200:203], v[54:57]
	v_mfma_f32_16x16x32_bf16 v[50:53], v[186:189], v[200:203], v[50:53]
	v_mfma_f32_16x16x32_bf16 v[38:41], v[178:181], v[208:211], v[38:41]
	v_mfma_f32_16x16x32_bf16 v[34:37], v[186:189], v[208:211], v[34:37]
	v_mfma_f32_16x16x32_bf16 v[22:25], v[178:181], v[216:219], v[22:25]
	v_mfma_f32_16x16x32_bf16 v[18:21], v[186:189], v[216:219], v[18:21]
	v_mfma_f32_16x16x32_bf16 v[6:9], v[178:181], v[224:227], v[6:9]
	v_mfma_f32_16x16x32_bf16 v[2:5], v[186:189], v[224:227], v[2:5]
	v_mfma_f32_16x16x32_bf16 v[54:57], v[182:185], v[204:207], v[54:57]
	v_mfma_f32_16x16x32_bf16 v[50:53], v[190:193], v[204:207], v[50:53]
	v_mfma_f32_16x16x32_bf16 v[38:41], v[182:185], v[212:215], v[38:41]
	v_mfma_f32_16x16x32_bf16 v[34:37], v[190:193], v[212:215], v[34:37]
	v_mfma_f32_16x16x32_bf16 v[22:25], v[182:185], v[220:223], v[22:25]
	v_mfma_f32_16x16x32_bf16 v[18:21], v[190:193], v[220:223], v[18:21]
	v_mfma_f32_16x16x32_bf16 v[6:9], v[182:185], v[228:231], v[6:9]
	v_mfma_f32_16x16x32_bf16 v[2:5], v[190:193], v[228:231], v[2:5]
	s_setprio 0
	s_waitcnt vmcnt(6)
	s_barrier
	s_add_i32 s69, s69, 2
	s_add_u32 s30, s30, 0x100
	s_addc_u32 s31, s31, 0
	s_add_u32 s67, s67, 0x100
	s_addc_u32 s68, s68, 0
	s_cmp_gt_u32 s69, 29
	s_cbranch_scc0 .LBB0_139
	s_branch .Lhb_X_139
; #define PG8_STAGE(bufoff, gbase, voff) do { _Pragma("unroll") for (int _i = 0; _i < 2; ++_i) \
;         __builtin_amdgcn_global_load_lds((const unsigned*)((const char*)(gbase) + (voff)[_i]), (PG8_LAS unsigned*)(lds + (bufoff) + ldsw + _i * 8192), 16, 0, 0); } while (0)
; #define PG8_LDA(dst, b, h) do { _Pragma("unroll") for (int m = 0; m < 4; ++m) _Pragma("unroll") for (int k = 0; k < 2; ++k) dst[m][k] = *(const PG8_LAS bf16x8*)(lds + PG8_SA(b, h) + aoff + m * 2048 + k * 1024); } while (0)
; #define PG8_LDB(dst, b, h) do { _Pragma("unroll") for (int n = 0; n < 2; ++n) _Pragma("unroll") for (int k = 0; k < 2; ++k) dst[n][k] = *(const PG8_LAS bf16x8*)(lds + PG8_SB(b, h) + boff + n * 2048 + k * 1024); } while (0)
; #define PG8_MMA(ai, bj, At, Bt) do { __builtin_amdgcn_s_setprio(1); _Pragma("unroll") for (int m = 0; m < 4; ++m) _Pragma("unroll") for (int n = 0; n < 2; ++n) _Pragma("unroll") for (int k = 0; k < 2; ++k) \
;         acc[ai][bj][m][n] = __builtin_amdgcn_mfma_f32_16x16x32_bf16(Bt[n][k], At[m][k], acc[ai][bj][m][n], 0, 0, 0); __builtin_amdgcn_s_setprio(0); } while (0)
; #define PG8_WAIT_V(n) asm volatile("s_waitcnt vmcnt(" #n ")" ::: "memory")
; #define PG8_WAIT_L(n) asm volatile("s_waitcnt lgkmcnt(" #n ")" ::: "memory")
; #define PG8_BAR __builtin_amdgcn_s_barrier()
; #define PG8_SCHED __builtin_amdgcn_sched_barrier(0)
; template <class Epi, class Sched, bool ALIGN_EPI = false, bool SP2 = false>
; __device__ __forceinline__ void gemm_phase(PG8_LAS unsigned char* lds, const Gemm g, const Sched& S, const Epi& E) {
;     ...
;             PG8_LDB(B0, 0, 0); PG8_LDB(B1, 0, 1); PG8_SCHED; PG8_LDA(At, 0, 0); PG8_STAGE(PG8_SA(1, 1), a1 + hstep, voffA);
;             PG8_WAIT_V(8); PG8_WAIT_L(0); PG8_BAR; PG8_MMA(0, 0, At, B0); PG8_MMA(0, 1, At, B1); PG8_BAR; PG8_SCHED;
;             PG8_LDA(At, 0, 1); PG8_STAGE(PG8_SB(0, 0), b2, voffB); PG8_STAGE(PG8_SB(0, 1), b2 + hstep, voffB); PG8_STAGE(PG8_SA(0, 0), a2, voffA);
;             PG8_WAIT_V(8); PG8_WAIT_L(0); PG8_BAR; PG8_MMA(1, 0, At, B0); PG8_MMA(1, 1, At, B1); PG8_BAR; PG8_SCHED;
.Lhb_T_139:
	s_add_u32 s36, s30, 0xfff80080
	s_addc_u32 s37, s31, -1
	s_add_i32 s70, 0, 0x10000
	s_cmp_eq_u32 s69, 28
	s_cselect_b32 s39, s25, s37
	s_cselect_b32 s38, s45, s36
	v_add_u32_e32 v142, s70, v148
	s_cselect_b32 s37, s23, s68
	s_cselect_b32 s36, s66, s67
	s_add_i32 s75, 0, 0x14000
	ds_read_b128 v[152:155], v142
	ds_read_b128 v[166:169], v142 offset:1024
	ds_read_b128 v[170:173], v142 offset:2048
	ds_read_b128 v[174:177], v142 offset:3072
	v_add_u32_e32 v142, s75, v148
	ds_read_b128 v[178:181], v142
	ds_read_b128 v[182:185], v142 offset:1024
	ds_read_b128 v[186:189], v142 offset:2048
	ds_read_b128 v[190:193], v142 offset:3072
	s_add_u32 s98, s30, 0xfff80000
	s_addc_u32 s99, s31, -1
	v_lshl_add_u64 v[144:145], s[98:99], 0, v[138:139]
	s_mov_b32 m0, s57
	s_nop 0
	global_load_lds_dwordx4 v[144:145], off
	v_lshl_add_u64 v[144:145], s[98:99], 0, v[140:141]
	s_mov_b32 m0, s58
	s_nop 0
	global_load_lds_dwordx4 v[144:145], off
	v_lshl_add_u64 v[144:145], s[30:31], 0, v[138:139]
	s_add_i32 m0, s53, 0xc000
	ds_read_b128 v[200:203], v151
	ds_read_b128 v[204:207], v151 offset:1024
	ds_read_b128 v[208:211], v151 offset:2048
	ds_read_b128 v[212:215], v151 offset:3072
	ds_read_b128 v[216:219], v151 offset:4096
	ds_read_b128 v[220:223], v151 offset:5120
	ds_read_b128 v[224:227], v151 offset:6144
	ds_read_b128 v[228:231], v151 offset:7168
	global_load_lds_dwordx4 v[144:145], off
	v_lshl_add_u64 v[144:145], s[30:31], 0, v[140:141]
	s_add_i32 m0, s53, 0xe000
	s_nop 0
	global_load_lds_dwordx4 v[144:145], off
	s_waitcnt vmcnt(8)
	s_waitcnt lgkmcnt(0)
	s_barrier
	s_setprio 2
	s_waitcnt lgkmcnt(0)
	v_mfma_f32_16x16x32_bf16 v[126:129], v[152:155], v[200:203], v[126:129]
	v_mfma_f32_16x16x32_bf16 v[122:125], v[170:173], v[200:203], v[122:125]
	v_mfma_f32_16x16x32_bf16 v[110:113], v[152:155], v[208:211], v[110:113]
	v_mfma_f32_16x16x32_bf16 v[106:109], v[170:173], v[208:211], v[106:109]
	v_mfma_f32_16x16x32_bf16 v[94:97], v[152:155], v[216:219], v[94:97]
	v_mfma_f32_16x16x32_bf16 v[90:93], v[170:173], v[216:219], v[90:93]
	v_mfma_f32_16x16x32_bf16 v[78:81], v[152:155], v[224:227], v[78:81]
	v_mfma_f32_16x16x32_bf16 v[74:77], v[170:173], v[224:227], v[74:77]
	v_mfma_f32_16x16x32_bf16 v[126:129], v[166:169], v[204:207], v[126:129]
	v_mfma_f32_16x16x32_bf16 v[122:125], v[174:177], v[204:207], v[122:125]
	v_mfma_f32_16x16x32_bf16 v[110:113], v[166:169], v[212:215], v[110:113]
	v_mfma_f32_16x16x32_bf16 v[106:109], v[174:177], v[212:215], v[106:109]
	v_mfma_f32_16x16x32_bf16 v[94:97], v[166:169], v[220:223], v[94:97]
	v_mfma_f32_16x16x32_bf16 v[90:93], v[174:177], v[220:223], v[90:93]
	v_mfma_f32_16x16x32_bf16 v[78:81], v[166:169], v[228:231], v[78:81]
	v_mfma_f32_16x16x32_bf16 v[74:77], v[174:177], v[228:231], v[74:77]
	v_mfma_f32_16x16x32_bf16 v[118:121], v[178:181], v[200:203], v[118:121]
	v_mfma_f32_16x16x32_bf16 v[114:117], v[186:189], v[200:203], v[114:117]
	v_mfma_f32_16x16x32_bf16 v[102:105], v[178:181], v[208:211], v[102:105]
	v_mfma_f32_16x16x32_bf16 v[98:101], v[186:189], v[208:211], v[98:101]
	v_mfma_f32_16x16x32_bf16 v[86:89], v[178:181], v[216:219], v[86:89]
	v_mfma_f32_16x16x32_bf16 v[82:85], v[186:189], v[216:219], v[82:85]
	v_mfma_f32_16x16x32_bf16 v[70:73], v[178:181], v[224:227], v[70:73]
	v_mfma_f32_16x16x32_bf16 v[66:69], v[186:189], v[224:227], v[66:69]
	v_mfma_f32_16x16x32_bf16 v[118:121], v[182:185], v[204:207], v[118:121]
	v_mfma_f32_16x16x32_bf16 v[114:117], v[190:193], v[204:207], v[114:117]
	v_mfma_f32_16x16x32_bf16 v[102:105], v[182:185], v[212:215], v[102:105]
	v_mfma_f32_16x16x32_bf16 v[98:101], v[190:193], v[212:215], v[98:101]
	v_mfma_f32_16x16x32_bf16 v[86:89], v[182:185], v[220:223], v[86:89]
	v_mfma_f32_16x16x32_bf16 v[82:85], v[190:193], v[220:223], v[82:85]
	v_mfma_f32_16x16x32_bf16 v[70:73], v[182:185], v[228:231], v[70:73]
	v_mfma_f32_16x16x32_bf16 v[66:69], v[190:193], v[228:231], v[66:69]
	s_setprio 0
	s_add_i32 s70, s70, s52
	v_lshl_add_u64 v[144:145], s[36:37], 0, v[158:159]
	s_mov_b32 m0, s70
	ds_read_b128 v[200:203], v151 offset:16384
	ds_read_b128 v[204:207], v151 offset:17408
	ds_read_b128 v[208:211], v151 offset:18432
	ds_read_b128 v[212:215], v151 offset:19456
	ds_read_b128 v[216:219], v151 offset:20480
	ds_read_b128 v[220:223], v151 offset:21504
	ds_read_b128 v[224:227], v151 offset:22528
	ds_read_b128 v[228:231], v151 offset:23552
	global_load_lds_dwordx4 v[144:145], off
	s_add_i32 m0, s70, 0x2000
	s_add_u32 s70, s36, 0x80000
	v_lshl_add_u64 v[156:157], s[36:37], 0, v[134:135]
	s_addc_u32 s71, s37, 0
	s_add_i32 s75, s75, s52
	global_load_lds_dwordx4 v[156:157], off
	v_lshl_add_u64 v[162:163], s[70:71], 0, v[158:159]
	s_mov_b32 m0, s75
	v_lshl_add_u64 v[164:165], s[38:39], 0, v[132:133]
	global_load_lds_dwordx4 v[162:163], off
	v_lshl_add_u64 v[162:163], s[70:71], 0, v[134:135]
	s_add_i32 m0, s75, 0x2000
	s_nop 0
	global_load_lds_dwordx4 v[162:163], off
	v_lshl_add_u64 v[162:163], s[38:39], 0, v[130:131]
	s_waitcnt vmcnt(6)
	s_waitcnt lgkmcnt(0)
	s_barrier
; #define PG8_STAGE(bufoff, gbase, voff) do { _Pragma("unroll") for (int _i = 0; _i < 2; ++_i) \
;         __builtin_amdgcn_global_load_lds((const unsigned*)((const char*)(gbase) + (voff)[_i]), (PG8_LAS unsigned*)(lds + (bufoff) + ldsw + _i * 8192), 16, 0, 0); } while (0)
; #define PG8_LDA(dst, b, h) do { _Pragma("unroll") for (int m = 0; m < 4; ++m) _Pragma("unroll") for (int k = 0; k < 2; ++k) dst[m][k] = *(const PG8_LAS bf16x8*)(lds + PG8_SA(b, h) + aoff + m * 2048 + k * 1024); } while (0)
; #define PG8_LDB(dst, b, h) do { _Pragma("unroll") for (int n = 0; n < 2; ++n) _Pragma("unroll") for (int k = 0; k < 2; ++k) dst[n][k] = *(const PG8_LAS bf16x8*)(lds + PG8_SB(b, h) + boff + n * 2048 + k * 1024); } while (0)
; #define PG8_MMA(ai, bj, At, Bt) do { __builtin_amdgcn_s_setprio(1); _Pragma("unroll") for (int m = 0; m < 4; ++m) _Pragma("unroll") for (int n = 0; n < 2; ++n) _Pragma("unroll") for (int k = 0; k < 2; ++k) \
;         acc[ai][bj][m][n] = __builtin_amdgcn_mfma_f32_16x16x32_bf16(Bt[n][k], At[m][k], acc[ai][bj][m][n], 0, 0, 0); __builtin_amdgcn_s_setprio(0); } while (0)
; #define PG8_WAIT_V(n) asm volatile("s_waitcnt vmcnt(" #n ")" ::: "memory")
; #define PG8_WAIT_L(n) asm volatile("s_waitcnt lgkmcnt(" #n ")" ::: "memory")
; #define PG8_BAR __builtin_amdgcn_s_barrier()
; #define PG8_SCHED __builtin_amdgcn_sched_barrier(0)
; template <class Epi, class Sched, bool ALIGN_EPI = false, bool SP2 = false>
; __device__ __forceinline__ void gemm_phase(PG8_LAS unsigned char* lds, const Gemm g, const Sched& S, const Epi& E) {
;     ...
;             PG8_WAIT_V(8); PG8_WAIT_L(0); PG8_BAR; PG8_MMA(1, 0, At, B0); PG8_MMA(1, 1, At, B1); PG8_BAR; PG8_SCHED;
;             PG8_LDB(B0, 1, 0); PG8_LDB(B1, 1, 1); PG8_SCHED; PG8_LDA(At, 1, 0); PG8_STAGE(PG8_SA(0, 1), a2 + hstep, voffA);
	s_setprio 2
	s_waitcnt lgkmcnt(0)
	v_mfma_f32_16x16x32_bf16 v[62:65], v[152:155], v[200:203], v[62:65]
	v_mfma_f32_16x16x32_bf16 v[58:61], v[170:173], v[200:203], v[58:61]
	v_mfma_f32_16x16x32_bf16 v[46:49], v[152:155], v[208:211], v[46:49]
	v_mfma_f32_16x16x32_bf16 v[42:45], v[170:173], v[208:211], v[42:45]
	v_mfma_f32_16x16x32_bf16 v[30:33], v[152:155], v[216:219], v[30:33]
	v_mfma_f32_16x16x32_bf16 v[26:29], v[170:173], v[216:219], v[26:29]
	v_mfma_f32_16x16x32_bf16 v[14:17], v[152:155], v[224:227], v[14:17]
	v_mfma_f32_16x16x32_bf16 v[10:13], v[170:173], v[224:227], v[10:13]
	v_mfma_f32_16x16x32_bf16 v[62:65], v[166:169], v[204:207], v[62:65]
	v_mfma_f32_16x16x32_bf16 v[58:61], v[174:177], v[204:207], v[58:61]
	v_mfma_f32_16x16x32_bf16 v[46:49], v[166:169], v[212:215], v[46:49]
	v_mfma_f32_16x16x32_bf16 v[42:45], v[174:177], v[212:215], v[42:45]
	v_mfma_f32_16x16x32_bf16 v[30:33], v[166:169], v[220:223], v[30:33]
	v_mfma_f32_16x16x32_bf16 v[26:29], v[174:177], v[220:223], v[26:29]
	v_mfma_f32_16x16x32_bf16 v[14:17], v[166:169], v[228:231], v[14:17]
	v_mfma_f32_16x16x32_bf16 v[10:13], v[174:177], v[228:231], v[10:13]
	v_mfma_f32_16x16x32_bf16 v[54:57], v[178:181], v[200:203], v[54:57]
	v_mfma_f32_16x16x32_bf16 v[50:53], v[186:189], v[200:203], v[50:53]
	v_mfma_f32_16x16x32_bf16 v[38:41], v[178:181], v[208:211], v[38:41]
	v_mfma_f32_16x16x32_bf16 v[34:37], v[186:189], v[208:211], v[34:37]
	v_mfma_f32_16x16x32_bf16 v[22:25], v[178:181], v[216:219], v[22:25]
	v_mfma_f32_16x16x32_bf16 v[18:21], v[186:189], v[216:219], v[18:21]
	v_mfma_f32_16x16x32_bf16 v[6:9], v[178:181], v[224:227], v[6:9]
	v_mfma_f32_16x16x32_bf16 v[2:5], v[186:189], v[224:227], v[2:5]
	v_mfma_f32_16x16x32_bf16 v[54:57], v[182:185], v[204:207], v[54:57]
	v_mfma_f32_16x16x32_bf16 v[50:53], v[190:193], v[204:207], v[50:53]
	v_mfma_f32_16x16x32_bf16 v[38:41], v[182:185], v[212:215], v[38:41]
	v_mfma_f32_16x16x32_bf16 v[34:37], v[190:193], v[212:215], v[34:37]
	v_mfma_f32_16x16x32_bf16 v[22:25], v[182:185], v[220:223], v[22:25]
	v_mfma_f32_16x16x32_bf16 v[18:21], v[190:193], v[220:223], v[18:21]
	v_mfma_f32_16x16x32_bf16 v[6:9], v[182:185], v[228:231], v[6:9]
	v_mfma_f32_16x16x32_bf16 v[2:5], v[190:193], v[228:231], v[2:5]
	s_setprio 0
	s_add_i32 s70, 0, 0x18000
	v_add_u32_e32 v142, s70, v148
	s_add_i32 s71, 0, 0x1c000
	ds_read_b128 v[152:155], v142
	ds_read_b128 v[166:169], v142 offset:1024
	ds_read_b128 v[170:173], v142 offset:2048
	ds_read_b128 v[174:177], v142 offset:3072
	v_add_u32_e32 v142, s71, v148
	ds_read_b128 v[178:181], v142
	ds_read_b128 v[182:185], v142 offset:1024
	ds_read_b128 v[186:189], v142 offset:2048
	ds_read_b128 v[190:193], v142 offset:3072
	s_add_u32 s38, s38, 0x80000
	s_addc_u32 s39, s39, 0
	s_mov_b32 m0, s53
	s_nop 0
	global_load_lds_dwordx4 v[162:163], off
	s_mov_b32 m0, s54
	s_nop 0
	global_load_lds_dwordx4 v[164:165], off
	s_mov_b32 m0, s55
	v_lshl_add_u64 v[232:233], s[38:39], 0, v[130:131]
	ds_read_b128 v[200:203], v151 offset:32768
	ds_read_b128 v[204:207], v151 offset:33792
	ds_read_b128 v[208:211], v151 offset:34816
	ds_read_b128 v[212:215], v151 offset:35840
	ds_read_b128 v[216:219], v151 offset:36864
	ds_read_b128 v[220:223], v151 offset:37888
	ds_read_b128 v[224:227], v151 offset:38912
	ds_read_b128 v[228:231], v151 offset:39936
	global_load_lds_dwordx4 v[232:233], off
	v_lshl_add_u64 v[232:233], s[38:39], 0, v[132:133]
	s_mov_b32 m0, s56
	s_nop 0
	global_load_lds_dwordx4 v[232:233], off
	s_waitcnt vmcnt(8)
	s_waitcnt lgkmcnt(0)
	s_barrier
; #define PG8_STAGE(bufoff, gbase, voff) do { _Pragma("unroll") for (int _i = 0; _i < 2; ++_i) \
;         __builtin_amdgcn_global_load_lds((const unsigned*)((const char*)(gbase) + (voff)[_i]), (PG8_LAS unsigned*)(lds + (bufoff) + ldsw + _i * 8192), 16, 0, 0); } while (0)
; #define PG8_LDA(dst, b, h) do { _Pragma("unroll") for (int m = 0; m < 4; ++m) _Pragma("unroll") for (int k = 0; k < 2; ++k) dst[m][k] = *(const PG8_LAS bf16x8*)(lds + PG8_SA(b, h) + aoff + m * 2048 + k * 1024); } while (0)
; #define PG8_LDB(dst, b, h) do { _Pragma("unroll") for (int n = 0; n < 2; ++n) _Pragma("unroll") for (int k = 0; k < 2; ++k) dst[n][k] = *(const PG8_LAS bf16x8*)(lds + PG8_SB(b, h) + boff + n * 2048 + k * 1024); } while (0)
; #define PG8_MMA(ai, bj, At, Bt) do { __builtin_amdgcn_s_setprio(1); _Pragma("unroll") for (int m = 0; m < 4; ++m) _Pragma("unroll") for (int n = 0; n < 2; ++n) _Pragma("unroll") for (int k = 0; k < 2; ++k) \
;         acc[ai][bj][m][n] = __builtin_amdgcn_mfma_f32_16x16x32_bf16(Bt[n][k], At[m][k], acc[ai][bj][m][n], 0, 0, 0); __builtin_amdgcn_s_setprio(0); } while (0)
; #define PG8_WAIT_V(n) asm volatile("s_waitcnt vmcnt(" #n ")" ::: "memory")
; #define PG8_WAIT_L(n) asm volatile("s_waitcnt lgkmcnt(" #n ")" ::: "memory")
; #define PG8_BAR __builtin_amdgcn_s_barrier()
; #define PG8_SCHED __builtin_amdgcn_sched_barrier(0)
; template <class Epi, class Sched, bool ALIGN_EPI = false, bool SP2 = false>
; __device__ __forceinline__ void gemm_phase(PG8_LAS unsigned char* lds, const Gemm g, const Sched& S, const Epi& E) {
;     ...
;             PG8_LDB(B0, 1, 0); PG8_LDB(B1, 1, 1); PG8_SCHED; PG8_LDA(At, 1, 0); PG8_STAGE(PG8_SA(0, 1), a2 + hstep, voffA);
;             PG8_WAIT_V(8); PG8_WAIT_L(0); PG8_BAR; PG8_MMA(0, 0, At, B0); PG8_MMA(0, 1, At, B1); PG8_BAR; PG8_SCHED;
;             PG8_LDA(At, 1, 1); PG8_STAGE(PG8_SB(1, 0), b3, voffB); PG8_STAGE(PG8_SB(1, 1), b3 + hstep, voffB); PG8_STAGE(PG8_SA(1, 0), a3, voffA);
;             PG8_WAIT_V(8); PG8_WAIT_L(0); PG8_BAR; PG8_MMA(1, 0, At, B0); PG8_MMA(1, 1, At, B1); PG8_BAR; PG8_SCHED;
;     ...
;         if constexpr (ALIGN_EPI) { if (wr == 0) PG8_BAR; }
	s_setprio 2
	s_waitcnt lgkmcnt(0)
	v_mfma_f32_16x16x32_bf16 v[126:129], v[152:155], v[200:203], v[126:129]
	v_mfma_f32_16x16x32_bf16 v[122:125], v[170:173], v[200:203], v[122:125]
	v_mfma_f32_16x16x32_bf16 v[110:113], v[152:155], v[208:211], v[110:113]
	v_mfma_f32_16x16x32_bf16 v[106:109], v[170:173], v[208:211], v[106:109]
	v_mfma_f32_16x16x32_bf16 v[94:97], v[152:155], v[216:219], v[94:97]
	v_mfma_f32_16x16x32_bf16 v[90:93], v[170:173], v[216:219], v[90:93]
	v_mfma_f32_16x16x32_bf16 v[78:81], v[152:155], v[224:227], v[78:81]
	v_mfma_f32_16x16x32_bf16 v[74:77], v[170:173], v[224:227], v[74:77]
	v_mfma_f32_16x16x32_bf16 v[126:129], v[166:169], v[204:207], v[126:129]
	v_mfma_f32_16x16x32_bf16 v[122:125], v[174:177], v[204:207], v[122:125]
	v_mfma_f32_16x16x32_bf16 v[110:113], v[166:169], v[212:215], v[110:113]
	v_mfma_f32_16x16x32_bf16 v[106:109], v[174:177], v[212:215], v[106:109]
	v_mfma_f32_16x16x32_bf16 v[94:97], v[166:169], v[220:223], v[94:97]
	v_mfma_f32_16x16x32_bf16 v[90:93], v[174:177], v[220:223], v[90:93]
	v_mfma_f32_16x16x32_bf16 v[78:81], v[166:169], v[228:231], v[78:81]
	v_mfma_f32_16x16x32_bf16 v[74:77], v[174:177], v[228:231], v[74:77]
	v_mfma_f32_16x16x32_bf16 v[118:121], v[178:181], v[200:203], v[118:121]
	v_mfma_f32_16x16x32_bf16 v[114:117], v[186:189], v[200:203], v[114:117]
	v_mfma_f32_16x16x32_bf16 v[102:105], v[178:181], v[208:211], v[102:105]
	v_mfma_f32_16x16x32_bf16 v[98:101], v[186:189], v[208:211], v[98:101]
	v_mfma_f32_16x16x32_bf16 v[86:89], v[178:181], v[216:219], v[86:89]
	v_mfma_f32_16x16x32_bf16 v[82:85], v[186:189], v[216:219], v[82:85]
	v_mfma_f32_16x16x32_bf16 v[70:73], v[178:181], v[224:227], v[70:73]
	v_mfma_f32_16x16x32_bf16 v[66:69], v[186:189], v[224:227], v[66:69]
	v_mfma_f32_16x16x32_bf16 v[118:121], v[182:185], v[204:207], v[118:121]
	v_mfma_f32_16x16x32_bf16 v[114:117], v[190:193], v[204:207], v[114:117]
	v_mfma_f32_16x16x32_bf16 v[102:105], v[182:185], v[212:215], v[102:105]
	v_mfma_f32_16x16x32_bf16 v[98:101], v[190:193], v[212:215], v[98:101]
	v_mfma_f32_16x16x32_bf16 v[86:89], v[182:185], v[220:223], v[86:89]
	v_mfma_f32_16x16x32_bf16 v[82:85], v[190:193], v[220:223], v[82:85]
	v_mfma_f32_16x16x32_bf16 v[70:73], v[182:185], v[228:231], v[70:73]
	v_mfma_f32_16x16x32_bf16 v[66:69], v[190:193], v[228:231], v[66:69]
	s_setprio 0
	s_add_i32 s38, s70, s52
	v_lshl_add_u64 v[144:145], v[144:145], 0, s[10:11]
	s_mov_b32 m0, s38
	ds_read_b128 v[200:203], v151 offset:49152
	ds_read_b128 v[204:207], v151 offset:50176
	ds_read_b128 v[208:211], v151 offset:51200
	ds_read_b128 v[212:215], v151 offset:52224
	ds_read_b128 v[216:219], v151 offset:53248
	ds_read_b128 v[220:223], v151 offset:54272
	ds_read_b128 v[224:227], v151 offset:55296
	ds_read_b128 v[228:231], v151 offset:56320
	global_load_lds_dwordx4 v[144:145], off
	s_add_i32 m0, s38, 0x2000
	s_add_u32 s36, s36, 0x80080
	v_lshl_add_u64 v[144:145], v[156:157], 0, s[10:11]
	s_addc_u32 s37, s37, 0
	s_add_i32 s38, s71, s52
	global_load_lds_dwordx4 v[144:145], off
	v_lshl_add_u64 v[144:145], s[36:37], 0, v[158:159]
	s_mov_b32 m0, s38
	s_nop 0
	global_load_lds_dwordx4 v[144:145], off
	v_lshl_add_u64 v[144:145], s[36:37], 0, v[134:135]
	s_add_i32 m0, s38, 0x2000
	s_nop 0
	global_load_lds_dwordx4 v[144:145], off
	s_waitcnt vmcnt(6)
	s_waitcnt lgkmcnt(0)
	s_barrier
	s_setprio 2
	s_waitcnt lgkmcnt(0)
	v_mfma_f32_16x16x32_bf16 v[62:65], v[152:155], v[200:203], v[62:65]
	v_mfma_f32_16x16x32_bf16 v[58:61], v[170:173], v[200:203], v[58:61]
	v_mfma_f32_16x16x32_bf16 v[46:49], v[152:155], v[208:211], v[46:49]
	v_mfma_f32_16x16x32_bf16 v[42:45], v[170:173], v[208:211], v[42:45]
	v_mfma_f32_16x16x32_bf16 v[30:33], v[152:155], v[216:219], v[30:33]
	v_mfma_f32_16x16x32_bf16 v[26:29], v[170:173], v[216:219], v[26:29]
	v_mfma_f32_16x16x32_bf16 v[14:17], v[152:155], v[224:227], v[14:17]
	v_mfma_f32_16x16x32_bf16 v[10:13], v[170:173], v[224:227], v[10:13]
	v_mfma_f32_16x16x32_bf16 v[62:65], v[166:169], v[204:207], v[62:65]
	v_mfma_f32_16x16x32_bf16 v[58:61], v[174:177], v[204:207], v[58:61]
	v_mfma_f32_16x16x32_bf16 v[46:49], v[166:169], v[212:215], v[46:49]
	v_mfma_f32_16x16x32_bf16 v[42:45], v[174:177], v[212:215], v[42:45]
	v_mfma_f32_16x16x32_bf16 v[30:33], v[166:169], v[220:223], v[30:33]
	v_mfma_f32_16x16x32_bf16 v[26:29], v[174:177], v[220:223], v[26:29]
	v_mfma_f32_16x16x32_bf16 v[14:17], v[166:169], v[228:231], v[14:17]
	v_mfma_f32_16x16x32_bf16 v[10:13], v[174:177], v[228:231], v[10:13]
	v_mfma_f32_16x16x32_bf16 v[54:57], v[178:181], v[200:203], v[54:57]
	v_mfma_f32_16x16x32_bf16 v[50:53], v[186:189], v[200:203], v[50:53]
	v_mfma_f32_16x16x32_bf16 v[38:41], v[178:181], v[208:211], v[38:41]
	v_mfma_f32_16x16x32_bf16 v[34:37], v[186:189], v[208:211], v[34:37]
	v_mfma_f32_16x16x32_bf16 v[22:25], v[178:181], v[216:219], v[22:25]
	v_mfma_f32_16x16x32_bf16 v[18:21], v[186:189], v[216:219], v[18:21]
	v_mfma_f32_16x16x32_bf16 v[6:9], v[178:181], v[224:227], v[6:9]
	v_mfma_f32_16x16x32_bf16 v[2:5], v[186:189], v[224:227], v[2:5]
	v_mfma_f32_16x16x32_bf16 v[54:57], v[182:185], v[204:207], v[54:57]
	v_mfma_f32_16x16x32_bf16 v[50:53], v[190:193], v[204:207], v[50:53]
	v_mfma_f32_16x16x32_bf16 v[38:41], v[182:185], v[212:215], v[38:41]
	v_mfma_f32_16x16x32_bf16 v[34:37], v[190:193], v[212:215], v[34:37]
	v_mfma_f32_16x16x32_bf16 v[22:25], v[182:185], v[220:223], v[22:25]
	v_mfma_f32_16x16x32_bf16 v[18:21], v[190:193], v[220:223], v[18:21]
	v_mfma_f32_16x16x32_bf16 v[6:9], v[182:185], v[228:231], v[6:9]
	v_mfma_f32_16x16x32_bf16 v[2:5], v[190:193], v[228:231], v[2:5]
	s_setprio 0
	s_add_i32 s69, s69, 2
	s_add_u32 s30, s30, 0x100
	s_addc_u32 s31, s31, 0
	s_add_u32 s67, s67, 0x100
	s_addc_u32 s68, s68, 0
	s_cmp_gt_u32 s69, 29
	s_cbranch_scc0 .Lhb_T_139
.Lhb_X_139:
	s_and_b64 vcc, exec, s[16:17]
	s_cbranch_vccz .LBB0_142

; #define PG8_BAR __builtin_amdgcn_s_barrier()
; template <class Epi, class Sched, bool ALIGN_EPI = false, bool SP2 = false>
; __device__ __forceinline__ void gemm_phase(PG8_LAS unsigned char* lds, const Gemm g, const Sched& S, const Epi& E) {
;     ...
;         cur = nxt; cA = nA; cB = nB; ++ui;
;         if constexpr (Epi::HAS_PREP) { if (cur.pm != prep_pm) { ++prep_gen; E.prep(cur, tid, prep_gen & 1); prep_pm = cur.pm; } }
;         if constexpr (ALIGN_EPI) { if (wr == 1) PG8_BAR; }
.LBB0_163:
	s_andn2_b64 vcc, exec, s[14:15]
	s_cbranch_vccnz .LBB0_134
	s_branch .LBB0_134

.LBB0_424:
	s_add_i32 s17, s17, 1
	s_mov_b64 s[12:13], 0
	s_branch .LBB0_418
.Ltr_122:
	s_branch .LBB0_122
.Ltr_123:
	s_branch .LBB0_123
.Ltr_124:
	s_branch .LBB0_124
.Ltr_939:
	s_branch .LBB0_939
.LBB0_425:
	s_cmp_lt_u32 s17, 0x40001
	s_mov_b64 s[4:5], 0
	s_cselect_b64 s[14:15], -1, 0
	s_and_b64 vcc, exec, s[14:15]
	s_cbranch_vccz .LBB0_418
	s_branch .LBB0_424

; #define PG8_STAGE(bufoff, gbase, voff) do { _Pragma("unroll") for (int _i = 0; _i < 2; ++_i) \
;         __builtin_amdgcn_global_load_lds((const unsigned*)((const char*)(gbase) + (voff)[_i]), (PG8_LAS unsigned*)(lds + (bufoff) + ldsw + _i * 8192), 16, 0, 0); } while (0)
; #define PG8_WAIT_V(n) asm volatile("s_waitcnt vmcnt(" #n ")" ::: "memory")
; #define PG8_BAR __builtin_amdgcn_s_barrier()
; template <class Epi, class Sched, bool ALIGN_EPI = false, bool SP2 = false>
; __device__ __forceinline__ void gemm_phase(PG8_LAS unsigned char* lds, const Gemm g, const Sched& S, const Epi& E) {
;     ...
;     for (int i = 0; i < 2; ++i) { int R, C; stage_rc(tid * 16 + i * 8192, R, C); const int Rb = Epi::PERM ? ((R & ~31) + perm32(R & 31)) : R;
;         voffA[i] = (unsigned)(R * K + C) * 2u; voffB[i] = (unsigned)(Rb * K + C) * 2u; }
;     const size_t kstep = (size_t)(BK * 2);
;     const size_t hstep = (size_t)HALF * K * 2;
;     const size_t tstep = 2 * hstep;
;     const unsigned ldsw = (unsigned)wid * 1024u;
;     const int aoff = lds_byte(wr * 64 + fr, fq * 8), boff = lds_byte(wc * 32 + fr, fq * 8);
;     ...
;     if constexpr (SP2) {
;         PG8_STAGE(PG8_SB(0, 0), cB, voffB); PG8_STAGE(PG8_SB(0, 1), cB + hstep, voffB); PG8_STAGE(PG8_SA(0, 0), cA, voffA); PG8_STAGE(PG8_SA(0, 1), cA + hstep, voffA);
;         if (wr == 1) PG8_BAR;
;         PG8_WAIT_V(2); PG8_BAR;
;         PG8_STAGE(PG8_SB(1, 0), cB + kstep, voffB); PG8_STAGE(PG8_SA(1, 0), cA + kstep, voffA); PG8_STAGE(PG8_SB(1, 1), cB + hstep + kstep, voffB);
;         PG8_WAIT_V(6); PG8_BAR;
.LBB0_653:
	s_andn2_b64 vcc, exec, s[0:1]
	v_readlane_b32 s0, v254, 39
	v_readlane_b32 s1, v254, 40
	s_waitcnt vmcnt(0)
	s_nop 0
	v_cndmask_b32_e64 v2, 0, 1, s[0:1]
	v_cmp_ne_u32_e64 s[40:41], 1, v2
	s_cbranch_vccnz .LBB0_744
	v_readlane_b32 s0, v253, 0
	v_mov_b32_e32 v2, v0
	v_readlane_b32 s1, v253, 1
	v_mov_b32_e32 v16, v0
	s_and_b64 vcc, exec, s[40:41]
	v_readfirstlane_b32 s16, v16
	s_cbranch_vccnz .LBB0_690
	v_lshlrev_b32_e32 v2, 4, v16
	s_waitcnt lgkmcnt(0)
	v_add_u32_e32 v3, 0x2000, v2
	v_ashrrev_i32_e32 v4, 31, v3
	v_lshrrev_b32_e32 v4, 22, v4
	v_add_u32_e32 v4, v3, v4
	v_ashrrev_i32_e32 v10, 10, v4
	s_load_dwordx2 s[14:15], s[0:1], 0x78
	v_mul_i32_i24_e32 v4, 0x400, v10
	v_sub_u32_e32 v3, v3, v4
	v_lshrrev_b32_e32 v4, 4, v3
	v_bitop3_b32 v3, v4, v3, 32 bitop3:0x6c
	v_ashrrev_i32_e32 v4, 31, v3
	s_waitcnt lgkmcnt(0)
	s_add_u32 s21, s14, 0x21800000
	v_lshrrev_b32_e32 v4, 26, v4
	s_addc_u32 s38, s15, 0
	s_lshl_b32 s0, s86, 23
	v_add_u32_e32 v4, v3, v4
	v_lshlrev_b32_e32 v5, 3, v10
	s_add_u32 s0, s14, s0
	v_ashrrev_i32_e32 v11, 6, v4
	v_and_b32_e32 v5, -16, v5
	s_addc_u32 s1, s15, 0
	v_add_u32_e32 v5, v11, v5
	s_add_u32 s39, s0, 0xb800000
	v_and_b32_e32 v6, 3, v11
	s_mov_b32 s0, 0xfffe0
	v_lshrrev_b32_e32 v7, 2, v5
	v_lshlrev_b32_e32 v8, 1, v5
	v_and_b32_e32 v4, 0xc0, v4
	v_and_or_b32 v6, v5, s0, v6
	v_and_b32_e32 v7, 4, v7
	v_and_b32_e32 v8, 24, v8
	v_sub_u32_e32 v3, v3, v4
	v_or3_b32 v6, v6, v7, v8
	v_lshlrev_b32_e32 v7, 5, v10
	v_ashrrev_i16_sdwa v3, v194, sext(v3) dst_sel:DWORD dst_unused:UNUSED_PAD src0_sel:DWORD src1_sel:BYTE_0
	v_and_b32_e32 v7, 32, v7
	v_bfe_i32 v12, v3, 0, 16
	v_add_lshl_u32 v3, v7, v12, 1
	v_lshl_add_u32 v166, v6, 12, v3
	v_lshl_add_u32 v168, v5, 12, v3
	v_bfe_i32 v3, v16, 27, 1
	v_lshrrev_b32_e32 v3, 22, v3
	v_add_u32_e32 v3, v2, v3
	v_and_b32_e32 v3, 0xfffffc00, v3
	v_sub_u32_e32 v2, v2, v3
	v_lshrrev_b32_e32 v3, 4, v2
	v_ashrrev_i32_e32 v4, 31, v16
	v_bitop3_b32 v2, v3, v2, 32 bitop3:0x6c
	v_lshrrev_b32_e32 v4, 26, v4
	v_ashrrev_i32_e32 v3, 31, v2
	v_add_u32_e32 v4, v16, v4
	v_lshrrev_b32_e32 v3, 26, v3
	v_ashrrev_i32_e32 v14, 6, v4
	v_add_u32_e32 v3, v2, v3
	v_lshlrev_b32_e32 v4, 3, v14
	v_ashrrev_i32_e32 v13, 6, v3
	v_and_b32_e32 v4, -16, v4
	v_add_u32_e32 v4, v13, v4
	v_and_b32_e32 v5, 3, v13
	v_lshrrev_b32_e32 v6, 2, v4
	v_lshlrev_b32_e32 v7, 1, v4
	v_and_b32_e32 v3, 0xc0, v3
	s_addc_u32 s46, s1, 0
	s_ashr_i32 s18, s16, 6
	v_and_or_b32 v5, v4, s0, v5
	v_and_b32_e32 v6, 4, v6
	v_and_b32_e32 v7, 24, v7
	v_sub_u32_e32 v2, v2, v3
	s_ashr_i32 s17, s16, 8
	s_lshl_b32 s47, s18, 10
	v_or3_b32 v5, v5, v6, v7
	v_lshlrev_b32_e32 v6, 5, v14
	v_ashrrev_i16_sdwa v2, v194, sext(v2) dst_sel:DWORD dst_unused:UNUSED_PAD src0_sel:DWORD src1_sel:BYTE_0
	v_readlane_b32 s0, v254, 54
	v_and_b32_e32 v6, 32, v6
	v_bfe_i32 v15, v2, 0, 16
	v_readlane_b32 s1, v254, 55
	s_add_u32 s30, s39, s0
	v_add_lshl_u32 v2, v6, v15, 1
	s_addc_u32 s31, s46, s1
	s_add_i32 s48, s47, 0
	v_lshl_add_u32 v158, v5, 12, v2
	s_add_i32 m0, s48, 0x10000
	v_lshl_add_u32 v170, v4, 12, v2
	global_load_lds_dwordx4 v158, s[30:31]
	s_add_i32 m0, s48, 0x12000
	s_add_u32 s0, s30, 0x80000
	global_load_lds_dwordx4 v166, s[30:31]
	s_addc_u32 s1, s31, 0
	s_add_i32 m0, s48, 0x14000
	v_mov_b32_e32 v167, v159
	global_load_lds_dwordx4 v158, s[0:1]
	s_add_i32 m0, s48, 0x16000
	v_mov_b32_e32 v171, v159
	global_load_lds_dwordx4 v166, s[0:1]
	v_readlane_b32 s0, v252, 24
	v_readlane_b32 s1, v252, 25
	s_add_u32 s0, s21, s0
	s_addc_u32 s1, s38, s1
	s_add_i32 s49, s48, 0x2000
	s_mov_b32 m0, s48
	s_add_u32 s4, s0, 0x80000
	global_load_lds_dwordx4 v170, s[0:1]
	s_mov_b32 m0, s49
	s_addc_u32 s5, s1, 0
	s_add_i32 s50, s48, 0x4000
	global_load_lds_dwordx4 v168, s[0:1]
	s_mov_b32 m0, s50
	s_add_i32 s51, s48, 0x6000
	global_load_lds_dwordx4 v170, s[4:5]
	s_mov_b32 m0, s51
	v_mov_b32_e32 v169, v159
	global_load_lds_dwordx4 v168, s[4:5]
	v_readlane_b32 s4, v253, 6
	v_readlane_b32 s5, v253, 7
	s_load_dword s52, s[4:5], 0x0
	s_cmp_eq_u32 s17, 1
	v_lshl_add_u64 v[8:9], s[30:31], 0, v[158:159]
	v_lshl_add_u64 v[6:7], s[30:31], 0, v[166:167]
	v_lshl_add_u64 v[2:3], s[0:1], 0, v[170:171]
	s_cselect_b64 s[4:5], -1, 0
	s_cmp_lg_u32 s17, 1
	v_lshl_add_u64 v[4:5], s[0:1], 0, v[168:169]
	s_cbranch_scc1 .LBB0_657
.LBB0_657:
	s_add_u32 s12, s14, 0x1d800000
	s_addc_u32 s13, s15, 0
	v_bfe_u32 v17, v16, 4, 2
	s_add_u32 s14, s14, 0xc00000
	v_and_b32_e32 v18, 15, v16
	v_lshlrev_b32_e32 v20, 4, v17
	v_lshlrev_b32_e32 v16, 2, v16
	s_addc_u32 s15, s15, 0
	s_and_b32 s53, s18, 3
	v_lshl_or_b32 v161, s17, 6, v18
	v_lshl_or_b32 v18, v18, 6, v20
	s_lshl_b32 s17, s17, 13
	v_and_b32_e32 v16, 32, v16
	s_add_i32 m0, s48, 0x18000
	v_lshl_add_u64 v[8:9], v[8:9], 0, s[10:11]
	v_bitop3_b32 v20, v18, s17, v16 bitop3:0xde
	s_lshl_b32 s17, s53, 12
	s_waitcnt vmcnt(2)
	s_barrier
	global_load_lds_dwordx4 v[8:9], off
	v_lshl_add_u64 v[6:7], v[6:7], 0, s[10:11]
	s_add_i32 m0, s48, 0x1a000
	s_add_i32 s54, s48, 0x8000
	s_add_i32 s55, s48, 0xa000
	global_load_lds_dwordx4 v[6:7], off
	v_lshl_add_u64 v[2:3], v[2:3], 0, s[10:11]
	s_mov_b32 m0, s54
	s_add_u32 s18, s30, 0x80080
	global_load_lds_dwordx4 v[2:3], off
	v_lshl_add_u64 v[2:3], v[4:5], 0, s[10:11]
	s_mov_b32 m0, s55
	s_addc_u32 s19, s31, 0
	global_load_lds_dwordx4 v[2:3], off
	s_add_i32 m0, s48, 0x1c000
	v_lshl_add_u64 v[2:3], s[18:19], 0, v[158:159]
	global_load_lds_dwordx4 v[2:3], off
	v_lshl_add_u64 v[2:3], s[18:19], 0, v[166:167]
	s_add_i32 m0, s48, 0x1e000
	v_lshlrev_b32_e32 v19, 3, v17
	global_load_lds_dwordx4 v[2:3], off
	v_lshlrev_b32_e32 v2, 15, v14
	v_and_b32_e32 v2, 0xffff0000, v2
	v_lshl_add_u32 v2, v13, 12, v2
	v_and_b32_e32 v3, 1, v14
	v_lshl_or_b32 v2, v3, 6, v2
	v_lshl_add_u32 v172, v15, 1, v2
	v_lshlrev_b32_e32 v2, 15, v10
	v_and_b32_e32 v2, 0xffff0000, v2
	s_waitcnt vmcnt(6)
	v_lshl_add_u32 v2, v11, 12, v2
	v_and_b32_e32 v3, 1, v10
	s_cmpk_lt_u32 s16, 0x100
	v_lshl_or_b32 v2, v3, 6, v2
	v_readlane_b32 s18, v252, 22
	v_bitop3_b32 v199, v18, s17, v16 bitop3:0xde
	v_lshl_or_b32 v200, s53, 5, v19
	s_cselect_b64 s[16:17], -1, 0
	s_mov_b32 s56, 0
	v_cmp_eq_u32_e64 s[42:43], 0, v17
	s_waitcnt lgkmcnt(0)
	s_ashr_i32 s57, s52, 31
	v_mov_b32_e32 v173, v159
	v_lshl_add_u32 v174, v12, 1, v2
	v_mov_b32_e32 v175, v159
	v_add_u32_e32 v201, 0, v20
	v_readlane_b32 s34, v254, 48
	s_mov_b32 s58, s18
	s_barrier
	v_readlane_b32 s19, v252, 23
	s_branch .LBB0_660

; #define PG8_STAGE(bufoff, gbase, voff) do { _Pragma("unroll") for (int _i = 0; _i < 2; ++_i) \
;         __builtin_amdgcn_global_load_lds((const unsigned*)((const char*)(gbase) + (voff)[_i]), (PG8_LAS unsigned*)(lds + (bufoff) + ldsw + _i * 8192), 16, 0, 0); } while (0)
; #define PG8_LDA(dst, b, h) do { _Pragma("unroll") for (int m = 0; m < 4; ++m) _Pragma("unroll") for (int k = 0; k < 2; ++k) dst[m][k] = *(const PG8_LAS bf16x8*)(lds + PG8_SA(b, h) + aoff + m * 2048 + k * 1024); } while (0)
; #define PG8_LDB(dst, b, h) do { _Pragma("unroll") for (int n = 0; n < 2; ++n) _Pragma("unroll") for (int k = 0; k < 2; ++k) dst[n][k] = *(const PG8_LAS bf16x8*)(lds + PG8_SB(b, h) + boff + n * 2048 + k * 1024); } while (0)
; #define PG8_MMA(ai, bj, At, Bt) do { __builtin_amdgcn_s_setprio(1); _Pragma("unroll") for (int m = 0; m < 4; ++m) _Pragma("unroll") for (int n = 0; n < 2; ++n) _Pragma("unroll") for (int k = 0; k < 2; ++k) \
;         acc[ai][bj][m][n] = __builtin_amdgcn_mfma_f32_16x16x32_bf16(Bt[n][k], At[m][k], acc[ai][bj][m][n], 0, 0, 0); __builtin_amdgcn_s_setprio(0); } while (0)
; #define PG8_WAIT_V(n) asm volatile("s_waitcnt vmcnt(" #n ")" ::: "memory")
; #define PG8_WAIT_L(n) asm volatile("s_waitcnt lgkmcnt(" #n ")" ::: "memory")
; #define PG8_BAR __builtin_amdgcn_s_barrier()
; #define PG8_SCHED __builtin_amdgcn_sched_barrier(0)
; template <class Epi, class Sched, bool ALIGN_EPI = false, bool SP2 = false>
; __device__ __forceinline__ void gemm_phase(PG8_LAS unsigned char* lds, const Gemm g, const Sched& S, const Epi& E) {
;     ...
;             PG8_LDB(B0, 0, 0); PG8_LDB(B1, 0, 1); PG8_SCHED; PG8_LDA(At, 0, 0); PG8_STAGE(PG8_SA(1, 1), a1 + hstep, voffA);
;             PG8_WAIT_V(8); PG8_WAIT_L(0); PG8_BAR; PG8_MMA(0, 0, At, B0); PG8_MMA(0, 1, At, B1); PG8_BAR; PG8_SCHED;
;     ...
;         for (int a = 0; a < 2; ++a)
; #pragma unroll
;             for (int b = 0; b < 2; ++b)
; #pragma unroll
;                 for (int m = 0; m < 4; ++m)
; #pragma unroll
;                     for (int n = 0; n < 2; ++n) acc[a][b][m][n] = (f32x4){0.f, 0.f, 0.f, 0.f};
.LBB0_666:
	s_ashr_i32 s23, s22, 31
	s_lshl_b64 s[24:25], s[22:23], 20
	s_add_u32 s24, s21, s24
	s_addc_u32 s25, s38, s25
	s_and_b64 s[28:29], s[44:45], exec
	s_cselect_b32 s23, s25, s1
	s_cselect_b32 s59, s24, s0
	s_ashr_i32 s19, s18, 31
	s_lshl_b64 s[28:29], s[18:19], 20
	s_add_u32 s28, s39, s28
	s_addc_u32 s29, s46, s29
	s_and_b64 s[36:37], s[44:45], exec
	s_cselect_b32 s19, s29, s31
	s_cselect_b32 s60, s28, s30
	s_add_u32 s0, s0, 0x80080
	s_addc_u32 s1, s1, 0
	s_add_u32 s61, s30, 0x100
	v_mov_b32_e32 v2, 0
	s_addc_u32 s62, s31, 0
	s_mov_b32 s63, -2
	v_mov_b32_e32 v3, v2
	v_mov_b32_e32 v4, v2
	v_mov_b32_e32 v5, v2
	v_mov_b32_e32 v6, v2
	v_mov_b32_e32 v7, v2
	v_mov_b32_e32 v8, v2
	v_mov_b32_e32 v9, v2
	v_mov_b32_e32 v18, v2
	v_mov_b32_e32 v19, v2
	v_mov_b32_e32 v20, v2
	v_mov_b32_e32 v21, v2
	v_mov_b32_e32 v22, v2
	v_mov_b32_e32 v23, v2
	v_mov_b32_e32 v24, v2
	v_mov_b32_e32 v25, v2
	v_mov_b32_e32 v34, v2
	v_mov_b32_e32 v35, v2
	v_mov_b32_e32 v36, v2
	v_mov_b32_e32 v37, v2
	v_mov_b32_e32 v38, v2
	v_mov_b32_e32 v39, v2
	v_mov_b32_e32 v40, v2
	v_mov_b32_e32 v41, v2
	v_mov_b32_e32 v50, v2
	v_mov_b32_e32 v51, v2
	v_mov_b32_e32 v52, v2
	v_mov_b32_e32 v53, v2
	v_mov_b32_e32 v54, v2
	v_mov_b32_e32 v55, v2
	v_mov_b32_e32 v56, v2
	v_mov_b32_e32 v57, v2
	v_mov_b32_e32 v10, v2
	v_mov_b32_e32 v11, v2
	v_mov_b32_e32 v12, v2
	v_mov_b32_e32 v13, v2
	v_mov_b32_e32 v14, v2
	v_mov_b32_e32 v15, v2
	v_mov_b32_e32 v16, v2
	v_mov_b32_e32 v17, v2
	v_mov_b32_e32 v26, v2
	v_mov_b32_e32 v27, v2
	v_mov_b32_e32 v28, v2
	v_mov_b32_e32 v29, v2
	v_mov_b32_e32 v30, v2
	v_mov_b32_e32 v31, v2
	v_mov_b32_e32 v32, v2
	v_mov_b32_e32 v33, v2
	v_mov_b32_e32 v42, v2
	v_mov_b32_e32 v43, v2
	v_mov_b32_e32 v44, v2
	v_mov_b32_e32 v45, v2
	v_mov_b32_e32 v46, v2
	v_mov_b32_e32 v47, v2
	v_mov_b32_e32 v48, v2
	v_mov_b32_e32 v49, v2
	v_mov_b32_e32 v58, v2
	v_mov_b32_e32 v59, v2
	v_mov_b32_e32 v60, v2
	v_mov_b32_e32 v61, v2
	v_mov_b32_e32 v62, v2
	v_mov_b32_e32 v63, v2
	v_mov_b32_e32 v64, v2
	v_mov_b32_e32 v65, v2
	v_mov_b32_e32 v66, v2
	v_mov_b32_e32 v67, v2
	v_mov_b32_e32 v68, v2
	v_mov_b32_e32 v69, v2
	v_mov_b32_e32 v70, v2
	v_mov_b32_e32 v71, v2
	v_mov_b32_e32 v72, v2
	v_mov_b32_e32 v73, v2
	v_mov_b32_e32 v82, v2
	v_mov_b32_e32 v83, v2
	v_mov_b32_e32 v84, v2
	v_mov_b32_e32 v85, v2
	v_mov_b32_e32 v86, v2
	v_mov_b32_e32 v87, v2
	v_mov_b32_e32 v88, v2
	v_mov_b32_e32 v89, v2
	v_mov_b32_e32 v98, v2
	v_mov_b32_e32 v99, v2
	v_mov_b32_e32 v100, v2
	v_mov_b32_e32 v101, v2
	v_mov_b32_e32 v102, v2
	v_mov_b32_e32 v103, v2
	v_mov_b32_e32 v104, v2
	v_mov_b32_e32 v105, v2
	v_mov_b32_e32 v114, v2
	v_mov_b32_e32 v115, v2
	v_mov_b32_e32 v116, v2
	v_mov_b32_e32 v117, v2
	v_mov_b32_e32 v118, v2
	v_mov_b32_e32 v119, v2
	v_mov_b32_e32 v120, v2
	v_mov_b32_e32 v121, v2
	v_mov_b32_e32 v74, v2
	v_mov_b32_e32 v75, v2
	v_mov_b32_e32 v76, v2
	v_mov_b32_e32 v77, v2
	v_mov_b32_e32 v78, v2
	v_mov_b32_e32 v79, v2
	v_mov_b32_e32 v80, v2
	v_mov_b32_e32 v81, v2
	v_mov_b32_e32 v90, v2
	v_mov_b32_e32 v91, v2
	v_mov_b32_e32 v92, v2
	v_mov_b32_e32 v93, v2
	v_mov_b32_e32 v94, v2
	v_mov_b32_e32 v95, v2
	v_mov_b32_e32 v96, v2
	v_mov_b32_e32 v97, v2
	v_mov_b32_e32 v106, v2
	v_mov_b32_e32 v107, v2
	v_mov_b32_e32 v108, v2
	v_mov_b32_e32 v109, v2
	v_mov_b32_e32 v110, v2
	v_mov_b32_e32 v111, v2
	v_mov_b32_e32 v112, v2
	v_mov_b32_e32 v113, v2
	v_mov_b32_e32 v122, v2
	v_mov_b32_e32 v123, v2
	v_mov_b32_e32 v124, v2
	v_mov_b32_e32 v125, v2
	v_mov_b32_e32 v126, v2
	v_mov_b32_e32 v127, v2
	v_mov_b32_e32 v128, v2
	v_mov_b32_e32 v129, v2
	s_and_b64 vcc, exec, s[4:5]
	s_cbranch_vccnz .Lhb_T_667
.LBB0_667:
	s_add_u32 s30, s0, 0xfff80080
	s_addc_u32 s31, s1, -1
	s_add_i32 s66, 0, 0x10000
	s_cmp_eq_u32 s63, 28
	s_cselect_b32 s37, s23, s31
	s_cselect_b32 s36, s59, s30
	s_cselect_b32 s31, s19, s62
	s_cselect_b32 s30, s60, s61
	s_add_i32 s68, 0, 0x14000
	v_add_u32_e32 v142, s66, v199
	v_add_u32_e32 v162, s68, v199
	ds_read_b128 v[130:133], v142
	ds_read_b128 v[134:137], v142 offset:1024
	ds_read_b128 v[138:141], v142 offset:2048
	ds_read_b128 v[142:145], v142 offset:3072
	ds_read_b128 v[146:149], v162
	ds_read_b128 v[150:153], v162 offset:1024
	ds_read_b128 v[154:157], v162 offset:2048
	ds_read_b128 v[162:165], v162 offset:3072
	s_add_u32 s98, s0, 0xfff80000
	s_addc_u32 s99, s1, -1
	v_lshl_add_u64 v[192:193], s[98:99], 0, v[172:173]
	s_mov_b32 m0, s54
	s_nop 0
	global_load_lds_dwordx4 v[192:193], off
	v_lshl_add_u64 v[192:193], s[98:99], 0, v[174:175]
	s_mov_b32 m0, s55
	s_nop 0
	global_load_lds_dwordx4 v[192:193], off
	v_lshl_add_u64 v[192:193], s[0:1], 0, v[172:173]
	s_add_i32 m0, s48, 0xc000
	ds_read_b128 v[176:179], v201
	ds_read_b128 v[180:183], v201 offset:1024
	ds_read_b128 v[184:187], v201 offset:2048
	ds_read_b128 v[188:191], v201 offset:3072
	ds_read_b128 v[202:205], v201 offset:4096
	ds_read_b128 v[206:209], v201 offset:5120
	ds_read_b128 v[210:213], v201 offset:6144
	ds_read_b128 v[214:217], v201 offset:7168
	global_load_lds_dwordx4 v[192:193], off
	v_lshl_add_u64 v[192:193], s[0:1], 0, v[174:175]
	s_add_i32 m0, s48, 0xe000
	s_nop 0
	global_load_lds_dwordx4 v[192:193], off
	s_waitcnt lgkmcnt(0)
	s_setprio 1
	s_waitcnt lgkmcnt(0)
; #define PG8_STAGE(bufoff, gbase, voff) do { _Pragma("unroll") for (int _i = 0; _i < 2; ++_i) \
;         __builtin_amdgcn_global_load_lds((const unsigned*)((const char*)(gbase) + (voff)[_i]), (PG8_LAS unsigned*)(lds + (bufoff) + ldsw + _i * 8192), 16, 0, 0); } while (0)
; #define PG8_LDA(dst, b, h) do { _Pragma("unroll") for (int m = 0; m < 4; ++m) _Pragma("unroll") for (int k = 0; k < 2; ++k) dst[m][k] = *(const PG8_LAS bf16x8*)(lds + PG8_SA(b, h) + aoff + m * 2048 + k * 1024); } while (0)
; #define PG8_MMA(ai, bj, At, Bt) do { __builtin_amdgcn_s_setprio(1); _Pragma("unroll") for (int m = 0; m < 4; ++m) _Pragma("unroll") for (int n = 0; n < 2; ++n) _Pragma("unroll") for (int k = 0; k < 2; ++k) \
;         acc[ai][bj][m][n] = __builtin_amdgcn_mfma_f32_16x16x32_bf16(Bt[n][k], At[m][k], acc[ai][bj][m][n], 0, 0, 0); __builtin_amdgcn_s_setprio(0); } while (0)
; #define PG8_WAIT_V(n) asm volatile("s_waitcnt vmcnt(" #n ")" ::: "memory")
; #define PG8_WAIT_L(n) asm volatile("s_waitcnt lgkmcnt(" #n ")" ::: "memory")
; #define PG8_BAR __builtin_amdgcn_s_barrier()
; #define PG8_SCHED __builtin_amdgcn_sched_barrier(0)
; template <class Epi, class Sched, bool ALIGN_EPI = false, bool SP2 = false>
; __device__ __forceinline__ void gemm_phase(PG8_LAS unsigned char* lds, const Gemm g, const Sched& S, const Epi& E) {
;     ...
;             PG8_WAIT_V(8); PG8_WAIT_L(0); PG8_BAR; PG8_MMA(0, 0, At, B0); PG8_MMA(0, 1, At, B1); PG8_BAR; PG8_SCHED;
;             PG8_LDA(At, 0, 1); PG8_STAGE(PG8_SB(0, 0), b2, voffB); PG8_STAGE(PG8_SB(0, 1), b2 + hstep, voffB); PG8_STAGE(PG8_SA(0, 0), a2, voffA);
;             PG8_WAIT_V(8); PG8_WAIT_L(0); PG8_BAR; PG8_MMA(1, 0, At, B0); PG8_MMA(1, 1, At, B1); PG8_BAR; PG8_SCHED;
	v_mfma_f32_16x16x32_bf16 v[126:129], v[130:133], v[176:179], v[126:129]
	v_mfma_f32_16x16x32_bf16 v[122:125], v[138:141], v[176:179], v[122:125]
	v_mfma_f32_16x16x32_bf16 v[110:113], v[130:133], v[184:187], v[110:113]
	v_mfma_f32_16x16x32_bf16 v[106:109], v[138:141], v[184:187], v[106:109]
	v_mfma_f32_16x16x32_bf16 v[94:97], v[130:133], v[202:205], v[94:97]
	v_mfma_f32_16x16x32_bf16 v[90:93], v[138:141], v[202:205], v[90:93]
	v_mfma_f32_16x16x32_bf16 v[78:81], v[130:133], v[210:213], v[78:81]
	v_mfma_f32_16x16x32_bf16 v[74:77], v[138:141], v[210:213], v[74:77]
	v_mfma_f32_16x16x32_bf16 v[126:129], v[134:137], v[180:183], v[126:129]
	v_mfma_f32_16x16x32_bf16 v[122:125], v[142:145], v[180:183], v[122:125]
	v_mfma_f32_16x16x32_bf16 v[110:113], v[134:137], v[188:191], v[110:113]
	v_mfma_f32_16x16x32_bf16 v[106:109], v[142:145], v[188:191], v[106:109]
	v_mfma_f32_16x16x32_bf16 v[94:97], v[134:137], v[206:209], v[94:97]
	v_mfma_f32_16x16x32_bf16 v[90:93], v[142:145], v[206:209], v[90:93]
	v_mfma_f32_16x16x32_bf16 v[78:81], v[134:137], v[214:217], v[78:81]
	v_mfma_f32_16x16x32_bf16 v[74:77], v[142:145], v[214:217], v[74:77]
	v_mfma_f32_16x16x32_bf16 v[118:121], v[146:149], v[176:179], v[118:121]
	v_mfma_f32_16x16x32_bf16 v[114:117], v[154:157], v[176:179], v[114:117]
	v_mfma_f32_16x16x32_bf16 v[102:105], v[146:149], v[184:187], v[102:105]
	v_mfma_f32_16x16x32_bf16 v[98:101], v[154:157], v[184:187], v[98:101]
	v_mfma_f32_16x16x32_bf16 v[86:89], v[146:149], v[202:205], v[86:89]
	v_mfma_f32_16x16x32_bf16 v[82:85], v[154:157], v[202:205], v[82:85]
	v_mfma_f32_16x16x32_bf16 v[70:73], v[146:149], v[210:213], v[70:73]
	v_mfma_f32_16x16x32_bf16 v[66:69], v[154:157], v[210:213], v[66:69]
	v_mfma_f32_16x16x32_bf16 v[118:121], v[150:153], v[180:183], v[118:121]
	v_mfma_f32_16x16x32_bf16 v[114:117], v[162:165], v[180:183], v[114:117]
	v_mfma_f32_16x16x32_bf16 v[102:105], v[150:153], v[188:191], v[102:105]
	v_mfma_f32_16x16x32_bf16 v[98:101], v[162:165], v[188:191], v[98:101]
	v_mfma_f32_16x16x32_bf16 v[86:89], v[150:153], v[206:209], v[86:89]
	v_mfma_f32_16x16x32_bf16 v[82:85], v[162:165], v[206:209], v[82:85]
	v_mfma_f32_16x16x32_bf16 v[70:73], v[150:153], v[214:217], v[70:73]
	v_mfma_f32_16x16x32_bf16 v[66:69], v[162:165], v[214:217], v[66:69]
	s_setprio 0
	s_waitcnt vmcnt(8)
	s_barrier
	s_add_i32 s66, s66, s47
	v_lshl_add_u64 v[192:193], s[30:31], 0, v[158:159]
	s_mov_b32 m0, s66
	ds_read_b128 v[176:179], v201 offset:16384
	ds_read_b128 v[180:183], v201 offset:17408
	ds_read_b128 v[184:187], v201 offset:18432
	ds_read_b128 v[188:191], v201 offset:19456
	ds_read_b128 v[202:205], v201 offset:20480
	ds_read_b128 v[206:209], v201 offset:21504
	ds_read_b128 v[210:213], v201 offset:22528
	ds_read_b128 v[214:217], v201 offset:23552
	global_load_lds_dwordx4 v[192:193], off
	s_add_i32 m0, s66, 0x2000
	s_add_u32 s66, s30, 0x80000
	v_lshl_add_u64 v[218:219], s[30:31], 0, v[166:167]
	s_addc_u32 s67, s31, 0
	s_add_i32 s68, s68, s47
	global_load_lds_dwordx4 v[218:219], off
	v_lshl_add_u64 v[220:221], s[66:67], 0, v[158:159]
	s_mov_b32 m0, s68
	v_lshl_add_u64 v[222:223], s[36:37], 0, v[168:169]
	global_load_lds_dwordx4 v[220:221], off
	v_lshl_add_u64 v[220:221], s[66:67], 0, v[166:167]
	s_add_i32 m0, s68, 0x2000
	s_nop 0
	global_load_lds_dwordx4 v[220:221], off
	v_lshl_add_u64 v[220:221], s[36:37], 0, v[170:171]
	s_waitcnt lgkmcnt(0)
	s_setprio 1
	s_waitcnt lgkmcnt(0)
	v_mfma_f32_16x16x32_bf16 v[62:65], v[130:133], v[176:179], v[62:65]
	v_mfma_f32_16x16x32_bf16 v[58:61], v[138:141], v[176:179], v[58:61]
	v_mfma_f32_16x16x32_bf16 v[46:49], v[130:133], v[184:187], v[46:49]
	v_mfma_f32_16x16x32_bf16 v[42:45], v[138:141], v[184:187], v[42:45]
	v_mfma_f32_16x16x32_bf16 v[30:33], v[130:133], v[202:205], v[30:33]
	v_mfma_f32_16x16x32_bf16 v[26:29], v[138:141], v[202:205], v[26:29]
	v_mfma_f32_16x16x32_bf16 v[14:17], v[130:133], v[210:213], v[14:17]
	v_mfma_f32_16x16x32_bf16 v[10:13], v[138:141], v[210:213], v[10:13]
	v_mfma_f32_16x16x32_bf16 v[62:65], v[134:137], v[180:183], v[62:65]
	v_mfma_f32_16x16x32_bf16 v[58:61], v[142:145], v[180:183], v[58:61]
	v_mfma_f32_16x16x32_bf16 v[46:49], v[134:137], v[188:191], v[46:49]
	v_mfma_f32_16x16x32_bf16 v[42:45], v[142:145], v[188:191], v[42:45]
	v_mfma_f32_16x16x32_bf16 v[30:33], v[134:137], v[206:209], v[30:33]
	v_mfma_f32_16x16x32_bf16 v[26:29], v[142:145], v[206:209], v[26:29]
	v_mfma_f32_16x16x32_bf16 v[14:17], v[134:137], v[214:217], v[14:17]
	v_mfma_f32_16x16x32_bf16 v[10:13], v[142:145], v[214:217], v[10:13]
	v_mfma_f32_16x16x32_bf16 v[54:57], v[146:149], v[176:179], v[54:57]
	v_mfma_f32_16x16x32_bf16 v[50:53], v[154:157], v[176:179], v[50:53]
	v_mfma_f32_16x16x32_bf16 v[38:41], v[146:149], v[184:187], v[38:41]
	v_mfma_f32_16x16x32_bf16 v[34:37], v[154:157], v[184:187], v[34:37]
	v_mfma_f32_16x16x32_bf16 v[22:25], v[146:149], v[202:205], v[22:25]
	v_mfma_f32_16x16x32_bf16 v[18:21], v[154:157], v[202:205], v[18:21]
	v_mfma_f32_16x16x32_bf16 v[6:9], v[146:149], v[210:213], v[6:9]
	v_mfma_f32_16x16x32_bf16 v[2:5], v[154:157], v[210:213], v[2:5]
	v_mfma_f32_16x16x32_bf16 v[54:57], v[150:153], v[180:183], v[54:57]
	v_mfma_f32_16x16x32_bf16 v[50:53], v[162:165], v[180:183], v[50:53]
	v_mfma_f32_16x16x32_bf16 v[38:41], v[150:153], v[188:191], v[38:41]
	v_mfma_f32_16x16x32_bf16 v[34:37], v[162:165], v[188:191], v[34:37]
	v_mfma_f32_16x16x32_bf16 v[22:25], v[150:153], v[206:209], v[22:25]
	v_mfma_f32_16x16x32_bf16 v[18:21], v[162:165], v[206:209], v[18:21]
	v_mfma_f32_16x16x32_bf16 v[6:9], v[150:153], v[214:217], v[6:9]
	v_mfma_f32_16x16x32_bf16 v[2:5], v[162:165], v[214:217], v[2:5]
	s_setprio 0
	s_waitcnt vmcnt(6)
	s_barrier
; #define PG8_STAGE(bufoff, gbase, voff) do { _Pragma("unroll") for (int _i = 0; _i < 2; ++_i) \
;         __builtin_amdgcn_global_load_lds((const unsigned*)((const char*)(gbase) + (voff)[_i]), (PG8_LAS unsigned*)(lds + (bufoff) + ldsw + _i * 8192), 16, 0, 0); } while (0)
; #define PG8_LDA(dst, b, h) do { _Pragma("unroll") for (int m = 0; m < 4; ++m) _Pragma("unroll") for (int k = 0; k < 2; ++k) dst[m][k] = *(const PG8_LAS bf16x8*)(lds + PG8_SA(b, h) + aoff + m * 2048 + k * 1024); } while (0)
; #define PG8_LDB(dst, b, h) do { _Pragma("unroll") for (int n = 0; n < 2; ++n) _Pragma("unroll") for (int k = 0; k < 2; ++k) dst[n][k] = *(const PG8_LAS bf16x8*)(lds + PG8_SB(b, h) + boff + n * 2048 + k * 1024); } while (0)
; #define PG8_MMA(ai, bj, At, Bt) do { __builtin_amdgcn_s_setprio(1); _Pragma("unroll") for (int m = 0; m < 4; ++m) _Pragma("unroll") for (int n = 0; n < 2; ++n) _Pragma("unroll") for (int k = 0; k < 2; ++k) \
;         acc[ai][bj][m][n] = __builtin_amdgcn_mfma_f32_16x16x32_bf16(Bt[n][k], At[m][k], acc[ai][bj][m][n], 0, 0, 0); __builtin_amdgcn_s_setprio(0); } while (0)
; #define PG8_WAIT_V(n) asm volatile("s_waitcnt vmcnt(" #n ")" ::: "memory")
; #define PG8_WAIT_L(n) asm volatile("s_waitcnt lgkmcnt(" #n ")" ::: "memory")
; #define PG8_BAR __builtin_amdgcn_s_barrier()
; #define PG8_SCHED __builtin_amdgcn_sched_barrier(0)
; template <class Epi, class Sched, bool ALIGN_EPI = false, bool SP2 = false>
; __device__ __forceinline__ void gemm_phase(PG8_LAS unsigned char* lds, const Gemm g, const Sched& S, const Epi& E) {
;     ...
;             PG8_LDB(B0, 1, 0); PG8_LDB(B1, 1, 1); PG8_SCHED; PG8_LDA(At, 1, 0); PG8_STAGE(PG8_SA(0, 1), a2 + hstep, voffA);
;             PG8_WAIT_V(8); PG8_WAIT_L(0); PG8_BAR; PG8_MMA(0, 0, At, B0); PG8_MMA(0, 1, At, B1); PG8_BAR; PG8_SCHED;
;             PG8_LDA(At, 1, 1); PG8_STAGE(PG8_SB(1, 0), b3, voffB); PG8_STAGE(PG8_SB(1, 1), b3 + hstep, voffB); PG8_STAGE(PG8_SA(1, 0), a3, voffA);
;             PG8_WAIT_V(8); PG8_WAIT_L(0); PG8_BAR; PG8_MMA(1, 0, At, B0); PG8_MMA(1, 1, At, B1); PG8_BAR; PG8_SCHED;
	s_add_i32 s66, 0, 0x18000
	s_add_i32 s67, 0, 0x1c000
	v_add_u32_e32 v142, s66, v199
	v_add_u32_e32 v162, s67, v199
	ds_read_b128 v[130:133], v142
	ds_read_b128 v[134:137], v142 offset:1024
	ds_read_b128 v[138:141], v142 offset:2048
	ds_read_b128 v[142:145], v142 offset:3072
	ds_read_b128 v[146:149], v162
	ds_read_b128 v[150:153], v162 offset:1024
	ds_read_b128 v[154:157], v162 offset:2048
	ds_read_b128 v[162:165], v162 offset:3072
	s_add_u32 s36, s36, 0x80000
	s_addc_u32 s37, s37, 0
	s_mov_b32 m0, s48
	s_nop 0
	global_load_lds_dwordx4 v[220:221], off
	s_mov_b32 m0, s49
	s_nop 0
	global_load_lds_dwordx4 v[222:223], off
	s_mov_b32 m0, s50
	v_lshl_add_u64 v[224:225], s[36:37], 0, v[170:171]
	ds_read_b128 v[176:179], v201 offset:32768
	ds_read_b128 v[180:183], v201 offset:33792
	ds_read_b128 v[184:187], v201 offset:34816
	ds_read_b128 v[188:191], v201 offset:35840
	ds_read_b128 v[202:205], v201 offset:36864
	ds_read_b128 v[206:209], v201 offset:37888
	ds_read_b128 v[210:213], v201 offset:38912
	ds_read_b128 v[214:217], v201 offset:39936
	global_load_lds_dwordx4 v[224:225], off
	v_lshl_add_u64 v[224:225], s[36:37], 0, v[168:169]
	s_mov_b32 m0, s51
	s_nop 0
	global_load_lds_dwordx4 v[224:225], off
	s_waitcnt lgkmcnt(0)
	s_setprio 1
	s_waitcnt lgkmcnt(0)
	v_mfma_f32_16x16x32_bf16 v[126:129], v[130:133], v[176:179], v[126:129]
	v_mfma_f32_16x16x32_bf16 v[122:125], v[138:141], v[176:179], v[122:125]
	v_mfma_f32_16x16x32_bf16 v[110:113], v[130:133], v[184:187], v[110:113]
	v_mfma_f32_16x16x32_bf16 v[106:109], v[138:141], v[184:187], v[106:109]
	v_mfma_f32_16x16x32_bf16 v[94:97], v[130:133], v[202:205], v[94:97]
	v_mfma_f32_16x16x32_bf16 v[90:93], v[138:141], v[202:205], v[90:93]
	v_mfma_f32_16x16x32_bf16 v[78:81], v[130:133], v[210:213], v[78:81]
	v_mfma_f32_16x16x32_bf16 v[74:77], v[138:141], v[210:213], v[74:77]
	v_mfma_f32_16x16x32_bf16 v[126:129], v[134:137], v[180:183], v[126:129]
	v_mfma_f32_16x16x32_bf16 v[122:125], v[142:145], v[180:183], v[122:125]
	v_mfma_f32_16x16x32_bf16 v[110:113], v[134:137], v[188:191], v[110:113]
	v_mfma_f32_16x16x32_bf16 v[106:109], v[142:145], v[188:191], v[106:109]
	v_mfma_f32_16x16x32_bf16 v[94:97], v[134:137], v[206:209], v[94:97]
	v_mfma_f32_16x16x32_bf16 v[90:93], v[142:145], v[206:209], v[90:93]
	v_mfma_f32_16x16x32_bf16 v[78:81], v[134:137], v[214:217], v[78:81]
	v_mfma_f32_16x16x32_bf16 v[74:77], v[142:145], v[214:217], v[74:77]
	v_mfma_f32_16x16x32_bf16 v[118:121], v[146:149], v[176:179], v[118:121]
	v_mfma_f32_16x16x32_bf16 v[114:117], v[154:157], v[176:179], v[114:117]
	v_mfma_f32_16x16x32_bf16 v[102:105], v[146:149], v[184:187], v[102:105]
	v_mfma_f32_16x16x32_bf16 v[98:101], v[154:157], v[184:187], v[98:101]
	v_mfma_f32_16x16x32_bf16 v[86:89], v[146:149], v[202:205], v[86:89]
	v_mfma_f32_16x16x32_bf16 v[82:85], v[154:157], v[202:205], v[82:85]
	v_mfma_f32_16x16x32_bf16 v[70:73], v[146:149], v[210:213], v[70:73]
	v_mfma_f32_16x16x32_bf16 v[66:69], v[154:157], v[210:213], v[66:69]
	v_mfma_f32_16x16x32_bf16 v[118:121], v[150:153], v[180:183], v[118:121]
	v_mfma_f32_16x16x32_bf16 v[114:117], v[162:165], v[180:183], v[114:117]
	v_mfma_f32_16x16x32_bf16 v[102:105], v[150:153], v[188:191], v[102:105]
	v_mfma_f32_16x16x32_bf16 v[98:101], v[162:165], v[188:191], v[98:101]
	v_mfma_f32_16x16x32_bf16 v[86:89], v[150:153], v[206:209], v[86:89]
	v_mfma_f32_16x16x32_bf16 v[82:85], v[162:165], v[206:209], v[82:85]
	v_mfma_f32_16x16x32_bf16 v[70:73], v[150:153], v[214:217], v[70:73]
	v_mfma_f32_16x16x32_bf16 v[66:69], v[162:165], v[214:217], v[66:69]
	s_setprio 0
	s_waitcnt vmcnt(8)
	s_barrier
	s_add_i32 s36, s66, s47
	v_lshl_add_u64 v[192:193], v[192:193], 0, s[10:11]
	s_mov_b32 m0, s36
	ds_read_b128 v[176:179], v201 offset:49152
	ds_read_b128 v[180:183], v201 offset:50176
	ds_read_b128 v[184:187], v201 offset:51200
	ds_read_b128 v[188:191], v201 offset:52224
	ds_read_b128 v[202:205], v201 offset:53248
	ds_read_b128 v[206:209], v201 offset:54272
	ds_read_b128 v[210:213], v201 offset:55296
	ds_read_b128 v[214:217], v201 offset:56320
	global_load_lds_dwordx4 v[192:193], off
	s_add_i32 m0, s36, 0x2000
	s_add_u32 s30, s30, 0x80080
	v_lshl_add_u64 v[192:193], v[218:219], 0, s[10:11]
	s_addc_u32 s31, s31, 0
	s_add_i32 s36, s67, s47
	global_load_lds_dwordx4 v[192:193], off
	v_lshl_add_u64 v[192:193], s[30:31], 0, v[158:159]
	s_mov_b32 m0, s36
	s_nop 0
	global_load_lds_dwordx4 v[192:193], off
	v_lshl_add_u64 v[192:193], s[30:31], 0, v[166:167]
	s_add_i32 m0, s36, 0x2000
	s_nop 0
	global_load_lds_dwordx4 v[192:193], off
	s_waitcnt lgkmcnt(0)
	s_setprio 1
	s_waitcnt lgkmcnt(0)
	v_mfma_f32_16x16x32_bf16 v[62:65], v[130:133], v[176:179], v[62:65]
	v_mfma_f32_16x16x32_bf16 v[58:61], v[138:141], v[176:179], v[58:61]
	v_mfma_f32_16x16x32_bf16 v[46:49], v[130:133], v[184:187], v[46:49]
	v_mfma_f32_16x16x32_bf16 v[42:45], v[138:141], v[184:187], v[42:45]
	v_mfma_f32_16x16x32_bf16 v[30:33], v[130:133], v[202:205], v[30:33]
	v_mfma_f32_16x16x32_bf16 v[26:29], v[138:141], v[202:205], v[26:29]
	v_mfma_f32_16x16x32_bf16 v[14:17], v[130:133], v[210:213], v[14:17]
	v_mfma_f32_16x16x32_bf16 v[10:13], v[138:141], v[210:213], v[10:13]
	v_mfma_f32_16x16x32_bf16 v[62:65], v[134:137], v[180:183], v[62:65]
	v_mfma_f32_16x16x32_bf16 v[58:61], v[142:145], v[180:183], v[58:61]
	v_mfma_f32_16x16x32_bf16 v[46:49], v[134:137], v[188:191], v[46:49]
	v_mfma_f32_16x16x32_bf16 v[42:45], v[142:145], v[188:191], v[42:45]
	v_mfma_f32_16x16x32_bf16 v[30:33], v[134:137], v[206:209], v[30:33]
	v_mfma_f32_16x16x32_bf16 v[26:29], v[142:145], v[206:209], v[26:29]
	v_mfma_f32_16x16x32_bf16 v[14:17], v[134:137], v[214:217], v[14:17]
	v_mfma_f32_16x16x32_bf16 v[10:13], v[142:145], v[214:217], v[10:13]
	v_mfma_f32_16x16x32_bf16 v[54:57], v[146:149], v[176:179], v[54:57]
	v_mfma_f32_16x16x32_bf16 v[50:53], v[154:157], v[176:179], v[50:53]
	v_mfma_f32_16x16x32_bf16 v[38:41], v[146:149], v[184:187], v[38:41]
	v_mfma_f32_16x16x32_bf16 v[34:37], v[154:157], v[184:187], v[34:37]
	v_mfma_f32_16x16x32_bf16 v[22:25], v[146:149], v[202:205], v[22:25]
	v_mfma_f32_16x16x32_bf16 v[18:21], v[154:157], v[202:205], v[18:21]
	v_mfma_f32_16x16x32_bf16 v[6:9], v[146:149], v[210:213], v[6:9]
	v_mfma_f32_16x16x32_bf16 v[2:5], v[154:157], v[210:213], v[2:5]
	v_mfma_f32_16x16x32_bf16 v[54:57], v[150:153], v[180:183], v[54:57]
	v_mfma_f32_16x16x32_bf16 v[50:53], v[162:165], v[180:183], v[50:53]
	v_mfma_f32_16x16x32_bf16 v[38:41], v[150:153], v[188:191], v[38:41]
	v_mfma_f32_16x16x32_bf16 v[34:37], v[162:165], v[188:191], v[34:37]
	v_mfma_f32_16x16x32_bf16 v[22:25], v[150:153], v[206:209], v[22:25]
	v_mfma_f32_16x16x32_bf16 v[18:21], v[162:165], v[206:209], v[18:21]
	v_mfma_f32_16x16x32_bf16 v[6:9], v[150:153], v[214:217], v[6:9]
	v_mfma_f32_16x16x32_bf16 v[2:5], v[162:165], v[214:217], v[2:5]
	s_setprio 0
	s_waitcnt vmcnt(6)
	s_barrier
	s_add_i32 s63, s63, 2
	s_add_u32 s0, s0, 0x100
	s_addc_u32 s1, s1, 0
	s_add_u32 s61, s61, 0x100
	s_addc_u32 s62, s62, 0
	s_cmp_gt_u32 s63, 29
	s_cbranch_scc0 .LBB0_667
	s_branch .Lhb_X_667
; #define PG8_STAGE(bufoff, gbase, voff) do { _Pragma("unroll") for (int _i = 0; _i < 2; ++_i) \
;         __builtin_amdgcn_global_load_lds((const unsigned*)((const char*)(gbase) + (voff)[_i]), (PG8_LAS unsigned*)(lds + (bufoff) + ldsw + _i * 8192), 16, 0, 0); } while (0)
; #define PG8_LDA(dst, b, h) do { _Pragma("unroll") for (int m = 0; m < 4; ++m) _Pragma("unroll") for (int k = 0; k < 2; ++k) dst[m][k] = *(const PG8_LAS bf16x8*)(lds + PG8_SA(b, h) + aoff + m * 2048 + k * 1024); } while (0)
; #define PG8_LDB(dst, b, h) do { _Pragma("unroll") for (int n = 0; n < 2; ++n) _Pragma("unroll") for (int k = 0; k < 2; ++k) dst[n][k] = *(const PG8_LAS bf16x8*)(lds + PG8_SB(b, h) + boff + n * 2048 + k * 1024); } while (0)
; #define PG8_MMA(ai, bj, At, Bt) do { __builtin_amdgcn_s_setprio(1); _Pragma("unroll") for (int m = 0; m < 4; ++m) _Pragma("unroll") for (int n = 0; n < 2; ++n) _Pragma("unroll") for (int k = 0; k < 2; ++k) \
;         acc[ai][bj][m][n] = __builtin_amdgcn_mfma_f32_16x16x32_bf16(Bt[n][k], At[m][k], acc[ai][bj][m][n], 0, 0, 0); __builtin_amdgcn_s_setprio(0); } while (0)
; #define PG8_WAIT_V(n) asm volatile("s_waitcnt vmcnt(" #n ")" ::: "memory")
; #define PG8_WAIT_L(n) asm volatile("s_waitcnt lgkmcnt(" #n ")" ::: "memory")
; #define PG8_BAR __builtin_amdgcn_s_barrier()
; #define PG8_SCHED __builtin_amdgcn_sched_barrier(0)
; template <class Epi, class Sched, bool ALIGN_EPI = false, bool SP2 = false>
; __device__ __forceinline__ void gemm_phase(PG8_LAS unsigned char* lds, const Gemm g, const Sched& S, const Epi& E) {
;     ...
;             PG8_LDB(B0, 0, 0); PG8_LDB(B1, 0, 1); PG8_SCHED; PG8_LDA(At, 0, 0); PG8_STAGE(PG8_SA(1, 1), a1 + hstep, voffA);
;             PG8_WAIT_V(8); PG8_WAIT_L(0); PG8_BAR; PG8_MMA(0, 0, At, B0); PG8_MMA(0, 1, At, B1); PG8_BAR; PG8_SCHED;
;             PG8_LDA(At, 0, 1); PG8_STAGE(PG8_SB(0, 0), b2, voffB); PG8_STAGE(PG8_SB(0, 1), b2 + hstep, voffB); PG8_STAGE(PG8_SA(0, 0), a2, voffA);
;             PG8_WAIT_V(8); PG8_WAIT_L(0); PG8_BAR; PG8_MMA(1, 0, At, B0); PG8_MMA(1, 1, At, B1); PG8_BAR; PG8_SCHED;
.Lhb_T_667:
	s_add_u32 s30, s0, 0xfff80080
	s_addc_u32 s31, s1, -1
	s_add_i32 s66, 0, 0x10000
	s_cmp_eq_u32 s63, 28
	s_cselect_b32 s37, s23, s31
	s_cselect_b32 s36, s59, s30
	s_cselect_b32 s31, s19, s62
	s_cselect_b32 s30, s60, s61
	s_add_i32 s68, 0, 0x14000
	v_add_u32_e32 v142, s66, v199
	v_add_u32_e32 v162, s68, v199
	ds_read_b128 v[130:133], v142
	ds_read_b128 v[134:137], v142 offset:1024
	ds_read_b128 v[138:141], v142 offset:2048
	ds_read_b128 v[142:145], v142 offset:3072
	ds_read_b128 v[146:149], v162
	ds_read_b128 v[150:153], v162 offset:1024
	ds_read_b128 v[154:157], v162 offset:2048
	ds_read_b128 v[162:165], v162 offset:3072
	s_add_u32 s98, s0, 0xfff80000
	s_addc_u32 s99, s1, -1
	v_lshl_add_u64 v[192:193], s[98:99], 0, v[172:173]
	s_mov_b32 m0, s54
	s_nop 0
	global_load_lds_dwordx4 v[192:193], off
	v_lshl_add_u64 v[192:193], s[98:99], 0, v[174:175]
	s_mov_b32 m0, s55
	s_nop 0
	global_load_lds_dwordx4 v[192:193], off
	v_lshl_add_u64 v[192:193], s[0:1], 0, v[172:173]
	s_add_i32 m0, s48, 0xc000
	ds_read_b128 v[176:179], v201
	ds_read_b128 v[180:183], v201 offset:1024
	ds_read_b128 v[184:187], v201 offset:2048
	ds_read_b128 v[188:191], v201 offset:3072
	ds_read_b128 v[202:205], v201 offset:4096
	ds_read_b128 v[206:209], v201 offset:5120
	ds_read_b128 v[210:213], v201 offset:6144
	ds_read_b128 v[214:217], v201 offset:7168
	global_load_lds_dwordx4 v[192:193], off
	v_lshl_add_u64 v[192:193], s[0:1], 0, v[174:175]
	s_add_i32 m0, s48, 0xe000
	s_nop 0
	global_load_lds_dwordx4 v[192:193], off
	s_waitcnt vmcnt(8)
	s_waitcnt lgkmcnt(0)
	s_barrier
	s_setprio 2
	s_waitcnt lgkmcnt(0)
	v_mfma_f32_16x16x32_bf16 v[126:129], v[130:133], v[176:179], v[126:129]
	v_mfma_f32_16x16x32_bf16 v[122:125], v[138:141], v[176:179], v[122:125]
	v_mfma_f32_16x16x32_bf16 v[110:113], v[130:133], v[184:187], v[110:113]
	v_mfma_f32_16x16x32_bf16 v[106:109], v[138:141], v[184:187], v[106:109]
	v_mfma_f32_16x16x32_bf16 v[94:97], v[130:133], v[202:205], v[94:97]
	v_mfma_f32_16x16x32_bf16 v[90:93], v[138:141], v[202:205], v[90:93]
	v_mfma_f32_16x16x32_bf16 v[78:81], v[130:133], v[210:213], v[78:81]
	v_mfma_f32_16x16x32_bf16 v[74:77], v[138:141], v[210:213], v[74:77]
	v_mfma_f32_16x16x32_bf16 v[126:129], v[134:137], v[180:183], v[126:129]
	v_mfma_f32_16x16x32_bf16 v[122:125], v[142:145], v[180:183], v[122:125]
	v_mfma_f32_16x16x32_bf16 v[110:113], v[134:137], v[188:191], v[110:113]
	v_mfma_f32_16x16x32_bf16 v[106:109], v[142:145], v[188:191], v[106:109]
	v_mfma_f32_16x16x32_bf16 v[94:97], v[134:137], v[206:209], v[94:97]
	v_mfma_f32_16x16x32_bf16 v[90:93], v[142:145], v[206:209], v[90:93]
	v_mfma_f32_16x16x32_bf16 v[78:81], v[134:137], v[214:217], v[78:81]
	v_mfma_f32_16x16x32_bf16 v[74:77], v[142:145], v[214:217], v[74:77]
	v_mfma_f32_16x16x32_bf16 v[118:121], v[146:149], v[176:179], v[118:121]
	v_mfma_f32_16x16x32_bf16 v[114:117], v[154:157], v[176:179], v[114:117]
	v_mfma_f32_16x16x32_bf16 v[102:105], v[146:149], v[184:187], v[102:105]
	v_mfma_f32_16x16x32_bf16 v[98:101], v[154:157], v[184:187], v[98:101]
	v_mfma_f32_16x16x32_bf16 v[86:89], v[146:149], v[202:205], v[86:89]
	v_mfma_f32_16x16x32_bf16 v[82:85], v[154:157], v[202:205], v[82:85]
	v_mfma_f32_16x16x32_bf16 v[70:73], v[146:149], v[210:213], v[70:73]
	v_mfma_f32_16x16x32_bf16 v[66:69], v[154:157], v[210:213], v[66:69]
	v_mfma_f32_16x16x32_bf16 v[118:121], v[150:153], v[180:183], v[118:121]
	v_mfma_f32_16x16x32_bf16 v[114:117], v[162:165], v[180:183], v[114:117]
	v_mfma_f32_16x16x32_bf16 v[102:105], v[150:153], v[188:191], v[102:105]
	v_mfma_f32_16x16x32_bf16 v[98:101], v[162:165], v[188:191], v[98:101]
	v_mfma_f32_16x16x32_bf16 v[86:89], v[150:153], v[206:209], v[86:89]
	v_mfma_f32_16x16x32_bf16 v[82:85], v[162:165], v[206:209], v[82:85]
	v_mfma_f32_16x16x32_bf16 v[70:73], v[150:153], v[214:217], v[70:73]
	v_mfma_f32_16x16x32_bf16 v[66:69], v[162:165], v[214:217], v[66:69]
	s_setprio 0
	s_add_i32 s66, s66, s47
	v_lshl_add_u64 v[192:193], s[30:31], 0, v[158:159]
	s_mov_b32 m0, s66
	ds_read_b128 v[176:179], v201 offset:16384
	ds_read_b128 v[180:183], v201 offset:17408
	ds_read_b128 v[184:187], v201 offset:18432
	ds_read_b128 v[188:191], v201 offset:19456
	ds_read_b128 v[202:205], v201 offset:20480
	ds_read_b128 v[206:209], v201 offset:21504
	ds_read_b128 v[210:213], v201 offset:22528
	ds_read_b128 v[214:217], v201 offset:23552
	global_load_lds_dwordx4 v[192:193], off
	s_add_i32 m0, s66, 0x2000
	s_add_u32 s66, s30, 0x80000
	v_lshl_add_u64 v[218:219], s[30:31], 0, v[166:167]
	s_addc_u32 s67, s31, 0
	s_add_i32 s68, s68, s47
	global_load_lds_dwordx4 v[218:219], off
	v_lshl_add_u64 v[220:221], s[66:67], 0, v[158:159]
	s_mov_b32 m0, s68
	v_lshl_add_u64 v[222:223], s[36:37], 0, v[168:169]
	global_load_lds_dwordx4 v[220:221], off
	v_lshl_add_u64 v[220:221], s[66:67], 0, v[166:167]
	s_add_i32 m0, s68, 0x2000
	s_nop 0
	global_load_lds_dwordx4 v[220:221], off
	v_lshl_add_u64 v[220:221], s[36:37], 0, v[170:171]
	s_waitcnt vmcnt(6)
	s_waitcnt lgkmcnt(0)
	s_barrier
; #define PG8_STAGE(bufoff, gbase, voff) do { _Pragma("unroll") for (int _i = 0; _i < 2; ++_i) \
;         __builtin_amdgcn_global_load_lds((const unsigned*)((const char*)(gbase) + (voff)[_i]), (PG8_LAS unsigned*)(lds + (bufoff) + ldsw + _i * 8192), 16, 0, 0); } while (0)
; #define PG8_LDA(dst, b, h) do { _Pragma("unroll") for (int m = 0; m < 4; ++m) _Pragma("unroll") for (int k = 0; k < 2; ++k) dst[m][k] = *(const PG8_LAS bf16x8*)(lds + PG8_SA(b, h) + aoff + m * 2048 + k * 1024); } while (0)
; #define PG8_LDB(dst, b, h) do { _Pragma("unroll") for (int n = 0; n < 2; ++n) _Pragma("unroll") for (int k = 0; k < 2; ++k) dst[n][k] = *(const PG8_LAS bf16x8*)(lds + PG8_SB(b, h) + boff + n * 2048 + k * 1024); } while (0)
; #define PG8_MMA(ai, bj, At, Bt) do { __builtin_amdgcn_s_setprio(1); _Pragma("unroll") for (int m = 0; m < 4; ++m) _Pragma("unroll") for (int n = 0; n < 2; ++n) _Pragma("unroll") for (int k = 0; k < 2; ++k) \
;         acc[ai][bj][m][n] = __builtin_amdgcn_mfma_f32_16x16x32_bf16(Bt[n][k], At[m][k], acc[ai][bj][m][n], 0, 0, 0); __builtin_amdgcn_s_setprio(0); } while (0)
; #define PG8_WAIT_V(n) asm volatile("s_waitcnt vmcnt(" #n ")" ::: "memory")
; #define PG8_WAIT_L(n) asm volatile("s_waitcnt lgkmcnt(" #n ")" ::: "memory")
; #define PG8_BAR __builtin_amdgcn_s_barrier()
; #define PG8_SCHED __builtin_amdgcn_sched_barrier(0)
; template <class Epi, class Sched, bool ALIGN_EPI = false, bool SP2 = false>
; __device__ __forceinline__ void gemm_phase(PG8_LAS unsigned char* lds, const Gemm g, const Sched& S, const Epi& E) {
;     ...
;             PG8_WAIT_V(8); PG8_WAIT_L(0); PG8_BAR; PG8_MMA(1, 0, At, B0); PG8_MMA(1, 1, At, B1); PG8_BAR; PG8_SCHED;
;             PG8_LDB(B0, 1, 0); PG8_LDB(B1, 1, 1); PG8_SCHED; PG8_LDA(At, 1, 0); PG8_STAGE(PG8_SA(0, 1), a2 + hstep, voffA);
	s_setprio 2
	s_waitcnt lgkmcnt(0)
	v_mfma_f32_16x16x32_bf16 v[62:65], v[130:133], v[176:179], v[62:65]
	v_mfma_f32_16x16x32_bf16 v[58:61], v[138:141], v[176:179], v[58:61]
	v_mfma_f32_16x16x32_bf16 v[46:49], v[130:133], v[184:187], v[46:49]
	v_mfma_f32_16x16x32_bf16 v[42:45], v[138:141], v[184:187], v[42:45]
	v_mfma_f32_16x16x32_bf16 v[30:33], v[130:133], v[202:205], v[30:33]
	v_mfma_f32_16x16x32_bf16 v[26:29], v[138:141], v[202:205], v[26:29]
	v_mfma_f32_16x16x32_bf16 v[14:17], v[130:133], v[210:213], v[14:17]
	v_mfma_f32_16x16x32_bf16 v[10:13], v[138:141], v[210:213], v[10:13]
	v_mfma_f32_16x16x32_bf16 v[62:65], v[134:137], v[180:183], v[62:65]
	v_mfma_f32_16x16x32_bf16 v[58:61], v[142:145], v[180:183], v[58:61]
	v_mfma_f32_16x16x32_bf16 v[46:49], v[134:137], v[188:191], v[46:49]
	v_mfma_f32_16x16x32_bf16 v[42:45], v[142:145], v[188:191], v[42:45]
	v_mfma_f32_16x16x32_bf16 v[30:33], v[134:137], v[206:209], v[30:33]
	v_mfma_f32_16x16x32_bf16 v[26:29], v[142:145], v[206:209], v[26:29]
	v_mfma_f32_16x16x32_bf16 v[14:17], v[134:137], v[214:217], v[14:17]
	v_mfma_f32_16x16x32_bf16 v[10:13], v[142:145], v[214:217], v[10:13]
	v_mfma_f32_16x16x32_bf16 v[54:57], v[146:149], v[176:179], v[54:57]
	v_mfma_f32_16x16x32_bf16 v[50:53], v[154:157], v[176:179], v[50:53]
	v_mfma_f32_16x16x32_bf16 v[38:41], v[146:149], v[184:187], v[38:41]
	v_mfma_f32_16x16x32_bf16 v[34:37], v[154:157], v[184:187], v[34:37]
	v_mfma_f32_16x16x32_bf16 v[22:25], v[146:149], v[202:205], v[22:25]
	v_mfma_f32_16x16x32_bf16 v[18:21], v[154:157], v[202:205], v[18:21]
	v_mfma_f32_16x16x32_bf16 v[6:9], v[146:149], v[210:213], v[6:9]
	v_mfma_f32_16x16x32_bf16 v[2:5], v[154:157], v[210:213], v[2:5]
	v_mfma_f32_16x16x32_bf16 v[54:57], v[150:153], v[180:183], v[54:57]
	v_mfma_f32_16x16x32_bf16 v[50:53], v[162:165], v[180:183], v[50:53]
	v_mfma_f32_16x16x32_bf16 v[38:41], v[150:153], v[188:191], v[38:41]
	v_mfma_f32_16x16x32_bf16 v[34:37], v[162:165], v[188:191], v[34:37]
	v_mfma_f32_16x16x32_bf16 v[22:25], v[150:153], v[206:209], v[22:25]
	v_mfma_f32_16x16x32_bf16 v[18:21], v[162:165], v[206:209], v[18:21]
	v_mfma_f32_16x16x32_bf16 v[6:9], v[150:153], v[214:217], v[6:9]
	v_mfma_f32_16x16x32_bf16 v[2:5], v[162:165], v[214:217], v[2:5]
	s_setprio 0
	s_add_i32 s66, 0, 0x18000
	s_add_i32 s67, 0, 0x1c000
	v_add_u32_e32 v142, s66, v199
	v_add_u32_e32 v162, s67, v199
	ds_read_b128 v[130:133], v142
	ds_read_b128 v[134:137], v142 offset:1024
	ds_read_b128 v[138:141], v142 offset:2048
	ds_read_b128 v[142:145], v142 offset:3072
	ds_read_b128 v[146:149], v162
	ds_read_b128 v[150:153], v162 offset:1024
	ds_read_b128 v[154:157], v162 offset:2048
	ds_read_b128 v[162:165], v162 offset:3072
	s_add_u32 s36, s36, 0x80000
	s_addc_u32 s37, s37, 0
	s_mov_b32 m0, s48
	s_nop 0
	global_load_lds_dwordx4 v[220:221], off
	s_mov_b32 m0, s49
	s_nop 0
	global_load_lds_dwordx4 v[222:223], off
	s_mov_b32 m0, s50
	v_lshl_add_u64 v[224:225], s[36:37], 0, v[170:171]
	ds_read_b128 v[176:179], v201 offset:32768
	ds_read_b128 v[180:183], v201 offset:33792
	ds_read_b128 v[184:187], v201 offset:34816
	ds_read_b128 v[188:191], v201 offset:35840
	ds_read_b128 v[202:205], v201 offset:36864
	ds_read_b128 v[206:209], v201 offset:37888
	ds_read_b128 v[210:213], v201 offset:38912
	ds_read_b128 v[214:217], v201 offset:39936
	global_load_lds_dwordx4 v[224:225], off
	v_lshl_add_u64 v[224:225], s[36:37], 0, v[168:169]
	s_mov_b32 m0, s51
	s_nop 0
	global_load_lds_dwordx4 v[224:225], off
	s_waitcnt vmcnt(8)
	s_waitcnt lgkmcnt(0)
	s_barrier
; #define PG8_STAGE(bufoff, gbase, voff) do { _Pragma("unroll") for (int _i = 0; _i < 2; ++_i) \
;         __builtin_amdgcn_global_load_lds((const unsigned*)((const char*)(gbase) + (voff)[_i]), (PG8_LAS unsigned*)(lds + (bufoff) + ldsw + _i * 8192), 16, 0, 0); } while (0)
; #define PG8_LDA(dst, b, h) do { _Pragma("unroll") for (int m = 0; m < 4; ++m) _Pragma("unroll") for (int k = 0; k < 2; ++k) dst[m][k] = *(const PG8_LAS bf16x8*)(lds + PG8_SA(b, h) + aoff + m * 2048 + k * 1024); } while (0)
; #define PG8_LDB(dst, b, h) do { _Pragma("unroll") for (int n = 0; n < 2; ++n) _Pragma("unroll") for (int k = 0; k < 2; ++k) dst[n][k] = *(const PG8_LAS bf16x8*)(lds + PG8_SB(b, h) + boff + n * 2048 + k * 1024); } while (0)
; #define PG8_MMA(ai, bj, At, Bt) do { __builtin_amdgcn_s_setprio(1); _Pragma("unroll") for (int m = 0; m < 4; ++m) _Pragma("unroll") for (int n = 0; n < 2; ++n) _Pragma("unroll") for (int k = 0; k < 2; ++k) \
;         acc[ai][bj][m][n] = __builtin_amdgcn_mfma_f32_16x16x32_bf16(Bt[n][k], At[m][k], acc[ai][bj][m][n], 0, 0, 0); __builtin_amdgcn_s_setprio(0); } while (0)
; #define PG8_WAIT_V(n) asm volatile("s_waitcnt vmcnt(" #n ")" ::: "memory")
; #define PG8_WAIT_L(n) asm volatile("s_waitcnt lgkmcnt(" #n ")" ::: "memory")
; #define PG8_BAR __builtin_amdgcn_s_barrier()
; #define PG8_SCHED __builtin_amdgcn_sched_barrier(0)
; template <class Epi, class Sched, bool ALIGN_EPI = false, bool SP2 = false>
; __device__ __forceinline__ void gemm_phase(PG8_LAS unsigned char* lds, const Gemm g, const Sched& S, const Epi& E) {
;     ...
;             PG8_LDB(B0, 1, 0); PG8_LDB(B1, 1, 1); PG8_SCHED; PG8_LDA(At, 1, 0); PG8_STAGE(PG8_SA(0, 1), a2 + hstep, voffA);
;             PG8_WAIT_V(8); PG8_WAIT_L(0); PG8_BAR; PG8_MMA(0, 0, At, B0); PG8_MMA(0, 1, At, B1); PG8_BAR; PG8_SCHED;
;             PG8_LDA(At, 1, 1); PG8_STAGE(PG8_SB(1, 0), b3, voffB); PG8_STAGE(PG8_SB(1, 1), b3 + hstep, voffB); PG8_STAGE(PG8_SA(1, 0), a3, voffA);
;             PG8_WAIT_V(8); PG8_WAIT_L(0); PG8_BAR; PG8_MMA(1, 0, At, B0); PG8_MMA(1, 1, At, B1); PG8_BAR; PG8_SCHED;
	s_setprio 2
	s_waitcnt lgkmcnt(0)
	v_mfma_f32_16x16x32_bf16 v[126:129], v[130:133], v[176:179], v[126:129]
	v_mfma_f32_16x16x32_bf16 v[122:125], v[138:141], v[176:179], v[122:125]
	v_mfma_f32_16x16x32_bf16 v[110:113], v[130:133], v[184:187], v[110:113]
	v_mfma_f32_16x16x32_bf16 v[106:109], v[138:141], v[184:187], v[106:109]
	v_mfma_f32_16x16x32_bf16 v[94:97], v[130:133], v[202:205], v[94:97]
	v_mfma_f32_16x16x32_bf16 v[90:93], v[138:141], v[202:205], v[90:93]
	v_mfma_f32_16x16x32_bf16 v[78:81], v[130:133], v[210:213], v[78:81]
	v_mfma_f32_16x16x32_bf16 v[74:77], v[138:141], v[210:213], v[74:77]
	v_mfma_f32_16x16x32_bf16 v[126:129], v[134:137], v[180:183], v[126:129]
	v_mfma_f32_16x16x32_bf16 v[122:125], v[142:145], v[180:183], v[122:125]
	v_mfma_f32_16x16x32_bf16 v[110:113], v[134:137], v[188:191], v[110:113]
	v_mfma_f32_16x16x32_bf16 v[106:109], v[142:145], v[188:191], v[106:109]
	v_mfma_f32_16x16x32_bf16 v[94:97], v[134:137], v[206:209], v[94:97]
	v_mfma_f32_16x16x32_bf16 v[90:93], v[142:145], v[206:209], v[90:93]
	v_mfma_f32_16x16x32_bf16 v[78:81], v[134:137], v[214:217], v[78:81]
	v_mfma_f32_16x16x32_bf16 v[74:77], v[142:145], v[214:217], v[74:77]
	v_mfma_f32_16x16x32_bf16 v[118:121], v[146:149], v[176:179], v[118:121]
	v_mfma_f32_16x16x32_bf16 v[114:117], v[154:157], v[176:179], v[114:117]
	v_mfma_f32_16x16x32_bf16 v[102:105], v[146:149], v[184:187], v[102:105]
	v_mfma_f32_16x16x32_bf16 v[98:101], v[154:157], v[184:187], v[98:101]
	v_mfma_f32_16x16x32_bf16 v[86:89], v[146:149], v[202:205], v[86:89]
	v_mfma_f32_16x16x32_bf16 v[82:85], v[154:157], v[202:205], v[82:85]
	v_mfma_f32_16x16x32_bf16 v[70:73], v[146:149], v[210:213], v[70:73]
	v_mfma_f32_16x16x32_bf16 v[66:69], v[154:157], v[210:213], v[66:69]
	v_mfma_f32_16x16x32_bf16 v[118:121], v[150:153], v[180:183], v[118:121]
	v_mfma_f32_16x16x32_bf16 v[114:117], v[162:165], v[180:183], v[114:117]
	v_mfma_f32_16x16x32_bf16 v[102:105], v[150:153], v[188:191], v[102:105]
	v_mfma_f32_16x16x32_bf16 v[98:101], v[162:165], v[188:191], v[98:101]
	v_mfma_f32_16x16x32_bf16 v[86:89], v[150:153], v[206:209], v[86:89]
	v_mfma_f32_16x16x32_bf16 v[82:85], v[162:165], v[206:209], v[82:85]
	v_mfma_f32_16x16x32_bf16 v[70:73], v[150:153], v[214:217], v[70:73]
	v_mfma_f32_16x16x32_bf16 v[66:69], v[162:165], v[214:217], v[66:69]
	s_setprio 0
	s_add_i32 s36, s66, s47
	v_lshl_add_u64 v[192:193], v[192:193], 0, s[10:11]
	s_mov_b32 m0, s36
	ds_read_b128 v[176:179], v201 offset:49152
	ds_read_b128 v[180:183], v201 offset:50176
	ds_read_b128 v[184:187], v201 offset:51200
	ds_read_b128 v[188:191], v201 offset:52224
	ds_read_b128 v[202:205], v201 offset:53248
	ds_read_b128 v[206:209], v201 offset:54272
	ds_read_b128 v[210:213], v201 offset:55296
	ds_read_b128 v[214:217], v201 offset:56320
	global_load_lds_dwordx4 v[192:193], off
	s_add_i32 m0, s36, 0x2000
	s_add_u32 s30, s30, 0x80080
	v_lshl_add_u64 v[192:193], v[218:219], 0, s[10:11]
	s_addc_u32 s31, s31, 0
	s_add_i32 s36, s67, s47
	global_load_lds_dwordx4 v[192:193], off
	v_lshl_add_u64 v[192:193], s[30:31], 0, v[158:159]
	s_mov_b32 m0, s36
	s_nop 0
	global_load_lds_dwordx4 v[192:193], off
	v_lshl_add_u64 v[192:193], s[30:31], 0, v[166:167]
	s_add_i32 m0, s36, 0x2000
	s_nop 0
	global_load_lds_dwordx4 v[192:193], off
	s_waitcnt vmcnt(6)
	s_waitcnt lgkmcnt(0)
	s_barrier
	s_setprio 2
	s_waitcnt lgkmcnt(0)
	v_mfma_f32_16x16x32_bf16 v[62:65], v[130:133], v[176:179], v[62:65]
	v_mfma_f32_16x16x32_bf16 v[58:61], v[138:141], v[176:179], v[58:61]
	v_mfma_f32_16x16x32_bf16 v[46:49], v[130:133], v[184:187], v[46:49]
	v_mfma_f32_16x16x32_bf16 v[42:45], v[138:141], v[184:187], v[42:45]
	v_mfma_f32_16x16x32_bf16 v[30:33], v[130:133], v[202:205], v[30:33]
	v_mfma_f32_16x16x32_bf16 v[26:29], v[138:141], v[202:205], v[26:29]
	v_mfma_f32_16x16x32_bf16 v[14:17], v[130:133], v[210:213], v[14:17]
	v_mfma_f32_16x16x32_bf16 v[10:13], v[138:141], v[210:213], v[10:13]
	v_mfma_f32_16x16x32_bf16 v[62:65], v[134:137], v[180:183], v[62:65]
	v_mfma_f32_16x16x32_bf16 v[58:61], v[142:145], v[180:183], v[58:61]
	v_mfma_f32_16x16x32_bf16 v[46:49], v[134:137], v[188:191], v[46:49]
	v_mfma_f32_16x16x32_bf16 v[42:45], v[142:145], v[188:191], v[42:45]
	v_mfma_f32_16x16x32_bf16 v[30:33], v[134:137], v[206:209], v[30:33]
	v_mfma_f32_16x16x32_bf16 v[26:29], v[142:145], v[206:209], v[26:29]
	v_mfma_f32_16x16x32_bf16 v[14:17], v[134:137], v[214:217], v[14:17]
	v_mfma_f32_16x16x32_bf16 v[10:13], v[142:145], v[214:217], v[10:13]
	v_mfma_f32_16x16x32_bf16 v[54:57], v[146:149], v[176:179], v[54:57]
	v_mfma_f32_16x16x32_bf16 v[50:53], v[154:157], v[176:179], v[50:53]
	v_mfma_f32_16x16x32_bf16 v[38:41], v[146:149], v[184:187], v[38:41]
	v_mfma_f32_16x16x32_bf16 v[34:37], v[154:157], v[184:187], v[34:37]
	v_mfma_f32_16x16x32_bf16 v[22:25], v[146:149], v[202:205], v[22:25]
	v_mfma_f32_16x16x32_bf16 v[18:21], v[154:157], v[202:205], v[18:21]
	v_mfma_f32_16x16x32_bf16 v[6:9], v[146:149], v[210:213], v[6:9]
	v_mfma_f32_16x16x32_bf16 v[2:5], v[154:157], v[210:213], v[2:5]
	v_mfma_f32_16x16x32_bf16 v[54:57], v[150:153], v[180:183], v[54:57]
	v_mfma_f32_16x16x32_bf16 v[50:53], v[162:165], v[180:183], v[50:53]
	v_mfma_f32_16x16x32_bf16 v[38:41], v[150:153], v[188:191], v[38:41]
	v_mfma_f32_16x16x32_bf16 v[34:37], v[162:165], v[188:191], v[34:37]
	v_mfma_f32_16x16x32_bf16 v[22:25], v[150:153], v[206:209], v[22:25]
	v_mfma_f32_16x16x32_bf16 v[18:21], v[162:165], v[206:209], v[18:21]
	v_mfma_f32_16x16x32_bf16 v[6:9], v[150:153], v[214:217], v[6:9]
	v_mfma_f32_16x16x32_bf16 v[2:5], v[162:165], v[214:217], v[2:5]
	s_setprio 0
	s_add_i32 s63, s63, 2
	s_add_u32 s0, s0, 0x100
	s_addc_u32 s1, s1, 0
	s_add_u32 s61, s61, 0x100
	s_addc_u32 s62, s62, 0
	s_cmp_gt_u32 s63, 29
	s_cbranch_scc0 .Lhb_T_667

; #define PG8_BAR __builtin_amdgcn_s_barrier()
; template <class Epi, class Sched, bool ALIGN_EPI = false, bool SP2 = false>
; __device__ __forceinline__ void gemm_phase(PG8_LAS unsigned char* lds, const Gemm g, const Sched& S, const Epi& E) {
;     ...
;         if constexpr (!Epi::AFTER_DRAIN) { if constexpr (Epi::HAS_PREP) E(acc, cur, wr, wc, fr, fq, prep_gen & 1); else E(acc, cur, wr, wc, fr, fq); S.done(cur); }
;         if (!has_next) break;
; #pragma unroll
;         for (int a = 0; a < 2; ++a)
; #pragma unroll
;             for (int b = 0; b < 2; ++b)
; #pragma unroll
;                 for (int m = 0; m < 4; ++m)
; #pragma unroll
;                     for (int n = 0; n < 2; ++n) acc[a][b][m][n] = (f32x4){0.f, 0.f, 0.f, 0.f};
;         cur = nxt; cA = nA; cB = nB; ++ui;
;         if constexpr (Epi::HAS_PREP) { if (cur.pm != prep_pm) { ++prep_gen; E.prep(cur, tid, prep_gen & 1); prep_pm = cur.pm; } }
;         if constexpr (ALIGN_EPI) { if (wr == 1) PG8_BAR; }
.LBB0_686:
	s_or_b64 exec, exec, s[30:31]
	s_andn2_b64 vcc, exec, s[44:45]
	s_mov_b64 s[0:1], -1
	s_cbranch_vccnz .LBB0_659
	s_andn2_b64 vcc, exec, s[4:5]
	s_cbranch_vccnz .LBB0_658
	s_branch .LBB0_658

; #define PG8_STAGE(bufoff, gbase, voff) do { _Pragma("unroll") for (int _i = 0; _i < 2; ++_i) \
;         __builtin_amdgcn_global_load_lds((const unsigned*)((const char*)(gbase) + (voff)[_i]), (PG8_LAS unsigned*)(lds + (bufoff) + ldsw + _i * 8192), 16, 0, 0); } while (0)
; #define PG8_WAIT_V(n) asm volatile("s_waitcnt vmcnt(" #n ")" ::: "memory")
; #define PG8_BAR __builtin_amdgcn_s_barrier()
; template <class Epi, class Sched, bool ALIGN_EPI = false, bool SP2 = false>
; __device__ __forceinline__ void gemm_phase(PG8_LAS unsigned char* lds, const Gemm g, const Sched& S, const Epi& E) {
;     ...
;     for (int i = 0; i < 2; ++i) { int R, C; stage_rc(tid * 16 + i * 8192, R, C); const int Rb = Epi::PERM ? ((R & ~31) + perm32(R & 31)) : R;
;         voffA[i] = (unsigned)(R * K + C) * 2u; voffB[i] = (unsigned)(Rb * K + C) * 2u; }
;     const size_t kstep = (size_t)(BK * 2);
;     const size_t hstep = (size_t)HALF * K * 2;
;     const size_t tstep = 2 * hstep;
;     const unsigned ldsw = (unsigned)wid * 1024u;
;     const int aoff = lds_byte(wr * 64 + fr, fq * 8), boff = lds_byte(wc * 32 + fr, fq * 8);
;     ...
;     if constexpr (SP2) {
;         PG8_STAGE(PG8_SB(0, 0), cB, voffB); PG8_STAGE(PG8_SB(0, 1), cB + hstep, voffB); PG8_STAGE(PG8_SA(0, 0), cA, voffA); PG8_STAGE(PG8_SA(0, 1), cA + hstep, voffA);
;         if (wr == 1) PG8_BAR;
;         PG8_WAIT_V(2); PG8_BAR;
;         PG8_STAGE(PG8_SB(1, 0), cB + kstep, voffB); PG8_STAGE(PG8_SA(1, 0), cA + kstep, voffA); PG8_STAGE(PG8_SB(1, 1), cB + hstep + kstep, voffB);
;         PG8_WAIT_V(6); PG8_BAR;
.LBB0_750:
	s_or_b64 exec, exec, s[12:13]
	v_ashrrev_i32_e32 v3, 31, v144
	v_lshrrev_b32_e32 v3, 26, v3
	v_add_u32_e32 v3, v144, v3
	v_ashrrev_i32_e32 v10, 6, v3
	v_bfe_i32 v3, v144, 27, 1
	v_lshlrev_b32_e32 v2, 4, v144
	v_lshrrev_b32_e32 v3, 22, v3
	v_add_u32_e32 v3, v2, v3
	v_and_b32_e32 v3, 0xfffffc00, v3
	v_sub_u32_e32 v3, v2, v3
	s_add_u32 s21, s0, 0x1d800000
	v_lshrrev_b32_e32 v4, 4, v3
	s_addc_u32 s34, s1, 0
	s_lshl_b32 s12, s86, 25
	v_bitop3_b32 v3, v4, v3, 32 bitop3:0x6c
	s_add_u32 s12, s0, s12
	v_ashrrev_i32_e32 v5, 31, v3
	s_addc_u32 s13, s1, 0
	v_lshrrev_b32_e32 v5, 26, v5
	s_add_u32 s38, s12, 0xd800000
	v_add_u32_e32 v5, v3, v5
	s_addc_u32 s39, s13, 0
	v_readlane_b32 s12, v252, 14
	v_lshlrev_b32_e32 v4, 3, v10
	v_ashrrev_i32_e32 v11, 6, v5
	v_and_b32_e32 v5, 0xc0, v5
	v_readlane_b32 s13, v252, 15
	s_add_u32 s36, s21, s12
	v_and_b32_e32 v4, -16, v4
	v_sub_u32_e32 v3, v3, v5
	s_addc_u32 s37, s34, s13
	v_readlane_b32 s12, v254, 46
	v_add_u32_e32 v4, v11, v4
	v_ashrrev_i16_sdwa v3, v194, sext(v3) dst_sel:DWORD dst_unused:UNUSED_PAD src0_sel:DWORD src1_sel:BYTE_0
	s_add_u32 s30, s38, s12
	v_lshlrev_b32_e32 v6, 5, v10
	v_bfe_i32 v12, v3, 0, 16
	v_lshlrev_b32_e32 v3, 1, v4
	v_lshrrev_b32_e32 v5, 2, v4
	v_and_b32_e32 v7, 3, v11
	s_mov_b32 s12, 0xfffe0
	v_and_b32_e32 v6, 32, v6
	v_and_b32_e32 v3, 24, v3
	v_and_b32_e32 v5, 4, v5
	v_and_or_b32 v7, v4, s12, v7
	v_or3_b32 v3, v7, v5, v3
	v_add_lshl_u32 v5, v6, v12, 1
	v_add_u32_e32 v2, 0x2000, v2
	v_lshl_add_u32 v158, v3, 12, v5
	v_ashrrev_i32_e32 v3, 31, v2
	v_lshrrev_b32_e32 v3, 22, v3
	v_add_u32_e32 v3, v2, v3
	v_ashrrev_i32_e32 v13, 10, v3
	v_mul_i32_i24_e32 v3, 0x400, v13
	v_sub_u32_e32 v2, v2, v3
	v_lshrrev_b32_e32 v3, 4, v2
	v_bitop3_b32 v2, v3, v2, 32 bitop3:0x6c
	v_lshl_add_u32 v130, v4, 12, v5
	v_ashrrev_i32_e32 v4, 31, v2
	v_lshrrev_b32_e32 v4, 26, v4
	v_add_u32_e32 v4, v2, v4
	v_readlane_b32 s13, v254, 47
	v_lshlrev_b32_e32 v3, 3, v13
	v_ashrrev_i32_e32 v14, 6, v4
	v_and_b32_e32 v4, 0xc0, v4
	s_addc_u32 s31, s39, s13
	v_and_b32_e32 v3, -16, v3
	v_sub_u32_e32 v2, v2, v4
	s_ashr_i32 s17, s16, 6
	v_add_u32_e32 v3, v14, v3
	v_ashrrev_i16_sdwa v2, v194, sext(v2) dst_sel:DWORD dst_unused:UNUSED_PAD src0_sel:DWORD src1_sel:BYTE_0
	s_lshl_b32 s46, s17, 10
	v_lshlrev_b32_e32 v5, 5, v13
	v_bfe_i32 v15, v2, 0, 16
	v_lshlrev_b32_e32 v2, 1, v3
	v_lshrrev_b32_e32 v4, 2, v3
	v_and_b32_e32 v6, 3, v14
	s_add_i32 s47, s46, 0
	v_and_b32_e32 v5, 32, v5
	v_and_b32_e32 v2, 24, v2
	v_and_b32_e32 v4, 4, v4
	v_and_or_b32 v6, v3, s12, v6
	s_add_i32 m0, s47, 0x10000
	s_ashr_i32 s18, s16, 8
	v_or3_b32 v2, v6, v4, v2
	v_add_lshl_u32 v4, v5, v15, 1
	global_load_lds_dwordx4 v158, s[30:31]
	s_add_i32 m0, s47, 0x12000
	v_lshl_add_u32 v134, v2, 12, v4
	s_add_u32 s12, s30, 0x80000
	global_load_lds_dwordx4 v134, s[30:31]
	s_addc_u32 s13, s31, 0
	s_add_i32 m0, s47, 0x14000
	s_add_i32 s48, s47, 0x2000
	global_load_lds_dwordx4 v158, s[12:13]
	s_add_i32 m0, s47, 0x16000
	v_lshl_add_u32 v132, v3, 12, v4
	global_load_lds_dwordx4 v134, s[12:13]
	s_mov_b32 m0, s47
	s_add_u32 s12, s36, 0x80000
	global_load_lds_dwordx4 v130, s[36:37]
	s_mov_b32 m0, s48
	s_addc_u32 s13, s37, 0
	s_add_i32 s49, s47, 0x4000
	global_load_lds_dwordx4 v132, s[36:37]
	s_mov_b32 m0, s49
	s_add_i32 s50, s47, 0x6000
	global_load_lds_dwordx4 v130, s[12:13]
	s_mov_b32 m0, s50
	v_mov_b32_e32 v135, v159
	global_load_lds_dwordx4 v132, s[12:13]
	v_readlane_b32 s12, v253, 6
	v_readlane_b32 s13, v253, 7
	s_load_dword s51, s[12:13], 0x0
	v_mov_b32_e32 v131, v159
	v_mov_b32_e32 v133, v159
	s_cmp_eq_u32 s18, 1
	v_lshl_add_u64 v[8:9], s[30:31], 0, v[158:159]
	v_lshl_add_u64 v[6:7], s[30:31], 0, v[134:135]
	v_lshl_add_u64 v[2:3], s[36:37], 0, v[130:131]
	s_cselect_b64 s[12:13], -1, 0
	s_cmp_lg_u32 s18, 1
	v_lshl_add_u64 v[4:5], s[36:37], 0, v[132:133]
	s_cbranch_scc1 .LBB0_752
.LBB0_752:
	v_lshrrev_b32_e32 v17, 1, v144
	v_and_b32_e32 v17, 24, v17
	v_and_b32_e32 v16, 15, v144
	v_lshlrev_b32_e32 v18, 1, v17
	s_add_u32 s14, s0, 0x25800000
	v_lshl_or_b32 v145, s18, 6, v16
	v_lshl_or_b32 v18, v16, 6, v18
	v_lshlrev_b32_e32 v16, 2, v16
	s_addc_u32 s15, s1, 0
	s_lshl_b32 s0, s18, 13
	v_and_b32_e32 v19, 32, v16
	v_bitop3_b32 v20, v18, s0, v19 bitop3:0xde
	s_lshl_b32 s0, s17, 5
	s_and_b32 s19, s0, 0x60
	s_add_i32 m0, s47, 0x18000
	v_lshl_add_u64 v[8:9], v[8:9], 0, s[10:11]
	s_lshl_b32 s0, s19, 7
	s_waitcnt vmcnt(2)
	s_barrier
	global_load_lds_dwordx4 v[8:9], off
	v_lshl_add_u64 v[6:7], v[6:7], 0, s[10:11]
	s_add_i32 m0, s47, 0x1a000
	s_add_i32 s52, s47, 0x8000
	s_add_i32 s53, s47, 0xa000
	v_bitop3_b32 v146, v18, s0, v19 bitop3:0xde
	global_load_lds_dwordx4 v[6:7], off
	v_lshl_add_u64 v[2:3], v[2:3], 0, s[10:11]
	s_mov_b32 m0, s52
	s_add_u32 s0, s30, 0x80080
	global_load_lds_dwordx4 v[2:3], off
	v_lshl_add_u64 v[2:3], v[4:5], 0, s[10:11]
	s_mov_b32 m0, s53
	s_addc_u32 s1, s31, 0
	global_load_lds_dwordx4 v[2:3], off
	s_add_i32 m0, s47, 0x1c000
	v_lshl_add_u64 v[2:3], s[0:1], 0, v[158:159]
	global_load_lds_dwordx4 v[2:3], off
	v_lshl_add_u64 v[2:3], s[0:1], 0, v[134:135]
	s_add_i32 m0, s47, 0x1e000
	s_cmpk_lt_u32 s16, 0x100
	global_load_lds_dwordx4 v[2:3], off
	v_lshlrev_b32_e32 v2, 15, v10
	v_and_b32_e32 v2, 0xffff0000, v2
	v_lshl_add_u32 v2, v11, 12, v2
	v_and_b32_e32 v3, 1, v10
	v_lshl_or_b32 v2, v3, 6, v2
	v_lshl_add_u32 v136, v12, 1, v2
	v_lshlrev_b32_e32 v2, 15, v13
	s_cselect_b64 s[16:17], -1, 0
	s_lshl_b32 s0, s18, 8
	s_add_i32 s1, 0, 0x20000
	v_and_b32_e32 v2, 0xffff0000, v2
	s_waitcnt vmcnt(6)
	s_add_i32 s0, s1, s0
	v_lshl_add_u32 v2, v14, 12, v2
	v_and_b32_e32 v3, 1, v13
	v_add_u32_e32 v147, s0, v16
	v_lshl_add_u32 v148, v144, 2, s1
	v_lshl_or_b32 v2, v3, 6, v2
	v_readlane_b32 s0, v252, 12
	s_waitcnt lgkmcnt(0)
	s_ashr_i32 s54, s51, 31
	v_or_b32_e32 v149, s19, v17
	v_mov_b32_e32 v137, v159
	v_lshl_add_u32 v138, v15, 1, v2
	v_mov_b32_e32 v139, v159
	s_mov_b32 s55, 0
	v_add_u32_e32 v150, 0, v20
	v_readlane_b32 s58, v254, 45
	s_mov_b32 s59, s0
	s_mov_b32 s57, s0
	s_mov_b32 s56, 0
	s_barrier
	v_readlane_b32 s1, v252, 13
	s_branch .LBB0_755

; #define PG8_STAGE(bufoff, gbase, voff) do { _Pragma("unroll") for (int _i = 0; _i < 2; ++_i) \
;         __builtin_amdgcn_global_load_lds((const unsigned*)((const char*)(gbase) + (voff)[_i]), (PG8_LAS unsigned*)(lds + (bufoff) + ldsw + _i * 8192), 16, 0, 0); } while (0)
; #define PG8_LDA(dst, b, h) do { _Pragma("unroll") for (int m = 0; m < 4; ++m) _Pragma("unroll") for (int k = 0; k < 2; ++k) dst[m][k] = *(const PG8_LAS bf16x8*)(lds + PG8_SA(b, h) + aoff + m * 2048 + k * 1024); } while (0)
; #define PG8_LDB(dst, b, h) do { _Pragma("unroll") for (int n = 0; n < 2; ++n) _Pragma("unroll") for (int k = 0; k < 2; ++k) dst[n][k] = *(const PG8_LAS bf16x8*)(lds + PG8_SB(b, h) + boff + n * 2048 + k * 1024); } while (0)
; #define PG8_MMA(ai, bj, At, Bt) do { __builtin_amdgcn_s_setprio(1); _Pragma("unroll") for (int m = 0; m < 4; ++m) _Pragma("unroll") for (int n = 0; n < 2; ++n) _Pragma("unroll") for (int k = 0; k < 2; ++k) \
;         acc[ai][bj][m][n] = __builtin_amdgcn_mfma_f32_16x16x32_bf16(Bt[n][k], At[m][k], acc[ai][bj][m][n], 0, 0, 0); __builtin_amdgcn_s_setprio(0); } while (0)
; #define PG8_WAIT_V(n) asm volatile("s_waitcnt vmcnt(" #n ")" ::: "memory")
; #define PG8_WAIT_L(n) asm volatile("s_waitcnt lgkmcnt(" #n ")" ::: "memory")
; #define PG8_BAR __builtin_amdgcn_s_barrier()
; #define PG8_SCHED __builtin_amdgcn_sched_barrier(0)
; template <class Epi, class Sched, bool ALIGN_EPI = false, bool SP2 = false>
; __device__ __forceinline__ void gemm_phase(PG8_LAS unsigned char* lds, const Gemm g, const Sched& S, const Epi& E) {
;     ...
;             PG8_LDB(B0, 0, 0); PG8_LDB(B1, 0, 1); PG8_SCHED; PG8_LDA(At, 0, 0); PG8_STAGE(PG8_SA(1, 1), a1 + hstep, voffA);
;             PG8_WAIT_V(8); PG8_WAIT_L(0); PG8_BAR; PG8_MMA(0, 0, At, B0); PG8_MMA(0, 1, At, B1); PG8_BAR; PG8_SCHED;
;     ...
;         for (int a = 0; a < 2; ++a)
; #pragma unroll
;             for (int b = 0; b < 2; ++b)
; #pragma unroll
;                 for (int m = 0; m < 4; ++m)
; #pragma unroll
;                     for (int n = 0; n < 2; ++n) acc[a][b][m][n] = (f32x4){0.f, 0.f, 0.f, 0.f};
.LBB0_761:
	s_ashr_i32 s23, s22, 31
	s_lshl_b64 s[0:1], s[22:23], 20
	s_add_u32 s24, s21, s0
	s_addc_u32 s25, s34, s1
	s_and_b64 s[0:1], s[44:45], exec
	s_cselect_b32 s23, s25, s37
	s_cselect_b32 s60, s24, s36
	s_ashr_i32 s19, s18, 31
	s_lshl_b64 s[0:1], s[18:19], 20
	s_add_u32 s28, s38, s0
	s_addc_u32 s29, s39, s1
	s_and_b64 s[0:1], s[44:45], exec
	s_cselect_b32 s19, s29, s31
	s_cselect_b32 s61, s28, s30
	s_add_u32 s0, s36, 0x80080
	s_addc_u32 s1, s37, 0
	s_add_u32 s62, s30, 0x100
	v_mov_b32_e32 v2, 0
	s_addc_u32 s63, s31, 0
	s_mov_b32 s66, -2
	v_mov_b32_e32 v3, v2
	v_mov_b32_e32 v4, v2
	v_mov_b32_e32 v5, v2
	v_mov_b32_e32 v6, v2
	v_mov_b32_e32 v7, v2
	v_mov_b32_e32 v8, v2
	v_mov_b32_e32 v9, v2
	v_mov_b32_e32 v18, v2
	v_mov_b32_e32 v19, v2
	v_mov_b32_e32 v20, v2
	v_mov_b32_e32 v21, v2
	v_mov_b32_e32 v22, v2
	v_mov_b32_e32 v23, v2
	v_mov_b32_e32 v24, v2
	v_mov_b32_e32 v25, v2
	v_mov_b32_e32 v34, v2
	v_mov_b32_e32 v35, v2
	v_mov_b32_e32 v36, v2
	v_mov_b32_e32 v37, v2
	v_mov_b32_e32 v38, v2
	v_mov_b32_e32 v39, v2
	v_mov_b32_e32 v40, v2
	v_mov_b32_e32 v41, v2
	v_mov_b32_e32 v50, v2
	v_mov_b32_e32 v51, v2
	v_mov_b32_e32 v52, v2
	v_mov_b32_e32 v53, v2
	v_mov_b32_e32 v54, v2
	v_mov_b32_e32 v55, v2
	v_mov_b32_e32 v56, v2
	v_mov_b32_e32 v57, v2
	v_mov_b32_e32 v10, v2
	v_mov_b32_e32 v11, v2
	v_mov_b32_e32 v12, v2
	v_mov_b32_e32 v13, v2
	v_mov_b32_e32 v14, v2
	v_mov_b32_e32 v15, v2
	v_mov_b32_e32 v16, v2
	v_mov_b32_e32 v17, v2
	v_mov_b32_e32 v26, v2
	v_mov_b32_e32 v27, v2
	v_mov_b32_e32 v28, v2
	v_mov_b32_e32 v29, v2
	v_mov_b32_e32 v30, v2
	v_mov_b32_e32 v31, v2
	v_mov_b32_e32 v32, v2
	v_mov_b32_e32 v33, v2
	v_mov_b32_e32 v42, v2
	v_mov_b32_e32 v43, v2
	v_mov_b32_e32 v44, v2
	v_mov_b32_e32 v45, v2
	v_mov_b32_e32 v46, v2
	v_mov_b32_e32 v47, v2
	v_mov_b32_e32 v48, v2
	v_mov_b32_e32 v49, v2
	v_mov_b32_e32 v58, v2
	v_mov_b32_e32 v59, v2
	v_mov_b32_e32 v60, v2
	v_mov_b32_e32 v61, v2
	v_mov_b32_e32 v62, v2
	v_mov_b32_e32 v63, v2
	v_mov_b32_e32 v64, v2
	v_mov_b32_e32 v65, v2
	v_mov_b32_e32 v66, v2
	v_mov_b32_e32 v67, v2
	v_mov_b32_e32 v68, v2
	v_mov_b32_e32 v69, v2
	v_mov_b32_e32 v70, v2
	v_mov_b32_e32 v71, v2
	v_mov_b32_e32 v72, v2
	v_mov_b32_e32 v73, v2
	v_mov_b32_e32 v82, v2
	v_mov_b32_e32 v83, v2
	v_mov_b32_e32 v84, v2
	v_mov_b32_e32 v85, v2
	v_mov_b32_e32 v86, v2
	v_mov_b32_e32 v87, v2
	v_mov_b32_e32 v88, v2
	v_mov_b32_e32 v89, v2
	v_mov_b32_e32 v98, v2
	v_mov_b32_e32 v99, v2
	v_mov_b32_e32 v100, v2
	v_mov_b32_e32 v101, v2
	v_mov_b32_e32 v102, v2
	v_mov_b32_e32 v103, v2
	v_mov_b32_e32 v104, v2
	v_mov_b32_e32 v105, v2
	v_mov_b32_e32 v114, v2
	v_mov_b32_e32 v115, v2
	v_mov_b32_e32 v116, v2
	v_mov_b32_e32 v117, v2
	v_mov_b32_e32 v118, v2
	v_mov_b32_e32 v119, v2
	v_mov_b32_e32 v120, v2
	v_mov_b32_e32 v121, v2
	v_mov_b32_e32 v74, v2
	v_mov_b32_e32 v75, v2
	v_mov_b32_e32 v76, v2
	v_mov_b32_e32 v77, v2
	v_mov_b32_e32 v78, v2
	v_mov_b32_e32 v79, v2
	v_mov_b32_e32 v80, v2
	v_mov_b32_e32 v81, v2
	v_mov_b32_e32 v90, v2
	v_mov_b32_e32 v91, v2
	v_mov_b32_e32 v92, v2
	v_mov_b32_e32 v93, v2
	v_mov_b32_e32 v94, v2
	v_mov_b32_e32 v95, v2
	v_mov_b32_e32 v96, v2
	v_mov_b32_e32 v97, v2
	v_mov_b32_e32 v106, v2
	v_mov_b32_e32 v107, v2
	v_mov_b32_e32 v108, v2
	v_mov_b32_e32 v109, v2
	v_mov_b32_e32 v110, v2
	v_mov_b32_e32 v111, v2
	v_mov_b32_e32 v112, v2
	v_mov_b32_e32 v113, v2
	v_mov_b32_e32 v122, v2
	v_mov_b32_e32 v123, v2
	v_mov_b32_e32 v124, v2
	v_mov_b32_e32 v125, v2
	v_mov_b32_e32 v126, v2
	v_mov_b32_e32 v127, v2
	v_mov_b32_e32 v128, v2
	v_mov_b32_e32 v129, v2
	s_and_b64 vcc, exec, s[12:13]
	s_cbranch_vccnz .Lhb_T_762
.LBB0_762:
	s_add_u32 s30, s0, 0xfff80080
	s_addc_u32 s31, s1, -1
	s_add_i32 s67, 0, 0x10000
	s_cmp_eq_u32 s66, 28
	s_cselect_b32 s37, s23, s31
	s_cselect_b32 s36, s60, s30
	v_add_u32_e32 v151, s67, v146
	s_cselect_b32 s31, s19, s63
	s_cselect_b32 s30, s61, s62
	s_add_i32 s70, 0, 0x14000
	ds_read_b128 v[140:143], v151
	ds_read_b128 v[152:155], v151 offset:1024
	ds_read_b128 v[162:165], v151 offset:2048
	ds_read_b128 v[166:169], v151 offset:3072
	v_add_u32_e32 v151, s70, v146
	ds_read_b128 v[170:173], v151
	ds_read_b128 v[174:177], v151 offset:1024
	ds_read_b128 v[178:181], v151 offset:2048
	ds_read_b128 v[182:185], v151 offset:3072
	s_add_u32 s98, s0, 0xfff80000
	s_addc_u32 s99, s1, -1
	v_lshl_add_u64 v[156:157], s[98:99], 0, v[136:137]
	s_mov_b32 m0, s52
	s_nop 0
	global_load_lds_dwordx4 v[156:157], off
	v_lshl_add_u64 v[156:157], s[98:99], 0, v[138:139]
	s_mov_b32 m0, s53
	s_nop 0
	global_load_lds_dwordx4 v[156:157], off
	v_lshl_add_u64 v[156:157], s[0:1], 0, v[136:137]
	s_add_i32 m0, s47, 0xc000
	ds_read_b128 v[186:189], v150
	ds_read_b128 v[190:193], v150 offset:1024
	ds_read_b128 v[200:203], v150 offset:2048
	ds_read_b128 v[204:207], v150 offset:3072
	ds_read_b128 v[208:211], v150 offset:4096
	ds_read_b128 v[212:215], v150 offset:5120
	ds_read_b128 v[216:219], v150 offset:6144
	ds_read_b128 v[220:223], v150 offset:7168
	global_load_lds_dwordx4 v[156:157], off
	v_lshl_add_u64 v[156:157], s[0:1], 0, v[138:139]
	s_add_i32 m0, s47, 0xe000
	s_nop 0
	global_load_lds_dwordx4 v[156:157], off
	s_waitcnt lgkmcnt(0)
	s_setprio 1
	s_waitcnt lgkmcnt(0)
; #define PG8_STAGE(bufoff, gbase, voff) do { _Pragma("unroll") for (int _i = 0; _i < 2; ++_i) \
;         __builtin_amdgcn_global_load_lds((const unsigned*)((const char*)(gbase) + (voff)[_i]), (PG8_LAS unsigned*)(lds + (bufoff) + ldsw + _i * 8192), 16, 0, 0); } while (0)
; #define PG8_LDA(dst, b, h) do { _Pragma("unroll") for (int m = 0; m < 4; ++m) _Pragma("unroll") for (int k = 0; k < 2; ++k) dst[m][k] = *(const PG8_LAS bf16x8*)(lds + PG8_SA(b, h) + aoff + m * 2048 + k * 1024); } while (0)
; #define PG8_MMA(ai, bj, At, Bt) do { __builtin_amdgcn_s_setprio(1); _Pragma("unroll") for (int m = 0; m < 4; ++m) _Pragma("unroll") for (int n = 0; n < 2; ++n) _Pragma("unroll") for (int k = 0; k < 2; ++k) \
;         acc[ai][bj][m][n] = __builtin_amdgcn_mfma_f32_16x16x32_bf16(Bt[n][k], At[m][k], acc[ai][bj][m][n], 0, 0, 0); __builtin_amdgcn_s_setprio(0); } while (0)
; #define PG8_WAIT_V(n) asm volatile("s_waitcnt vmcnt(" #n ")" ::: "memory")
; #define PG8_WAIT_L(n) asm volatile("s_waitcnt lgkmcnt(" #n ")" ::: "memory")
; #define PG8_BAR __builtin_amdgcn_s_barrier()
; #define PG8_SCHED __builtin_amdgcn_sched_barrier(0)
; template <class Epi, class Sched, bool ALIGN_EPI = false, bool SP2 = false>
; __device__ __forceinline__ void gemm_phase(PG8_LAS unsigned char* lds, const Gemm g, const Sched& S, const Epi& E) {
;     ...
;             PG8_WAIT_V(8); PG8_WAIT_L(0); PG8_BAR; PG8_MMA(0, 0, At, B0); PG8_MMA(0, 1, At, B1); PG8_BAR; PG8_SCHED;
;             PG8_LDA(At, 0, 1); PG8_STAGE(PG8_SB(0, 0), b2, voffB); PG8_STAGE(PG8_SB(0, 1), b2 + hstep, voffB); PG8_STAGE(PG8_SA(0, 0), a2, voffA);
;             PG8_WAIT_V(8); PG8_WAIT_L(0); PG8_BAR; PG8_MMA(1, 0, At, B0); PG8_MMA(1, 1, At, B1); PG8_BAR; PG8_SCHED;
	v_mfma_f32_16x16x32_bf16 v[126:129], v[140:143], v[186:189], v[126:129]
	v_mfma_f32_16x16x32_bf16 v[122:125], v[162:165], v[186:189], v[122:125]
	v_mfma_f32_16x16x32_bf16 v[110:113], v[140:143], v[200:203], v[110:113]
	v_mfma_f32_16x16x32_bf16 v[106:109], v[162:165], v[200:203], v[106:109]
	v_mfma_f32_16x16x32_bf16 v[94:97], v[140:143], v[208:211], v[94:97]
	v_mfma_f32_16x16x32_bf16 v[90:93], v[162:165], v[208:211], v[90:93]
	v_mfma_f32_16x16x32_bf16 v[78:81], v[140:143], v[216:219], v[78:81]
	v_mfma_f32_16x16x32_bf16 v[74:77], v[162:165], v[216:219], v[74:77]
	v_mfma_f32_16x16x32_bf16 v[126:129], v[152:155], v[190:193], v[126:129]
	v_mfma_f32_16x16x32_bf16 v[122:125], v[166:169], v[190:193], v[122:125]
	v_mfma_f32_16x16x32_bf16 v[110:113], v[152:155], v[204:207], v[110:113]
	v_mfma_f32_16x16x32_bf16 v[106:109], v[166:169], v[204:207], v[106:109]
	v_mfma_f32_16x16x32_bf16 v[94:97], v[152:155], v[212:215], v[94:97]
	v_mfma_f32_16x16x32_bf16 v[90:93], v[166:169], v[212:215], v[90:93]
	v_mfma_f32_16x16x32_bf16 v[78:81], v[152:155], v[220:223], v[78:81]
	v_mfma_f32_16x16x32_bf16 v[74:77], v[166:169], v[220:223], v[74:77]
	v_mfma_f32_16x16x32_bf16 v[118:121], v[170:173], v[186:189], v[118:121]
	v_mfma_f32_16x16x32_bf16 v[114:117], v[178:181], v[186:189], v[114:117]
	v_mfma_f32_16x16x32_bf16 v[102:105], v[170:173], v[200:203], v[102:105]
	v_mfma_f32_16x16x32_bf16 v[98:101], v[178:181], v[200:203], v[98:101]
	v_mfma_f32_16x16x32_bf16 v[86:89], v[170:173], v[208:211], v[86:89]
	v_mfma_f32_16x16x32_bf16 v[82:85], v[178:181], v[208:211], v[82:85]
	v_mfma_f32_16x16x32_bf16 v[70:73], v[170:173], v[216:219], v[70:73]
	v_mfma_f32_16x16x32_bf16 v[66:69], v[178:181], v[216:219], v[66:69]
	v_mfma_f32_16x16x32_bf16 v[118:121], v[174:177], v[190:193], v[118:121]
	v_mfma_f32_16x16x32_bf16 v[114:117], v[182:185], v[190:193], v[114:117]
	v_mfma_f32_16x16x32_bf16 v[102:105], v[174:177], v[204:207], v[102:105]
	v_mfma_f32_16x16x32_bf16 v[98:101], v[182:185], v[204:207], v[98:101]
	v_mfma_f32_16x16x32_bf16 v[86:89], v[174:177], v[212:215], v[86:89]
	v_mfma_f32_16x16x32_bf16 v[82:85], v[182:185], v[212:215], v[82:85]
	v_mfma_f32_16x16x32_bf16 v[70:73], v[174:177], v[220:223], v[70:73]
	v_mfma_f32_16x16x32_bf16 v[66:69], v[182:185], v[220:223], v[66:69]
	s_setprio 0
	s_waitcnt vmcnt(8)
	s_barrier
	s_add_i32 s67, s67, s46
	v_lshl_add_u64 v[156:157], s[30:31], 0, v[158:159]
	s_mov_b32 m0, s67
	ds_read_b128 v[186:189], v150 offset:16384
	ds_read_b128 v[190:193], v150 offset:17408
	ds_read_b128 v[200:203], v150 offset:18432
	ds_read_b128 v[204:207], v150 offset:19456
	ds_read_b128 v[208:211], v150 offset:20480
	ds_read_b128 v[212:215], v150 offset:21504
	ds_read_b128 v[216:219], v150 offset:22528
	ds_read_b128 v[220:223], v150 offset:23552
	global_load_lds_dwordx4 v[156:157], off
	s_add_i32 m0, s67, 0x2000
	s_add_u32 s68, s30, 0x80000
	v_lshl_add_u64 v[224:225], s[30:31], 0, v[134:135]
	s_addc_u32 s69, s31, 0
	s_add_i32 s67, s70, s46
	global_load_lds_dwordx4 v[224:225], off
	v_lshl_add_u64 v[226:227], s[68:69], 0, v[158:159]
	s_mov_b32 m0, s67
	v_lshl_add_u64 v[228:229], s[36:37], 0, v[132:133]
	global_load_lds_dwordx4 v[226:227], off
	v_lshl_add_u64 v[226:227], s[68:69], 0, v[134:135]
	s_add_i32 m0, s67, 0x2000
	s_nop 0
	global_load_lds_dwordx4 v[226:227], off
	v_lshl_add_u64 v[226:227], s[36:37], 0, v[130:131]
	s_waitcnt lgkmcnt(0)
	s_setprio 1
	s_waitcnt lgkmcnt(0)
	v_mfma_f32_16x16x32_bf16 v[62:65], v[140:143], v[186:189], v[62:65]
	v_mfma_f32_16x16x32_bf16 v[58:61], v[162:165], v[186:189], v[58:61]
	v_mfma_f32_16x16x32_bf16 v[46:49], v[140:143], v[200:203], v[46:49]
	v_mfma_f32_16x16x32_bf16 v[42:45], v[162:165], v[200:203], v[42:45]
	v_mfma_f32_16x16x32_bf16 v[30:33], v[140:143], v[208:211], v[30:33]
	v_mfma_f32_16x16x32_bf16 v[26:29], v[162:165], v[208:211], v[26:29]
	v_mfma_f32_16x16x32_bf16 v[14:17], v[140:143], v[216:219], v[14:17]
	v_mfma_f32_16x16x32_bf16 v[10:13], v[162:165], v[216:219], v[10:13]
	v_mfma_f32_16x16x32_bf16 v[62:65], v[152:155], v[190:193], v[62:65]
	v_mfma_f32_16x16x32_bf16 v[58:61], v[166:169], v[190:193], v[58:61]
	v_mfma_f32_16x16x32_bf16 v[46:49], v[152:155], v[204:207], v[46:49]
	v_mfma_f32_16x16x32_bf16 v[42:45], v[166:169], v[204:207], v[42:45]
	v_mfma_f32_16x16x32_bf16 v[30:33], v[152:155], v[212:215], v[30:33]
	v_mfma_f32_16x16x32_bf16 v[26:29], v[166:169], v[212:215], v[26:29]
	v_mfma_f32_16x16x32_bf16 v[14:17], v[152:155], v[220:223], v[14:17]
	v_mfma_f32_16x16x32_bf16 v[10:13], v[166:169], v[220:223], v[10:13]
	v_mfma_f32_16x16x32_bf16 v[54:57], v[170:173], v[186:189], v[54:57]
	v_mfma_f32_16x16x32_bf16 v[50:53], v[178:181], v[186:189], v[50:53]
	v_mfma_f32_16x16x32_bf16 v[38:41], v[170:173], v[200:203], v[38:41]
	v_mfma_f32_16x16x32_bf16 v[34:37], v[178:181], v[200:203], v[34:37]
	v_mfma_f32_16x16x32_bf16 v[22:25], v[170:173], v[208:211], v[22:25]
	v_mfma_f32_16x16x32_bf16 v[18:21], v[178:181], v[208:211], v[18:21]
	v_mfma_f32_16x16x32_bf16 v[6:9], v[170:173], v[216:219], v[6:9]
	v_mfma_f32_16x16x32_bf16 v[2:5], v[178:181], v[216:219], v[2:5]
	v_mfma_f32_16x16x32_bf16 v[54:57], v[174:177], v[190:193], v[54:57]
	v_mfma_f32_16x16x32_bf16 v[50:53], v[182:185], v[190:193], v[50:53]
	v_mfma_f32_16x16x32_bf16 v[38:41], v[174:177], v[204:207], v[38:41]
	v_mfma_f32_16x16x32_bf16 v[34:37], v[182:185], v[204:207], v[34:37]
	v_mfma_f32_16x16x32_bf16 v[22:25], v[174:177], v[212:215], v[22:25]
	v_mfma_f32_16x16x32_bf16 v[18:21], v[182:185], v[212:215], v[18:21]
	v_mfma_f32_16x16x32_bf16 v[6:9], v[174:177], v[220:223], v[6:9]
	v_mfma_f32_16x16x32_bf16 v[2:5], v[182:185], v[220:223], v[2:5]
	s_setprio 0
	s_waitcnt vmcnt(6)
	s_barrier
; #define PG8_STAGE(bufoff, gbase, voff) do { _Pragma("unroll") for (int _i = 0; _i < 2; ++_i) \
;         __builtin_amdgcn_global_load_lds((const unsigned*)((const char*)(gbase) + (voff)[_i]), (PG8_LAS unsigned*)(lds + (bufoff) + ldsw + _i * 8192), 16, 0, 0); } while (0)
; #define PG8_LDA(dst, b, h) do { _Pragma("unroll") for (int m = 0; m < 4; ++m) _Pragma("unroll") for (int k = 0; k < 2; ++k) dst[m][k] = *(const PG8_LAS bf16x8*)(lds + PG8_SA(b, h) + aoff + m * 2048 + k * 1024); } while (0)
; #define PG8_LDB(dst, b, h) do { _Pragma("unroll") for (int n = 0; n < 2; ++n) _Pragma("unroll") for (int k = 0; k < 2; ++k) dst[n][k] = *(const PG8_LAS bf16x8*)(lds + PG8_SB(b, h) + boff + n * 2048 + k * 1024); } while (0)
; #define PG8_MMA(ai, bj, At, Bt) do { __builtin_amdgcn_s_setprio(1); _Pragma("unroll") for (int m = 0; m < 4; ++m) _Pragma("unroll") for (int n = 0; n < 2; ++n) _Pragma("unroll") for (int k = 0; k < 2; ++k) \
;         acc[ai][bj][m][n] = __builtin_amdgcn_mfma_f32_16x16x32_bf16(Bt[n][k], At[m][k], acc[ai][bj][m][n], 0, 0, 0); __builtin_amdgcn_s_setprio(0); } while (0)
; #define PG8_WAIT_V(n) asm volatile("s_waitcnt vmcnt(" #n ")" ::: "memory")
; #define PG8_WAIT_L(n) asm volatile("s_waitcnt lgkmcnt(" #n ")" ::: "memory")
; #define PG8_BAR __builtin_amdgcn_s_barrier()
; #define PG8_SCHED __builtin_amdgcn_sched_barrier(0)
; template <class Epi, class Sched, bool ALIGN_EPI = false, bool SP2 = false>
; __device__ __forceinline__ void gemm_phase(PG8_LAS unsigned char* lds, const Gemm g, const Sched& S, const Epi& E) {
;     ...
;             PG8_LDB(B0, 1, 0); PG8_LDB(B1, 1, 1); PG8_SCHED; PG8_LDA(At, 1, 0); PG8_STAGE(PG8_SA(0, 1), a2 + hstep, voffA);
;             PG8_WAIT_V(8); PG8_WAIT_L(0); PG8_BAR; PG8_MMA(0, 0, At, B0); PG8_MMA(0, 1, At, B1); PG8_BAR; PG8_SCHED;
;             PG8_LDA(At, 1, 1); PG8_STAGE(PG8_SB(1, 0), b3, voffB); PG8_STAGE(PG8_SB(1, 1), b3 + hstep, voffB); PG8_STAGE(PG8_SA(1, 0), a3, voffA);
;             PG8_WAIT_V(8); PG8_WAIT_L(0); PG8_BAR; PG8_MMA(1, 0, At, B0); PG8_MMA(1, 1, At, B1); PG8_BAR; PG8_SCHED;
	s_add_i32 s67, 0, 0x18000
	v_add_u32_e32 v151, s67, v146
	s_add_i32 s68, 0, 0x1c000
	ds_read_b128 v[140:143], v151
	ds_read_b128 v[152:155], v151 offset:1024
	ds_read_b128 v[162:165], v151 offset:2048
	ds_read_b128 v[166:169], v151 offset:3072
	v_add_u32_e32 v151, s68, v146
	ds_read_b128 v[170:173], v151
	ds_read_b128 v[174:177], v151 offset:1024
	ds_read_b128 v[178:181], v151 offset:2048
	ds_read_b128 v[182:185], v151 offset:3072
	s_add_u32 s36, s36, 0x80000
	s_addc_u32 s37, s37, 0
	s_mov_b32 m0, s47
	s_nop 0
	global_load_lds_dwordx4 v[226:227], off
	s_mov_b32 m0, s48
	s_nop 0
	global_load_lds_dwordx4 v[228:229], off
	s_mov_b32 m0, s49
	v_lshl_add_u64 v[230:231], s[36:37], 0, v[130:131]
	ds_read_b128 v[186:189], v150 offset:32768
	ds_read_b128 v[190:193], v150 offset:33792
	ds_read_b128 v[200:203], v150 offset:34816
	ds_read_b128 v[204:207], v150 offset:35840
	ds_read_b128 v[208:211], v150 offset:36864
	ds_read_b128 v[212:215], v150 offset:37888
	ds_read_b128 v[216:219], v150 offset:38912
	ds_read_b128 v[220:223], v150 offset:39936
	global_load_lds_dwordx4 v[230:231], off
	v_lshl_add_u64 v[230:231], s[36:37], 0, v[132:133]
	s_mov_b32 m0, s50
	s_nop 0
	global_load_lds_dwordx4 v[230:231], off
	s_waitcnt lgkmcnt(0)
	s_setprio 1
	s_waitcnt lgkmcnt(0)
	v_mfma_f32_16x16x32_bf16 v[126:129], v[140:143], v[186:189], v[126:129]
	v_mfma_f32_16x16x32_bf16 v[122:125], v[162:165], v[186:189], v[122:125]
	v_mfma_f32_16x16x32_bf16 v[110:113], v[140:143], v[200:203], v[110:113]
	v_mfma_f32_16x16x32_bf16 v[106:109], v[162:165], v[200:203], v[106:109]
	v_mfma_f32_16x16x32_bf16 v[94:97], v[140:143], v[208:211], v[94:97]
	v_mfma_f32_16x16x32_bf16 v[90:93], v[162:165], v[208:211], v[90:93]
	v_mfma_f32_16x16x32_bf16 v[78:81], v[140:143], v[216:219], v[78:81]
	v_mfma_f32_16x16x32_bf16 v[74:77], v[162:165], v[216:219], v[74:77]
	v_mfma_f32_16x16x32_bf16 v[126:129], v[152:155], v[190:193], v[126:129]
	v_mfma_f32_16x16x32_bf16 v[122:125], v[166:169], v[190:193], v[122:125]
	v_mfma_f32_16x16x32_bf16 v[110:113], v[152:155], v[204:207], v[110:113]
	v_mfma_f32_16x16x32_bf16 v[106:109], v[166:169], v[204:207], v[106:109]
	v_mfma_f32_16x16x32_bf16 v[94:97], v[152:155], v[212:215], v[94:97]
	v_mfma_f32_16x16x32_bf16 v[90:93], v[166:169], v[212:215], v[90:93]
	v_mfma_f32_16x16x32_bf16 v[78:81], v[152:155], v[220:223], v[78:81]
	v_mfma_f32_16x16x32_bf16 v[74:77], v[166:169], v[220:223], v[74:77]
	v_mfma_f32_16x16x32_bf16 v[118:121], v[170:173], v[186:189], v[118:121]
	v_mfma_f32_16x16x32_bf16 v[114:117], v[178:181], v[186:189], v[114:117]
	v_mfma_f32_16x16x32_bf16 v[102:105], v[170:173], v[200:203], v[102:105]
	v_mfma_f32_16x16x32_bf16 v[98:101], v[178:181], v[200:203], v[98:101]
	v_mfma_f32_16x16x32_bf16 v[86:89], v[170:173], v[208:211], v[86:89]
	v_mfma_f32_16x16x32_bf16 v[82:85], v[178:181], v[208:211], v[82:85]
	v_mfma_f32_16x16x32_bf16 v[70:73], v[170:173], v[216:219], v[70:73]
	v_mfma_f32_16x16x32_bf16 v[66:69], v[178:181], v[216:219], v[66:69]
	v_mfma_f32_16x16x32_bf16 v[118:121], v[174:177], v[190:193], v[118:121]
	v_mfma_f32_16x16x32_bf16 v[114:117], v[182:185], v[190:193], v[114:117]
	v_mfma_f32_16x16x32_bf16 v[102:105], v[174:177], v[204:207], v[102:105]
	v_mfma_f32_16x16x32_bf16 v[98:101], v[182:185], v[204:207], v[98:101]
	v_mfma_f32_16x16x32_bf16 v[86:89], v[174:177], v[212:215], v[86:89]
	v_mfma_f32_16x16x32_bf16 v[82:85], v[182:185], v[212:215], v[82:85]
	v_mfma_f32_16x16x32_bf16 v[70:73], v[174:177], v[220:223], v[70:73]
	v_mfma_f32_16x16x32_bf16 v[66:69], v[182:185], v[220:223], v[66:69]
	s_setprio 0
	s_waitcnt vmcnt(8)
	s_barrier
	s_add_i32 s36, s67, s46
	v_lshl_add_u64 v[156:157], v[156:157], 0, s[10:11]
	s_mov_b32 m0, s36
	ds_read_b128 v[186:189], v150 offset:49152
	ds_read_b128 v[190:193], v150 offset:50176
	ds_read_b128 v[200:203], v150 offset:51200
	ds_read_b128 v[204:207], v150 offset:52224
	ds_read_b128 v[208:211], v150 offset:53248
	ds_read_b128 v[212:215], v150 offset:54272
	ds_read_b128 v[216:219], v150 offset:55296
	ds_read_b128 v[220:223], v150 offset:56320
	global_load_lds_dwordx4 v[156:157], off
	s_add_i32 m0, s36, 0x2000
	s_add_u32 s30, s30, 0x80080
	v_lshl_add_u64 v[156:157], v[224:225], 0, s[10:11]
	s_addc_u32 s31, s31, 0
	s_add_i32 s36, s68, s46
	global_load_lds_dwordx4 v[156:157], off
	v_lshl_add_u64 v[156:157], s[30:31], 0, v[158:159]
	s_mov_b32 m0, s36
	s_nop 0
	global_load_lds_dwordx4 v[156:157], off
	v_lshl_add_u64 v[156:157], s[30:31], 0, v[134:135]
	s_add_i32 m0, s36, 0x2000
	s_nop 0
	global_load_lds_dwordx4 v[156:157], off
	s_waitcnt lgkmcnt(0)
	s_setprio 1
	s_waitcnt lgkmcnt(0)
	v_mfma_f32_16x16x32_bf16 v[62:65], v[140:143], v[186:189], v[62:65]
	v_mfma_f32_16x16x32_bf16 v[58:61], v[162:165], v[186:189], v[58:61]
	v_mfma_f32_16x16x32_bf16 v[46:49], v[140:143], v[200:203], v[46:49]
	v_mfma_f32_16x16x32_bf16 v[42:45], v[162:165], v[200:203], v[42:45]
	v_mfma_f32_16x16x32_bf16 v[30:33], v[140:143], v[208:211], v[30:33]
	v_mfma_f32_16x16x32_bf16 v[26:29], v[162:165], v[208:211], v[26:29]
	v_mfma_f32_16x16x32_bf16 v[14:17], v[140:143], v[216:219], v[14:17]
	v_mfma_f32_16x16x32_bf16 v[10:13], v[162:165], v[216:219], v[10:13]
	v_mfma_f32_16x16x32_bf16 v[62:65], v[152:155], v[190:193], v[62:65]
	v_mfma_f32_16x16x32_bf16 v[58:61], v[166:169], v[190:193], v[58:61]
	v_mfma_f32_16x16x32_bf16 v[46:49], v[152:155], v[204:207], v[46:49]
	v_mfma_f32_16x16x32_bf16 v[42:45], v[166:169], v[204:207], v[42:45]
	v_mfma_f32_16x16x32_bf16 v[30:33], v[152:155], v[212:215], v[30:33]
	v_mfma_f32_16x16x32_bf16 v[26:29], v[166:169], v[212:215], v[26:29]
	v_mfma_f32_16x16x32_bf16 v[14:17], v[152:155], v[220:223], v[14:17]
	v_mfma_f32_16x16x32_bf16 v[10:13], v[166:169], v[220:223], v[10:13]
	v_mfma_f32_16x16x32_bf16 v[54:57], v[170:173], v[186:189], v[54:57]
	v_mfma_f32_16x16x32_bf16 v[50:53], v[178:181], v[186:189], v[50:53]
	v_mfma_f32_16x16x32_bf16 v[38:41], v[170:173], v[200:203], v[38:41]
	v_mfma_f32_16x16x32_bf16 v[34:37], v[178:181], v[200:203], v[34:37]
	v_mfma_f32_16x16x32_bf16 v[22:25], v[170:173], v[208:211], v[22:25]
	v_mfma_f32_16x16x32_bf16 v[18:21], v[178:181], v[208:211], v[18:21]
	v_mfma_f32_16x16x32_bf16 v[6:9], v[170:173], v[216:219], v[6:9]
	v_mfma_f32_16x16x32_bf16 v[2:5], v[178:181], v[216:219], v[2:5]
	v_mfma_f32_16x16x32_bf16 v[54:57], v[174:177], v[190:193], v[54:57]
	v_mfma_f32_16x16x32_bf16 v[50:53], v[182:185], v[190:193], v[50:53]
	v_mfma_f32_16x16x32_bf16 v[38:41], v[174:177], v[204:207], v[38:41]
	v_mfma_f32_16x16x32_bf16 v[34:37], v[182:185], v[204:207], v[34:37]
	v_mfma_f32_16x16x32_bf16 v[22:25], v[174:177], v[212:215], v[22:25]
	v_mfma_f32_16x16x32_bf16 v[18:21], v[182:185], v[212:215], v[18:21]
	v_mfma_f32_16x16x32_bf16 v[6:9], v[174:177], v[220:223], v[6:9]
	v_mfma_f32_16x16x32_bf16 v[2:5], v[182:185], v[220:223], v[2:5]
	s_setprio 0
	s_waitcnt vmcnt(6)
	s_barrier
	s_add_i32 s66, s66, 2
	s_add_u32 s0, s0, 0x100
	s_addc_u32 s1, s1, 0
	s_add_u32 s62, s62, 0x100
	s_addc_u32 s63, s63, 0
	s_cmp_gt_u32 s66, 29
	s_cbranch_scc0 .LBB0_762
	s_branch .Lhb_X_762
; #define PG8_STAGE(bufoff, gbase, voff) do { _Pragma("unroll") for (int _i = 0; _i < 2; ++_i) \
;         __builtin_amdgcn_global_load_lds((const unsigned*)((const char*)(gbase) + (voff)[_i]), (PG8_LAS unsigned*)(lds + (bufoff) + ldsw + _i * 8192), 16, 0, 0); } while (0)
; #define PG8_LDA(dst, b, h) do { _Pragma("unroll") for (int m = 0; m < 4; ++m) _Pragma("unroll") for (int k = 0; k < 2; ++k) dst[m][k] = *(const PG8_LAS bf16x8*)(lds + PG8_SA(b, h) + aoff + m * 2048 + k * 1024); } while (0)
; #define PG8_LDB(dst, b, h) do { _Pragma("unroll") for (int n = 0; n < 2; ++n) _Pragma("unroll") for (int k = 0; k < 2; ++k) dst[n][k] = *(const PG8_LAS bf16x8*)(lds + PG8_SB(b, h) + boff + n * 2048 + k * 1024); } while (0)
; #define PG8_MMA(ai, bj, At, Bt) do { __builtin_amdgcn_s_setprio(1); _Pragma("unroll") for (int m = 0; m < 4; ++m) _Pragma("unroll") for (int n = 0; n < 2; ++n) _Pragma("unroll") for (int k = 0; k < 2; ++k) \
;         acc[ai][bj][m][n] = __builtin_amdgcn_mfma_f32_16x16x32_bf16(Bt[n][k], At[m][k], acc[ai][bj][m][n], 0, 0, 0); __builtin_amdgcn_s_setprio(0); } while (0)
; #define PG8_WAIT_V(n) asm volatile("s_waitcnt vmcnt(" #n ")" ::: "memory")
; #define PG8_WAIT_L(n) asm volatile("s_waitcnt lgkmcnt(" #n ")" ::: "memory")
; #define PG8_BAR __builtin_amdgcn_s_barrier()
; #define PG8_SCHED __builtin_amdgcn_sched_barrier(0)
; template <class Epi, class Sched, bool ALIGN_EPI = false, bool SP2 = false>
; __device__ __forceinline__ void gemm_phase(PG8_LAS unsigned char* lds, const Gemm g, const Sched& S, const Epi& E) {
;     ...
;             if constexpr (SP2) {
;             PG8_LDB(B0, 0, 0); PG8_LDB(B1, 0, 1); PG8_SCHED; PG8_LDA(At, 0, 0); PG8_STAGE(PG8_SA(1, 1), a1 + hstep, voffA);
;             PG8_WAIT_V(8); PG8_WAIT_L(0); PG8_BAR; PG8_MMA(0, 0, At, B0); PG8_MMA(0, 1, At, B1); PG8_BAR; PG8_SCHED;
;             PG8_LDA(At, 0, 1); PG8_STAGE(PG8_SB(0, 0), b2, voffB); PG8_STAGE(PG8_SB(0, 1), b2 + hstep, voffB); PG8_STAGE(PG8_SA(0, 0), a2, voffA);
;             PG8_WAIT_V(8); PG8_WAIT_L(0); PG8_BAR; PG8_MMA(1, 0, At, B0); PG8_MMA(1, 1, At, B1); PG8_BAR; PG8_SCHED;
.Lhb_T_762:
	s_add_u32 s30, s0, 0xfff80080
	s_addc_u32 s31, s1, -1
	s_add_i32 s67, 0, 0x10000
	s_cmp_eq_u32 s66, 28
	s_cselect_b32 s37, s23, s31
	s_cselect_b32 s36, s60, s30
	v_add_u32_e32 v151, s67, v146
	s_cselect_b32 s31, s19, s63
	s_cselect_b32 s30, s61, s62
	s_add_i32 s70, 0, 0x14000
	ds_read_b128 v[140:143], v151
	ds_read_b128 v[152:155], v151 offset:1024
	ds_read_b128 v[162:165], v151 offset:2048
	ds_read_b128 v[166:169], v151 offset:3072
	v_add_u32_e32 v151, s70, v146
	ds_read_b128 v[170:173], v151
	ds_read_b128 v[174:177], v151 offset:1024
	ds_read_b128 v[178:181], v151 offset:2048
	ds_read_b128 v[182:185], v151 offset:3072
	s_add_u32 s98, s0, 0xfff80000
	s_addc_u32 s99, s1, -1
	v_lshl_add_u64 v[156:157], s[98:99], 0, v[136:137]
	s_mov_b32 m0, s52
	s_nop 0
	global_load_lds_dwordx4 v[156:157], off
	v_lshl_add_u64 v[156:157], s[98:99], 0, v[138:139]
	s_mov_b32 m0, s53
	s_nop 0
	global_load_lds_dwordx4 v[156:157], off
	v_lshl_add_u64 v[156:157], s[0:1], 0, v[136:137]
	s_add_i32 m0, s47, 0xc000
	ds_read_b128 v[186:189], v150
	ds_read_b128 v[190:193], v150 offset:1024
	ds_read_b128 v[200:203], v150 offset:2048
	ds_read_b128 v[204:207], v150 offset:3072
	ds_read_b128 v[208:211], v150 offset:4096
	ds_read_b128 v[212:215], v150 offset:5120
	ds_read_b128 v[216:219], v150 offset:6144
	ds_read_b128 v[220:223], v150 offset:7168
	global_load_lds_dwordx4 v[156:157], off
	v_lshl_add_u64 v[156:157], s[0:1], 0, v[138:139]
	s_add_i32 m0, s47, 0xe000
	s_nop 0
	global_load_lds_dwordx4 v[156:157], off
	s_waitcnt vmcnt(8)
	s_waitcnt lgkmcnt(0)
	s_barrier
	s_setprio 2
	s_waitcnt lgkmcnt(0)
	v_mfma_f32_16x16x32_bf16 v[126:129], v[140:143], v[186:189], v[126:129]
	v_mfma_f32_16x16x32_bf16 v[122:125], v[162:165], v[186:189], v[122:125]
	v_mfma_f32_16x16x32_bf16 v[110:113], v[140:143], v[200:203], v[110:113]
	v_mfma_f32_16x16x32_bf16 v[106:109], v[162:165], v[200:203], v[106:109]
	v_mfma_f32_16x16x32_bf16 v[94:97], v[140:143], v[208:211], v[94:97]
	v_mfma_f32_16x16x32_bf16 v[90:93], v[162:165], v[208:211], v[90:93]
	v_mfma_f32_16x16x32_bf16 v[78:81], v[140:143], v[216:219], v[78:81]
	v_mfma_f32_16x16x32_bf16 v[74:77], v[162:165], v[216:219], v[74:77]
	v_mfma_f32_16x16x32_bf16 v[126:129], v[152:155], v[190:193], v[126:129]
	v_mfma_f32_16x16x32_bf16 v[122:125], v[166:169], v[190:193], v[122:125]
	v_mfma_f32_16x16x32_bf16 v[110:113], v[152:155], v[204:207], v[110:113]
	v_mfma_f32_16x16x32_bf16 v[106:109], v[166:169], v[204:207], v[106:109]
	v_mfma_f32_16x16x32_bf16 v[94:97], v[152:155], v[212:215], v[94:97]
	v_mfma_f32_16x16x32_bf16 v[90:93], v[166:169], v[212:215], v[90:93]
	v_mfma_f32_16x16x32_bf16 v[78:81], v[152:155], v[220:223], v[78:81]
	v_mfma_f32_16x16x32_bf16 v[74:77], v[166:169], v[220:223], v[74:77]
	v_mfma_f32_16x16x32_bf16 v[118:121], v[170:173], v[186:189], v[118:121]
	v_mfma_f32_16x16x32_bf16 v[114:117], v[178:181], v[186:189], v[114:117]
	v_mfma_f32_16x16x32_bf16 v[102:105], v[170:173], v[200:203], v[102:105]
	v_mfma_f32_16x16x32_bf16 v[98:101], v[178:181], v[200:203], v[98:101]
	v_mfma_f32_16x16x32_bf16 v[86:89], v[170:173], v[208:211], v[86:89]
	v_mfma_f32_16x16x32_bf16 v[82:85], v[178:181], v[208:211], v[82:85]
	v_mfma_f32_16x16x32_bf16 v[70:73], v[170:173], v[216:219], v[70:73]
	v_mfma_f32_16x16x32_bf16 v[66:69], v[178:181], v[216:219], v[66:69]
	v_mfma_f32_16x16x32_bf16 v[118:121], v[174:177], v[190:193], v[118:121]
	v_mfma_f32_16x16x32_bf16 v[114:117], v[182:185], v[190:193], v[114:117]
	v_mfma_f32_16x16x32_bf16 v[102:105], v[174:177], v[204:207], v[102:105]
	v_mfma_f32_16x16x32_bf16 v[98:101], v[182:185], v[204:207], v[98:101]
	v_mfma_f32_16x16x32_bf16 v[86:89], v[174:177], v[212:215], v[86:89]
	v_mfma_f32_16x16x32_bf16 v[82:85], v[182:185], v[212:215], v[82:85]
	v_mfma_f32_16x16x32_bf16 v[70:73], v[174:177], v[220:223], v[70:73]
	v_mfma_f32_16x16x32_bf16 v[66:69], v[182:185], v[220:223], v[66:69]
	s_setprio 0
	s_add_i32 s67, s67, s46
	v_lshl_add_u64 v[156:157], s[30:31], 0, v[158:159]
	s_mov_b32 m0, s67
	ds_read_b128 v[186:189], v150 offset:16384
	ds_read_b128 v[190:193], v150 offset:17408
	ds_read_b128 v[200:203], v150 offset:18432
	ds_read_b128 v[204:207], v150 offset:19456
	ds_read_b128 v[208:211], v150 offset:20480
	ds_read_b128 v[212:215], v150 offset:21504
	ds_read_b128 v[216:219], v150 offset:22528
	ds_read_b128 v[220:223], v150 offset:23552
	global_load_lds_dwordx4 v[156:157], off
	s_add_i32 m0, s67, 0x2000
	s_add_u32 s68, s30, 0x80000
	v_lshl_add_u64 v[224:225], s[30:31], 0, v[134:135]
	s_addc_u32 s69, s31, 0
	s_add_i32 s67, s70, s46
	global_load_lds_dwordx4 v[224:225], off
	v_lshl_add_u64 v[226:227], s[68:69], 0, v[158:159]
	s_mov_b32 m0, s67
	v_lshl_add_u64 v[228:229], s[36:37], 0, v[132:133]
	global_load_lds_dwordx4 v[226:227], off
	v_lshl_add_u64 v[226:227], s[68:69], 0, v[134:135]
	s_add_i32 m0, s67, 0x2000
	s_nop 0
	global_load_lds_dwordx4 v[226:227], off
	v_lshl_add_u64 v[226:227], s[36:37], 0, v[130:131]
	s_waitcnt vmcnt(6)
	s_waitcnt lgkmcnt(0)
	s_barrier
; #define PG8_STAGE(bufoff, gbase, voff) do { _Pragma("unroll") for (int _i = 0; _i < 2; ++_i) \
;         __builtin_amdgcn_global_load_lds((const unsigned*)((const char*)(gbase) + (voff)[_i]), (PG8_LAS unsigned*)(lds + (bufoff) + ldsw + _i * 8192), 16, 0, 0); } while (0)
; #define PG8_LDA(dst, b, h) do { _Pragma("unroll") for (int m = 0; m < 4; ++m) _Pragma("unroll") for (int k = 0; k < 2; ++k) dst[m][k] = *(const PG8_LAS bf16x8*)(lds + PG8_SA(b, h) + aoff + m * 2048 + k * 1024); } while (0)
; #define PG8_LDB(dst, b, h) do { _Pragma("unroll") for (int n = 0; n < 2; ++n) _Pragma("unroll") for (int k = 0; k < 2; ++k) dst[n][k] = *(const PG8_LAS bf16x8*)(lds + PG8_SB(b, h) + boff + n * 2048 + k * 1024); } while (0)
; #define PG8_MMA(ai, bj, At, Bt) do { __builtin_amdgcn_s_setprio(1); _Pragma("unroll") for (int m = 0; m < 4; ++m) _Pragma("unroll") for (int n = 0; n < 2; ++n) _Pragma("unroll") for (int k = 0; k < 2; ++k) \
;         acc[ai][bj][m][n] = __builtin_amdgcn_mfma_f32_16x16x32_bf16(Bt[n][k], At[m][k], acc[ai][bj][m][n], 0, 0, 0); __builtin_amdgcn_s_setprio(0); } while (0)
; #define PG8_WAIT_V(n) asm volatile("s_waitcnt vmcnt(" #n ")" ::: "memory")
; #define PG8_WAIT_L(n) asm volatile("s_waitcnt lgkmcnt(" #n ")" ::: "memory")
; #define PG8_BAR __builtin_amdgcn_s_barrier()
; #define PG8_SCHED __builtin_amdgcn_sched_barrier(0)
; template <class Epi, class Sched, bool ALIGN_EPI = false, bool SP2 = false>
; __device__ __forceinline__ void gemm_phase(PG8_LAS unsigned char* lds, const Gemm g, const Sched& S, const Epi& E) {
;     ...
;             PG8_WAIT_V(8); PG8_WAIT_L(0); PG8_BAR; PG8_MMA(1, 0, At, B0); PG8_MMA(1, 1, At, B1); PG8_BAR; PG8_SCHED;
;             PG8_LDB(B0, 1, 0); PG8_LDB(B1, 1, 1); PG8_SCHED; PG8_LDA(At, 1, 0); PG8_STAGE(PG8_SA(0, 1), a2 + hstep, voffA);
	s_setprio 2
	s_waitcnt lgkmcnt(0)
	v_mfma_f32_16x16x32_bf16 v[62:65], v[140:143], v[186:189], v[62:65]
	v_mfma_f32_16x16x32_bf16 v[58:61], v[162:165], v[186:189], v[58:61]
	v_mfma_f32_16x16x32_bf16 v[46:49], v[140:143], v[200:203], v[46:49]
	v_mfma_f32_16x16x32_bf16 v[42:45], v[162:165], v[200:203], v[42:45]
	v_mfma_f32_16x16x32_bf16 v[30:33], v[140:143], v[208:211], v[30:33]
	v_mfma_f32_16x16x32_bf16 v[26:29], v[162:165], v[208:211], v[26:29]
	v_mfma_f32_16x16x32_bf16 v[14:17], v[140:143], v[216:219], v[14:17]
	v_mfma_f32_16x16x32_bf16 v[10:13], v[162:165], v[216:219], v[10:13]
	v_mfma_f32_16x16x32_bf16 v[62:65], v[152:155], v[190:193], v[62:65]
	v_mfma_f32_16x16x32_bf16 v[58:61], v[166:169], v[190:193], v[58:61]
	v_mfma_f32_16x16x32_bf16 v[46:49], v[152:155], v[204:207], v[46:49]
	v_mfma_f32_16x16x32_bf16 v[42:45], v[166:169], v[204:207], v[42:45]
	v_mfma_f32_16x16x32_bf16 v[30:33], v[152:155], v[212:215], v[30:33]
	v_mfma_f32_16x16x32_bf16 v[26:29], v[166:169], v[212:215], v[26:29]
	v_mfma_f32_16x16x32_bf16 v[14:17], v[152:155], v[220:223], v[14:17]
	v_mfma_f32_16x16x32_bf16 v[10:13], v[166:169], v[220:223], v[10:13]
	v_mfma_f32_16x16x32_bf16 v[54:57], v[170:173], v[186:189], v[54:57]
	v_mfma_f32_16x16x32_bf16 v[50:53], v[178:181], v[186:189], v[50:53]
	v_mfma_f32_16x16x32_bf16 v[38:41], v[170:173], v[200:203], v[38:41]
	v_mfma_f32_16x16x32_bf16 v[34:37], v[178:181], v[200:203], v[34:37]
	v_mfma_f32_16x16x32_bf16 v[22:25], v[170:173], v[208:211], v[22:25]
	v_mfma_f32_16x16x32_bf16 v[18:21], v[178:181], v[208:211], v[18:21]
	v_mfma_f32_16x16x32_bf16 v[6:9], v[170:173], v[216:219], v[6:9]
	v_mfma_f32_16x16x32_bf16 v[2:5], v[178:181], v[216:219], v[2:5]
	v_mfma_f32_16x16x32_bf16 v[54:57], v[174:177], v[190:193], v[54:57]
	v_mfma_f32_16x16x32_bf16 v[50:53], v[182:185], v[190:193], v[50:53]
	v_mfma_f32_16x16x32_bf16 v[38:41], v[174:177], v[204:207], v[38:41]
	v_mfma_f32_16x16x32_bf16 v[34:37], v[182:185], v[204:207], v[34:37]
	v_mfma_f32_16x16x32_bf16 v[22:25], v[174:177], v[212:215], v[22:25]
	v_mfma_f32_16x16x32_bf16 v[18:21], v[182:185], v[212:215], v[18:21]
	v_mfma_f32_16x16x32_bf16 v[6:9], v[174:177], v[220:223], v[6:9]
	v_mfma_f32_16x16x32_bf16 v[2:5], v[182:185], v[220:223], v[2:5]
	s_setprio 0
	s_add_i32 s67, 0, 0x18000
	v_add_u32_e32 v151, s67, v146
	s_add_i32 s68, 0, 0x1c000
	ds_read_b128 v[140:143], v151
	ds_read_b128 v[152:155], v151 offset:1024
	ds_read_b128 v[162:165], v151 offset:2048
	ds_read_b128 v[166:169], v151 offset:3072
	v_add_u32_e32 v151, s68, v146
	ds_read_b128 v[170:173], v151
	ds_read_b128 v[174:177], v151 offset:1024
	ds_read_b128 v[178:181], v151 offset:2048
	ds_read_b128 v[182:185], v151 offset:3072
	s_add_u32 s36, s36, 0x80000
	s_addc_u32 s37, s37, 0
	s_mov_b32 m0, s47
	s_nop 0
	global_load_lds_dwordx4 v[226:227], off
	s_mov_b32 m0, s48
	s_nop 0
	global_load_lds_dwordx4 v[228:229], off
	s_mov_b32 m0, s49
	v_lshl_add_u64 v[230:231], s[36:37], 0, v[130:131]
	ds_read_b128 v[186:189], v150 offset:32768
	ds_read_b128 v[190:193], v150 offset:33792
	ds_read_b128 v[200:203], v150 offset:34816
	ds_read_b128 v[204:207], v150 offset:35840
	ds_read_b128 v[208:211], v150 offset:36864
	ds_read_b128 v[212:215], v150 offset:37888
	ds_read_b128 v[216:219], v150 offset:38912
	ds_read_b128 v[220:223], v150 offset:39936
	global_load_lds_dwordx4 v[230:231], off
	v_lshl_add_u64 v[230:231], s[36:37], 0, v[132:133]
	s_mov_b32 m0, s50
	s_nop 0
	global_load_lds_dwordx4 v[230:231], off
	s_waitcnt vmcnt(8)
	s_waitcnt lgkmcnt(0)
	s_barrier
; #define PG8_STAGE(bufoff, gbase, voff) do { _Pragma("unroll") for (int _i = 0; _i < 2; ++_i) \
;         __builtin_amdgcn_global_load_lds((const unsigned*)((const char*)(gbase) + (voff)[_i]), (PG8_LAS unsigned*)(lds + (bufoff) + ldsw + _i * 8192), 16, 0, 0); } while (0)
; #define PG8_LDA(dst, b, h) do { _Pragma("unroll") for (int m = 0; m < 4; ++m) _Pragma("unroll") for (int k = 0; k < 2; ++k) dst[m][k] = *(const PG8_LAS bf16x8*)(lds + PG8_SA(b, h) + aoff + m * 2048 + k * 1024); } while (0)
; #define PG8_LDB(dst, b, h) do { _Pragma("unroll") for (int n = 0; n < 2; ++n) _Pragma("unroll") for (int k = 0; k < 2; ++k) dst[n][k] = *(const PG8_LAS bf16x8*)(lds + PG8_SB(b, h) + boff + n * 2048 + k * 1024); } while (0)
; #define PG8_MMA(ai, bj, At, Bt) do { __builtin_amdgcn_s_setprio(1); _Pragma("unroll") for (int m = 0; m < 4; ++m) _Pragma("unroll") for (int n = 0; n < 2; ++n) _Pragma("unroll") for (int k = 0; k < 2; ++k) \
;         acc[ai][bj][m][n] = __builtin_amdgcn_mfma_f32_16x16x32_bf16(Bt[n][k], At[m][k], acc[ai][bj][m][n], 0, 0, 0); __builtin_amdgcn_s_setprio(0); } while (0)
; #define PG8_WAIT_V(n) asm volatile("s_waitcnt vmcnt(" #n ")" ::: "memory")
; #define PG8_WAIT_L(n) asm volatile("s_waitcnt lgkmcnt(" #n ")" ::: "memory")
; #define PG8_BAR __builtin_amdgcn_s_barrier()
; #define PG8_SCHED __builtin_amdgcn_sched_barrier(0)
; template <class Epi, class Sched, bool ALIGN_EPI = false, bool SP2 = false>
; __device__ __forceinline__ void gemm_phase(PG8_LAS unsigned char* lds, const Gemm g, const Sched& S, const Epi& E) {
;     ...
;             PG8_LDB(B0, 1, 0); PG8_LDB(B1, 1, 1); PG8_SCHED; PG8_LDA(At, 1, 0); PG8_STAGE(PG8_SA(0, 1), a2 + hstep, voffA);
;             PG8_WAIT_V(8); PG8_WAIT_L(0); PG8_BAR; PG8_MMA(0, 0, At, B0); PG8_MMA(0, 1, At, B1); PG8_BAR; PG8_SCHED;
;             PG8_LDA(At, 1, 1); PG8_STAGE(PG8_SB(1, 0), b3, voffB); PG8_STAGE(PG8_SB(1, 1), b3 + hstep, voffB); PG8_STAGE(PG8_SA(1, 0), a3, voffA);
;             PG8_WAIT_V(8); PG8_WAIT_L(0); PG8_BAR; PG8_MMA(1, 0, At, B0); PG8_MMA(1, 1, At, B1); PG8_BAR; PG8_SCHED;
;     ...
;         if constexpr (ALIGN_EPI) { if (wr == 0) PG8_BAR; }
	s_setprio 2
	s_waitcnt lgkmcnt(0)
	v_mfma_f32_16x16x32_bf16 v[126:129], v[140:143], v[186:189], v[126:129]
	v_mfma_f32_16x16x32_bf16 v[122:125], v[162:165], v[186:189], v[122:125]
	v_mfma_f32_16x16x32_bf16 v[110:113], v[140:143], v[200:203], v[110:113]
	v_mfma_f32_16x16x32_bf16 v[106:109], v[162:165], v[200:203], v[106:109]
	v_mfma_f32_16x16x32_bf16 v[94:97], v[140:143], v[208:211], v[94:97]
	v_mfma_f32_16x16x32_bf16 v[90:93], v[162:165], v[208:211], v[90:93]
	v_mfma_f32_16x16x32_bf16 v[78:81], v[140:143], v[216:219], v[78:81]
	v_mfma_f32_16x16x32_bf16 v[74:77], v[162:165], v[216:219], v[74:77]
	v_mfma_f32_16x16x32_bf16 v[126:129], v[152:155], v[190:193], v[126:129]
	v_mfma_f32_16x16x32_bf16 v[122:125], v[166:169], v[190:193], v[122:125]
	v_mfma_f32_16x16x32_bf16 v[110:113], v[152:155], v[204:207], v[110:113]
	v_mfma_f32_16x16x32_bf16 v[106:109], v[166:169], v[204:207], v[106:109]
	v_mfma_f32_16x16x32_bf16 v[94:97], v[152:155], v[212:215], v[94:97]
	v_mfma_f32_16x16x32_bf16 v[90:93], v[166:169], v[212:215], v[90:93]
	v_mfma_f32_16x16x32_bf16 v[78:81], v[152:155], v[220:223], v[78:81]
	v_mfma_f32_16x16x32_bf16 v[74:77], v[166:169], v[220:223], v[74:77]
	v_mfma_f32_16x16x32_bf16 v[118:121], v[170:173], v[186:189], v[118:121]
	v_mfma_f32_16x16x32_bf16 v[114:117], v[178:181], v[186:189], v[114:117]
	v_mfma_f32_16x16x32_bf16 v[102:105], v[170:173], v[200:203], v[102:105]
	v_mfma_f32_16x16x32_bf16 v[98:101], v[178:181], v[200:203], v[98:101]
	v_mfma_f32_16x16x32_bf16 v[86:89], v[170:173], v[208:211], v[86:89]
	v_mfma_f32_16x16x32_bf16 v[82:85], v[178:181], v[208:211], v[82:85]
	v_mfma_f32_16x16x32_bf16 v[70:73], v[170:173], v[216:219], v[70:73]
	v_mfma_f32_16x16x32_bf16 v[66:69], v[178:181], v[216:219], v[66:69]
	v_mfma_f32_16x16x32_bf16 v[118:121], v[174:177], v[190:193], v[118:121]
	v_mfma_f32_16x16x32_bf16 v[114:117], v[182:185], v[190:193], v[114:117]
	v_mfma_f32_16x16x32_bf16 v[102:105], v[174:177], v[204:207], v[102:105]
	v_mfma_f32_16x16x32_bf16 v[98:101], v[182:185], v[204:207], v[98:101]
	v_mfma_f32_16x16x32_bf16 v[86:89], v[174:177], v[212:215], v[86:89]
	v_mfma_f32_16x16x32_bf16 v[82:85], v[182:185], v[212:215], v[82:85]
	v_mfma_f32_16x16x32_bf16 v[70:73], v[174:177], v[220:223], v[70:73]
	v_mfma_f32_16x16x32_bf16 v[66:69], v[182:185], v[220:223], v[66:69]
	s_setprio 0
	s_add_i32 s36, s67, s46
	v_lshl_add_u64 v[156:157], v[156:157], 0, s[10:11]
	s_mov_b32 m0, s36
	ds_read_b128 v[186:189], v150 offset:49152
	ds_read_b128 v[190:193], v150 offset:50176
	ds_read_b128 v[200:203], v150 offset:51200
	ds_read_b128 v[204:207], v150 offset:52224
	ds_read_b128 v[208:211], v150 offset:53248
	ds_read_b128 v[212:215], v150 offset:54272
	ds_read_b128 v[216:219], v150 offset:55296
	ds_read_b128 v[220:223], v150 offset:56320
	global_load_lds_dwordx4 v[156:157], off
	s_add_i32 m0, s36, 0x2000
	s_add_u32 s30, s30, 0x80080
	v_lshl_add_u64 v[156:157], v[224:225], 0, s[10:11]
	s_addc_u32 s31, s31, 0
	s_add_i32 s36, s68, s46
	global_load_lds_dwordx4 v[156:157], off
	v_lshl_add_u64 v[156:157], s[30:31], 0, v[158:159]
	s_mov_b32 m0, s36
	s_nop 0
	global_load_lds_dwordx4 v[156:157], off
	v_lshl_add_u64 v[156:157], s[30:31], 0, v[134:135]
	s_add_i32 m0, s36, 0x2000
	s_nop 0
	global_load_lds_dwordx4 v[156:157], off
	s_waitcnt vmcnt(6)
	s_waitcnt lgkmcnt(0)
	s_barrier
	s_setprio 2
	s_waitcnt lgkmcnt(0)
	v_mfma_f32_16x16x32_bf16 v[62:65], v[140:143], v[186:189], v[62:65]
	v_mfma_f32_16x16x32_bf16 v[58:61], v[162:165], v[186:189], v[58:61]
	v_mfma_f32_16x16x32_bf16 v[46:49], v[140:143], v[200:203], v[46:49]
	v_mfma_f32_16x16x32_bf16 v[42:45], v[162:165], v[200:203], v[42:45]
	v_mfma_f32_16x16x32_bf16 v[30:33], v[140:143], v[208:211], v[30:33]
	v_mfma_f32_16x16x32_bf16 v[26:29], v[162:165], v[208:211], v[26:29]
	v_mfma_f32_16x16x32_bf16 v[14:17], v[140:143], v[216:219], v[14:17]
	v_mfma_f32_16x16x32_bf16 v[10:13], v[162:165], v[216:219], v[10:13]
	v_mfma_f32_16x16x32_bf16 v[62:65], v[152:155], v[190:193], v[62:65]
	v_mfma_f32_16x16x32_bf16 v[58:61], v[166:169], v[190:193], v[58:61]
	v_mfma_f32_16x16x32_bf16 v[46:49], v[152:155], v[204:207], v[46:49]
	v_mfma_f32_16x16x32_bf16 v[42:45], v[166:169], v[204:207], v[42:45]
	v_mfma_f32_16x16x32_bf16 v[30:33], v[152:155], v[212:215], v[30:33]
	v_mfma_f32_16x16x32_bf16 v[26:29], v[166:169], v[212:215], v[26:29]
	v_mfma_f32_16x16x32_bf16 v[14:17], v[152:155], v[220:223], v[14:17]
	v_mfma_f32_16x16x32_bf16 v[10:13], v[166:169], v[220:223], v[10:13]
	v_mfma_f32_16x16x32_bf16 v[54:57], v[170:173], v[186:189], v[54:57]
	v_mfma_f32_16x16x32_bf16 v[50:53], v[178:181], v[186:189], v[50:53]
	v_mfma_f32_16x16x32_bf16 v[38:41], v[170:173], v[200:203], v[38:41]
	v_mfma_f32_16x16x32_bf16 v[34:37], v[178:181], v[200:203], v[34:37]
	v_mfma_f32_16x16x32_bf16 v[22:25], v[170:173], v[208:211], v[22:25]
	v_mfma_f32_16x16x32_bf16 v[18:21], v[178:181], v[208:211], v[18:21]
	v_mfma_f32_16x16x32_bf16 v[6:9], v[170:173], v[216:219], v[6:9]
	v_mfma_f32_16x16x32_bf16 v[2:5], v[178:181], v[216:219], v[2:5]
	v_mfma_f32_16x16x32_bf16 v[54:57], v[174:177], v[190:193], v[54:57]
	v_mfma_f32_16x16x32_bf16 v[50:53], v[182:185], v[190:193], v[50:53]
	v_mfma_f32_16x16x32_bf16 v[38:41], v[174:177], v[204:207], v[38:41]
	v_mfma_f32_16x16x32_bf16 v[34:37], v[182:185], v[204:207], v[34:37]
	v_mfma_f32_16x16x32_bf16 v[22:25], v[174:177], v[212:215], v[22:25]
	v_mfma_f32_16x16x32_bf16 v[18:21], v[182:185], v[212:215], v[18:21]
	v_mfma_f32_16x16x32_bf16 v[6:9], v[174:177], v[220:223], v[6:9]
	v_mfma_f32_16x16x32_bf16 v[2:5], v[182:185], v[220:223], v[2:5]
	s_setprio 0
	s_add_i32 s66, s66, 2
	s_add_u32 s0, s0, 0x100
	s_addc_u32 s1, s1, 0
	s_add_u32 s62, s62, 0x100
	s_addc_u32 s63, s63, 0
	s_cmp_gt_u32 s66, 29
	s_cbranch_scc0 .Lhb_T_762
.Lhb_X_762:
	s_and_b64 vcc, exec, s[16:17]
	s_mov_b64 s[60:61], s[90:91]
	s_mov_b64 s[62:63], s[88:89]
	s_cbranch_vccz .LBB0_765

; #define PG8_BAR __builtin_amdgcn_s_barrier()
; template <class Epi, class Sched, bool ALIGN_EPI = false, bool SP2 = false>
; __device__ __forceinline__ void gemm_phase(PG8_LAS unsigned char* lds, const Gemm g, const Sched& S, const Epi& E) {
;     ...
;         cur = nxt; cA = nA; cB = nB; ++ui;
;         if constexpr (Epi::HAS_PREP) { if (cur.pm != prep_pm) { ++prep_gen; E.prep(cur, tid, prep_gen & 1); prep_pm = cur.pm; } }
;         if constexpr (ALIGN_EPI) { if (wr == 1) PG8_BAR; }
.LBB0_770:
	s_andn2_b64 vcc, exec, s[12:13]
	s_cbranch_vccnz .LBB0_753
	s_branch .LBB0_753

; #define PG8_STAGE(bufoff, gbase, voff) do { _Pragma("unroll") for (int _i = 0; _i < 2; ++_i) \
;         __builtin_amdgcn_global_load_lds((const unsigned*)((const char*)(gbase) + (voff)[_i]), (PG8_LAS unsigned*)(lds + (bufoff) + ldsw + _i * 8192), 16, 0, 0); } while (0)
; #define PG8_WAIT_V(n) asm volatile("s_waitcnt vmcnt(" #n ")" ::: "memory")
; #define PG8_BAR __builtin_amdgcn_s_barrier()
; template <class Epi, class Sched, bool ALIGN_EPI = false, bool SP2 = false>
; __device__ __forceinline__ void gemm_phase(PG8_LAS unsigned char* lds, const Gemm g, const Sched& S, const Epi& E) {
;     ...
;     for (int i = 0; i < 2; ++i) { int R, C; stage_rc(tid * 16 + i * 8192, R, C); const int Rb = Epi::PERM ? ((R & ~31) + perm32(R & 31)) : R;
;         voffA[i] = (unsigned)(R * K + C) * 2u; voffB[i] = (unsigned)(Rb * K + C) * 2u; }
;     const size_t kstep = (size_t)(BK * 2);
;     const size_t hstep = (size_t)HALF * K * 2;
;     const size_t tstep = 2 * hstep;
;     const unsigned ldsw = (unsigned)wid * 1024u;
;     const int aoff = lds_byte(wr * 64 + fr, fq * 8), boff = lds_byte(wc * 32 + fr, fq * 8);
;     ...
;     if constexpr (SP2) {
;         PG8_STAGE(PG8_SB(0, 0), cB, voffB); PG8_STAGE(PG8_SB(0, 1), cB + hstep, voffB); PG8_STAGE(PG8_SA(0, 0), cA, voffA); PG8_STAGE(PG8_SA(0, 1), cA + hstep, voffA);
;         if (wr == 1) PG8_BAR;
;         PG8_WAIT_V(2); PG8_BAR;
;         PG8_STAGE(PG8_SB(1, 0), cB + kstep, voffB); PG8_STAGE(PG8_SA(1, 0), cA + kstep, voffA); PG8_STAGE(PG8_SB(1, 1), cB + hstep + kstep, voffB);
;         PG8_WAIT_V(6); PG8_BAR;
.LBB0_827:
	v_readlane_b32 s12, v253, 2
	v_readlane_b32 s14, v253, 4
	v_readlane_b32 s15, v253, 5
	s_cmp_le_i32 s14, s21
	s_cselect_b64 s[0:1], -1, 0
	s_cmp_lt_i32 s21, s15
	s_cselect_b64 s[4:5], -1, 0
	s_and_b64 s[0:1], s[0:1], s[4:5]
	s_andn2_b64 vcc, exec, s[0:1]
	v_readlane_b32 s13, v253, 3
	s_cbranch_vccnz .Ltr_124
	v_readlane_b32 s4, v253, 0
	v_mov_b32_e32 v2, v0
	v_readlane_b32 s5, v253, 1
	s_load_dwordx2 s[14:15], s[4:5], 0x78
	v_readlane_b32 s0, v253, 6
	v_readlane_b32 s1, v253, 7
	s_load_dword s21, s[0:1], 0x0
	s_waitcnt lgkmcnt(0)
	s_add_u32 s46, s14, 0x1d800000
	s_addc_u32 s47, s15, 0
	s_add_u32 s38, s14, 0x25800000
	s_addc_u32 s39, s15, 0
	s_lshl_b32 s0, s86, 25
	s_add_u32 s0, s14, s0
	s_addc_u32 s1, s15, 0
	s_add_u32 s48, s0, 0x15800000
	s_addc_u32 s49, s1, 0
	s_cmp_eq_u32 s86, 3
	s_mov_b64 s[0:1], -1
	s_cbranch_scc1 .LBB0_866
	v_mov_b32_e32 v16, v0
	s_and_b64 vcc, exec, s[40:41]
	v_readfirstlane_b32 s16, v16
	s_cbranch_vccnz .LBB0_865
	v_lshlrev_b32_e32 v2, 4, v16
	v_add_u32_e32 v3, 0x2000, v2
	v_ashrrev_i32_e32 v4, 31, v3
	v_lshrrev_b32_e32 v4, 22, v4
	v_add_u32_e32 v4, v3, v4
	v_ashrrev_i32_e32 v10, 10, v4
	v_mul_i32_i24_e32 v4, 0x400, v10
	v_sub_u32_e32 v3, v3, v4
	v_lshrrev_b32_e32 v4, 4, v3
	v_bitop3_b32 v3, v4, v3, 32 bitop3:0x6c
	v_ashrrev_i32_e32 v4, 31, v3
	v_lshrrev_b32_e32 v4, 26, v4
	v_add_u32_e32 v4, v3, v4
	v_lshlrev_b32_e32 v5, 3, v10
	v_ashrrev_i32_e32 v11, 6, v4
	v_and_b32_e32 v5, -16, v5
	v_add_u32_e32 v5, v11, v5
	v_and_b32_e32 v6, 3, v11
	s_mov_b32 s0, 0x3ffe0
	v_lshrrev_b32_e32 v7, 2, v5
	v_lshlrev_b32_e32 v8, 1, v5
	v_and_b32_e32 v4, 0xc0, v4
	v_and_or_b32 v6, v5, s0, v6
	v_and_b32_e32 v7, 4, v7
	v_and_b32_e32 v8, 24, v8
	v_sub_u32_e32 v3, v3, v4
	v_or3_b32 v6, v6, v7, v8
	v_lshlrev_b32_e32 v7, 5, v10
	v_ashrrev_i16_sdwa v3, v194, sext(v3) dst_sel:DWORD dst_unused:UNUSED_PAD src0_sel:DWORD src1_sel:BYTE_0
	v_and_b32_e32 v7, 32, v7
	v_bfe_i32 v12, v3, 0, 16
	v_add_lshl_u32 v3, v7, v12, 1
	v_lshl_add_u32 v166, v6, 14, v3
	v_lshl_add_u32 v168, v5, 14, v3
	v_bfe_i32 v3, v16, 27, 1
	v_lshrrev_b32_e32 v3, 22, v3
	v_add_u32_e32 v3, v2, v3
	v_and_b32_e32 v3, 0xfffffc00, v3
	v_sub_u32_e32 v2, v2, v3
	v_lshrrev_b32_e32 v3, 4, v2
	v_ashrrev_i32_e32 v4, 31, v16
	v_bitop3_b32 v2, v3, v2, 32 bitop3:0x6c
	v_lshrrev_b32_e32 v4, 26, v4
	v_ashrrev_i32_e32 v3, 31, v2
	v_add_u32_e32 v4, v16, v4
	v_lshrrev_b32_e32 v3, 26, v3
	v_ashrrev_i32_e32 v14, 6, v4
	v_add_u32_e32 v3, v2, v3
	v_lshlrev_b32_e32 v4, 3, v14
	v_ashrrev_i32_e32 v13, 6, v3
	v_and_b32_e32 v4, -16, v4
	v_add_u32_e32 v4, v13, v4
	v_and_b32_e32 v5, 3, v13
	v_lshrrev_b32_e32 v6, 2, v4
	v_lshlrev_b32_e32 v7, 1, v4
	v_and_b32_e32 v3, 0xc0, v3
	s_ashr_i32 s18, s16, 6
	v_and_or_b32 v5, v4, s0, v5
	v_and_b32_e32 v6, 4, v6
	v_and_b32_e32 v7, 24, v7
	v_sub_u32_e32 v2, v2, v3
	s_ashr_i32 s17, s16, 8
	s_lshl_b32 s50, s18, 10
	v_or3_b32 v5, v5, v6, v7
	v_lshlrev_b32_e32 v6, 5, v14
	v_ashrrev_i16_sdwa v2, v194, sext(v2) dst_sel:DWORD dst_unused:UNUSED_PAD src0_sel:DWORD src1_sel:BYTE_0
	v_readlane_b32 s0, v254, 52
	v_and_b32_e32 v6, 32, v6
	v_bfe_i32 v15, v2, 0, 16
	v_readlane_b32 s1, v254, 53
	s_add_u32 s30, s48, s0
	v_add_lshl_u32 v2, v6, v15, 1
	s_addc_u32 s31, s49, s1
	s_add_i32 s51, s50, 0
	v_lshl_add_u32 v158, v5, 14, v2
	s_add_i32 m0, s51, 0x10000
	v_lshl_add_u32 v170, v4, 14, v2
	global_load_lds_dwordx4 v158, s[30:31]
	s_add_i32 m0, s51, 0x12000
	s_add_u32 s0, s30, 0x200000
	global_load_lds_dwordx4 v166, s[30:31]
	s_addc_u32 s1, s31, 0
	s_add_i32 m0, s51, 0x14000
	v_mov_b32_e32 v167, v159
	global_load_lds_dwordx4 v158, s[0:1]
	s_add_i32 m0, s51, 0x16000
	v_mov_b32_e32 v171, v159
	global_load_lds_dwordx4 v166, s[0:1]
	v_readlane_b32 s0, v252, 16
	v_readlane_b32 s1, v252, 17
	s_add_u32 s0, s38, s0
	s_addc_u32 s1, s39, s1
	s_add_i32 s52, s51, 0x2000
	s_mov_b32 m0, s51
	s_add_u32 s12, s0, 0x200000
	global_load_lds_dwordx4 v170, s[0:1]
	s_mov_b32 m0, s52
	s_addc_u32 s13, s1, 0
	s_add_i32 s53, s51, 0x4000
	global_load_lds_dwordx4 v168, s[0:1]
	s_mov_b32 m0, s53
	s_add_i32 s54, s51, 0x6000
	global_load_lds_dwordx4 v170, s[12:13]
	s_mov_b32 m0, s54
	v_mov_b32_e32 v169, v159
	global_load_lds_dwordx4 v168, s[12:13]
	s_cmp_eq_u32 s17, 1
	v_lshl_add_u64 v[8:9], s[30:31], 0, v[158:159]
	v_lshl_add_u64 v[6:7], s[30:31], 0, v[166:167]
	v_lshl_add_u64 v[2:3], s[0:1], 0, v[170:171]
	s_cselect_b64 s[12:13], -1, 0
	s_cmp_lg_u32 s17, 1
	v_lshl_add_u64 v[4:5], s[0:1], 0, v[168:169]
	s_cbranch_scc1 .LBB0_832
.LBB0_832:
	v_bfe_u32 v17, v16, 4, 2
	s_add_u32 s14, s14, 0xa00000
	v_and_b32_e32 v18, 15, v16
	v_lshlrev_b32_e32 v20, 4, v17
	v_lshlrev_b32_e32 v16, 2, v16
	s_addc_u32 s15, s15, 0
	s_and_b32 s55, s18, 3
	v_lshl_or_b32 v161, s17, 6, v18
	v_lshl_or_b32 v18, v18, 6, v20
	s_lshl_b32 s17, s17, 13
	v_and_b32_e32 v16, 32, v16
	s_add_i32 m0, s51, 0x18000
	v_lshl_add_u64 v[8:9], v[8:9], 0, s[10:11]
	v_bitop3_b32 v20, v18, s17, v16 bitop3:0xde
	s_lshl_b32 s17, s55, 12
	s_waitcnt vmcnt(2)
	s_barrier
	global_load_lds_dwordx4 v[8:9], off
	v_lshl_add_u64 v[6:7], v[6:7], 0, s[10:11]
	s_add_i32 m0, s51, 0x1a000
	s_add_i32 s56, s51, 0x8000
	s_add_i32 s57, s51, 0xa000
	global_load_lds_dwordx4 v[6:7], off
	v_lshl_add_u64 v[2:3], v[2:3], 0, s[10:11]
	s_mov_b32 m0, s56
	s_add_u32 s18, s30, 0x200080
	global_load_lds_dwordx4 v[2:3], off
	v_lshl_add_u64 v[2:3], v[4:5], 0, s[10:11]
	s_mov_b32 m0, s57
	s_addc_u32 s19, s31, 0
	global_load_lds_dwordx4 v[2:3], off
	s_add_i32 m0, s51, 0x1c000
	v_lshl_add_u64 v[2:3], s[18:19], 0, v[158:159]
	global_load_lds_dwordx4 v[2:3], off
	v_lshl_add_u64 v[2:3], s[18:19], 0, v[166:167]
	s_add_i32 m0, s51, 0x1e000
	v_lshlrev_b32_e32 v19, 3, v17
	global_load_lds_dwordx4 v[2:3], off
	v_lshlrev_b32_e32 v2, 17, v14
	v_and_b32_e32 v2, 0xfffc0000, v2
	v_lshl_add_u32 v2, v13, 14, v2
	v_and_b32_e32 v3, 1, v14
	v_lshl_or_b32 v2, v3, 6, v2
	v_lshl_add_u32 v172, v15, 1, v2
	v_lshlrev_b32_e32 v2, 17, v10
	v_and_b32_e32 v2, 0xfffc0000, v2
	s_waitcnt vmcnt(6)
	v_lshl_add_u32 v2, v11, 14, v2
	v_and_b32_e32 v3, 1, v10
	s_cmpk_lt_u32 s16, 0x100
	v_lshl_or_b32 v2, v3, 6, v2
	v_readlane_b32 s18, v252, 22
	v_bitop3_b32 v199, v18, s17, v16 bitop3:0xde
	v_lshl_or_b32 v200, s55, 5, v19
	s_cselect_b64 s[16:17], -1, 0
	s_mov_b32 s58, 0
	v_cmp_eq_u32_e64 s[42:43], 0, v17
	s_ashr_i32 s59, s21, 31
	v_mov_b32_e32 v173, v159
	v_lshl_add_u32 v174, v12, 1, v2
	v_mov_b32_e32 v175, v159
	v_add_u32_e32 v201, 0, v20
	v_readlane_b32 s34, v254, 48
	s_mov_b32 s60, s18
	s_barrier
	v_readlane_b32 s19, v252, 23
	s_branch .LBB0_835

; #define PG8_STAGE(bufoff, gbase, voff) do { _Pragma("unroll") for (int _i = 0; _i < 2; ++_i) \
;         __builtin_amdgcn_global_load_lds((const unsigned*)((const char*)(gbase) + (voff)[_i]), (PG8_LAS unsigned*)(lds + (bufoff) + ldsw + _i * 8192), 16, 0, 0); } while (0)
; #define PG8_LDA(dst, b, h) do { _Pragma("unroll") for (int m = 0; m < 4; ++m) _Pragma("unroll") for (int k = 0; k < 2; ++k) dst[m][k] = *(const PG8_LAS bf16x8*)(lds + PG8_SA(b, h) + aoff + m * 2048 + k * 1024); } while (0)
; #define PG8_LDB(dst, b, h) do { _Pragma("unroll") for (int n = 0; n < 2; ++n) _Pragma("unroll") for (int k = 0; k < 2; ++k) dst[n][k] = *(const PG8_LAS bf16x8*)(lds + PG8_SB(b, h) + boff + n * 2048 + k * 1024); } while (0)
; #define PG8_WAIT_V(n) asm volatile("s_waitcnt vmcnt(" #n ")" ::: "memory")
; #define PG8_WAIT_L(n) asm volatile("s_waitcnt lgkmcnt(" #n ")" ::: "memory")
; #define PG8_BAR __builtin_amdgcn_s_barrier()
; #define PG8_SCHED __builtin_amdgcn_sched_barrier(0)
; template <class Epi, class Sched, bool ALIGN_EPI = false, bool SP2 = false>
; __device__ __forceinline__ void gemm_phase(PG8_LAS unsigned char* lds, const Gemm g, const Sched& S, const Epi& E) {
;     ...
;         const bool has_next = S.next(ui + 1, nxt);
;         const char* nA = has_next ? (const char*)g.A + (size_t)nxt.pm * tstep : cA; const char* nB = has_next ? (const char*)g.Bt + (size_t)nxt.pn * tstep : cB;
;         for (int t = 0; t < nt; t += 2) {
;             const bool last = (t == nt - 2);
;             const char* a1 = cA + (size_t)(t + 1) * kstep;
;             const char* a2 = last ? nA : cA + (size_t)(t + 2) * kstep; const char* b2 = last ? nB : cB + (size_t)(t + 2) * kstep;
;             const char* a3 = a2 + kstep; const char* b3 = b2 + kstep;
;             if (last && has_next) S.a_ready(nxt);
;             if constexpr (SP2) {
;             PG8_LDB(B0, 0, 0); PG8_LDB(B1, 0, 1); PG8_SCHED; PG8_LDA(At, 0, 0); PG8_STAGE(PG8_SA(1, 1), a1 + hstep, voffA);
;             PG8_WAIT_V(8); PG8_WAIT_L(0); PG8_BAR; PG8_MMA(0, 0, At, B0); PG8_MMA(0, 1, At, B1); PG8_BAR; PG8_SCHED;
;     ...
;         for (int a = 0; a < 2; ++a)
; #pragma unroll
;             for (int b = 0; b < 2; ++b)
; #pragma unroll
;                 for (int m = 0; m < 4; ++m)
; #pragma unroll
;                     for (int n = 0; n < 2; ++n) acc[a][b][m][n] = (f32x4){0.f, 0.f, 0.f, 0.f};
.LBB0_841:
	s_ashr_i32 s23, s22, 31
	s_lshl_b64 s[24:25], s[22:23], 22
	s_add_u32 s24, s38, s24
	s_addc_u32 s25, s39, s25
	s_and_b64 s[28:29], s[44:45], exec
	s_cselect_b32 s23, s25, s1
	s_cselect_b32 s61, s24, s0
	s_ashr_i32 s19, s18, 31
	s_lshl_b64 s[28:29], s[18:19], 22
	s_add_u32 s28, s48, s28
	s_addc_u32 s29, s49, s29
	s_and_b64 s[36:37], s[44:45], exec
	s_cselect_b32 s19, s29, s31
	s_cselect_b32 s62, s28, s30
	s_add_u32 s0, s0, 0x200080
	s_addc_u32 s1, s1, 0
	s_add_u32 s63, s30, 0x100
	v_mov_b32_e32 v2, 0
	s_addc_u32 s66, s31, 0
	s_mov_b32 s67, -2
	v_mov_b32_e32 v3, v2
	v_mov_b32_e32 v4, v2
	v_mov_b32_e32 v5, v2
	v_mov_b32_e32 v6, v2
	v_mov_b32_e32 v7, v2
	v_mov_b32_e32 v8, v2
	v_mov_b32_e32 v9, v2
	v_mov_b32_e32 v18, v2
	v_mov_b32_e32 v19, v2
	v_mov_b32_e32 v20, v2
	v_mov_b32_e32 v21, v2
	v_mov_b32_e32 v22, v2
	v_mov_b32_e32 v23, v2
	v_mov_b32_e32 v24, v2
	v_mov_b32_e32 v25, v2
	v_mov_b32_e32 v34, v2
	v_mov_b32_e32 v35, v2
	v_mov_b32_e32 v36, v2
	v_mov_b32_e32 v37, v2
	v_mov_b32_e32 v38, v2
	v_mov_b32_e32 v39, v2
	v_mov_b32_e32 v40, v2
	v_mov_b32_e32 v41, v2
	v_mov_b32_e32 v50, v2
	v_mov_b32_e32 v51, v2
	v_mov_b32_e32 v52, v2
	v_mov_b32_e32 v53, v2
	v_mov_b32_e32 v54, v2
	v_mov_b32_e32 v55, v2
	v_mov_b32_e32 v56, v2
	v_mov_b32_e32 v57, v2
	v_mov_b32_e32 v10, v2
	v_mov_b32_e32 v11, v2
	v_mov_b32_e32 v12, v2
	v_mov_b32_e32 v13, v2
	v_mov_b32_e32 v14, v2
	v_mov_b32_e32 v15, v2
	v_mov_b32_e32 v16, v2
	v_mov_b32_e32 v17, v2
	v_mov_b32_e32 v26, v2
	v_mov_b32_e32 v27, v2
	v_mov_b32_e32 v28, v2
	v_mov_b32_e32 v29, v2
	v_mov_b32_e32 v30, v2
	v_mov_b32_e32 v31, v2
	v_mov_b32_e32 v32, v2
	v_mov_b32_e32 v33, v2
	v_mov_b32_e32 v42, v2
	v_mov_b32_e32 v43, v2
	v_mov_b32_e32 v44, v2
	v_mov_b32_e32 v45, v2
	v_mov_b32_e32 v46, v2
	v_mov_b32_e32 v47, v2
	v_mov_b32_e32 v48, v2
	v_mov_b32_e32 v49, v2
	v_mov_b32_e32 v58, v2
	v_mov_b32_e32 v59, v2
	v_mov_b32_e32 v60, v2
	v_mov_b32_e32 v61, v2
	v_mov_b32_e32 v62, v2
	v_mov_b32_e32 v63, v2
	v_mov_b32_e32 v64, v2
	v_mov_b32_e32 v65, v2
	v_mov_b32_e32 v66, v2
	v_mov_b32_e32 v67, v2
	v_mov_b32_e32 v68, v2
	v_mov_b32_e32 v69, v2
	v_mov_b32_e32 v70, v2
	v_mov_b32_e32 v71, v2
	v_mov_b32_e32 v72, v2
	v_mov_b32_e32 v73, v2
	v_mov_b32_e32 v82, v2
	v_mov_b32_e32 v83, v2
	v_mov_b32_e32 v84, v2
	v_mov_b32_e32 v85, v2
	v_mov_b32_e32 v86, v2
	v_mov_b32_e32 v87, v2
	v_mov_b32_e32 v88, v2
	v_mov_b32_e32 v89, v2
	v_mov_b32_e32 v98, v2
	v_mov_b32_e32 v99, v2
	v_mov_b32_e32 v100, v2
	v_mov_b32_e32 v101, v2
	v_mov_b32_e32 v102, v2
	v_mov_b32_e32 v103, v2
	v_mov_b32_e32 v104, v2
	v_mov_b32_e32 v105, v2
	v_mov_b32_e32 v114, v2
	v_mov_b32_e32 v115, v2
	v_mov_b32_e32 v116, v2
	v_mov_b32_e32 v117, v2
	v_mov_b32_e32 v118, v2
	v_mov_b32_e32 v119, v2
	v_mov_b32_e32 v120, v2
	v_mov_b32_e32 v121, v2
	v_mov_b32_e32 v74, v2
	v_mov_b32_e32 v75, v2
	v_mov_b32_e32 v76, v2
	v_mov_b32_e32 v77, v2
	v_mov_b32_e32 v78, v2
	v_mov_b32_e32 v79, v2
	v_mov_b32_e32 v80, v2
	v_mov_b32_e32 v81, v2
	v_mov_b32_e32 v90, v2
	v_mov_b32_e32 v91, v2
	v_mov_b32_e32 v92, v2
	v_mov_b32_e32 v93, v2
	v_mov_b32_e32 v94, v2
	v_mov_b32_e32 v95, v2
	v_mov_b32_e32 v96, v2
	v_mov_b32_e32 v97, v2
	v_mov_b32_e32 v106, v2
	v_mov_b32_e32 v107, v2
	v_mov_b32_e32 v108, v2
	v_mov_b32_e32 v109, v2
	v_mov_b32_e32 v110, v2
	v_mov_b32_e32 v111, v2
	v_mov_b32_e32 v112, v2
	v_mov_b32_e32 v113, v2
	v_mov_b32_e32 v122, v2
	v_mov_b32_e32 v123, v2
	v_mov_b32_e32 v124, v2
	v_mov_b32_e32 v125, v2
	v_mov_b32_e32 v126, v2
	v_mov_b32_e32 v127, v2
	v_mov_b32_e32 v128, v2
	v_mov_b32_e32 v129, v2
	s_and_b64 vcc, exec, s[12:13]
	s_cbranch_vccnz .Lhb_T_842
.LBB0_842:
	s_add_u32 s30, s0, 0xffe00080
	s_addc_u32 s31, s1, -1
	s_add_i32 s68, 0, 0x10000
	s_cmpk_eq_i32 s67, 0x7c
	s_cselect_b32 s37, s23, s31
	s_cselect_b32 s36, s61, s30
	s_cselect_b32 s31, s19, s66
	s_cselect_b32 s30, s62, s63
	s_add_i32 s70, 0, 0x14000
	v_add_u32_e32 v142, s68, v199
	v_add_u32_e32 v162, s70, v199
	ds_read_b128 v[130:133], v142
	ds_read_b128 v[134:137], v142 offset:1024
	ds_read_b128 v[138:141], v142 offset:2048
	ds_read_b128 v[142:145], v142 offset:3072
	ds_read_b128 v[146:149], v162
	ds_read_b128 v[150:153], v162 offset:1024
	ds_read_b128 v[154:157], v162 offset:2048
	ds_read_b128 v[162:165], v162 offset:3072
	s_add_u32 s98, s0, 0xffe00000
	s_addc_u32 s99, s1, -1
	v_lshl_add_u64 v[192:193], s[98:99], 0, v[172:173]
	s_mov_b32 m0, s56
	s_nop 0
	global_load_lds_dwordx4 v[192:193], off
	v_lshl_add_u64 v[192:193], s[98:99], 0, v[174:175]
	s_mov_b32 m0, s57
	s_nop 0
	global_load_lds_dwordx4 v[192:193], off
	v_lshl_add_u64 v[192:193], s[0:1], 0, v[172:173]
	s_add_i32 m0, s51, 0xc000
	ds_read_b128 v[176:179], v201
	ds_read_b128 v[180:183], v201 offset:1024
	ds_read_b128 v[184:187], v201 offset:2048
	ds_read_b128 v[188:191], v201 offset:3072
	ds_read_b128 v[202:205], v201 offset:4096
	ds_read_b128 v[206:209], v201 offset:5120
	ds_read_b128 v[210:213], v201 offset:6144
	ds_read_b128 v[214:217], v201 offset:7168
	global_load_lds_dwordx4 v[192:193], off
	v_lshl_add_u64 v[192:193], s[0:1], 0, v[174:175]
	s_add_i32 m0, s51, 0xe000
	s_nop 0
	global_load_lds_dwordx4 v[192:193], off
	s_waitcnt lgkmcnt(0)
	s_setprio 1
	s_waitcnt lgkmcnt(0)
; #define PG8_STAGE(bufoff, gbase, voff) do { _Pragma("unroll") for (int _i = 0; _i < 2; ++_i) \
;         __builtin_amdgcn_global_load_lds((const unsigned*)((const char*)(gbase) + (voff)[_i]), (PG8_LAS unsigned*)(lds + (bufoff) + ldsw + _i * 8192), 16, 0, 0); } while (0)
; #define PG8_LDA(dst, b, h) do { _Pragma("unroll") for (int m = 0; m < 4; ++m) _Pragma("unroll") for (int k = 0; k < 2; ++k) dst[m][k] = *(const PG8_LAS bf16x8*)(lds + PG8_SA(b, h) + aoff + m * 2048 + k * 1024); } while (0)
; #define PG8_LDB(dst, b, h) do { _Pragma("unroll") for (int n = 0; n < 2; ++n) _Pragma("unroll") for (int k = 0; k < 2; ++k) dst[n][k] = *(const PG8_LAS bf16x8*)(lds + PG8_SB(b, h) + boff + n * 2048 + k * 1024); } while (0)
; #define PG8_MMA(ai, bj, At, Bt) do { __builtin_amdgcn_s_setprio(1); _Pragma("unroll") for (int m = 0; m < 4; ++m) _Pragma("unroll") for (int n = 0; n < 2; ++n) _Pragma("unroll") for (int k = 0; k < 2; ++k) \
;         acc[ai][bj][m][n] = __builtin_amdgcn_mfma_f32_16x16x32_bf16(Bt[n][k], At[m][k], acc[ai][bj][m][n], 0, 0, 0); __builtin_amdgcn_s_setprio(0); } while (0)
; #define PG8_WAIT_V(n) asm volatile("s_waitcnt vmcnt(" #n ")" ::: "memory")
; #define PG8_WAIT_L(n) asm volatile("s_waitcnt lgkmcnt(" #n ")" ::: "memory")
; #define PG8_BAR __builtin_amdgcn_s_barrier()
; #define PG8_SCHED __builtin_amdgcn_sched_barrier(0)
; template <class Epi, class Sched, bool ALIGN_EPI = false, bool SP2 = false>
; __device__ __forceinline__ void gemm_phase(PG8_LAS unsigned char* lds, const Gemm g, const Sched& S, const Epi& E) {
;     ...
;             PG8_WAIT_V(8); PG8_WAIT_L(0); PG8_BAR; PG8_MMA(0, 0, At, B0); PG8_MMA(0, 1, At, B1); PG8_BAR; PG8_SCHED;
;             PG8_LDA(At, 0, 1); PG8_STAGE(PG8_SB(0, 0), b2, voffB); PG8_STAGE(PG8_SB(0, 1), b2 + hstep, voffB); PG8_STAGE(PG8_SA(0, 0), a2, voffA);
;             PG8_WAIT_V(8); PG8_WAIT_L(0); PG8_BAR; PG8_MMA(1, 0, At, B0); PG8_MMA(1, 1, At, B1); PG8_BAR; PG8_SCHED;
;             PG8_LDB(B0, 1, 0); PG8_LDB(B1, 1, 1); PG8_SCHED; PG8_LDA(At, 1, 0); PG8_STAGE(PG8_SA(0, 1), a2 + hstep, voffA);
	v_mfma_f32_16x16x32_bf16 v[126:129], v[130:133], v[176:179], v[126:129]
	v_mfma_f32_16x16x32_bf16 v[122:125], v[138:141], v[176:179], v[122:125]
	v_mfma_f32_16x16x32_bf16 v[110:113], v[130:133], v[184:187], v[110:113]
	v_mfma_f32_16x16x32_bf16 v[106:109], v[138:141], v[184:187], v[106:109]
	v_mfma_f32_16x16x32_bf16 v[94:97], v[130:133], v[202:205], v[94:97]
	v_mfma_f32_16x16x32_bf16 v[90:93], v[138:141], v[202:205], v[90:93]
	v_mfma_f32_16x16x32_bf16 v[78:81], v[130:133], v[210:213], v[78:81]
	v_mfma_f32_16x16x32_bf16 v[74:77], v[138:141], v[210:213], v[74:77]
	v_mfma_f32_16x16x32_bf16 v[126:129], v[134:137], v[180:183], v[126:129]
	v_mfma_f32_16x16x32_bf16 v[122:125], v[142:145], v[180:183], v[122:125]
	v_mfma_f32_16x16x32_bf16 v[110:113], v[134:137], v[188:191], v[110:113]
	v_mfma_f32_16x16x32_bf16 v[106:109], v[142:145], v[188:191], v[106:109]
	v_mfma_f32_16x16x32_bf16 v[94:97], v[134:137], v[206:209], v[94:97]
	v_mfma_f32_16x16x32_bf16 v[90:93], v[142:145], v[206:209], v[90:93]
	v_mfma_f32_16x16x32_bf16 v[78:81], v[134:137], v[214:217], v[78:81]
	v_mfma_f32_16x16x32_bf16 v[74:77], v[142:145], v[214:217], v[74:77]
	v_mfma_f32_16x16x32_bf16 v[118:121], v[146:149], v[176:179], v[118:121]
	v_mfma_f32_16x16x32_bf16 v[114:117], v[154:157], v[176:179], v[114:117]
	v_mfma_f32_16x16x32_bf16 v[102:105], v[146:149], v[184:187], v[102:105]
	v_mfma_f32_16x16x32_bf16 v[98:101], v[154:157], v[184:187], v[98:101]
	v_mfma_f32_16x16x32_bf16 v[86:89], v[146:149], v[202:205], v[86:89]
	v_mfma_f32_16x16x32_bf16 v[82:85], v[154:157], v[202:205], v[82:85]
	v_mfma_f32_16x16x32_bf16 v[70:73], v[146:149], v[210:213], v[70:73]
	v_mfma_f32_16x16x32_bf16 v[66:69], v[154:157], v[210:213], v[66:69]
	v_mfma_f32_16x16x32_bf16 v[118:121], v[150:153], v[180:183], v[118:121]
	v_mfma_f32_16x16x32_bf16 v[114:117], v[162:165], v[180:183], v[114:117]
	v_mfma_f32_16x16x32_bf16 v[102:105], v[150:153], v[188:191], v[102:105]
	v_mfma_f32_16x16x32_bf16 v[98:101], v[162:165], v[188:191], v[98:101]
	v_mfma_f32_16x16x32_bf16 v[86:89], v[150:153], v[206:209], v[86:89]
	v_mfma_f32_16x16x32_bf16 v[82:85], v[162:165], v[206:209], v[82:85]
	v_mfma_f32_16x16x32_bf16 v[70:73], v[150:153], v[214:217], v[70:73]
	v_mfma_f32_16x16x32_bf16 v[66:69], v[162:165], v[214:217], v[66:69]
	s_setprio 0
	s_waitcnt vmcnt(8)
	s_barrier
	s_add_i32 s68, s68, s50
	v_lshl_add_u64 v[192:193], s[30:31], 0, v[158:159]
	s_mov_b32 m0, s68
	ds_read_b128 v[176:179], v201 offset:16384
	ds_read_b128 v[180:183], v201 offset:17408
	ds_read_b128 v[184:187], v201 offset:18432
	ds_read_b128 v[188:191], v201 offset:19456
	ds_read_b128 v[202:205], v201 offset:20480
	ds_read_b128 v[206:209], v201 offset:21504
	ds_read_b128 v[210:213], v201 offset:22528
	ds_read_b128 v[214:217], v201 offset:23552
	global_load_lds_dwordx4 v[192:193], off
	s_add_i32 m0, s68, 0x2000
	s_add_u32 s68, s30, 0x200000
	v_lshl_add_u64 v[218:219], s[30:31], 0, v[166:167]
	s_addc_u32 s69, s31, 0
	s_add_i32 s70, s70, s50
	global_load_lds_dwordx4 v[218:219], off
	v_lshl_add_u64 v[220:221], s[68:69], 0, v[158:159]
	s_mov_b32 m0, s70
	v_lshl_add_u64 v[222:223], s[36:37], 0, v[168:169]
	global_load_lds_dwordx4 v[220:221], off
	v_lshl_add_u64 v[220:221], s[68:69], 0, v[166:167]
	s_add_i32 m0, s70, 0x2000
	s_nop 0
	global_load_lds_dwordx4 v[220:221], off
	v_lshl_add_u64 v[220:221], s[36:37], 0, v[170:171]
	s_waitcnt lgkmcnt(0)
	s_setprio 1
	s_waitcnt lgkmcnt(0)
	v_mfma_f32_16x16x32_bf16 v[62:65], v[130:133], v[176:179], v[62:65]
	v_mfma_f32_16x16x32_bf16 v[58:61], v[138:141], v[176:179], v[58:61]
	v_mfma_f32_16x16x32_bf16 v[46:49], v[130:133], v[184:187], v[46:49]
	v_mfma_f32_16x16x32_bf16 v[42:45], v[138:141], v[184:187], v[42:45]
	v_mfma_f32_16x16x32_bf16 v[30:33], v[130:133], v[202:205], v[30:33]
	v_mfma_f32_16x16x32_bf16 v[26:29], v[138:141], v[202:205], v[26:29]
	v_mfma_f32_16x16x32_bf16 v[14:17], v[130:133], v[210:213], v[14:17]
	v_mfma_f32_16x16x32_bf16 v[10:13], v[138:141], v[210:213], v[10:13]
	v_mfma_f32_16x16x32_bf16 v[62:65], v[134:137], v[180:183], v[62:65]
	v_mfma_f32_16x16x32_bf16 v[58:61], v[142:145], v[180:183], v[58:61]
	v_mfma_f32_16x16x32_bf16 v[46:49], v[134:137], v[188:191], v[46:49]
	v_mfma_f32_16x16x32_bf16 v[42:45], v[142:145], v[188:191], v[42:45]
	v_mfma_f32_16x16x32_bf16 v[30:33], v[134:137], v[206:209], v[30:33]
	v_mfma_f32_16x16x32_bf16 v[26:29], v[142:145], v[206:209], v[26:29]
	v_mfma_f32_16x16x32_bf16 v[14:17], v[134:137], v[214:217], v[14:17]
	v_mfma_f32_16x16x32_bf16 v[10:13], v[142:145], v[214:217], v[10:13]
	v_mfma_f32_16x16x32_bf16 v[54:57], v[146:149], v[176:179], v[54:57]
	v_mfma_f32_16x16x32_bf16 v[50:53], v[154:157], v[176:179], v[50:53]
	v_mfma_f32_16x16x32_bf16 v[38:41], v[146:149], v[184:187], v[38:41]
	v_mfma_f32_16x16x32_bf16 v[34:37], v[154:157], v[184:187], v[34:37]
	v_mfma_f32_16x16x32_bf16 v[22:25], v[146:149], v[202:205], v[22:25]
	v_mfma_f32_16x16x32_bf16 v[18:21], v[154:157], v[202:205], v[18:21]
	v_mfma_f32_16x16x32_bf16 v[6:9], v[146:149], v[210:213], v[6:9]
	v_mfma_f32_16x16x32_bf16 v[2:5], v[154:157], v[210:213], v[2:5]
	v_mfma_f32_16x16x32_bf16 v[54:57], v[150:153], v[180:183], v[54:57]
	v_mfma_f32_16x16x32_bf16 v[50:53], v[162:165], v[180:183], v[50:53]
	v_mfma_f32_16x16x32_bf16 v[38:41], v[150:153], v[188:191], v[38:41]
	v_mfma_f32_16x16x32_bf16 v[34:37], v[162:165], v[188:191], v[34:37]
	v_mfma_f32_16x16x32_bf16 v[22:25], v[150:153], v[206:209], v[22:25]
	v_mfma_f32_16x16x32_bf16 v[18:21], v[162:165], v[206:209], v[18:21]
	v_mfma_f32_16x16x32_bf16 v[6:9], v[150:153], v[214:217], v[6:9]
	v_mfma_f32_16x16x32_bf16 v[2:5], v[162:165], v[214:217], v[2:5]
	s_setprio 0
	s_waitcnt vmcnt(6)
	s_barrier
; #define PG8_STAGE(bufoff, gbase, voff) do { _Pragma("unroll") for (int _i = 0; _i < 2; ++_i) \
;         __builtin_amdgcn_global_load_lds((const unsigned*)((const char*)(gbase) + (voff)[_i]), (PG8_LAS unsigned*)(lds + (bufoff) + ldsw + _i * 8192), 16, 0, 0); } while (0)
; #define PG8_LDA(dst, b, h) do { _Pragma("unroll") for (int m = 0; m < 4; ++m) _Pragma("unroll") for (int k = 0; k < 2; ++k) dst[m][k] = *(const PG8_LAS bf16x8*)(lds + PG8_SA(b, h) + aoff + m * 2048 + k * 1024); } while (0)
; #define PG8_LDB(dst, b, h) do { _Pragma("unroll") for (int n = 0; n < 2; ++n) _Pragma("unroll") for (int k = 0; k < 2; ++k) dst[n][k] = *(const PG8_LAS bf16x8*)(lds + PG8_SB(b, h) + boff + n * 2048 + k * 1024); } while (0)
; #define PG8_MMA(ai, bj, At, Bt) do { __builtin_amdgcn_s_setprio(1); _Pragma("unroll") for (int m = 0; m < 4; ++m) _Pragma("unroll") for (int n = 0; n < 2; ++n) _Pragma("unroll") for (int k = 0; k < 2; ++k) \
;         acc[ai][bj][m][n] = __builtin_amdgcn_mfma_f32_16x16x32_bf16(Bt[n][k], At[m][k], acc[ai][bj][m][n], 0, 0, 0); __builtin_amdgcn_s_setprio(0); } while (0)
; #define PG8_WAIT_V(n) asm volatile("s_waitcnt vmcnt(" #n ")" ::: "memory")
; #define PG8_WAIT_L(n) asm volatile("s_waitcnt lgkmcnt(" #n ")" ::: "memory")
; #define PG8_BAR __builtin_amdgcn_s_barrier()
; #define PG8_SCHED __builtin_amdgcn_sched_barrier(0)
; template <class Epi, class Sched, bool ALIGN_EPI = false, bool SP2 = false>
; __device__ __forceinline__ void gemm_phase(PG8_LAS unsigned char* lds, const Gemm g, const Sched& S, const Epi& E) {
;     ...
;             PG8_LDB(B0, 1, 0); PG8_LDB(B1, 1, 1); PG8_SCHED; PG8_LDA(At, 1, 0); PG8_STAGE(PG8_SA(0, 1), a2 + hstep, voffA);
;             PG8_WAIT_V(8); PG8_WAIT_L(0); PG8_BAR; PG8_MMA(0, 0, At, B0); PG8_MMA(0, 1, At, B1); PG8_BAR; PG8_SCHED;
;             PG8_LDA(At, 1, 1); PG8_STAGE(PG8_SB(1, 0), b3, voffB); PG8_STAGE(PG8_SB(1, 1), b3 + hstep, voffB); PG8_STAGE(PG8_SA(1, 0), a3, voffA);
;             PG8_WAIT_V(8); PG8_WAIT_L(0); PG8_BAR; PG8_MMA(1, 0, At, B0); PG8_MMA(1, 1, At, B1); PG8_BAR; PG8_SCHED;
	s_add_i32 s68, 0, 0x18000
	s_add_i32 s69, 0, 0x1c000
	v_add_u32_e32 v142, s68, v199
	v_add_u32_e32 v162, s69, v199
	ds_read_b128 v[130:133], v142
	ds_read_b128 v[134:137], v142 offset:1024
	ds_read_b128 v[138:141], v142 offset:2048
	ds_read_b128 v[142:145], v142 offset:3072
	ds_read_b128 v[146:149], v162
	ds_read_b128 v[150:153], v162 offset:1024
	ds_read_b128 v[154:157], v162 offset:2048
	ds_read_b128 v[162:165], v162 offset:3072
	s_add_u32 s36, s36, 0x200000
	s_addc_u32 s37, s37, 0
	s_mov_b32 m0, s51
	s_nop 0
	global_load_lds_dwordx4 v[220:221], off
	s_mov_b32 m0, s52
	s_nop 0
	global_load_lds_dwordx4 v[222:223], off
	s_mov_b32 m0, s53
	v_lshl_add_u64 v[224:225], s[36:37], 0, v[170:171]
	ds_read_b128 v[176:179], v201 offset:32768
	ds_read_b128 v[180:183], v201 offset:33792
	ds_read_b128 v[184:187], v201 offset:34816
	ds_read_b128 v[188:191], v201 offset:35840
	ds_read_b128 v[202:205], v201 offset:36864
	ds_read_b128 v[206:209], v201 offset:37888
	ds_read_b128 v[210:213], v201 offset:38912
	ds_read_b128 v[214:217], v201 offset:39936
	global_load_lds_dwordx4 v[224:225], off
	v_lshl_add_u64 v[224:225], s[36:37], 0, v[168:169]
	s_mov_b32 m0, s54
	s_nop 0
	global_load_lds_dwordx4 v[224:225], off
	s_waitcnt lgkmcnt(0)
	s_setprio 1
	s_waitcnt lgkmcnt(0)
	v_mfma_f32_16x16x32_bf16 v[126:129], v[130:133], v[176:179], v[126:129]
	v_mfma_f32_16x16x32_bf16 v[122:125], v[138:141], v[176:179], v[122:125]
	v_mfma_f32_16x16x32_bf16 v[110:113], v[130:133], v[184:187], v[110:113]
	v_mfma_f32_16x16x32_bf16 v[106:109], v[138:141], v[184:187], v[106:109]
	v_mfma_f32_16x16x32_bf16 v[94:97], v[130:133], v[202:205], v[94:97]
	v_mfma_f32_16x16x32_bf16 v[90:93], v[138:141], v[202:205], v[90:93]
	v_mfma_f32_16x16x32_bf16 v[78:81], v[130:133], v[210:213], v[78:81]
	v_mfma_f32_16x16x32_bf16 v[74:77], v[138:141], v[210:213], v[74:77]
	v_mfma_f32_16x16x32_bf16 v[126:129], v[134:137], v[180:183], v[126:129]
	v_mfma_f32_16x16x32_bf16 v[122:125], v[142:145], v[180:183], v[122:125]
	v_mfma_f32_16x16x32_bf16 v[110:113], v[134:137], v[188:191], v[110:113]
	v_mfma_f32_16x16x32_bf16 v[106:109], v[142:145], v[188:191], v[106:109]
	v_mfma_f32_16x16x32_bf16 v[94:97], v[134:137], v[206:209], v[94:97]
	v_mfma_f32_16x16x32_bf16 v[90:93], v[142:145], v[206:209], v[90:93]
	v_mfma_f32_16x16x32_bf16 v[78:81], v[134:137], v[214:217], v[78:81]
	v_mfma_f32_16x16x32_bf16 v[74:77], v[142:145], v[214:217], v[74:77]
	v_mfma_f32_16x16x32_bf16 v[118:121], v[146:149], v[176:179], v[118:121]
	v_mfma_f32_16x16x32_bf16 v[114:117], v[154:157], v[176:179], v[114:117]
	v_mfma_f32_16x16x32_bf16 v[102:105], v[146:149], v[184:187], v[102:105]
	v_mfma_f32_16x16x32_bf16 v[98:101], v[154:157], v[184:187], v[98:101]
	v_mfma_f32_16x16x32_bf16 v[86:89], v[146:149], v[202:205], v[86:89]
	v_mfma_f32_16x16x32_bf16 v[82:85], v[154:157], v[202:205], v[82:85]
	v_mfma_f32_16x16x32_bf16 v[70:73], v[146:149], v[210:213], v[70:73]
	v_mfma_f32_16x16x32_bf16 v[66:69], v[154:157], v[210:213], v[66:69]
	v_mfma_f32_16x16x32_bf16 v[118:121], v[150:153], v[180:183], v[118:121]
	v_mfma_f32_16x16x32_bf16 v[114:117], v[162:165], v[180:183], v[114:117]
	v_mfma_f32_16x16x32_bf16 v[102:105], v[150:153], v[188:191], v[102:105]
	v_mfma_f32_16x16x32_bf16 v[98:101], v[162:165], v[188:191], v[98:101]
	v_mfma_f32_16x16x32_bf16 v[86:89], v[150:153], v[206:209], v[86:89]
	v_mfma_f32_16x16x32_bf16 v[82:85], v[162:165], v[206:209], v[82:85]
	v_mfma_f32_16x16x32_bf16 v[70:73], v[150:153], v[214:217], v[70:73]
	v_mfma_f32_16x16x32_bf16 v[66:69], v[162:165], v[214:217], v[66:69]
	s_setprio 0
	s_waitcnt vmcnt(8)
	s_barrier
	s_add_i32 s36, s68, s50
	v_lshl_add_u64 v[192:193], v[192:193], 0, s[10:11]
	s_mov_b32 m0, s36
	ds_read_b128 v[176:179], v201 offset:49152
	ds_read_b128 v[180:183], v201 offset:50176
	ds_read_b128 v[184:187], v201 offset:51200
	ds_read_b128 v[188:191], v201 offset:52224
	ds_read_b128 v[202:205], v201 offset:53248
	ds_read_b128 v[206:209], v201 offset:54272
	ds_read_b128 v[210:213], v201 offset:55296
	ds_read_b128 v[214:217], v201 offset:56320
	global_load_lds_dwordx4 v[192:193], off
	s_add_i32 m0, s36, 0x2000
	s_add_u32 s30, s30, 0x200080
	v_lshl_add_u64 v[192:193], v[218:219], 0, s[10:11]
	s_addc_u32 s31, s31, 0
	s_add_i32 s36, s69, s50
	global_load_lds_dwordx4 v[192:193], off
	v_lshl_add_u64 v[192:193], s[30:31], 0, v[158:159]
	s_mov_b32 m0, s36
	s_nop 0
	global_load_lds_dwordx4 v[192:193], off
	v_lshl_add_u64 v[192:193], s[30:31], 0, v[166:167]
	s_add_i32 m0, s36, 0x2000
	s_nop 0
	global_load_lds_dwordx4 v[192:193], off
	s_waitcnt lgkmcnt(0)
	s_setprio 1
	s_waitcnt lgkmcnt(0)
	v_mfma_f32_16x16x32_bf16 v[62:65], v[130:133], v[176:179], v[62:65]
	v_mfma_f32_16x16x32_bf16 v[58:61], v[138:141], v[176:179], v[58:61]
	v_mfma_f32_16x16x32_bf16 v[46:49], v[130:133], v[184:187], v[46:49]
	v_mfma_f32_16x16x32_bf16 v[42:45], v[138:141], v[184:187], v[42:45]
	v_mfma_f32_16x16x32_bf16 v[30:33], v[130:133], v[202:205], v[30:33]
	v_mfma_f32_16x16x32_bf16 v[26:29], v[138:141], v[202:205], v[26:29]
	v_mfma_f32_16x16x32_bf16 v[14:17], v[130:133], v[210:213], v[14:17]
	v_mfma_f32_16x16x32_bf16 v[10:13], v[138:141], v[210:213], v[10:13]
	v_mfma_f32_16x16x32_bf16 v[62:65], v[134:137], v[180:183], v[62:65]
	v_mfma_f32_16x16x32_bf16 v[58:61], v[142:145], v[180:183], v[58:61]
	v_mfma_f32_16x16x32_bf16 v[46:49], v[134:137], v[188:191], v[46:49]
	v_mfma_f32_16x16x32_bf16 v[42:45], v[142:145], v[188:191], v[42:45]
	v_mfma_f32_16x16x32_bf16 v[30:33], v[134:137], v[206:209], v[30:33]
	v_mfma_f32_16x16x32_bf16 v[26:29], v[142:145], v[206:209], v[26:29]
	v_mfma_f32_16x16x32_bf16 v[14:17], v[134:137], v[214:217], v[14:17]
	v_mfma_f32_16x16x32_bf16 v[10:13], v[142:145], v[214:217], v[10:13]
	v_mfma_f32_16x16x32_bf16 v[54:57], v[146:149], v[176:179], v[54:57]
	v_mfma_f32_16x16x32_bf16 v[50:53], v[154:157], v[176:179], v[50:53]
	v_mfma_f32_16x16x32_bf16 v[38:41], v[146:149], v[184:187], v[38:41]
	v_mfma_f32_16x16x32_bf16 v[34:37], v[154:157], v[184:187], v[34:37]
	v_mfma_f32_16x16x32_bf16 v[22:25], v[146:149], v[202:205], v[22:25]
	v_mfma_f32_16x16x32_bf16 v[18:21], v[154:157], v[202:205], v[18:21]
	v_mfma_f32_16x16x32_bf16 v[6:9], v[146:149], v[210:213], v[6:9]
	v_mfma_f32_16x16x32_bf16 v[2:5], v[154:157], v[210:213], v[2:5]
	v_mfma_f32_16x16x32_bf16 v[54:57], v[150:153], v[180:183], v[54:57]
	v_mfma_f32_16x16x32_bf16 v[50:53], v[162:165], v[180:183], v[50:53]
	v_mfma_f32_16x16x32_bf16 v[38:41], v[150:153], v[188:191], v[38:41]
	v_mfma_f32_16x16x32_bf16 v[34:37], v[162:165], v[188:191], v[34:37]
	v_mfma_f32_16x16x32_bf16 v[22:25], v[150:153], v[206:209], v[22:25]
	v_mfma_f32_16x16x32_bf16 v[18:21], v[162:165], v[206:209], v[18:21]
	v_mfma_f32_16x16x32_bf16 v[6:9], v[150:153], v[214:217], v[6:9]
	v_mfma_f32_16x16x32_bf16 v[2:5], v[162:165], v[214:217], v[2:5]
	s_setprio 0
	s_waitcnt vmcnt(6)
	s_barrier
	s_add_i32 s67, s67, 2
	s_add_u32 s0, s0, 0x100
	s_addc_u32 s1, s1, 0
	s_add_u32 s63, s63, 0x100
	s_addc_u32 s66, s66, 0
	s_cmpk_gt_u32 s67, 0x7d
	s_cbranch_scc0 .LBB0_842
	s_branch .Lhb_X_842
; #define PG8_STAGE(bufoff, gbase, voff) do { _Pragma("unroll") for (int _i = 0; _i < 2; ++_i) \
;         __builtin_amdgcn_global_load_lds((const unsigned*)((const char*)(gbase) + (voff)[_i]), (PG8_LAS unsigned*)(lds + (bufoff) + ldsw + _i * 8192), 16, 0, 0); } while (0)
; #define PG8_LDA(dst, b, h) do { _Pragma("unroll") for (int m = 0; m < 4; ++m) _Pragma("unroll") for (int k = 0; k < 2; ++k) dst[m][k] = *(const PG8_LAS bf16x8*)(lds + PG8_SA(b, h) + aoff + m * 2048 + k * 1024); } while (0)
; #define PG8_LDB(dst, b, h) do { _Pragma("unroll") for (int n = 0; n < 2; ++n) _Pragma("unroll") for (int k = 0; k < 2; ++k) dst[n][k] = *(const PG8_LAS bf16x8*)(lds + PG8_SB(b, h) + boff + n * 2048 + k * 1024); } while (0)
; #define PG8_MMA(ai, bj, At, Bt) do { __builtin_amdgcn_s_setprio(1); _Pragma("unroll") for (int m = 0; m < 4; ++m) _Pragma("unroll") for (int n = 0; n < 2; ++n) _Pragma("unroll") for (int k = 0; k < 2; ++k) \
;         acc[ai][bj][m][n] = __builtin_amdgcn_mfma_f32_16x16x32_bf16(Bt[n][k], At[m][k], acc[ai][bj][m][n], 0, 0, 0); __builtin_amdgcn_s_setprio(0); } while (0)
; #define PG8_WAIT_V(n) asm volatile("s_waitcnt vmcnt(" #n ")" ::: "memory")
; #define PG8_WAIT_L(n) asm volatile("s_waitcnt lgkmcnt(" #n ")" ::: "memory")
; #define PG8_BAR __builtin_amdgcn_s_barrier()
; #define PG8_SCHED __builtin_amdgcn_sched_barrier(0)
; template <class Epi, class Sched, bool ALIGN_EPI = false, bool SP2 = false>
; __device__ __forceinline__ void gemm_phase(PG8_LAS unsigned char* lds, const Gemm g, const Sched& S, const Epi& E) {
;     ...
;             PG8_LDB(B0, 0, 0); PG8_LDB(B1, 0, 1); PG8_SCHED; PG8_LDA(At, 0, 0); PG8_STAGE(PG8_SA(1, 1), a1 + hstep, voffA);
;             PG8_WAIT_V(8); PG8_WAIT_L(0); PG8_BAR; PG8_MMA(0, 0, At, B0); PG8_MMA(0, 1, At, B1); PG8_BAR; PG8_SCHED;
;             PG8_LDA(At, 0, 1); PG8_STAGE(PG8_SB(0, 0), b2, voffB); PG8_STAGE(PG8_SB(0, 1), b2 + hstep, voffB); PG8_STAGE(PG8_SA(0, 0), a2, voffA);
;             PG8_WAIT_V(8); PG8_WAIT_L(0); PG8_BAR; PG8_MMA(1, 0, At, B0); PG8_MMA(1, 1, At, B1); PG8_BAR; PG8_SCHED;
.Lhb_T_842:
	s_add_u32 s30, s0, 0xffe00080
	s_addc_u32 s31, s1, -1
	s_add_i32 s68, 0, 0x10000
	s_cmpk_eq_i32 s67, 0x7c
	s_cselect_b32 s37, s23, s31
	s_cselect_b32 s36, s61, s30
	s_cselect_b32 s31, s19, s66
	s_cselect_b32 s30, s62, s63
	s_add_i32 s70, 0, 0x14000
	v_add_u32_e32 v142, s68, v199
	v_add_u32_e32 v162, s70, v199
	ds_read_b128 v[130:133], v142
	ds_read_b128 v[134:137], v142 offset:1024
	ds_read_b128 v[138:141], v142 offset:2048
	ds_read_b128 v[142:145], v142 offset:3072
	ds_read_b128 v[146:149], v162
	ds_read_b128 v[150:153], v162 offset:1024
	ds_read_b128 v[154:157], v162 offset:2048
	ds_read_b128 v[162:165], v162 offset:3072
	s_add_u32 s98, s0, 0xffe00000
	s_addc_u32 s99, s1, -1
	v_lshl_add_u64 v[192:193], s[98:99], 0, v[172:173]
	s_mov_b32 m0, s56
	s_nop 0
	global_load_lds_dwordx4 v[192:193], off
	v_lshl_add_u64 v[192:193], s[98:99], 0, v[174:175]
	s_mov_b32 m0, s57
	s_nop 0
	global_load_lds_dwordx4 v[192:193], off
	v_lshl_add_u64 v[192:193], s[0:1], 0, v[172:173]
	s_add_i32 m0, s51, 0xc000
	ds_read_b128 v[176:179], v201
	ds_read_b128 v[180:183], v201 offset:1024
	ds_read_b128 v[184:187], v201 offset:2048
	ds_read_b128 v[188:191], v201 offset:3072
	ds_read_b128 v[202:205], v201 offset:4096
	ds_read_b128 v[206:209], v201 offset:5120
	ds_read_b128 v[210:213], v201 offset:6144
	ds_read_b128 v[214:217], v201 offset:7168
	global_load_lds_dwordx4 v[192:193], off
	v_lshl_add_u64 v[192:193], s[0:1], 0, v[174:175]
	s_add_i32 m0, s51, 0xe000
	s_nop 0
	global_load_lds_dwordx4 v[192:193], off
	s_waitcnt vmcnt(8)
	s_waitcnt lgkmcnt(0)
	s_barrier
	s_setprio 2
	s_waitcnt lgkmcnt(0)
	v_mfma_f32_16x16x32_bf16 v[126:129], v[130:133], v[176:179], v[126:129]
	v_mfma_f32_16x16x32_bf16 v[122:125], v[138:141], v[176:179], v[122:125]
	v_mfma_f32_16x16x32_bf16 v[110:113], v[130:133], v[184:187], v[110:113]
	v_mfma_f32_16x16x32_bf16 v[106:109], v[138:141], v[184:187], v[106:109]
	v_mfma_f32_16x16x32_bf16 v[94:97], v[130:133], v[202:205], v[94:97]
	v_mfma_f32_16x16x32_bf16 v[90:93], v[138:141], v[202:205], v[90:93]
	v_mfma_f32_16x16x32_bf16 v[78:81], v[130:133], v[210:213], v[78:81]
	v_mfma_f32_16x16x32_bf16 v[74:77], v[138:141], v[210:213], v[74:77]
	v_mfma_f32_16x16x32_bf16 v[126:129], v[134:137], v[180:183], v[126:129]
	v_mfma_f32_16x16x32_bf16 v[122:125], v[142:145], v[180:183], v[122:125]
	v_mfma_f32_16x16x32_bf16 v[110:113], v[134:137], v[188:191], v[110:113]
	v_mfma_f32_16x16x32_bf16 v[106:109], v[142:145], v[188:191], v[106:109]
	v_mfma_f32_16x16x32_bf16 v[94:97], v[134:137], v[206:209], v[94:97]
	v_mfma_f32_16x16x32_bf16 v[90:93], v[142:145], v[206:209], v[90:93]
	v_mfma_f32_16x16x32_bf16 v[78:81], v[134:137], v[214:217], v[78:81]
	v_mfma_f32_16x16x32_bf16 v[74:77], v[142:145], v[214:217], v[74:77]
	v_mfma_f32_16x16x32_bf16 v[118:121], v[146:149], v[176:179], v[118:121]
	v_mfma_f32_16x16x32_bf16 v[114:117], v[154:157], v[176:179], v[114:117]
	v_mfma_f32_16x16x32_bf16 v[102:105], v[146:149], v[184:187], v[102:105]
	v_mfma_f32_16x16x32_bf16 v[98:101], v[154:157], v[184:187], v[98:101]
	v_mfma_f32_16x16x32_bf16 v[86:89], v[146:149], v[202:205], v[86:89]
	v_mfma_f32_16x16x32_bf16 v[82:85], v[154:157], v[202:205], v[82:85]
	v_mfma_f32_16x16x32_bf16 v[70:73], v[146:149], v[210:213], v[70:73]
	v_mfma_f32_16x16x32_bf16 v[66:69], v[154:157], v[210:213], v[66:69]
	v_mfma_f32_16x16x32_bf16 v[118:121], v[150:153], v[180:183], v[118:121]
	v_mfma_f32_16x16x32_bf16 v[114:117], v[162:165], v[180:183], v[114:117]
	v_mfma_f32_16x16x32_bf16 v[102:105], v[150:153], v[188:191], v[102:105]
	v_mfma_f32_16x16x32_bf16 v[98:101], v[162:165], v[188:191], v[98:101]
	v_mfma_f32_16x16x32_bf16 v[86:89], v[150:153], v[206:209], v[86:89]
	v_mfma_f32_16x16x32_bf16 v[82:85], v[162:165], v[206:209], v[82:85]
	v_mfma_f32_16x16x32_bf16 v[70:73], v[150:153], v[214:217], v[70:73]
	v_mfma_f32_16x16x32_bf16 v[66:69], v[162:165], v[214:217], v[66:69]
	s_setprio 0
	s_add_i32 s68, s68, s50
	v_lshl_add_u64 v[192:193], s[30:31], 0, v[158:159]
	s_mov_b32 m0, s68
	ds_read_b128 v[176:179], v201 offset:16384
	ds_read_b128 v[180:183], v201 offset:17408
	ds_read_b128 v[184:187], v201 offset:18432
	ds_read_b128 v[188:191], v201 offset:19456
	ds_read_b128 v[202:205], v201 offset:20480
	ds_read_b128 v[206:209], v201 offset:21504
	ds_read_b128 v[210:213], v201 offset:22528
	ds_read_b128 v[214:217], v201 offset:23552
	global_load_lds_dwordx4 v[192:193], off
	s_add_i32 m0, s68, 0x2000
	s_add_u32 s68, s30, 0x200000
	v_lshl_add_u64 v[218:219], s[30:31], 0, v[166:167]
	s_addc_u32 s69, s31, 0
	s_add_i32 s70, s70, s50
	global_load_lds_dwordx4 v[218:219], off
	v_lshl_add_u64 v[220:221], s[68:69], 0, v[158:159]
	s_mov_b32 m0, s70
	v_lshl_add_u64 v[222:223], s[36:37], 0, v[168:169]
	global_load_lds_dwordx4 v[220:221], off
	v_lshl_add_u64 v[220:221], s[68:69], 0, v[166:167]
	s_add_i32 m0, s70, 0x2000
	s_nop 0
	global_load_lds_dwordx4 v[220:221], off
	v_lshl_add_u64 v[220:221], s[36:37], 0, v[170:171]
	s_waitcnt vmcnt(6)
	s_waitcnt lgkmcnt(0)
	s_barrier
; #define PG8_STAGE(bufoff, gbase, voff) do { _Pragma("unroll") for (int _i = 0; _i < 2; ++_i) \
;         __builtin_amdgcn_global_load_lds((const unsigned*)((const char*)(gbase) + (voff)[_i]), (PG8_LAS unsigned*)(lds + (bufoff) + ldsw + _i * 8192), 16, 0, 0); } while (0)
; #define PG8_LDA(dst, b, h) do { _Pragma("unroll") for (int m = 0; m < 4; ++m) _Pragma("unroll") for (int k = 0; k < 2; ++k) dst[m][k] = *(const PG8_LAS bf16x8*)(lds + PG8_SA(b, h) + aoff + m * 2048 + k * 1024); } while (0)
; #define PG8_LDB(dst, b, h) do { _Pragma("unroll") for (int n = 0; n < 2; ++n) _Pragma("unroll") for (int k = 0; k < 2; ++k) dst[n][k] = *(const PG8_LAS bf16x8*)(lds + PG8_SB(b, h) + boff + n * 2048 + k * 1024); } while (0)
; #define PG8_MMA(ai, bj, At, Bt) do { __builtin_amdgcn_s_setprio(1); _Pragma("unroll") for (int m = 0; m < 4; ++m) _Pragma("unroll") for (int n = 0; n < 2; ++n) _Pragma("unroll") for (int k = 0; k < 2; ++k) \
;         acc[ai][bj][m][n] = __builtin_amdgcn_mfma_f32_16x16x32_bf16(Bt[n][k], At[m][k], acc[ai][bj][m][n], 0, 0, 0); __builtin_amdgcn_s_setprio(0); } while (0)
; #define PG8_WAIT_V(n) asm volatile("s_waitcnt vmcnt(" #n ")" ::: "memory")
; #define PG8_WAIT_L(n) asm volatile("s_waitcnt lgkmcnt(" #n ")" ::: "memory")
; #define PG8_BAR __builtin_amdgcn_s_barrier()
; #define PG8_SCHED __builtin_amdgcn_sched_barrier(0)
; template <class Epi, class Sched, bool ALIGN_EPI = false, bool SP2 = false>
; __device__ __forceinline__ void gemm_phase(PG8_LAS unsigned char* lds, const Gemm g, const Sched& S, const Epi& E) {
;     ...
;             PG8_WAIT_V(8); PG8_WAIT_L(0); PG8_BAR; PG8_MMA(1, 0, At, B0); PG8_MMA(1, 1, At, B1); PG8_BAR; PG8_SCHED;
;             PG8_LDB(B0, 1, 0); PG8_LDB(B1, 1, 1); PG8_SCHED; PG8_LDA(At, 1, 0); PG8_STAGE(PG8_SA(0, 1), a2 + hstep, voffA);
	s_setprio 2
	s_waitcnt lgkmcnt(0)
	v_mfma_f32_16x16x32_bf16 v[62:65], v[130:133], v[176:179], v[62:65]
	v_mfma_f32_16x16x32_bf16 v[58:61], v[138:141], v[176:179], v[58:61]
	v_mfma_f32_16x16x32_bf16 v[46:49], v[130:133], v[184:187], v[46:49]
	v_mfma_f32_16x16x32_bf16 v[42:45], v[138:141], v[184:187], v[42:45]
	v_mfma_f32_16x16x32_bf16 v[30:33], v[130:133], v[202:205], v[30:33]
	v_mfma_f32_16x16x32_bf16 v[26:29], v[138:141], v[202:205], v[26:29]
	v_mfma_f32_16x16x32_bf16 v[14:17], v[130:133], v[210:213], v[14:17]
	v_mfma_f32_16x16x32_bf16 v[10:13], v[138:141], v[210:213], v[10:13]
	v_mfma_f32_16x16x32_bf16 v[62:65], v[134:137], v[180:183], v[62:65]
	v_mfma_f32_16x16x32_bf16 v[58:61], v[142:145], v[180:183], v[58:61]
	v_mfma_f32_16x16x32_bf16 v[46:49], v[134:137], v[188:191], v[46:49]
	v_mfma_f32_16x16x32_bf16 v[42:45], v[142:145], v[188:191], v[42:45]
	v_mfma_f32_16x16x32_bf16 v[30:33], v[134:137], v[206:209], v[30:33]
	v_mfma_f32_16x16x32_bf16 v[26:29], v[142:145], v[206:209], v[26:29]
	v_mfma_f32_16x16x32_bf16 v[14:17], v[134:137], v[214:217], v[14:17]
	v_mfma_f32_16x16x32_bf16 v[10:13], v[142:145], v[214:217], v[10:13]
	v_mfma_f32_16x16x32_bf16 v[54:57], v[146:149], v[176:179], v[54:57]
	v_mfma_f32_16x16x32_bf16 v[50:53], v[154:157], v[176:179], v[50:53]
	v_mfma_f32_16x16x32_bf16 v[38:41], v[146:149], v[184:187], v[38:41]
	v_mfma_f32_16x16x32_bf16 v[34:37], v[154:157], v[184:187], v[34:37]
	v_mfma_f32_16x16x32_bf16 v[22:25], v[146:149], v[202:205], v[22:25]
	v_mfma_f32_16x16x32_bf16 v[18:21], v[154:157], v[202:205], v[18:21]
	v_mfma_f32_16x16x32_bf16 v[6:9], v[146:149], v[210:213], v[6:9]
	v_mfma_f32_16x16x32_bf16 v[2:5], v[154:157], v[210:213], v[2:5]
	v_mfma_f32_16x16x32_bf16 v[54:57], v[150:153], v[180:183], v[54:57]
	v_mfma_f32_16x16x32_bf16 v[50:53], v[162:165], v[180:183], v[50:53]
	v_mfma_f32_16x16x32_bf16 v[38:41], v[150:153], v[188:191], v[38:41]
	v_mfma_f32_16x16x32_bf16 v[34:37], v[162:165], v[188:191], v[34:37]
	v_mfma_f32_16x16x32_bf16 v[22:25], v[150:153], v[206:209], v[22:25]
	v_mfma_f32_16x16x32_bf16 v[18:21], v[162:165], v[206:209], v[18:21]
	v_mfma_f32_16x16x32_bf16 v[6:9], v[150:153], v[214:217], v[6:9]
	v_mfma_f32_16x16x32_bf16 v[2:5], v[162:165], v[214:217], v[2:5]
	s_setprio 0
	s_add_i32 s68, 0, 0x18000
	s_add_i32 s69, 0, 0x1c000
	v_add_u32_e32 v142, s68, v199
	v_add_u32_e32 v162, s69, v199
	ds_read_b128 v[130:133], v142
	ds_read_b128 v[134:137], v142 offset:1024
	ds_read_b128 v[138:141], v142 offset:2048
	ds_read_b128 v[142:145], v142 offset:3072
	ds_read_b128 v[146:149], v162
	ds_read_b128 v[150:153], v162 offset:1024
	ds_read_b128 v[154:157], v162 offset:2048
	ds_read_b128 v[162:165], v162 offset:3072
	s_add_u32 s36, s36, 0x200000
	s_addc_u32 s37, s37, 0
	s_mov_b32 m0, s51
	s_nop 0
	global_load_lds_dwordx4 v[220:221], off
	s_mov_b32 m0, s52
	s_nop 0
	global_load_lds_dwordx4 v[222:223], off
	s_mov_b32 m0, s53
	v_lshl_add_u64 v[224:225], s[36:37], 0, v[170:171]
	ds_read_b128 v[176:179], v201 offset:32768
	ds_read_b128 v[180:183], v201 offset:33792
	ds_read_b128 v[184:187], v201 offset:34816
	ds_read_b128 v[188:191], v201 offset:35840
	ds_read_b128 v[202:205], v201 offset:36864
	ds_read_b128 v[206:209], v201 offset:37888
	ds_read_b128 v[210:213], v201 offset:38912
	ds_read_b128 v[214:217], v201 offset:39936
	global_load_lds_dwordx4 v[224:225], off
	v_lshl_add_u64 v[224:225], s[36:37], 0, v[168:169]
	s_mov_b32 m0, s54
	s_nop 0
	global_load_lds_dwordx4 v[224:225], off
	s_waitcnt vmcnt(8)
	s_waitcnt lgkmcnt(0)
	s_barrier
; #define PG8_STAGE(bufoff, gbase, voff) do { _Pragma("unroll") for (int _i = 0; _i < 2; ++_i) \
;         __builtin_amdgcn_global_load_lds((const unsigned*)((const char*)(gbase) + (voff)[_i]), (PG8_LAS unsigned*)(lds + (bufoff) + ldsw + _i * 8192), 16, 0, 0); } while (0)
; #define PG8_LDA(dst, b, h) do { _Pragma("unroll") for (int m = 0; m < 4; ++m) _Pragma("unroll") for (int k = 0; k < 2; ++k) dst[m][k] = *(const PG8_LAS bf16x8*)(lds + PG8_SA(b, h) + aoff + m * 2048 + k * 1024); } while (0)
; #define PG8_LDB(dst, b, h) do { _Pragma("unroll") for (int n = 0; n < 2; ++n) _Pragma("unroll") for (int k = 0; k < 2; ++k) dst[n][k] = *(const PG8_LAS bf16x8*)(lds + PG8_SB(b, h) + boff + n * 2048 + k * 1024); } while (0)
; #define PG8_MMA(ai, bj, At, Bt) do { __builtin_amdgcn_s_setprio(1); _Pragma("unroll") for (int m = 0; m < 4; ++m) _Pragma("unroll") for (int n = 0; n < 2; ++n) _Pragma("unroll") for (int k = 0; k < 2; ++k) \
;         acc[ai][bj][m][n] = __builtin_amdgcn_mfma_f32_16x16x32_bf16(Bt[n][k], At[m][k], acc[ai][bj][m][n], 0, 0, 0); __builtin_amdgcn_s_setprio(0); } while (0)
; #define PG8_WAIT_V(n) asm volatile("s_waitcnt vmcnt(" #n ")" ::: "memory")
; #define PG8_WAIT_L(n) asm volatile("s_waitcnt lgkmcnt(" #n ")" ::: "memory")
; #define PG8_BAR __builtin_amdgcn_s_barrier()
; #define PG8_SCHED __builtin_amdgcn_sched_barrier(0)
; template <class Epi, class Sched, bool ALIGN_EPI = false, bool SP2 = false>
; __device__ __forceinline__ void gemm_phase(PG8_LAS unsigned char* lds, const Gemm g, const Sched& S, const Epi& E) {
;     ...
;             PG8_LDB(B0, 1, 0); PG8_LDB(B1, 1, 1); PG8_SCHED; PG8_LDA(At, 1, 0); PG8_STAGE(PG8_SA(0, 1), a2 + hstep, voffA);
;             PG8_WAIT_V(8); PG8_WAIT_L(0); PG8_BAR; PG8_MMA(0, 0, At, B0); PG8_MMA(0, 1, At, B1); PG8_BAR; PG8_SCHED;
;             PG8_LDA(At, 1, 1); PG8_STAGE(PG8_SB(1, 0), b3, voffB); PG8_STAGE(PG8_SB(1, 1), b3 + hstep, voffB); PG8_STAGE(PG8_SA(1, 0), a3, voffA);
;             PG8_WAIT_V(8); PG8_WAIT_L(0); PG8_BAR; PG8_MMA(1, 0, At, B0); PG8_MMA(1, 1, At, B1); PG8_BAR; PG8_SCHED;
	s_setprio 2
	s_waitcnt lgkmcnt(0)
	v_mfma_f32_16x16x32_bf16 v[126:129], v[130:133], v[176:179], v[126:129]
	v_mfma_f32_16x16x32_bf16 v[122:125], v[138:141], v[176:179], v[122:125]
	v_mfma_f32_16x16x32_bf16 v[110:113], v[130:133], v[184:187], v[110:113]
	v_mfma_f32_16x16x32_bf16 v[106:109], v[138:141], v[184:187], v[106:109]
	v_mfma_f32_16x16x32_bf16 v[94:97], v[130:133], v[202:205], v[94:97]
	v_mfma_f32_16x16x32_bf16 v[90:93], v[138:141], v[202:205], v[90:93]
	v_mfma_f32_16x16x32_bf16 v[78:81], v[130:133], v[210:213], v[78:81]
	v_mfma_f32_16x16x32_bf16 v[74:77], v[138:141], v[210:213], v[74:77]
	v_mfma_f32_16x16x32_bf16 v[126:129], v[134:137], v[180:183], v[126:129]
	v_mfma_f32_16x16x32_bf16 v[122:125], v[142:145], v[180:183], v[122:125]
	v_mfma_f32_16x16x32_bf16 v[110:113], v[134:137], v[188:191], v[110:113]
	v_mfma_f32_16x16x32_bf16 v[106:109], v[142:145], v[188:191], v[106:109]
	v_mfma_f32_16x16x32_bf16 v[94:97], v[134:137], v[206:209], v[94:97]
	v_mfma_f32_16x16x32_bf16 v[90:93], v[142:145], v[206:209], v[90:93]
	v_mfma_f32_16x16x32_bf16 v[78:81], v[134:137], v[214:217], v[78:81]
	v_mfma_f32_16x16x32_bf16 v[74:77], v[142:145], v[214:217], v[74:77]
	v_mfma_f32_16x16x32_bf16 v[118:121], v[146:149], v[176:179], v[118:121]
	v_mfma_f32_16x16x32_bf16 v[114:117], v[154:157], v[176:179], v[114:117]
	v_mfma_f32_16x16x32_bf16 v[102:105], v[146:149], v[184:187], v[102:105]
	v_mfma_f32_16x16x32_bf16 v[98:101], v[154:157], v[184:187], v[98:101]
	v_mfma_f32_16x16x32_bf16 v[86:89], v[146:149], v[202:205], v[86:89]
	v_mfma_f32_16x16x32_bf16 v[82:85], v[154:157], v[202:205], v[82:85]
	v_mfma_f32_16x16x32_bf16 v[70:73], v[146:149], v[210:213], v[70:73]
	v_mfma_f32_16x16x32_bf16 v[66:69], v[154:157], v[210:213], v[66:69]
	v_mfma_f32_16x16x32_bf16 v[118:121], v[150:153], v[180:183], v[118:121]
	v_mfma_f32_16x16x32_bf16 v[114:117], v[162:165], v[180:183], v[114:117]
	v_mfma_f32_16x16x32_bf16 v[102:105], v[150:153], v[188:191], v[102:105]
	v_mfma_f32_16x16x32_bf16 v[98:101], v[162:165], v[188:191], v[98:101]
	v_mfma_f32_16x16x32_bf16 v[86:89], v[150:153], v[206:209], v[86:89]
	v_mfma_f32_16x16x32_bf16 v[82:85], v[162:165], v[206:209], v[82:85]
	v_mfma_f32_16x16x32_bf16 v[70:73], v[150:153], v[214:217], v[70:73]
	v_mfma_f32_16x16x32_bf16 v[66:69], v[162:165], v[214:217], v[66:69]
	s_setprio 0
	s_add_i32 s36, s68, s50
	v_lshl_add_u64 v[192:193], v[192:193], 0, s[10:11]
	s_mov_b32 m0, s36
	ds_read_b128 v[176:179], v201 offset:49152
	ds_read_b128 v[180:183], v201 offset:50176
	ds_read_b128 v[184:187], v201 offset:51200
	ds_read_b128 v[188:191], v201 offset:52224
	ds_read_b128 v[202:205], v201 offset:53248
	ds_read_b128 v[206:209], v201 offset:54272
	ds_read_b128 v[210:213], v201 offset:55296
	ds_read_b128 v[214:217], v201 offset:56320
	global_load_lds_dwordx4 v[192:193], off
	s_add_i32 m0, s36, 0x2000
	s_add_u32 s30, s30, 0x200080
	v_lshl_add_u64 v[192:193], v[218:219], 0, s[10:11]
	s_addc_u32 s31, s31, 0
	s_add_i32 s36, s69, s50
	global_load_lds_dwordx4 v[192:193], off
	v_lshl_add_u64 v[192:193], s[30:31], 0, v[158:159]
	s_mov_b32 m0, s36
	s_nop 0
	global_load_lds_dwordx4 v[192:193], off
	v_lshl_add_u64 v[192:193], s[30:31], 0, v[166:167]
	s_add_i32 m0, s36, 0x2000
	s_nop 0
	global_load_lds_dwordx4 v[192:193], off
	s_waitcnt vmcnt(6)
	s_waitcnt lgkmcnt(0)
	s_barrier
	s_setprio 2
	s_waitcnt lgkmcnt(0)
	v_mfma_f32_16x16x32_bf16 v[62:65], v[130:133], v[176:179], v[62:65]
	v_mfma_f32_16x16x32_bf16 v[58:61], v[138:141], v[176:179], v[58:61]
	v_mfma_f32_16x16x32_bf16 v[46:49], v[130:133], v[184:187], v[46:49]
	v_mfma_f32_16x16x32_bf16 v[42:45], v[138:141], v[184:187], v[42:45]
	v_mfma_f32_16x16x32_bf16 v[30:33], v[130:133], v[202:205], v[30:33]
	v_mfma_f32_16x16x32_bf16 v[26:29], v[138:141], v[202:205], v[26:29]
	v_mfma_f32_16x16x32_bf16 v[14:17], v[130:133], v[210:213], v[14:17]
	v_mfma_f32_16x16x32_bf16 v[10:13], v[138:141], v[210:213], v[10:13]
	v_mfma_f32_16x16x32_bf16 v[62:65], v[134:137], v[180:183], v[62:65]
	v_mfma_f32_16x16x32_bf16 v[58:61], v[142:145], v[180:183], v[58:61]
	v_mfma_f32_16x16x32_bf16 v[46:49], v[134:137], v[188:191], v[46:49]
	v_mfma_f32_16x16x32_bf16 v[42:45], v[142:145], v[188:191], v[42:45]
	v_mfma_f32_16x16x32_bf16 v[30:33], v[134:137], v[206:209], v[30:33]
	v_mfma_f32_16x16x32_bf16 v[26:29], v[142:145], v[206:209], v[26:29]
	v_mfma_f32_16x16x32_bf16 v[14:17], v[134:137], v[214:217], v[14:17]
	v_mfma_f32_16x16x32_bf16 v[10:13], v[142:145], v[214:217], v[10:13]
	v_mfma_f32_16x16x32_bf16 v[54:57], v[146:149], v[176:179], v[54:57]
	v_mfma_f32_16x16x32_bf16 v[50:53], v[154:157], v[176:179], v[50:53]
	v_mfma_f32_16x16x32_bf16 v[38:41], v[146:149], v[184:187], v[38:41]
	v_mfma_f32_16x16x32_bf16 v[34:37], v[154:157], v[184:187], v[34:37]
	v_mfma_f32_16x16x32_bf16 v[22:25], v[146:149], v[202:205], v[22:25]
	v_mfma_f32_16x16x32_bf16 v[18:21], v[154:157], v[202:205], v[18:21]
	v_mfma_f32_16x16x32_bf16 v[6:9], v[146:149], v[210:213], v[6:9]
	v_mfma_f32_16x16x32_bf16 v[2:5], v[154:157], v[210:213], v[2:5]
	v_mfma_f32_16x16x32_bf16 v[54:57], v[150:153], v[180:183], v[54:57]
	v_mfma_f32_16x16x32_bf16 v[50:53], v[162:165], v[180:183], v[50:53]
	v_mfma_f32_16x16x32_bf16 v[38:41], v[150:153], v[188:191], v[38:41]
	v_mfma_f32_16x16x32_bf16 v[34:37], v[162:165], v[188:191], v[34:37]
	v_mfma_f32_16x16x32_bf16 v[22:25], v[150:153], v[206:209], v[22:25]
	v_mfma_f32_16x16x32_bf16 v[18:21], v[162:165], v[206:209], v[18:21]
	v_mfma_f32_16x16x32_bf16 v[6:9], v[150:153], v[214:217], v[6:9]
	v_mfma_f32_16x16x32_bf16 v[2:5], v[162:165], v[214:217], v[2:5]
	s_setprio 0
	s_add_i32 s67, s67, 2
	s_add_u32 s0, s0, 0x100
	s_addc_u32 s1, s1, 0
	s_add_u32 s63, s63, 0x100
	s_addc_u32 s66, s66, 0
	s_cmpk_gt_u32 s67, 0x7d
	s_cbranch_scc0 .Lhb_T_842

; #define PG8_BAR __builtin_amdgcn_s_barrier()
; template <class Epi, class Sched, bool ALIGN_EPI = false, bool SP2 = false>
; __device__ __forceinline__ void gemm_phase(PG8_LAS unsigned char* lds, const Gemm g, const Sched& S, const Epi& E) {
;     ...
;         if constexpr (!Epi::AFTER_DRAIN) { if constexpr (Epi::HAS_PREP) E(acc, cur, wr, wc, fr, fq, prep_gen & 1); else E(acc, cur, wr, wc, fr, fq); S.done(cur); }
;         if (!has_next) break;
; #pragma unroll
;         for (int a = 0; a < 2; ++a)
; #pragma unroll
;             for (int b = 0; b < 2; ++b)
; #pragma unroll
;                 for (int m = 0; m < 4; ++m)
; #pragma unroll
;                     for (int n = 0; n < 2; ++n) acc[a][b][m][n] = (f32x4){0.f, 0.f, 0.f, 0.f};
;         cur = nxt; cA = nA; cB = nB; ++ui;
;         if constexpr (Epi::HAS_PREP) { if (cur.pm != prep_pm) { ++prep_gen; E.prep(cur, tid, prep_gen & 1); prep_pm = cur.pm; } }
;         if constexpr (ALIGN_EPI) { if (wr == 1) PG8_BAR; }
.LBB0_861:
	s_or_b64 exec, exec, s[30:31]
	s_andn2_b64 vcc, exec, s[44:45]
	s_mov_b64 s[0:1], -1
	s_cbranch_vccnz .LBB0_834
	s_andn2_b64 vcc, exec, s[12:13]
	s_cbranch_vccnz .LBB0_833
	s_branch .LBB0_833

; #define PG8_STAGE(bufoff, gbase, voff) do { _Pragma("unroll") for (int _i = 0; _i < 2; ++_i) \
;         __builtin_amdgcn_global_load_lds((const unsigned*)((const char*)(gbase) + (voff)[_i]), (PG8_LAS unsigned*)(lds + (bufoff) + ldsw + _i * 8192), 16, 0, 0); } while (0)
; #define PG8_WAIT_V(n) asm volatile("s_waitcnt vmcnt(" #n ")" ::: "memory")
; #define PG8_BAR __builtin_amdgcn_s_barrier()
; template <class Epi, class Sched, bool ALIGN_EPI = false, bool SP2 = false>
; __device__ __forceinline__ void gemm_phase(PG8_LAS unsigned char* lds, const Gemm g, const Sched& S, const Epi& E) {
;     ...
;     for (int i = 0; i < 2; ++i) { int R, C; stage_rc(tid * 16 + i * 8192, R, C); const int Rb = Epi::PERM ? ((R & ~31) + perm32(R & 31)) : R;
;         voffA[i] = (unsigned)(R * K + C) * 2u; voffB[i] = (unsigned)(Rb * K + C) * 2u; }
;     const size_t kstep = (size_t)(BK * 2);
;     const size_t hstep = (size_t)HALF * K * 2;
;     const size_t tstep = 2 * hstep;
;     const unsigned ldsw = (unsigned)wid * 1024u;
;     const int aoff = lds_byte(wr * 64 + fr, fq * 8), boff = lds_byte(wc * 32 + fr, fq * 8);
;     ...
;     if constexpr (SP2) {
;         PG8_STAGE(PG8_SB(0, 0), cB, voffB); PG8_STAGE(PG8_SB(0, 1), cB + hstep, voffB); PG8_STAGE(PG8_SA(0, 0), cA, voffA); PG8_STAGE(PG8_SA(0, 1), cA + hstep, voffA);
;         if (wr == 1) PG8_BAR;
;         PG8_WAIT_V(2); PG8_BAR;
;         PG8_STAGE(PG8_SB(1, 0), cB + kstep, voffB); PG8_STAGE(PG8_SA(1, 0), cA + kstep, voffA); PG8_STAGE(PG8_SB(1, 1), cB + hstep + kstep, voffB);
;         PG8_WAIT_V(6); PG8_BAR;
.LBB0_866:
	s_andn2_b64 vcc, exec, s[0:1]
	s_cbranch_vccnz .LBB0_887
	v_mov_b32_e32 v16, v0
	s_and_b64 vcc, exec, s[40:41]
	v_readfirstlane_b32 s14, v16
	s_cbranch_vccnz .LBB0_887
	v_lshlrev_b32_e32 v2, 4, v16
	s_waitcnt lgkmcnt(0)
	v_add_u32_e32 v3, 0x2000, v2
	v_ashrrev_i32_e32 v4, 31, v3
	v_lshrrev_b32_e32 v4, 22, v4
	v_add_u32_e32 v4, v3, v4
	v_ashrrev_i32_e32 v10, 10, v4
	v_mul_i32_i24_e32 v4, 0x400, v10
	v_sub_u32_e32 v3, v3, v4
	v_lshrrev_b32_e32 v4, 4, v3
	v_bitop3_b32 v3, v4, v3, 32 bitop3:0x6c
	v_ashrrev_i32_e32 v4, 31, v3
	v_lshrrev_b32_e32 v4, 26, v4
	v_add_u32_e32 v4, v3, v4
	v_lshlrev_b32_e32 v5, 3, v10
	v_ashrrev_i32_e32 v11, 6, v4
	v_and_b32_e32 v5, -16, v5
	v_add_u32_e32 v5, v11, v5
	v_and_b32_e32 v6, 3, v11
	s_mov_b32 s0, 0x3ffe0
	v_lshrrev_b32_e32 v7, 2, v5
	v_lshlrev_b32_e32 v8, 1, v5
	v_and_b32_e32 v4, 0xc0, v4
	v_and_or_b32 v6, v5, s0, v6
	v_and_b32_e32 v7, 4, v7
	v_and_b32_e32 v8, 24, v8
	v_sub_u32_e32 v3, v3, v4
	v_or3_b32 v6, v6, v7, v8
	v_lshlrev_b32_e32 v7, 5, v10
	v_ashrrev_i16_sdwa v3, v194, sext(v3) dst_sel:DWORD dst_unused:UNUSED_PAD src0_sel:DWORD src1_sel:BYTE_0
	v_and_b32_e32 v7, 32, v7
	v_bfe_i32 v12, v3, 0, 16
	v_add_lshl_u32 v3, v7, v12, 1
	v_lshl_add_u32 v150, v6, 14, v3
	v_lshl_add_u32 v152, v5, 14, v3
	v_bfe_i32 v3, v16, 27, 1
	v_lshrrev_b32_e32 v3, 22, v3
	v_add_u32_e32 v3, v2, v3
	v_and_b32_e32 v3, 0xfffffc00, v3
	v_sub_u32_e32 v2, v2, v3
	v_lshrrev_b32_e32 v3, 4, v2
	v_ashrrev_i32_e32 v4, 31, v16
	v_bitop3_b32 v2, v3, v2, 32 bitop3:0x6c
	v_lshrrev_b32_e32 v4, 26, v4
	v_ashrrev_i32_e32 v3, 31, v2
	v_add_u32_e32 v4, v16, v4
	v_lshrrev_b32_e32 v3, 26, v3
	v_ashrrev_i32_e32 v14, 6, v4
	v_add_u32_e32 v3, v2, v3
	v_lshlrev_b32_e32 v4, 3, v14
	v_ashrrev_i32_e32 v13, 6, v3
	v_and_b32_e32 v4, -16, v4
	v_add_u32_e32 v4, v13, v4
	v_and_b32_e32 v5, 3, v13
	v_lshrrev_b32_e32 v6, 2, v4
	v_lshlrev_b32_e32 v7, 1, v4
	v_and_b32_e32 v3, 0xc0, v3
	s_ashr_i32 s15, s14, 6
	v_and_or_b32 v5, v4, s0, v5
	v_and_b32_e32 v6, 4, v6
	v_and_b32_e32 v7, 24, v7
	v_sub_u32_e32 v2, v2, v3
	s_ashr_i32 s16, s14, 8
	s_lshl_b32 s34, s15, 10
	v_or3_b32 v5, v5, v6, v7
	v_lshlrev_b32_e32 v6, 5, v14
	v_ashrrev_i16_sdwa v2, v194, sext(v2) dst_sel:DWORD dst_unused:UNUSED_PAD src0_sel:DWORD src1_sel:BYTE_0
	v_readlane_b32 s0, v254, 52
	v_and_b32_e32 v6, 32, v6
	v_bfe_i32 v15, v2, 0, 16
	v_readlane_b32 s1, v254, 53
	s_add_u32 s28, s48, s0
	v_add_lshl_u32 v2, v6, v15, 1
	s_addc_u32 s29, s49, s1
	s_add_i32 s36, s34, 0
	v_lshl_add_u32 v158, v5, 14, v2
	s_add_i32 m0, s36, 0x10000
	v_lshl_add_u32 v154, v4, 14, v2
	global_load_lds_dwordx4 v158, s[28:29]
	s_add_i32 m0, s36, 0x12000
	s_add_u32 s0, s28, 0x200000
	global_load_lds_dwordx4 v150, s[28:29]
	s_addc_u32 s1, s29, 0
	s_add_i32 m0, s36, 0x14000
	s_load_dwordx2 s[4:5], s[4:5], 0x70
	global_load_lds_dwordx4 v158, s[0:1]
	s_add_i32 m0, s36, 0x16000
	v_mov_b32_e32 v151, v159
	global_load_lds_dwordx4 v150, s[0:1]
	v_readlane_b32 s0, v252, 16
	v_readlane_b32 s1, v252, 17
	s_add_u32 s0, s38, s0
	s_addc_u32 s1, s39, s1
	s_add_i32 s37, s36, 0x2000
	s_mov_b32 m0, s36
	s_add_u32 s12, s0, 0x200000
	global_load_lds_dwordx4 v154, s[0:1]
	s_mov_b32 m0, s37
	s_addc_u32 s13, s1, 0
	s_add_i32 s42, s36, 0x4000
	global_load_lds_dwordx4 v152, s[0:1]
	s_mov_b32 m0, s42
	s_add_i32 s43, s36, 0x6000
	global_load_lds_dwordx4 v154, s[12:13]
	s_mov_b32 m0, s43
	v_mov_b32_e32 v155, v159
	global_load_lds_dwordx4 v152, s[12:13]
	v_mov_b32_e32 v153, v159
	s_cmp_eq_u32 s16, 1
	v_lshl_add_u64 v[8:9], s[28:29], 0, v[158:159]
	v_lshl_add_u64 v[6:7], s[28:29], 0, v[150:151]
	v_lshl_add_u64 v[2:3], s[0:1], 0, v[154:155]
	s_cselect_b64 s[12:13], -1, 0
	s_cmp_lg_u32 s16, 1
	v_lshl_add_u64 v[4:5], s[0:1], 0, v[152:153]
	s_cbranch_scc1 .LBB0_870
.LBB0_870:
	v_lshrrev_b32_e32 v18, 1, v16
	v_and_b32_e32 v18, 24, v18
	s_lshl_b32 s15, s15, 5
	v_and_b32_e32 v17, 15, v16
	v_lshlrev_b32_e32 v19, 1, v18
	v_lshlrev_b32_e32 v16, 2, v16
	s_and_b32 s18, s15, 0x60
	s_add_i32 m0, s36, 0x18000
	v_lshl_add_u64 v[8:9], v[8:9], 0, s[10:11]
	v_lshl_or_b32 v161, s16, 6, v17
	v_lshl_or_b32 v17, v17, 6, v19
	s_lshl_b32 s16, s16, 13
	v_and_b32_e32 v16, 32, v16
	s_lshl_b32 s15, s18, 7
	s_waitcnt vmcnt(2)
	s_barrier
	global_load_lds_dwordx4 v[8:9], off
	v_lshl_add_u64 v[6:7], v[6:7], 0, s[10:11]
	s_add_i32 m0, s36, 0x1a000
	s_add_i32 s44, s36, 0x8000
	s_add_i32 s45, s36, 0xa000
	v_bitop3_b32 v19, v17, s16, v16 bitop3:0xde
	global_load_lds_dwordx4 v[6:7], off
	v_lshl_add_u64 v[2:3], v[2:3], 0, s[10:11]
	s_mov_b32 m0, s44
	s_add_u32 s16, s28, 0x200080
	global_load_lds_dwordx4 v[2:3], off
	v_lshl_add_u64 v[2:3], v[4:5], 0, s[10:11]
	s_mov_b32 m0, s45
	s_addc_u32 s17, s29, 0
	global_load_lds_dwordx4 v[2:3], off
	s_add_i32 m0, s36, 0x1c000
	v_lshl_add_u64 v[2:3], s[16:17], 0, v[158:159]
	global_load_lds_dwordx4 v[2:3], off
	v_lshl_add_u64 v[2:3], s[16:17], 0, v[150:151]
	s_add_i32 m0, s36, 0x1e000
	s_cmpk_lt_u32 s14, 0x100
	global_load_lds_dwordx4 v[2:3], off
	v_lshlrev_b32_e32 v2, 17, v14
	v_and_b32_e32 v2, 0xfffc0000, v2
	v_lshl_add_u32 v2, v13, 14, v2
	v_and_b32_e32 v3, 1, v14
	v_lshl_or_b32 v2, v3, 6, v2
	v_lshl_add_u32 v156, v15, 1, v2
	v_lshlrev_b32_e32 v2, 17, v10
	v_and_b32_e32 v2, 0xfffc0000, v2
	s_waitcnt vmcnt(6)
	v_lshl_add_u32 v2, v11, 14, v2
	v_and_b32_e32 v3, 1, v10
	v_lshl_or_b32 v2, v3, 6, v2
	v_readlane_b32 s16, v252, 22
	v_bitop3_b32 v178, v17, s15, v16 bitop3:0xde
	s_cselect_b64 s[14:15], -1, 0
	s_ashr_i32 s50, s21, 31
	v_or_b32_e32 v179, s18, v18
	v_mov_b32_e32 v157, v159
	v_lshl_add_u32 v166, v12, 1, v2
	v_mov_b32_e32 v167, v159
	s_mov_b32 s51, 0
	v_add_u32_e32 v180, 0, v19
	v_readlane_b32 s52, v254, 48
	s_mov_b32 s53, s16
	s_barrier
	v_readlane_b32 s17, v252, 23
	s_branch .LBB0_873

; #define PG8_STAGE(bufoff, gbase, voff) do { _Pragma("unroll") for (int _i = 0; _i < 2; ++_i) \
;         __builtin_amdgcn_global_load_lds((const unsigned*)((const char*)(gbase) + (voff)[_i]), (PG8_LAS unsigned*)(lds + (bufoff) + ldsw + _i * 8192), 16, 0, 0); } while (0)
; #define PG8_LDA(dst, b, h) do { _Pragma("unroll") for (int m = 0; m < 4; ++m) _Pragma("unroll") for (int k = 0; k < 2; ++k) dst[m][k] = *(const PG8_LAS bf16x8*)(lds + PG8_SA(b, h) + aoff + m * 2048 + k * 1024); } while (0)
; #define PG8_LDB(dst, b, h) do { _Pragma("unroll") for (int n = 0; n < 2; ++n) _Pragma("unroll") for (int k = 0; k < 2; ++k) dst[n][k] = *(const PG8_LAS bf16x8*)(lds + PG8_SB(b, h) + boff + n * 2048 + k * 1024); } while (0)
; #define PG8_WAIT_V(n) asm volatile("s_waitcnt vmcnt(" #n ")" ::: "memory")
; #define PG8_WAIT_L(n) asm volatile("s_waitcnt lgkmcnt(" #n ")" ::: "memory")
; #define PG8_BAR __builtin_amdgcn_s_barrier()
; #define PG8_SCHED __builtin_amdgcn_sched_barrier(0)
; template <class Epi, class Sched, bool ALIGN_EPI = false, bool SP2 = false>
; __device__ __forceinline__ void gemm_phase(PG8_LAS unsigned char* lds, const Gemm g, const Sched& S, const Epi& E) {
;     ...
;         const bool has_next = S.next(ui + 1, nxt);
;         const char* nA = has_next ? (const char*)g.A + (size_t)nxt.pm * tstep : cA; const char* nB = has_next ? (const char*)g.Bt + (size_t)nxt.pn * tstep : cB;
;         for (int t = 0; t < nt; t += 2) {
;             const bool last = (t == nt - 2);
;             const char* a1 = cA + (size_t)(t + 1) * kstep;
;             const char* a2 = last ? nA : cA + (size_t)(t + 2) * kstep; const char* b2 = last ? nB : cB + (size_t)(t + 2) * kstep;
;             const char* a3 = a2 + kstep; const char* b3 = b2 + kstep;
;             if (last && has_next) S.a_ready(nxt);
;             if constexpr (SP2) {
;             PG8_LDB(B0, 0, 0); PG8_LDB(B1, 0, 1); PG8_SCHED; PG8_LDA(At, 0, 0); PG8_STAGE(PG8_SA(1, 1), a1 + hstep, voffA);
;             PG8_WAIT_V(8); PG8_WAIT_L(0); PG8_BAR; PG8_MMA(0, 0, At, B0); PG8_MMA(0, 1, At, B1); PG8_BAR; PG8_SCHED;
;     ...
;         for (int a = 0; a < 2; ++a)
; #pragma unroll
;             for (int b = 0; b < 2; ++b)
; #pragma unroll
;                 for (int m = 0; m < 4; ++m)
; #pragma unroll
;                     for (int n = 0; n < 2; ++n) acc[a][b][m][n] = (f32x4){0.f, 0.f, 0.f, 0.f};
.LBB0_879:
	s_ashr_i32 s19, s18, 31
	s_lshl_b64 s[22:23], s[18:19], 22
	s_add_u32 s22, s38, s22
	s_addc_u32 s23, s39, s23
	s_and_b64 s[24:25], s[40:41], exec
	s_cselect_b32 s19, s23, s1
	s_cselect_b32 s54, s22, s0
	s_ashr_i32 s17, s16, 31
	s_lshl_b64 s[24:25], s[16:17], 22
	s_add_u32 s24, s48, s24
	s_addc_u32 s25, s49, s25
	s_and_b64 s[30:31], s[40:41], exec
	s_cselect_b32 s17, s25, s29
	s_cselect_b32 s55, s24, s28
	s_add_u32 s0, s0, 0x200080
	s_addc_u32 s1, s1, 0
	s_add_u32 s56, s28, 0x100
	v_mov_b32_e32 v2, 0
	s_addc_u32 s57, s29, 0
	s_mov_b32 s58, -2
	v_mov_b32_e32 v3, v2
	v_mov_b32_e32 v4, v2
	v_mov_b32_e32 v5, v2
	v_mov_b32_e32 v6, v2
	v_mov_b32_e32 v7, v2
	v_mov_b32_e32 v8, v2
	v_mov_b32_e32 v9, v2
	v_mov_b32_e32 v14, v2
	v_mov_b32_e32 v15, v2
	v_mov_b32_e32 v16, v2
	v_mov_b32_e32 v17, v2
	v_mov_b32_e32 v22, v2
	v_mov_b32_e32 v23, v2
	v_mov_b32_e32 v24, v2
	v_mov_b32_e32 v25, v2
	v_mov_b32_e32 v30, v2
	v_mov_b32_e32 v31, v2
	v_mov_b32_e32 v32, v2
	v_mov_b32_e32 v33, v2
	v_mov_b32_e32 v38, v2
	v_mov_b32_e32 v39, v2
	v_mov_b32_e32 v40, v2
	v_mov_b32_e32 v41, v2
	v_mov_b32_e32 v46, v2
	v_mov_b32_e32 v47, v2
	v_mov_b32_e32 v48, v2
	v_mov_b32_e32 v49, v2
	v_mov_b32_e32 v54, v2
	v_mov_b32_e32 v55, v2
	v_mov_b32_e32 v56, v2
	v_mov_b32_e32 v57, v2
	v_mov_b32_e32 v10, v2
	v_mov_b32_e32 v11, v2
	v_mov_b32_e32 v12, v2
	v_mov_b32_e32 v13, v2
	v_mov_b32_e32 v18, v2
	v_mov_b32_e32 v19, v2
	v_mov_b32_e32 v20, v2
	v_mov_b32_e32 v21, v2
	v_mov_b32_e32 v26, v2
	v_mov_b32_e32 v27, v2
	v_mov_b32_e32 v28, v2
	v_mov_b32_e32 v29, v2
	v_mov_b32_e32 v34, v2
	v_mov_b32_e32 v35, v2
	v_mov_b32_e32 v36, v2
	v_mov_b32_e32 v37, v2
	v_mov_b32_e32 v42, v2
	v_mov_b32_e32 v43, v2
	v_mov_b32_e32 v44, v2
	v_mov_b32_e32 v45, v2
	v_mov_b32_e32 v50, v2
	v_mov_b32_e32 v51, v2
	v_mov_b32_e32 v52, v2
	v_mov_b32_e32 v53, v2
	v_mov_b32_e32 v58, v2
	v_mov_b32_e32 v59, v2
	v_mov_b32_e32 v60, v2
	v_mov_b32_e32 v61, v2
	v_mov_b32_e32 v62, v2
	v_mov_b32_e32 v63, v2
	v_mov_b32_e32 v64, v2
	v_mov_b32_e32 v65, v2
	v_mov_b32_e32 v66, v2
	v_mov_b32_e32 v67, v2
	v_mov_b32_e32 v68, v2
	v_mov_b32_e32 v69, v2
	v_mov_b32_e32 v70, v2
	v_mov_b32_e32 v71, v2
	v_mov_b32_e32 v72, v2
	v_mov_b32_e32 v73, v2
	v_mov_b32_e32 v78, v2
	v_mov_b32_e32 v79, v2
	v_mov_b32_e32 v80, v2
	v_mov_b32_e32 v81, v2
	v_mov_b32_e32 v86, v2
	v_mov_b32_e32 v87, v2
	v_mov_b32_e32 v88, v2
	v_mov_b32_e32 v89, v2
	v_mov_b32_e32 v98, v2
	v_mov_b32_e32 v99, v2
	v_mov_b32_e32 v100, v2
	v_mov_b32_e32 v101, v2
	v_mov_b32_e32 v102, v2
	v_mov_b32_e32 v103, v2
	v_mov_b32_e32 v104, v2
	v_mov_b32_e32 v105, v2
	v_mov_b32_e32 v106, v2
	v_mov_b32_e32 v107, v2
	v_mov_b32_e32 v108, v2
	v_mov_b32_e32 v109, v2
	v_mov_b32_e32 v110, v2
	v_mov_b32_e32 v111, v2
	v_mov_b32_e32 v112, v2
	v_mov_b32_e32 v113, v2
	v_mov_b32_e32 v74, v2
	v_mov_b32_e32 v75, v2
	v_mov_b32_e32 v76, v2
	v_mov_b32_e32 v77, v2
	v_mov_b32_e32 v82, v2
	v_mov_b32_e32 v83, v2
	v_mov_b32_e32 v84, v2
	v_mov_b32_e32 v85, v2
	v_mov_b32_e32 v90, v2
	v_mov_b32_e32 v91, v2
	v_mov_b32_e32 v92, v2
	v_mov_b32_e32 v93, v2
	v_mov_b32_e32 v94, v2
	v_mov_b32_e32 v95, v2
	v_mov_b32_e32 v96, v2
	v_mov_b32_e32 v97, v2
	v_mov_b32_e32 v114, v2
	v_mov_b32_e32 v115, v2
	v_mov_b32_e32 v116, v2
	v_mov_b32_e32 v117, v2
	v_mov_b32_e32 v118, v2
	v_mov_b32_e32 v119, v2
	v_mov_b32_e32 v120, v2
	v_mov_b32_e32 v121, v2
	v_mov_b32_e32 v122, v2
	v_mov_b32_e32 v123, v2
	v_mov_b32_e32 v124, v2
	v_mov_b32_e32 v125, v2
	v_mov_b32_e32 v126, v2
	v_mov_b32_e32 v127, v2
	v_mov_b32_e32 v128, v2
	v_mov_b32_e32 v129, v2
	s_and_b64 vcc, exec, s[12:13]
	s_cbranch_vccnz .Lhb_T_880
.LBB0_880:
	s_add_u32 s28, s0, 0xffe00080
	s_addc_u32 s29, s1, -1
	s_add_i32 s59, 0, 0x10000
	s_cmpk_eq_i32 s58, 0x7c
	s_cselect_b32 s31, s19, s29
	s_cselect_b32 s30, s54, s28
	s_cselect_b32 s29, s17, s57
	s_cselect_b32 s28, s55, s56
	s_add_i32 s62, 0, 0x14000
	v_add_u32_e32 v142, s59, v178
	v_add_u32_e32 v172, s62, v178
	ds_read_b128 v[130:133], v142
	ds_read_b128 v[134:137], v142 offset:1024
	ds_read_b128 v[138:141], v142 offset:2048
	ds_read_b128 v[142:145], v142 offset:3072
	ds_read_b128 v[146:149], v172
	ds_read_b128 v[162:165], v172 offset:1024
	ds_read_b128 v[168:171], v172 offset:2048
	ds_read_b128 v[172:175], v172 offset:3072
	s_add_u32 s98, s0, 0xffe00000
	s_addc_u32 s99, s1, -1
	v_lshl_add_u64 v[176:177], s[98:99], 0, v[156:157]
	s_mov_b32 m0, s44
	s_nop 0
	global_load_lds_dwordx4 v[176:177], off
	v_lshl_add_u64 v[176:177], s[98:99], 0, v[166:167]
	s_mov_b32 m0, s45
	s_nop 0
	global_load_lds_dwordx4 v[176:177], off
	v_lshl_add_u64 v[176:177], s[0:1], 0, v[156:157]
	s_add_i32 m0, s36, 0xc000
	ds_read_b128 v[182:185], v180
	ds_read_b128 v[186:189], v180 offset:1024
	ds_read_b128 v[190:193], v180 offset:2048
	ds_read_b128 v[200:203], v180 offset:3072
	ds_read_b128 v[204:207], v180 offset:4096
	ds_read_b128 v[208:211], v180 offset:5120
	ds_read_b128 v[212:215], v180 offset:6144
	ds_read_b128 v[216:219], v180 offset:7168
	global_load_lds_dwordx4 v[176:177], off
	v_lshl_add_u64 v[176:177], s[0:1], 0, v[166:167]
	s_add_i32 m0, s36, 0xe000
	s_nop 0
	global_load_lds_dwordx4 v[176:177], off
	s_waitcnt lgkmcnt(0)
	s_setprio 1
	s_waitcnt lgkmcnt(0)
; #define PG8_STAGE(bufoff, gbase, voff) do { _Pragma("unroll") for (int _i = 0; _i < 2; ++_i) \
;         __builtin_amdgcn_global_load_lds((const unsigned*)((const char*)(gbase) + (voff)[_i]), (PG8_LAS unsigned*)(lds + (bufoff) + ldsw + _i * 8192), 16, 0, 0); } while (0)
; #define PG8_LDA(dst, b, h) do { _Pragma("unroll") for (int m = 0; m < 4; ++m) _Pragma("unroll") for (int k = 0; k < 2; ++k) dst[m][k] = *(const PG8_LAS bf16x8*)(lds + PG8_SA(b, h) + aoff + m * 2048 + k * 1024); } while (0)
; #define PG8_LDB(dst, b, h) do { _Pragma("unroll") for (int n = 0; n < 2; ++n) _Pragma("unroll") for (int k = 0; k < 2; ++k) dst[n][k] = *(const PG8_LAS bf16x8*)(lds + PG8_SB(b, h) + boff + n * 2048 + k * 1024); } while (0)
; #define PG8_MMA(ai, bj, At, Bt) do { __builtin_amdgcn_s_setprio(1); _Pragma("unroll") for (int m = 0; m < 4; ++m) _Pragma("unroll") for (int n = 0; n < 2; ++n) _Pragma("unroll") for (int k = 0; k < 2; ++k) \
;         acc[ai][bj][m][n] = __builtin_amdgcn_mfma_f32_16x16x32_bf16(Bt[n][k], At[m][k], acc[ai][bj][m][n], 0, 0, 0); __builtin_amdgcn_s_setprio(0); } while (0)
; #define PG8_WAIT_V(n) asm volatile("s_waitcnt vmcnt(" #n ")" ::: "memory")
; #define PG8_WAIT_L(n) asm volatile("s_waitcnt lgkmcnt(" #n ")" ::: "memory")
; #define PG8_BAR __builtin_amdgcn_s_barrier()
; #define PG8_SCHED __builtin_amdgcn_sched_barrier(0)
; template <class Epi, class Sched, bool ALIGN_EPI = false, bool SP2 = false>
; __device__ __forceinline__ void gemm_phase(PG8_LAS unsigned char* lds, const Gemm g, const Sched& S, const Epi& E) {
;     ...
;             PG8_WAIT_V(8); PG8_WAIT_L(0); PG8_BAR; PG8_MMA(0, 0, At, B0); PG8_MMA(0, 1, At, B1); PG8_BAR; PG8_SCHED;
;             PG8_LDA(At, 0, 1); PG8_STAGE(PG8_SB(0, 0), b2, voffB); PG8_STAGE(PG8_SB(0, 1), b2 + hstep, voffB); PG8_STAGE(PG8_SA(0, 0), a2, voffA);
;             PG8_WAIT_V(8); PG8_WAIT_L(0); PG8_BAR; PG8_MMA(1, 0, At, B0); PG8_MMA(1, 1, At, B1); PG8_BAR; PG8_SCHED;
;             PG8_LDB(B0, 1, 0); PG8_LDB(B1, 1, 1); PG8_SCHED; PG8_LDA(At, 1, 0); PG8_STAGE(PG8_SA(0, 1), a2 + hstep, voffA);
	v_mfma_f32_16x16x32_bf16 v[126:129], v[130:133], v[182:185], v[126:129]
	v_mfma_f32_16x16x32_bf16 v[122:125], v[138:141], v[182:185], v[122:125]
	v_mfma_f32_16x16x32_bf16 v[118:121], v[130:133], v[190:193], v[118:121]
	v_mfma_f32_16x16x32_bf16 v[114:117], v[138:141], v[190:193], v[114:117]
	v_mfma_f32_16x16x32_bf16 v[94:97], v[130:133], v[204:207], v[94:97]
	v_mfma_f32_16x16x32_bf16 v[90:93], v[138:141], v[204:207], v[90:93]
	v_mfma_f32_16x16x32_bf16 v[82:85], v[130:133], v[212:215], v[82:85]
	v_mfma_f32_16x16x32_bf16 v[74:77], v[138:141], v[212:215], v[74:77]
	v_mfma_f32_16x16x32_bf16 v[126:129], v[134:137], v[186:189], v[126:129]
	v_mfma_f32_16x16x32_bf16 v[122:125], v[142:145], v[186:189], v[122:125]
	v_mfma_f32_16x16x32_bf16 v[118:121], v[134:137], v[200:203], v[118:121]
	v_mfma_f32_16x16x32_bf16 v[114:117], v[142:145], v[200:203], v[114:117]
	v_mfma_f32_16x16x32_bf16 v[94:97], v[134:137], v[208:211], v[94:97]
	v_mfma_f32_16x16x32_bf16 v[90:93], v[142:145], v[208:211], v[90:93]
	v_mfma_f32_16x16x32_bf16 v[82:85], v[134:137], v[216:219], v[82:85]
	v_mfma_f32_16x16x32_bf16 v[74:77], v[142:145], v[216:219], v[74:77]
	v_mfma_f32_16x16x32_bf16 v[110:113], v[146:149], v[182:185], v[110:113]
	v_mfma_f32_16x16x32_bf16 v[106:109], v[168:171], v[182:185], v[106:109]
	v_mfma_f32_16x16x32_bf16 v[102:105], v[146:149], v[190:193], v[102:105]
	v_mfma_f32_16x16x32_bf16 v[98:101], v[168:171], v[190:193], v[98:101]
	v_mfma_f32_16x16x32_bf16 v[86:89], v[146:149], v[204:207], v[86:89]
	v_mfma_f32_16x16x32_bf16 v[78:81], v[168:171], v[204:207], v[78:81]
	v_mfma_f32_16x16x32_bf16 v[70:73], v[146:149], v[212:215], v[70:73]
	v_mfma_f32_16x16x32_bf16 v[66:69], v[168:171], v[212:215], v[66:69]
	v_mfma_f32_16x16x32_bf16 v[110:113], v[162:165], v[186:189], v[110:113]
	v_mfma_f32_16x16x32_bf16 v[106:109], v[172:175], v[186:189], v[106:109]
	v_mfma_f32_16x16x32_bf16 v[102:105], v[162:165], v[200:203], v[102:105]
	v_mfma_f32_16x16x32_bf16 v[98:101], v[172:175], v[200:203], v[98:101]
	v_mfma_f32_16x16x32_bf16 v[86:89], v[162:165], v[208:211], v[86:89]
	v_mfma_f32_16x16x32_bf16 v[78:81], v[172:175], v[208:211], v[78:81]
	v_mfma_f32_16x16x32_bf16 v[70:73], v[162:165], v[216:219], v[70:73]
	v_mfma_f32_16x16x32_bf16 v[66:69], v[172:175], v[216:219], v[66:69]
	s_setprio 0
	s_waitcnt vmcnt(8)
	s_barrier
	s_add_i32 s59, s59, s34
	v_lshl_add_u64 v[176:177], s[28:29], 0, v[158:159]
	s_mov_b32 m0, s59
	ds_read_b128 v[182:185], v180 offset:16384
	ds_read_b128 v[186:189], v180 offset:17408
	ds_read_b128 v[190:193], v180 offset:18432
	ds_read_b128 v[200:203], v180 offset:19456
	ds_read_b128 v[204:207], v180 offset:20480
	ds_read_b128 v[208:211], v180 offset:21504
	ds_read_b128 v[212:215], v180 offset:22528
	ds_read_b128 v[216:219], v180 offset:23552
	global_load_lds_dwordx4 v[176:177], off
	s_add_i32 m0, s59, 0x2000
	s_add_u32 s60, s28, 0x200000
	v_lshl_add_u64 v[220:221], s[28:29], 0, v[150:151]
	s_addc_u32 s61, s29, 0
	s_add_i32 s59, s62, s34
	global_load_lds_dwordx4 v[220:221], off
	v_lshl_add_u64 v[222:223], s[60:61], 0, v[158:159]
	s_mov_b32 m0, s59
	v_lshl_add_u64 v[224:225], s[30:31], 0, v[152:153]
	global_load_lds_dwordx4 v[222:223], off
	v_lshl_add_u64 v[222:223], s[60:61], 0, v[150:151]
	s_add_i32 m0, s59, 0x2000
	s_nop 0
	global_load_lds_dwordx4 v[222:223], off
	v_lshl_add_u64 v[222:223], s[30:31], 0, v[154:155]
	s_waitcnt lgkmcnt(0)
	s_setprio 1
	s_waitcnt lgkmcnt(0)
	v_mfma_f32_16x16x32_bf16 v[62:65], v[130:133], v[182:185], v[62:65]
	v_mfma_f32_16x16x32_bf16 v[58:61], v[138:141], v[182:185], v[58:61]
	v_mfma_f32_16x16x32_bf16 v[50:53], v[130:133], v[190:193], v[50:53]
	v_mfma_f32_16x16x32_bf16 v[42:45], v[138:141], v[190:193], v[42:45]
	v_mfma_f32_16x16x32_bf16 v[34:37], v[130:133], v[204:207], v[34:37]
	v_mfma_f32_16x16x32_bf16 v[26:29], v[138:141], v[204:207], v[26:29]
	v_mfma_f32_16x16x32_bf16 v[18:21], v[130:133], v[212:215], v[18:21]
	v_mfma_f32_16x16x32_bf16 v[10:13], v[138:141], v[212:215], v[10:13]
	v_mfma_f32_16x16x32_bf16 v[62:65], v[134:137], v[186:189], v[62:65]
	v_mfma_f32_16x16x32_bf16 v[58:61], v[142:145], v[186:189], v[58:61]
	v_mfma_f32_16x16x32_bf16 v[50:53], v[134:137], v[200:203], v[50:53]
	v_mfma_f32_16x16x32_bf16 v[42:45], v[142:145], v[200:203], v[42:45]
	v_mfma_f32_16x16x32_bf16 v[34:37], v[134:137], v[208:211], v[34:37]
	v_mfma_f32_16x16x32_bf16 v[26:29], v[142:145], v[208:211], v[26:29]
	v_mfma_f32_16x16x32_bf16 v[18:21], v[134:137], v[216:219], v[18:21]
	v_mfma_f32_16x16x32_bf16 v[10:13], v[142:145], v[216:219], v[10:13]
	v_mfma_f32_16x16x32_bf16 v[54:57], v[146:149], v[182:185], v[54:57]
	v_mfma_f32_16x16x32_bf16 v[46:49], v[168:171], v[182:185], v[46:49]
	v_mfma_f32_16x16x32_bf16 v[38:41], v[146:149], v[190:193], v[38:41]
	v_mfma_f32_16x16x32_bf16 v[30:33], v[168:171], v[190:193], v[30:33]
	v_mfma_f32_16x16x32_bf16 v[22:25], v[146:149], v[204:207], v[22:25]
	v_mfma_f32_16x16x32_bf16 v[14:17], v[168:171], v[204:207], v[14:17]
	v_mfma_f32_16x16x32_bf16 v[6:9], v[146:149], v[212:215], v[6:9]
	v_mfma_f32_16x16x32_bf16 v[2:5], v[168:171], v[212:215], v[2:5]
	v_mfma_f32_16x16x32_bf16 v[54:57], v[162:165], v[186:189], v[54:57]
	v_mfma_f32_16x16x32_bf16 v[46:49], v[172:175], v[186:189], v[46:49]
	v_mfma_f32_16x16x32_bf16 v[38:41], v[162:165], v[200:203], v[38:41]
	v_mfma_f32_16x16x32_bf16 v[30:33], v[172:175], v[200:203], v[30:33]
	v_mfma_f32_16x16x32_bf16 v[22:25], v[162:165], v[208:211], v[22:25]
	v_mfma_f32_16x16x32_bf16 v[14:17], v[172:175], v[208:211], v[14:17]
	v_mfma_f32_16x16x32_bf16 v[6:9], v[162:165], v[216:219], v[6:9]
	v_mfma_f32_16x16x32_bf16 v[2:5], v[172:175], v[216:219], v[2:5]
	s_setprio 0
	s_waitcnt vmcnt(6)
	s_barrier
; #define PG8_STAGE(bufoff, gbase, voff) do { _Pragma("unroll") for (int _i = 0; _i < 2; ++_i) \
;         __builtin_amdgcn_global_load_lds((const unsigned*)((const char*)(gbase) + (voff)[_i]), (PG8_LAS unsigned*)(lds + (bufoff) + ldsw + _i * 8192), 16, 0, 0); } while (0)
; #define PG8_LDA(dst, b, h) do { _Pragma("unroll") for (int m = 0; m < 4; ++m) _Pragma("unroll") for (int k = 0; k < 2; ++k) dst[m][k] = *(const PG8_LAS bf16x8*)(lds + PG8_SA(b, h) + aoff + m * 2048 + k * 1024); } while (0)
; #define PG8_LDB(dst, b, h) do { _Pragma("unroll") for (int n = 0; n < 2; ++n) _Pragma("unroll") for (int k = 0; k < 2; ++k) dst[n][k] = *(const PG8_LAS bf16x8*)(lds + PG8_SB(b, h) + boff + n * 2048 + k * 1024); } while (0)
; #define PG8_MMA(ai, bj, At, Bt) do { __builtin_amdgcn_s_setprio(1); _Pragma("unroll") for (int m = 0; m < 4; ++m) _Pragma("unroll") for (int n = 0; n < 2; ++n) _Pragma("unroll") for (int k = 0; k < 2; ++k) \
;         acc[ai][bj][m][n] = __builtin_amdgcn_mfma_f32_16x16x32_bf16(Bt[n][k], At[m][k], acc[ai][bj][m][n], 0, 0, 0); __builtin_amdgcn_s_setprio(0); } while (0)
; #define PG8_WAIT_V(n) asm volatile("s_waitcnt vmcnt(" #n ")" ::: "memory")
; #define PG8_WAIT_L(n) asm volatile("s_waitcnt lgkmcnt(" #n ")" ::: "memory")
; #define PG8_BAR __builtin_amdgcn_s_barrier()
; #define PG8_SCHED __builtin_amdgcn_sched_barrier(0)
; template <class Epi, class Sched, bool ALIGN_EPI = false, bool SP2 = false>
; __device__ __forceinline__ void gemm_phase(PG8_LAS unsigned char* lds, const Gemm g, const Sched& S, const Epi& E) {
;     ...
;             PG8_LDB(B0, 1, 0); PG8_LDB(B1, 1, 1); PG8_SCHED; PG8_LDA(At, 1, 0); PG8_STAGE(PG8_SA(0, 1), a2 + hstep, voffA);
;             PG8_WAIT_V(8); PG8_WAIT_L(0); PG8_BAR; PG8_MMA(0, 0, At, B0); PG8_MMA(0, 1, At, B1); PG8_BAR; PG8_SCHED;
;             PG8_LDA(At, 1, 1); PG8_STAGE(PG8_SB(1, 0), b3, voffB); PG8_STAGE(PG8_SB(1, 1), b3 + hstep, voffB); PG8_STAGE(PG8_SA(1, 0), a3, voffA);
;             PG8_WAIT_V(8); PG8_WAIT_L(0); PG8_BAR; PG8_MMA(1, 0, At, B0); PG8_MMA(1, 1, At, B1); PG8_BAR; PG8_SCHED;
	s_add_i32 s59, 0, 0x18000
	s_add_i32 s60, 0, 0x1c000
	v_add_u32_e32 v142, s59, v178
	v_add_u32_e32 v172, s60, v178
	ds_read_b128 v[130:133], v142
	ds_read_b128 v[134:137], v142 offset:1024
	ds_read_b128 v[138:141], v142 offset:2048
	ds_read_b128 v[142:145], v142 offset:3072
	ds_read_b128 v[146:149], v172
	ds_read_b128 v[162:165], v172 offset:1024
	ds_read_b128 v[168:171], v172 offset:2048
	ds_read_b128 v[172:175], v172 offset:3072
	s_add_u32 s30, s30, 0x200000
	s_addc_u32 s31, s31, 0
	s_mov_b32 m0, s36
	s_nop 0
	global_load_lds_dwordx4 v[222:223], off
	s_mov_b32 m0, s37
	s_nop 0
	global_load_lds_dwordx4 v[224:225], off
	s_mov_b32 m0, s42
	v_lshl_add_u64 v[226:227], s[30:31], 0, v[154:155]
	ds_read_b128 v[182:185], v180 offset:32768
	ds_read_b128 v[186:189], v180 offset:33792
	ds_read_b128 v[190:193], v180 offset:34816
	ds_read_b128 v[200:203], v180 offset:35840
	ds_read_b128 v[204:207], v180 offset:36864
	ds_read_b128 v[208:211], v180 offset:37888
	ds_read_b128 v[212:215], v180 offset:38912
	ds_read_b128 v[216:219], v180 offset:39936
	global_load_lds_dwordx4 v[226:227], off
	v_lshl_add_u64 v[226:227], s[30:31], 0, v[152:153]
	s_mov_b32 m0, s43
	s_nop 0
	global_load_lds_dwordx4 v[226:227], off
	s_waitcnt lgkmcnt(0)
	s_setprio 1
	s_waitcnt lgkmcnt(0)
	v_mfma_f32_16x16x32_bf16 v[126:129], v[130:133], v[182:185], v[126:129]
	v_mfma_f32_16x16x32_bf16 v[122:125], v[138:141], v[182:185], v[122:125]
	v_mfma_f32_16x16x32_bf16 v[118:121], v[130:133], v[190:193], v[118:121]
	v_mfma_f32_16x16x32_bf16 v[114:117], v[138:141], v[190:193], v[114:117]
	v_mfma_f32_16x16x32_bf16 v[94:97], v[130:133], v[204:207], v[94:97]
	v_mfma_f32_16x16x32_bf16 v[90:93], v[138:141], v[204:207], v[90:93]
	v_mfma_f32_16x16x32_bf16 v[82:85], v[130:133], v[212:215], v[82:85]
	v_mfma_f32_16x16x32_bf16 v[74:77], v[138:141], v[212:215], v[74:77]
	v_mfma_f32_16x16x32_bf16 v[126:129], v[134:137], v[186:189], v[126:129]
	v_mfma_f32_16x16x32_bf16 v[122:125], v[142:145], v[186:189], v[122:125]
	v_mfma_f32_16x16x32_bf16 v[118:121], v[134:137], v[200:203], v[118:121]
	v_mfma_f32_16x16x32_bf16 v[114:117], v[142:145], v[200:203], v[114:117]
	v_mfma_f32_16x16x32_bf16 v[94:97], v[134:137], v[208:211], v[94:97]
	v_mfma_f32_16x16x32_bf16 v[90:93], v[142:145], v[208:211], v[90:93]
	v_mfma_f32_16x16x32_bf16 v[82:85], v[134:137], v[216:219], v[82:85]
	v_mfma_f32_16x16x32_bf16 v[74:77], v[142:145], v[216:219], v[74:77]
	v_mfma_f32_16x16x32_bf16 v[110:113], v[146:149], v[182:185], v[110:113]
	v_mfma_f32_16x16x32_bf16 v[106:109], v[168:171], v[182:185], v[106:109]
	v_mfma_f32_16x16x32_bf16 v[102:105], v[146:149], v[190:193], v[102:105]
	v_mfma_f32_16x16x32_bf16 v[98:101], v[168:171], v[190:193], v[98:101]
	v_mfma_f32_16x16x32_bf16 v[86:89], v[146:149], v[204:207], v[86:89]
	v_mfma_f32_16x16x32_bf16 v[78:81], v[168:171], v[204:207], v[78:81]
	v_mfma_f32_16x16x32_bf16 v[70:73], v[146:149], v[212:215], v[70:73]
	v_mfma_f32_16x16x32_bf16 v[66:69], v[168:171], v[212:215], v[66:69]
	v_mfma_f32_16x16x32_bf16 v[110:113], v[162:165], v[186:189], v[110:113]
	v_mfma_f32_16x16x32_bf16 v[106:109], v[172:175], v[186:189], v[106:109]
	v_mfma_f32_16x16x32_bf16 v[102:105], v[162:165], v[200:203], v[102:105]
	v_mfma_f32_16x16x32_bf16 v[98:101], v[172:175], v[200:203], v[98:101]
	v_mfma_f32_16x16x32_bf16 v[86:89], v[162:165], v[208:211], v[86:89]
	v_mfma_f32_16x16x32_bf16 v[78:81], v[172:175], v[208:211], v[78:81]
	v_mfma_f32_16x16x32_bf16 v[70:73], v[162:165], v[216:219], v[70:73]
	v_mfma_f32_16x16x32_bf16 v[66:69], v[172:175], v[216:219], v[66:69]
	s_setprio 0
	s_waitcnt vmcnt(8)
	s_barrier
	s_add_i32 s30, s59, s34
	v_lshl_add_u64 v[176:177], v[176:177], 0, s[10:11]
	s_mov_b32 m0, s30
	ds_read_b128 v[182:185], v180 offset:49152
	ds_read_b128 v[186:189], v180 offset:50176
	ds_read_b128 v[190:193], v180 offset:51200
	ds_read_b128 v[200:203], v180 offset:52224
	ds_read_b128 v[204:207], v180 offset:53248
	ds_read_b128 v[208:211], v180 offset:54272
	ds_read_b128 v[212:215], v180 offset:55296
	ds_read_b128 v[216:219], v180 offset:56320
	global_load_lds_dwordx4 v[176:177], off
	s_add_i32 m0, s30, 0x2000
	s_add_u32 s28, s28, 0x200080
	v_lshl_add_u64 v[176:177], v[220:221], 0, s[10:11]
	s_addc_u32 s29, s29, 0
	s_add_i32 s30, s60, s34
	global_load_lds_dwordx4 v[176:177], off
	v_lshl_add_u64 v[176:177], s[28:29], 0, v[158:159]
	s_mov_b32 m0, s30
	s_nop 0
	global_load_lds_dwordx4 v[176:177], off
	v_lshl_add_u64 v[176:177], s[28:29], 0, v[150:151]
	s_add_i32 m0, s30, 0x2000
	s_nop 0
	global_load_lds_dwordx4 v[176:177], off
	s_waitcnt lgkmcnt(0)
	s_setprio 1
	s_waitcnt lgkmcnt(0)
	v_mfma_f32_16x16x32_bf16 v[62:65], v[130:133], v[182:185], v[62:65]
	v_mfma_f32_16x16x32_bf16 v[58:61], v[138:141], v[182:185], v[58:61]
	v_mfma_f32_16x16x32_bf16 v[50:53], v[130:133], v[190:193], v[50:53]
	v_mfma_f32_16x16x32_bf16 v[42:45], v[138:141], v[190:193], v[42:45]
	v_mfma_f32_16x16x32_bf16 v[34:37], v[130:133], v[204:207], v[34:37]
	v_mfma_f32_16x16x32_bf16 v[26:29], v[138:141], v[204:207], v[26:29]
	v_mfma_f32_16x16x32_bf16 v[18:21], v[130:133], v[212:215], v[18:21]
	v_mfma_f32_16x16x32_bf16 v[10:13], v[138:141], v[212:215], v[10:13]
	v_mfma_f32_16x16x32_bf16 v[62:65], v[134:137], v[186:189], v[62:65]
	v_mfma_f32_16x16x32_bf16 v[58:61], v[142:145], v[186:189], v[58:61]
	v_mfma_f32_16x16x32_bf16 v[50:53], v[134:137], v[200:203], v[50:53]
	v_mfma_f32_16x16x32_bf16 v[42:45], v[142:145], v[200:203], v[42:45]
	v_mfma_f32_16x16x32_bf16 v[34:37], v[134:137], v[208:211], v[34:37]
	v_mfma_f32_16x16x32_bf16 v[26:29], v[142:145], v[208:211], v[26:29]
	v_mfma_f32_16x16x32_bf16 v[18:21], v[134:137], v[216:219], v[18:21]
	v_mfma_f32_16x16x32_bf16 v[10:13], v[142:145], v[216:219], v[10:13]
	v_mfma_f32_16x16x32_bf16 v[54:57], v[146:149], v[182:185], v[54:57]
	v_mfma_f32_16x16x32_bf16 v[46:49], v[168:171], v[182:185], v[46:49]
	v_mfma_f32_16x16x32_bf16 v[38:41], v[146:149], v[190:193], v[38:41]
	v_mfma_f32_16x16x32_bf16 v[30:33], v[168:171], v[190:193], v[30:33]
	v_mfma_f32_16x16x32_bf16 v[22:25], v[146:149], v[204:207], v[22:25]
	v_mfma_f32_16x16x32_bf16 v[14:17], v[168:171], v[204:207], v[14:17]
	v_mfma_f32_16x16x32_bf16 v[6:9], v[146:149], v[212:215], v[6:9]
	v_mfma_f32_16x16x32_bf16 v[2:5], v[168:171], v[212:215], v[2:5]
	v_mfma_f32_16x16x32_bf16 v[54:57], v[162:165], v[186:189], v[54:57]
	v_mfma_f32_16x16x32_bf16 v[46:49], v[172:175], v[186:189], v[46:49]
	v_mfma_f32_16x16x32_bf16 v[38:41], v[162:165], v[200:203], v[38:41]
	v_mfma_f32_16x16x32_bf16 v[30:33], v[172:175], v[200:203], v[30:33]
	v_mfma_f32_16x16x32_bf16 v[22:25], v[162:165], v[208:211], v[22:25]
	v_mfma_f32_16x16x32_bf16 v[14:17], v[172:175], v[208:211], v[14:17]
	v_mfma_f32_16x16x32_bf16 v[6:9], v[162:165], v[216:219], v[6:9]
	v_mfma_f32_16x16x32_bf16 v[2:5], v[172:175], v[216:219], v[2:5]
	s_setprio 0
	s_waitcnt vmcnt(6)
	s_barrier
	s_add_i32 s58, s58, 2
	s_add_u32 s0, s0, 0x100
	s_addc_u32 s1, s1, 0
	s_add_u32 s56, s56, 0x100
	s_addc_u32 s57, s57, 0
	s_cmpk_gt_u32 s58, 0x7d
	s_cbranch_scc0 .LBB0_880
	s_branch .Lhb_X_880
; #define PG8_STAGE(bufoff, gbase, voff) do { _Pragma("unroll") for (int _i = 0; _i < 2; ++_i) \
;         __builtin_amdgcn_global_load_lds((const unsigned*)((const char*)(gbase) + (voff)[_i]), (PG8_LAS unsigned*)(lds + (bufoff) + ldsw + _i * 8192), 16, 0, 0); } while (0)
; #define PG8_LDA(dst, b, h) do { _Pragma("unroll") for (int m = 0; m < 4; ++m) _Pragma("unroll") for (int k = 0; k < 2; ++k) dst[m][k] = *(const PG8_LAS bf16x8*)(lds + PG8_SA(b, h) + aoff + m * 2048 + k * 1024); } while (0)
; #define PG8_LDB(dst, b, h) do { _Pragma("unroll") for (int n = 0; n < 2; ++n) _Pragma("unroll") for (int k = 0; k < 2; ++k) dst[n][k] = *(const PG8_LAS bf16x8*)(lds + PG8_SB(b, h) + boff + n * 2048 + k * 1024); } while (0)
; #define PG8_MMA(ai, bj, At, Bt) do { __builtin_amdgcn_s_setprio(1); _Pragma("unroll") for (int m = 0; m < 4; ++m) _Pragma("unroll") for (int n = 0; n < 2; ++n) _Pragma("unroll") for (int k = 0; k < 2; ++k) \
;         acc[ai][bj][m][n] = __builtin_amdgcn_mfma_f32_16x16x32_bf16(Bt[n][k], At[m][k], acc[ai][bj][m][n], 0, 0, 0); __builtin_amdgcn_s_setprio(0); } while (0)
; #define PG8_WAIT_V(n) asm volatile("s_waitcnt vmcnt(" #n ")" ::: "memory")
; #define PG8_WAIT_L(n) asm volatile("s_waitcnt lgkmcnt(" #n ")" ::: "memory")
; #define PG8_BAR __builtin_amdgcn_s_barrier()
; #define PG8_SCHED __builtin_amdgcn_sched_barrier(0)
; template <class Epi, class Sched, bool ALIGN_EPI = false, bool SP2 = false>
; __device__ __forceinline__ void gemm_phase(PG8_LAS unsigned char* lds, const Gemm g, const Sched& S, const Epi& E) {
;     ...
;             PG8_LDB(B0, 0, 0); PG8_LDB(B1, 0, 1); PG8_SCHED; PG8_LDA(At, 0, 0); PG8_STAGE(PG8_SA(1, 1), a1 + hstep, voffA);
;             PG8_WAIT_V(8); PG8_WAIT_L(0); PG8_BAR; PG8_MMA(0, 0, At, B0); PG8_MMA(0, 1, At, B1); PG8_BAR; PG8_SCHED;
;             PG8_LDA(At, 0, 1); PG8_STAGE(PG8_SB(0, 0), b2, voffB); PG8_STAGE(PG8_SB(0, 1), b2 + hstep, voffB); PG8_STAGE(PG8_SA(0, 0), a2, voffA);
;             PG8_WAIT_V(8); PG8_WAIT_L(0); PG8_BAR; PG8_MMA(1, 0, At, B0); PG8_MMA(1, 1, At, B1); PG8_BAR; PG8_SCHED;
.Lhb_T_880:
	s_add_u32 s28, s0, 0xffe00080
	s_addc_u32 s29, s1, -1
	s_add_i32 s59, 0, 0x10000
	s_cmpk_eq_i32 s58, 0x7c
	s_cselect_b32 s31, s19, s29
	s_cselect_b32 s30, s54, s28
	s_cselect_b32 s29, s17, s57
	s_cselect_b32 s28, s55, s56
	s_add_i32 s62, 0, 0x14000
	v_add_u32_e32 v142, s59, v178
	v_add_u32_e32 v172, s62, v178
	ds_read_b128 v[130:133], v142
	ds_read_b128 v[134:137], v142 offset:1024
	ds_read_b128 v[138:141], v142 offset:2048
	ds_read_b128 v[142:145], v142 offset:3072
	ds_read_b128 v[146:149], v172
	ds_read_b128 v[162:165], v172 offset:1024
	ds_read_b128 v[168:171], v172 offset:2048
	ds_read_b128 v[172:175], v172 offset:3072
	s_add_u32 s98, s0, 0xffe00000
	s_addc_u32 s99, s1, -1
	v_lshl_add_u64 v[176:177], s[98:99], 0, v[156:157]
	s_mov_b32 m0, s44
	s_nop 0
	global_load_lds_dwordx4 v[176:177], off
	v_lshl_add_u64 v[176:177], s[98:99], 0, v[166:167]
	s_mov_b32 m0, s45
	s_nop 0
	global_load_lds_dwordx4 v[176:177], off
	v_lshl_add_u64 v[176:177], s[0:1], 0, v[156:157]
	s_add_i32 m0, s36, 0xc000
	ds_read_b128 v[182:185], v180
	ds_read_b128 v[186:189], v180 offset:1024
	ds_read_b128 v[190:193], v180 offset:2048
	ds_read_b128 v[200:203], v180 offset:3072
	ds_read_b128 v[204:207], v180 offset:4096
	ds_read_b128 v[208:211], v180 offset:5120
	ds_read_b128 v[212:215], v180 offset:6144
	ds_read_b128 v[216:219], v180 offset:7168
	global_load_lds_dwordx4 v[176:177], off
	v_lshl_add_u64 v[176:177], s[0:1], 0, v[166:167]
	s_add_i32 m0, s36, 0xe000
	s_nop 0
	global_load_lds_dwordx4 v[176:177], off
	s_waitcnt vmcnt(8)
	s_waitcnt lgkmcnt(0)
	s_barrier
	s_setprio 2
	s_waitcnt lgkmcnt(0)
	v_mfma_f32_16x16x32_bf16 v[126:129], v[130:133], v[182:185], v[126:129]
	v_mfma_f32_16x16x32_bf16 v[122:125], v[138:141], v[182:185], v[122:125]
	v_mfma_f32_16x16x32_bf16 v[118:121], v[130:133], v[190:193], v[118:121]
	v_mfma_f32_16x16x32_bf16 v[114:117], v[138:141], v[190:193], v[114:117]
	v_mfma_f32_16x16x32_bf16 v[94:97], v[130:133], v[204:207], v[94:97]
	v_mfma_f32_16x16x32_bf16 v[90:93], v[138:141], v[204:207], v[90:93]
	v_mfma_f32_16x16x32_bf16 v[82:85], v[130:133], v[212:215], v[82:85]
	v_mfma_f32_16x16x32_bf16 v[74:77], v[138:141], v[212:215], v[74:77]
	v_mfma_f32_16x16x32_bf16 v[126:129], v[134:137], v[186:189], v[126:129]
	v_mfma_f32_16x16x32_bf16 v[122:125], v[142:145], v[186:189], v[122:125]
	v_mfma_f32_16x16x32_bf16 v[118:121], v[134:137], v[200:203], v[118:121]
	v_mfma_f32_16x16x32_bf16 v[114:117], v[142:145], v[200:203], v[114:117]
	v_mfma_f32_16x16x32_bf16 v[94:97], v[134:137], v[208:211], v[94:97]
	v_mfma_f32_16x16x32_bf16 v[90:93], v[142:145], v[208:211], v[90:93]
	v_mfma_f32_16x16x32_bf16 v[82:85], v[134:137], v[216:219], v[82:85]
	v_mfma_f32_16x16x32_bf16 v[74:77], v[142:145], v[216:219], v[74:77]
	v_mfma_f32_16x16x32_bf16 v[110:113], v[146:149], v[182:185], v[110:113]
	v_mfma_f32_16x16x32_bf16 v[106:109], v[168:171], v[182:185], v[106:109]
	v_mfma_f32_16x16x32_bf16 v[102:105], v[146:149], v[190:193], v[102:105]
	v_mfma_f32_16x16x32_bf16 v[98:101], v[168:171], v[190:193], v[98:101]
	v_mfma_f32_16x16x32_bf16 v[86:89], v[146:149], v[204:207], v[86:89]
	v_mfma_f32_16x16x32_bf16 v[78:81], v[168:171], v[204:207], v[78:81]
	v_mfma_f32_16x16x32_bf16 v[70:73], v[146:149], v[212:215], v[70:73]
	v_mfma_f32_16x16x32_bf16 v[66:69], v[168:171], v[212:215], v[66:69]
	v_mfma_f32_16x16x32_bf16 v[110:113], v[162:165], v[186:189], v[110:113]
	v_mfma_f32_16x16x32_bf16 v[106:109], v[172:175], v[186:189], v[106:109]
	v_mfma_f32_16x16x32_bf16 v[102:105], v[162:165], v[200:203], v[102:105]
	v_mfma_f32_16x16x32_bf16 v[98:101], v[172:175], v[200:203], v[98:101]
	v_mfma_f32_16x16x32_bf16 v[86:89], v[162:165], v[208:211], v[86:89]
	v_mfma_f32_16x16x32_bf16 v[78:81], v[172:175], v[208:211], v[78:81]
	v_mfma_f32_16x16x32_bf16 v[70:73], v[162:165], v[216:219], v[70:73]
	v_mfma_f32_16x16x32_bf16 v[66:69], v[172:175], v[216:219], v[66:69]
	s_setprio 0
	s_add_i32 s59, s59, s34
	v_lshl_add_u64 v[176:177], s[28:29], 0, v[158:159]
	s_mov_b32 m0, s59
	ds_read_b128 v[182:185], v180 offset:16384
	ds_read_b128 v[186:189], v180 offset:17408
	ds_read_b128 v[190:193], v180 offset:18432
	ds_read_b128 v[200:203], v180 offset:19456
	ds_read_b128 v[204:207], v180 offset:20480
	ds_read_b128 v[208:211], v180 offset:21504
	ds_read_b128 v[212:215], v180 offset:22528
	ds_read_b128 v[216:219], v180 offset:23552
	global_load_lds_dwordx4 v[176:177], off
	s_add_i32 m0, s59, 0x2000
	s_add_u32 s60, s28, 0x200000
	v_lshl_add_u64 v[220:221], s[28:29], 0, v[150:151]
	s_addc_u32 s61, s29, 0
	s_add_i32 s59, s62, s34
	global_load_lds_dwordx4 v[220:221], off
	v_lshl_add_u64 v[222:223], s[60:61], 0, v[158:159]
	s_mov_b32 m0, s59
	v_lshl_add_u64 v[224:225], s[30:31], 0, v[152:153]
	global_load_lds_dwordx4 v[222:223], off
	v_lshl_add_u64 v[222:223], s[60:61], 0, v[150:151]
	s_add_i32 m0, s59, 0x2000
	s_nop 0
	global_load_lds_dwordx4 v[222:223], off
	v_lshl_add_u64 v[222:223], s[30:31], 0, v[154:155]
	s_waitcnt vmcnt(6)
	s_waitcnt lgkmcnt(0)
	s_barrier
; #define PG8_STAGE(bufoff, gbase, voff) do { _Pragma("unroll") for (int _i = 0; _i < 2; ++_i) \
;         __builtin_amdgcn_global_load_lds((const unsigned*)((const char*)(gbase) + (voff)[_i]), (PG8_LAS unsigned*)(lds + (bufoff) + ldsw + _i * 8192), 16, 0, 0); } while (0)
; #define PG8_LDA(dst, b, h) do { _Pragma("unroll") for (int m = 0; m < 4; ++m) _Pragma("unroll") for (int k = 0; k < 2; ++k) dst[m][k] = *(const PG8_LAS bf16x8*)(lds + PG8_SA(b, h) + aoff + m * 2048 + k * 1024); } while (0)
; #define PG8_LDB(dst, b, h) do { _Pragma("unroll") for (int n = 0; n < 2; ++n) _Pragma("unroll") for (int k = 0; k < 2; ++k) dst[n][k] = *(const PG8_LAS bf16x8*)(lds + PG8_SB(b, h) + boff + n * 2048 + k * 1024); } while (0)
; #define PG8_MMA(ai, bj, At, Bt) do { __builtin_amdgcn_s_setprio(1); _Pragma("unroll") for (int m = 0; m < 4; ++m) _Pragma("unroll") for (int n = 0; n < 2; ++n) _Pragma("unroll") for (int k = 0; k < 2; ++k) \
;         acc[ai][bj][m][n] = __builtin_amdgcn_mfma_f32_16x16x32_bf16(Bt[n][k], At[m][k], acc[ai][bj][m][n], 0, 0, 0); __builtin_amdgcn_s_setprio(0); } while (0)
; #define PG8_WAIT_V(n) asm volatile("s_waitcnt vmcnt(" #n ")" ::: "memory")
; #define PG8_WAIT_L(n) asm volatile("s_waitcnt lgkmcnt(" #n ")" ::: "memory")
; #define PG8_BAR __builtin_amdgcn_s_barrier()
; #define PG8_SCHED __builtin_amdgcn_sched_barrier(0)
; template <class Epi, class Sched, bool ALIGN_EPI = false, bool SP2 = false>
; __device__ __forceinline__ void gemm_phase(PG8_LAS unsigned char* lds, const Gemm g, const Sched& S, const Epi& E) {
;     ...
;             PG8_WAIT_V(8); PG8_WAIT_L(0); PG8_BAR; PG8_MMA(1, 0, At, B0); PG8_MMA(1, 1, At, B1); PG8_BAR; PG8_SCHED;
;             PG8_LDB(B0, 1, 0); PG8_LDB(B1, 1, 1); PG8_SCHED; PG8_LDA(At, 1, 0); PG8_STAGE(PG8_SA(0, 1), a2 + hstep, voffA);
	s_setprio 2
	s_waitcnt lgkmcnt(0)
	v_mfma_f32_16x16x32_bf16 v[62:65], v[130:133], v[182:185], v[62:65]
	v_mfma_f32_16x16x32_bf16 v[58:61], v[138:141], v[182:185], v[58:61]
	v_mfma_f32_16x16x32_bf16 v[50:53], v[130:133], v[190:193], v[50:53]
	v_mfma_f32_16x16x32_bf16 v[42:45], v[138:141], v[190:193], v[42:45]
	v_mfma_f32_16x16x32_bf16 v[34:37], v[130:133], v[204:207], v[34:37]
	v_mfma_f32_16x16x32_bf16 v[26:29], v[138:141], v[204:207], v[26:29]
	v_mfma_f32_16x16x32_bf16 v[18:21], v[130:133], v[212:215], v[18:21]
	v_mfma_f32_16x16x32_bf16 v[10:13], v[138:141], v[212:215], v[10:13]
	v_mfma_f32_16x16x32_bf16 v[62:65], v[134:137], v[186:189], v[62:65]
	v_mfma_f32_16x16x32_bf16 v[58:61], v[142:145], v[186:189], v[58:61]
	v_mfma_f32_16x16x32_bf16 v[50:53], v[134:137], v[200:203], v[50:53]
	v_mfma_f32_16x16x32_bf16 v[42:45], v[142:145], v[200:203], v[42:45]
	v_mfma_f32_16x16x32_bf16 v[34:37], v[134:137], v[208:211], v[34:37]
	v_mfma_f32_16x16x32_bf16 v[26:29], v[142:145], v[208:211], v[26:29]
	v_mfma_f32_16x16x32_bf16 v[18:21], v[134:137], v[216:219], v[18:21]
	v_mfma_f32_16x16x32_bf16 v[10:13], v[142:145], v[216:219], v[10:13]
	v_mfma_f32_16x16x32_bf16 v[54:57], v[146:149], v[182:185], v[54:57]
	v_mfma_f32_16x16x32_bf16 v[46:49], v[168:171], v[182:185], v[46:49]
	v_mfma_f32_16x16x32_bf16 v[38:41], v[146:149], v[190:193], v[38:41]
	v_mfma_f32_16x16x32_bf16 v[30:33], v[168:171], v[190:193], v[30:33]
	v_mfma_f32_16x16x32_bf16 v[22:25], v[146:149], v[204:207], v[22:25]
	v_mfma_f32_16x16x32_bf16 v[14:17], v[168:171], v[204:207], v[14:17]
	v_mfma_f32_16x16x32_bf16 v[6:9], v[146:149], v[212:215], v[6:9]
	v_mfma_f32_16x16x32_bf16 v[2:5], v[168:171], v[212:215], v[2:5]
	v_mfma_f32_16x16x32_bf16 v[54:57], v[162:165], v[186:189], v[54:57]
	v_mfma_f32_16x16x32_bf16 v[46:49], v[172:175], v[186:189], v[46:49]
	v_mfma_f32_16x16x32_bf16 v[38:41], v[162:165], v[200:203], v[38:41]
	v_mfma_f32_16x16x32_bf16 v[30:33], v[172:175], v[200:203], v[30:33]
	v_mfma_f32_16x16x32_bf16 v[22:25], v[162:165], v[208:211], v[22:25]
	v_mfma_f32_16x16x32_bf16 v[14:17], v[172:175], v[208:211], v[14:17]
	v_mfma_f32_16x16x32_bf16 v[6:9], v[162:165], v[216:219], v[6:9]
	v_mfma_f32_16x16x32_bf16 v[2:5], v[172:175], v[216:219], v[2:5]
	s_setprio 0
	s_add_i32 s59, 0, 0x18000
	s_add_i32 s60, 0, 0x1c000
	v_add_u32_e32 v142, s59, v178
	v_add_u32_e32 v172, s60, v178
	ds_read_b128 v[130:133], v142
	ds_read_b128 v[134:137], v142 offset:1024
	ds_read_b128 v[138:141], v142 offset:2048
	ds_read_b128 v[142:145], v142 offset:3072
	ds_read_b128 v[146:149], v172
	ds_read_b128 v[162:165], v172 offset:1024
	ds_read_b128 v[168:171], v172 offset:2048
	ds_read_b128 v[172:175], v172 offset:3072
	s_add_u32 s30, s30, 0x200000
	s_addc_u32 s31, s31, 0
	s_mov_b32 m0, s36
	s_nop 0
	global_load_lds_dwordx4 v[222:223], off
	s_mov_b32 m0, s37
	s_nop 0
	global_load_lds_dwordx4 v[224:225], off
	s_mov_b32 m0, s42
	v_lshl_add_u64 v[226:227], s[30:31], 0, v[154:155]
	ds_read_b128 v[182:185], v180 offset:32768
	ds_read_b128 v[186:189], v180 offset:33792
	ds_read_b128 v[190:193], v180 offset:34816
	ds_read_b128 v[200:203], v180 offset:35840
	ds_read_b128 v[204:207], v180 offset:36864
	ds_read_b128 v[208:211], v180 offset:37888
	ds_read_b128 v[212:215], v180 offset:38912
	ds_read_b128 v[216:219], v180 offset:39936
	global_load_lds_dwordx4 v[226:227], off
	v_lshl_add_u64 v[226:227], s[30:31], 0, v[152:153]
	s_mov_b32 m0, s43
	s_nop 0
	global_load_lds_dwordx4 v[226:227], off
	s_waitcnt vmcnt(8)
	s_waitcnt lgkmcnt(0)
	s_barrier
; #define PG8_STAGE(bufoff, gbase, voff) do { _Pragma("unroll") for (int _i = 0; _i < 2; ++_i) \
;         __builtin_amdgcn_global_load_lds((const unsigned*)((const char*)(gbase) + (voff)[_i]), (PG8_LAS unsigned*)(lds + (bufoff) + ldsw + _i * 8192), 16, 0, 0); } while (0)
; #define PG8_LDA(dst, b, h) do { _Pragma("unroll") for (int m = 0; m < 4; ++m) _Pragma("unroll") for (int k = 0; k < 2; ++k) dst[m][k] = *(const PG8_LAS bf16x8*)(lds + PG8_SA(b, h) + aoff + m * 2048 + k * 1024); } while (0)
; #define PG8_LDB(dst, b, h) do { _Pragma("unroll") for (int n = 0; n < 2; ++n) _Pragma("unroll") for (int k = 0; k < 2; ++k) dst[n][k] = *(const PG8_LAS bf16x8*)(lds + PG8_SB(b, h) + boff + n * 2048 + k * 1024); } while (0)
; #define PG8_MMA(ai, bj, At, Bt) do { __builtin_amdgcn_s_setprio(1); _Pragma("unroll") for (int m = 0; m < 4; ++m) _Pragma("unroll") for (int n = 0; n < 2; ++n) _Pragma("unroll") for (int k = 0; k < 2; ++k) \
;         acc[ai][bj][m][n] = __builtin_amdgcn_mfma_f32_16x16x32_bf16(Bt[n][k], At[m][k], acc[ai][bj][m][n], 0, 0, 0); __builtin_amdgcn_s_setprio(0); } while (0)
; #define PG8_WAIT_V(n) asm volatile("s_waitcnt vmcnt(" #n ")" ::: "memory")
; #define PG8_WAIT_L(n) asm volatile("s_waitcnt lgkmcnt(" #n ")" ::: "memory")
; #define PG8_BAR __builtin_amdgcn_s_barrier()
; #define PG8_SCHED __builtin_amdgcn_sched_barrier(0)
; template <class Epi, class Sched, bool ALIGN_EPI = false, bool SP2 = false>
; __device__ __forceinline__ void gemm_phase(PG8_LAS unsigned char* lds, const Gemm g, const Sched& S, const Epi& E) {
;     ...
;             PG8_LDB(B0, 1, 0); PG8_LDB(B1, 1, 1); PG8_SCHED; PG8_LDA(At, 1, 0); PG8_STAGE(PG8_SA(0, 1), a2 + hstep, voffA);
;             PG8_WAIT_V(8); PG8_WAIT_L(0); PG8_BAR; PG8_MMA(0, 0, At, B0); PG8_MMA(0, 1, At, B1); PG8_BAR; PG8_SCHED;
;             PG8_LDA(At, 1, 1); PG8_STAGE(PG8_SB(1, 0), b3, voffB); PG8_STAGE(PG8_SB(1, 1), b3 + hstep, voffB); PG8_STAGE(PG8_SA(1, 0), a3, voffA);
;             PG8_WAIT_V(8); PG8_WAIT_L(0); PG8_BAR; PG8_MMA(1, 0, At, B0); PG8_MMA(1, 1, At, B1); PG8_BAR; PG8_SCHED;
	s_setprio 2
	s_waitcnt lgkmcnt(0)
	v_mfma_f32_16x16x32_bf16 v[126:129], v[130:133], v[182:185], v[126:129]
	v_mfma_f32_16x16x32_bf16 v[122:125], v[138:141], v[182:185], v[122:125]
	v_mfma_f32_16x16x32_bf16 v[118:121], v[130:133], v[190:193], v[118:121]
	v_mfma_f32_16x16x32_bf16 v[114:117], v[138:141], v[190:193], v[114:117]
	v_mfma_f32_16x16x32_bf16 v[94:97], v[130:133], v[204:207], v[94:97]
	v_mfma_f32_16x16x32_bf16 v[90:93], v[138:141], v[204:207], v[90:93]
	v_mfma_f32_16x16x32_bf16 v[82:85], v[130:133], v[212:215], v[82:85]
	v_mfma_f32_16x16x32_bf16 v[74:77], v[138:141], v[212:215], v[74:77]
	v_mfma_f32_16x16x32_bf16 v[126:129], v[134:137], v[186:189], v[126:129]
	v_mfma_f32_16x16x32_bf16 v[122:125], v[142:145], v[186:189], v[122:125]
	v_mfma_f32_16x16x32_bf16 v[118:121], v[134:137], v[200:203], v[118:121]
	v_mfma_f32_16x16x32_bf16 v[114:117], v[142:145], v[200:203], v[114:117]
	v_mfma_f32_16x16x32_bf16 v[94:97], v[134:137], v[208:211], v[94:97]
	v_mfma_f32_16x16x32_bf16 v[90:93], v[142:145], v[208:211], v[90:93]
	v_mfma_f32_16x16x32_bf16 v[82:85], v[134:137], v[216:219], v[82:85]
	v_mfma_f32_16x16x32_bf16 v[74:77], v[142:145], v[216:219], v[74:77]
	v_mfma_f32_16x16x32_bf16 v[110:113], v[146:149], v[182:185], v[110:113]
	v_mfma_f32_16x16x32_bf16 v[106:109], v[168:171], v[182:185], v[106:109]
	v_mfma_f32_16x16x32_bf16 v[102:105], v[146:149], v[190:193], v[102:105]
	v_mfma_f32_16x16x32_bf16 v[98:101], v[168:171], v[190:193], v[98:101]
	v_mfma_f32_16x16x32_bf16 v[86:89], v[146:149], v[204:207], v[86:89]
	v_mfma_f32_16x16x32_bf16 v[78:81], v[168:171], v[204:207], v[78:81]
	v_mfma_f32_16x16x32_bf16 v[70:73], v[146:149], v[212:215], v[70:73]
	v_mfma_f32_16x16x32_bf16 v[66:69], v[168:171], v[212:215], v[66:69]
	v_mfma_f32_16x16x32_bf16 v[110:113], v[162:165], v[186:189], v[110:113]
	v_mfma_f32_16x16x32_bf16 v[106:109], v[172:175], v[186:189], v[106:109]
	v_mfma_f32_16x16x32_bf16 v[102:105], v[162:165], v[200:203], v[102:105]
	v_mfma_f32_16x16x32_bf16 v[98:101], v[172:175], v[200:203], v[98:101]
	v_mfma_f32_16x16x32_bf16 v[86:89], v[162:165], v[208:211], v[86:89]
	v_mfma_f32_16x16x32_bf16 v[78:81], v[172:175], v[208:211], v[78:81]
	v_mfma_f32_16x16x32_bf16 v[70:73], v[162:165], v[216:219], v[70:73]
	v_mfma_f32_16x16x32_bf16 v[66:69], v[172:175], v[216:219], v[66:69]
	s_setprio 0
	s_add_i32 s30, s59, s34
	v_lshl_add_u64 v[176:177], v[176:177], 0, s[10:11]
	s_mov_b32 m0, s30
	ds_read_b128 v[182:185], v180 offset:49152
	ds_read_b128 v[186:189], v180 offset:50176
	ds_read_b128 v[190:193], v180 offset:51200
	ds_read_b128 v[200:203], v180 offset:52224
	ds_read_b128 v[204:207], v180 offset:53248
	ds_read_b128 v[208:211], v180 offset:54272
	ds_read_b128 v[212:215], v180 offset:55296
	ds_read_b128 v[216:219], v180 offset:56320
	global_load_lds_dwordx4 v[176:177], off
	s_add_i32 m0, s30, 0x2000
	s_add_u32 s28, s28, 0x200080
	v_lshl_add_u64 v[176:177], v[220:221], 0, s[10:11]
	s_addc_u32 s29, s29, 0
	s_add_i32 s30, s60, s34
	global_load_lds_dwordx4 v[176:177], off
	v_lshl_add_u64 v[176:177], s[28:29], 0, v[158:159]
	s_mov_b32 m0, s30
	s_nop 0
	global_load_lds_dwordx4 v[176:177], off
	v_lshl_add_u64 v[176:177], s[28:29], 0, v[150:151]
	s_add_i32 m0, s30, 0x2000
	s_nop 0
	global_load_lds_dwordx4 v[176:177], off
	s_waitcnt vmcnt(6)
	s_waitcnt lgkmcnt(0)
	s_barrier
	s_setprio 2
	s_waitcnt lgkmcnt(0)
	v_mfma_f32_16x16x32_bf16 v[62:65], v[130:133], v[182:185], v[62:65]
	v_mfma_f32_16x16x32_bf16 v[58:61], v[138:141], v[182:185], v[58:61]
	v_mfma_f32_16x16x32_bf16 v[50:53], v[130:133], v[190:193], v[50:53]
	v_mfma_f32_16x16x32_bf16 v[42:45], v[138:141], v[190:193], v[42:45]
	v_mfma_f32_16x16x32_bf16 v[34:37], v[130:133], v[204:207], v[34:37]
	v_mfma_f32_16x16x32_bf16 v[26:29], v[138:141], v[204:207], v[26:29]
	v_mfma_f32_16x16x32_bf16 v[18:21], v[130:133], v[212:215], v[18:21]
	v_mfma_f32_16x16x32_bf16 v[10:13], v[138:141], v[212:215], v[10:13]
	v_mfma_f32_16x16x32_bf16 v[62:65], v[134:137], v[186:189], v[62:65]
	v_mfma_f32_16x16x32_bf16 v[58:61], v[142:145], v[186:189], v[58:61]
	v_mfma_f32_16x16x32_bf16 v[50:53], v[134:137], v[200:203], v[50:53]
	v_mfma_f32_16x16x32_bf16 v[42:45], v[142:145], v[200:203], v[42:45]
	v_mfma_f32_16x16x32_bf16 v[34:37], v[134:137], v[208:211], v[34:37]
	v_mfma_f32_16x16x32_bf16 v[26:29], v[142:145], v[208:211], v[26:29]
	v_mfma_f32_16x16x32_bf16 v[18:21], v[134:137], v[216:219], v[18:21]
	v_mfma_f32_16x16x32_bf16 v[10:13], v[142:145], v[216:219], v[10:13]
	v_mfma_f32_16x16x32_bf16 v[54:57], v[146:149], v[182:185], v[54:57]
	v_mfma_f32_16x16x32_bf16 v[46:49], v[168:171], v[182:185], v[46:49]
	v_mfma_f32_16x16x32_bf16 v[38:41], v[146:149], v[190:193], v[38:41]
	v_mfma_f32_16x16x32_bf16 v[30:33], v[168:171], v[190:193], v[30:33]
	v_mfma_f32_16x16x32_bf16 v[22:25], v[146:149], v[204:207], v[22:25]
	v_mfma_f32_16x16x32_bf16 v[14:17], v[168:171], v[204:207], v[14:17]
	v_mfma_f32_16x16x32_bf16 v[6:9], v[146:149], v[212:215], v[6:9]
	v_mfma_f32_16x16x32_bf16 v[2:5], v[168:171], v[212:215], v[2:5]
	v_mfma_f32_16x16x32_bf16 v[54:57], v[162:165], v[186:189], v[54:57]
	v_mfma_f32_16x16x32_bf16 v[46:49], v[172:175], v[186:189], v[46:49]
	v_mfma_f32_16x16x32_bf16 v[38:41], v[162:165], v[200:203], v[38:41]
	v_mfma_f32_16x16x32_bf16 v[30:33], v[172:175], v[200:203], v[30:33]
	v_mfma_f32_16x16x32_bf16 v[22:25], v[162:165], v[208:211], v[22:25]
	v_mfma_f32_16x16x32_bf16 v[14:17], v[172:175], v[208:211], v[14:17]
	v_mfma_f32_16x16x32_bf16 v[6:9], v[162:165], v[216:219], v[6:9]
	v_mfma_f32_16x16x32_bf16 v[2:5], v[172:175], v[216:219], v[2:5]
	s_setprio 0
	s_add_i32 s58, s58, 2
	s_add_u32 s0, s0, 0x100
	s_addc_u32 s1, s1, 0
	s_add_u32 s56, s56, 0x100
	s_addc_u32 s57, s57, 0
	s_cmpk_gt_u32 s58, 0x7d
	s_cbranch_scc0 .Lhb_T_880

; __device__ __forceinline__ unsigned cvt_pk_bf16(float lo, float hi) { f32x2 v = {lo, hi}; bf16x2_t b = __builtin_convertvector(v, bf16x2_t); return __builtin_bit_cast(unsigned, b); }
;     __device__ __forceinline__ void operator()(const f32x4 (&acc)[2][2][4][2], const Unit& u, int wr, int wc, int fr, int fq) const {
;         const int col0 = u.pn * BM + wc * 32 + 8 * fq;
; #pragma unroll
;         for (int ai = 0; ai < 2; ++ai) {
;             u32x4 xr[4][2];
; #pragma unroll
;             for (int m = 0; m < 4; ++m)
; #pragma unroll
;                 for (int bj = 0; bj < 2; ++bj) xr[m][bj] = *(const u32x4*)(xb + (size_t)(u.pm * BM + ai * HALF + wr * 64 + m * 16 + fr) * 2048 + col0 + bj * HALF);
; #pragma unroll
;             for (int m = 0; m < 4; ++m) { const int row = u.pm * BM + ai * HALF + wr * 64 + m * 16 + fr; const size_t off = (size_t)row * 2048 + col0; float sq = 0.f;
; #pragma unroll
;                 for (int bj = 0; bj < 2; ++bj) { const size_t o2 = off + bj * HALF; const u32x4 xw = xr[m][bj];
;                     f32x4 x0, x1; x0[0] = __uint_as_float(xw.x << 16); x0[1] = __uint_as_float(xw.x & 0xffff0000u); x0[2] = __uint_as_float(xw.y << 16); x0[3] = __uint_as_float(xw.y & 0xffff0000u);
;                     x1[0] = __uint_as_float(xw.z << 16); x1[1] = __uint_as_float(xw.z & 0xffff0000u); x1[2] = __uint_as_float(xw.w << 16); x1[3] = __uint_as_float(xw.w & 0xffff0000u);
;                     x0 = x0 + acc[ai][bj][m][0]; x1 = x1 + acc[ai][bj][m][1];
;                     if (FINAL) { *(f32x4*)(out + o2) = x0; *(f32x4*)(out + o2 + 4) = x1; }
;                     else { u32x4 w; w.x = cvt_pk_bf16(x0[0], x0[1]); w.y = cvt_pk_bf16(x0[2], x0[3]); w.z = cvt_pk_bf16(x1[0], x1[1]); w.w = cvt_pk_bf16(x1[2], x1[3]); *(u32x4*)(xb + o2) = w; }
.LBB0_883:
	v_lshl_or_b32 v190, s52, 8, v179
	v_lshl_add_u32 v170, s53, 8, v161
	v_ashrrev_i32_e32 v191, 31, v190
	v_ashrrev_i32_e32 v171, 31, v170
	v_lshl_add_u64 v[168:169], v[190:191], 1, s[46:47]
	v_lshlrev_b64 v[130:131], 12, v[170:171]
	v_lshl_add_u64 v[130:131], v[168:169], 0, v[130:131]
	global_load_dwordx4 v[162:165], v[130:131], off
	global_load_dwordx4 v[182:185], v[130:131], off offset:256
	v_or_b32_e32 v176, 16, v170
	v_ashrrev_i32_e32 v177, 31, v176
	v_lshlrev_b64 v[130:131], 12, v[176:177]
	v_lshl_add_u64 v[130:131], v[168:169], 0, v[130:131]
	global_load_dwordx4 v[186:189], v[130:131], off
	global_load_dwordx4 v[146:149], v[130:131], off offset:256
	v_or_b32_e32 v174, 32, v170
	v_ashrrev_i32_e32 v175, 31, v174
	v_lshlrev_b64 v[130:131], 12, v[174:175]
	v_lshl_add_u64 v[130:131], v[168:169], 0, v[130:131]
	global_load_dwordx4 v[142:145], v[130:131], off
	global_load_dwordx4 v[138:141], v[130:131], off offset:256
	v_or_b32_e32 v172, 48, v170
	v_ashrrev_i32_e32 v173, 31, v172
	v_lshlrev_b64 v[130:131], 12, v[172:173]
	v_lshl_add_u64 v[130:131], v[168:169], 0, v[130:131]
	global_load_dwordx4 v[134:137], v[130:131], off
	s_nop 0
	global_load_dwordx4 v[130:133], v[130:131], off offset:256
	s_mov_b64 s[0:1], -1
	s_andn2_b64 vcc, exec, s[40:41]
	s_mov_b64 s[60:61], s[90:91]
	s_mov_b64 s[62:63], s[88:89]
	s_waitcnt vmcnt(0)
	v_lshlrev_b32_e32 v192, 16, v162
	v_and_b32_e32 v193, 0xffff0000, v162
	v_lshlrev_b32_e32 v162, 16, v163
	v_and_b32_e32 v163, 0xffff0000, v163
	v_lshlrev_b32_e32 v200, 16, v164
	v_and_b32_e32 v201, 0xffff0000, v164
	v_lshlrev_b32_e32 v164, 16, v165
	v_and_b32_e32 v165, 0xffff0000, v165
	v_pk_add_f32 v[128:129], v[128:129], v[162:163]
	v_pk_add_f32 v[162:163], v[122:123], v[200:201]
	v_lshlrev_b64 v[122:123], 13, v[170:171]
	v_pk_add_f32 v[164:165], v[124:125], v[164:165]
	v_lshl_add_u64 v[124:125], s[4:5], 0, v[122:123]
	v_lshlrev_b64 v[122:123], 2, v[190:191]
	v_pk_add_f32 v[126:127], v[126:127], v[192:193]
	v_lshl_add_u64 v[124:125], v[124:125], 0, v[122:123]
	global_store_dwordx4 v[124:125], v[126:129], off
	global_store_dwordx4 v[124:125], v[162:165], off offset:16
	s_nop 0
	v_lshlrev_b32_e32 v126, 16, v182
	v_and_b32_e32 v127, 0xffff0000, v182
	v_lshlrev_b32_e32 v128, 16, v183
	v_and_b32_e32 v129, 0xffff0000, v183
	v_lshlrev_b32_e32 v162, 16, v184
	v_and_b32_e32 v163, 0xffff0000, v184
	v_lshlrev_b32_e32 v164, 16, v185
	v_and_b32_e32 v165, 0xffff0000, v185
	v_pk_add_f32 v[112:113], v[112:113], v[128:129]
	v_pk_add_f32 v[110:111], v[110:111], v[126:127]
	v_pk_add_f32 v[108:109], v[108:109], v[164:165]
	v_pk_add_f32 v[106:107], v[106:107], v[162:163]
	global_store_dwordx4 v[124:125], v[110:113], off offset:512
	global_store_dwordx4 v[124:125], v[106:109], off offset:528
	s_nop 0
	v_lshlrev_b32_e32 v110, 16, v188
	v_and_b32_e32 v111, 0xffff0000, v188
	v_pk_add_f32 v[110:111], v[114:115], v[110:111]
	v_lshlrev_b64 v[114:115], 13, v[176:177]
	v_lshlrev_b32_e32 v106, 16, v186
	v_and_b32_e32 v107, 0xffff0000, v186
	v_lshlrev_b32_e32 v108, 16, v187
	v_and_b32_e32 v109, 0xffff0000, v187
	v_lshl_add_u64 v[114:115], s[4:5], 0, v[114:115]
	v_lshlrev_b32_e32 v112, 16, v189
	v_and_b32_e32 v113, 0xffff0000, v189
	v_pk_add_f32 v[108:109], v[120:121], v[108:109]
	v_pk_add_f32 v[106:107], v[118:119], v[106:107]
	v_lshl_add_u64 v[114:115], v[114:115], 0, v[122:123]
	v_pk_add_f32 v[112:113], v[116:117], v[112:113]
	global_store_dwordx4 v[114:115], v[106:109], off
	global_store_dwordx4 v[114:115], v[110:113], off offset:16
	s_nop 0
	v_lshlrev_b32_e32 v106, 16, v146
	v_and_b32_e32 v107, 0xffff0000, v146
	v_lshlrev_b32_e32 v108, 16, v147
	v_and_b32_e32 v109, 0xffff0000, v147
	v_lshlrev_b32_e32 v110, 16, v148
	v_and_b32_e32 v111, 0xffff0000, v148
	v_lshlrev_b32_e32 v112, 16, v149
	v_and_b32_e32 v113, 0xffff0000, v149
	v_pk_add_f32 v[104:105], v[104:105], v[108:109]
	v_pk_add_f32 v[102:103], v[102:103], v[106:107]
	v_pk_add_f32 v[98:99], v[98:99], v[110:111]
	v_pk_add_f32 v[100:101], v[100:101], v[112:113]
	global_store_dwordx4 v[114:115], v[102:105], off offset:512
	global_store_dwordx4 v[114:115], v[98:101], off offset:528
	s_nop 0
	v_lshlrev_b32_e32 v102, 16, v144
	v_lshlrev_b32_e32 v98, 16, v142
	v_and_b32_e32 v99, 0xffff0000, v142
	v_pk_add_f32 v[94:95], v[94:95], v[98:99]
	v_lshlrev_b64 v[98:99], 13, v[174:175]
	v_lshlrev_b32_e32 v100, 16, v143
	v_and_b32_e32 v101, 0xffff0000, v143
	v_and_b32_e32 v103, 0xffff0000, v144
	v_lshlrev_b32_e32 v104, 16, v145
	v_and_b32_e32 v105, 0xffff0000, v145
	v_lshl_add_u64 v[98:99], s[4:5], 0, v[98:99]
	v_pk_add_f32 v[96:97], v[96:97], v[100:101]
	v_pk_add_f32 v[92:93], v[92:93], v[104:105]
	v_pk_add_f32 v[90:91], v[90:91], v[102:103]
	v_lshl_add_u64 v[98:99], v[98:99], 0, v[122:123]
	global_store_dwordx4 v[98:99], v[94:97], off
	global_store_dwordx4 v[98:99], v[90:93], off offset:16
	v_add_u32_e32 v100, 0x90, v170
	v_lshlrev_b32_e32 v94, 16, v140
	v_lshlrev_b32_e32 v90, 16, v138
	v_and_b32_e32 v91, 0xffff0000, v138
	v_lshlrev_b32_e32 v92, 16, v139
	v_and_b32_e32 v93, 0xffff0000, v139
	v_and_b32_e32 v95, 0xffff0000, v140
	v_lshlrev_b32_e32 v96, 16, v141
	v_and_b32_e32 v97, 0xffff0000, v141
	v_pk_add_f32 v[88:89], v[88:89], v[92:93]
	v_pk_add_f32 v[86:87], v[86:87], v[90:91]
	v_pk_add_f32 v[78:79], v[78:79], v[94:95]
	v_pk_add_f32 v[80:81], v[80:81], v[96:97]
	global_store_dwordx4 v[98:99], v[86:89], off offset:512
	global_store_dwordx4 v[98:99], v[78:81], off offset:528
	v_add_u32_e32 v98, 0x80, v170
	v_lshlrev_b32_e32 v86, 16, v136
	v_lshlrev_b32_e32 v78, 16, v134
	v_and_b32_e32 v79, 0xffff0000, v134
	v_pk_add_f32 v[78:79], v[82:83], v[78:79]
	v_lshlrev_b64 v[82:83], 13, v[172:173]
; __device__ __forceinline__ unsigned cvt_pk_bf16(float lo, float hi) { f32x2 v = {lo, hi}; bf16x2_t b = __builtin_convertvector(v, bf16x2_t); return __builtin_bit_cast(unsigned, b); }
;     __device__ __forceinline__ void operator()(const f32x4 (&acc)[2][2][4][2], const Unit& u, int wr, int wc, int fr, int fq) const {
;     ...
;         for (int ai = 0; ai < 2; ++ai) {
;             u32x4 xr[4][2];
; #pragma unroll
;             for (int m = 0; m < 4; ++m)
; #pragma unroll
;                 for (int bj = 0; bj < 2; ++bj) xr[m][bj] = *(const u32x4*)(xb + (size_t)(u.pm * BM + ai * HALF + wr * 64 + m * 16 + fr) * 2048 + col0 + bj * HALF);
; #pragma unroll
;             for (int m = 0; m < 4; ++m) { const int row = u.pm * BM + ai * HALF + wr * 64 + m * 16 + fr; const size_t off = (size_t)row * 2048 + col0; float sq = 0.f;
; #pragma unroll
;                 for (int bj = 0; bj < 2; ++bj) { const size_t o2 = off + bj * HALF; const u32x4 xw = xr[m][bj];
;                     f32x4 x0, x1; x0[0] = __uint_as_float(xw.x << 16); x0[1] = __uint_as_float(xw.x & 0xffff0000u); x0[2] = __uint_as_float(xw.y << 16); x0[3] = __uint_as_float(xw.y & 0xffff0000u);
;                     x1[0] = __uint_as_float(xw.z << 16); x1[1] = __uint_as_float(xw.z & 0xffff0000u); x1[2] = __uint_as_float(xw.w << 16); x1[3] = __uint_as_float(xw.w & 0xffff0000u);
;                     x0 = x0 + acc[ai][bj][m][0]; x1 = x1 + acc[ai][bj][m][1];
;                     if (FINAL) { *(f32x4*)(out + o2) = x0; *(f32x4*)(out + o2 + 4) = x1; }
;                     else { u32x4 w; w.x = cvt_pk_bf16(x0[0], x0[1]); w.y = cvt_pk_bf16(x0[2], x0[3]); w.z = cvt_pk_bf16(x1[0], x1[1]); w.w = cvt_pk_bf16(x1[2], x1[3]); *(u32x4*)(xb + o2) = w; }
	v_lshlrev_b32_e32 v80, 16, v135
	v_and_b32_e32 v81, 0xffff0000, v135
	v_and_b32_e32 v87, 0xffff0000, v136
	v_lshlrev_b32_e32 v88, 16, v137
	v_and_b32_e32 v89, 0xffff0000, v137
	v_lshl_add_u64 v[82:83], s[4:5], 0, v[82:83]
	v_pk_add_f32 v[80:81], v[84:85], v[80:81]
	v_pk_add_f32 v[76:77], v[76:77], v[88:89]
	v_pk_add_f32 v[74:75], v[74:75], v[86:87]
	v_lshl_add_u64 v[82:83], v[82:83], 0, v[122:123]
	global_store_dwordx4 v[82:83], v[78:81], off
	global_store_dwordx4 v[82:83], v[74:77], off offset:16
	v_ashrrev_i32_e32 v99, 31, v98
	v_lshlrev_b32_e32 v78, 16, v132
	v_lshlrev_b32_e32 v74, 16, v130
	v_and_b32_e32 v75, 0xffff0000, v130
	v_lshlrev_b32_e32 v76, 16, v131
	v_and_b32_e32 v77, 0xffff0000, v131
	v_and_b32_e32 v79, 0xffff0000, v132
	v_lshlrev_b32_e32 v80, 16, v133
	v_and_b32_e32 v81, 0xffff0000, v133
	v_pk_add_f32 v[72:73], v[72:73], v[76:77]
	v_pk_add_f32 v[70:71], v[70:71], v[74:75]
	v_pk_add_f32 v[66:67], v[66:67], v[78:79]
	v_pk_add_f32 v[68:69], v[68:69], v[80:81]
	global_store_dwordx4 v[82:83], v[70:73], off offset:512
	global_store_dwordx4 v[82:83], v[66:69], off offset:528
	v_ashrrev_i32_e32 v101, 31, v100
	v_add_u32_e32 v102, 0xa0, v170
	v_lshlrev_b64 v[66:67], 12, v[98:99]
	v_lshl_add_u64 v[66:67], v[168:169], 0, v[66:67]
	global_load_dwordx4 v[70:73], v[66:67], off
	global_load_dwordx4 v[74:77], v[66:67], off offset:256
	v_lshlrev_b64 v[66:67], 12, v[100:101]
	v_lshl_add_u64 v[66:67], v[168:169], 0, v[66:67]
	global_load_dwordx4 v[78:81], v[66:67], off
	global_load_dwordx4 v[82:85], v[66:67], off offset:256
	v_ashrrev_i32_e32 v103, 31, v102
	v_lshlrev_b64 v[66:67], 12, v[102:103]
	v_lshl_add_u64 v[66:67], v[168:169], 0, v[66:67]
	global_load_dwordx4 v[86:89], v[66:67], off
	global_load_dwordx4 v[90:93], v[66:67], off offset:256
	v_add_u32_e32 v104, 0xb0, v170
	v_ashrrev_i32_e32 v105, 31, v104
	v_lshlrev_b64 v[66:67], 12, v[104:105]
	v_lshl_add_u64 v[66:67], v[168:169], 0, v[66:67]
	global_load_dwordx4 v[94:97], v[66:67], off
	s_nop 0
	global_load_dwordx4 v[66:69], v[66:67], off offset:256
	s_waitcnt vmcnt(7)
	v_lshlrev_b32_e32 v106, 16, v70
	v_and_b32_e32 v107, 0xffff0000, v70
	v_lshlrev_b32_e32 v70, 16, v71
	v_and_b32_e32 v71, 0xffff0000, v71
	v_pk_add_f32 v[64:65], v[64:65], v[70:71]
	v_lshlrev_b64 v[70:71], 13, v[98:99]
	v_lshlrev_b32_e32 v108, 16, v72
	v_and_b32_e32 v109, 0xffff0000, v72
	v_lshlrev_b32_e32 v72, 16, v73
	v_and_b32_e32 v73, 0xffff0000, v73
	v_lshl_add_u64 v[70:71], s[4:5], 0, v[70:71]
	v_pk_add_f32 v[62:63], v[62:63], v[106:107]
	v_pk_add_f32 v[60:61], v[60:61], v[72:73]
	v_pk_add_f32 v[58:59], v[58:59], v[108:109]
	v_lshl_add_u64 v[70:71], v[70:71], 0, v[122:123]
	global_store_dwordx4 v[70:71], v[62:65], off
	global_store_dwordx4 v[70:71], v[58:61], off offset:16
	s_waitcnt vmcnt(8)
	v_lshlrev_b32_e32 v62, 16, v76
	v_lshlrev_b32_e32 v58, 16, v74
	v_and_b32_e32 v59, 0xffff0000, v74
	v_lshlrev_b32_e32 v60, 16, v75
	v_and_b32_e32 v61, 0xffff0000, v75
	v_and_b32_e32 v63, 0xffff0000, v76
	v_lshlrev_b32_e32 v64, 16, v77
	v_and_b32_e32 v65, 0xffff0000, v77
	v_pk_add_f32 v[56:57], v[56:57], v[60:61]
	v_pk_add_f32 v[54:55], v[54:55], v[58:59]
	v_pk_add_f32 v[46:47], v[46:47], v[62:63]
	v_pk_add_f32 v[48:49], v[48:49], v[64:65]
	global_store_dwordx4 v[70:71], v[54:57], off offset:512
	global_store_dwordx4 v[70:71], v[46:49], off offset:528
	s_waitcnt vmcnt(9)
; __device__ __forceinline__ unsigned cvt_pk_bf16(float lo, float hi) { f32x2 v = {lo, hi}; bf16x2_t b = __builtin_convertvector(v, bf16x2_t); return __builtin_bit_cast(unsigned, b); }
; #define PG8_BAR __builtin_amdgcn_s_barrier()
;     __device__ __forceinline__ void operator()(const f32x4 (&acc)[2][2][4][2], const Unit& u, int wr, int wc, int fr, int fq) const {
;     ...
;                 for (int bj = 0; bj < 2; ++bj) { const size_t o2 = off + bj * HALF; const u32x4 xw = xr[m][bj];
;                     f32x4 x0, x1; x0[0] = __uint_as_float(xw.x << 16); x0[1] = __uint_as_float(xw.x & 0xffff0000u); x0[2] = __uint_as_float(xw.y << 16); x0[3] = __uint_as_float(xw.y & 0xffff0000u);
;                     x1[0] = __uint_as_float(xw.z << 16); x1[1] = __uint_as_float(xw.z & 0xffff0000u); x1[2] = __uint_as_float(xw.w << 16); x1[3] = __uint_as_float(xw.w & 0xffff0000u);
;                     x0 = x0 + acc[ai][bj][m][0]; x1 = x1 + acc[ai][bj][m][1];
;                     if (FINAL) { *(f32x4*)(out + o2) = x0; *(f32x4*)(out + o2 + 4) = x1; }
;                     else { u32x4 w; w.x = cvt_pk_bf16(x0[0], x0[1]); w.y = cvt_pk_bf16(x0[2], x0[3]); w.z = cvt_pk_bf16(x1[0], x1[1]); w.w = cvt_pk_bf16(x1[2], x1[3]); *(u32x4*)(xb + o2) = w; }
; template <class Epi, class Sched, bool ALIGN_EPI = false, bool SP2 = false>
; __device__ __forceinline__ void gemm_phase(PG8_LAS unsigned char* lds, const Gemm g, const Sched& S, const Epi& E) {
;     ...
;         cur = nxt; cA = nA; cB = nB; ++ui;
;         if constexpr (Epi::HAS_PREP) { if (cur.pm != prep_pm) { ++prep_gen; E.prep(cur, tid, prep_gen & 1); prep_pm = cur.pm; } }
;         if constexpr (ALIGN_EPI) { if (wr == 1) PG8_BAR; }
	v_lshlrev_b32_e32 v54, 16, v80
	v_lshlrev_b32_e32 v46, 16, v78
	v_and_b32_e32 v47, 0xffff0000, v78
	v_pk_add_f32 v[46:47], v[50:51], v[46:47]
	v_lshlrev_b64 v[50:51], 13, v[100:101]
	v_lshlrev_b32_e32 v48, 16, v79
	v_and_b32_e32 v49, 0xffff0000, v79
	v_and_b32_e32 v55, 0xffff0000, v80
	v_lshlrev_b32_e32 v56, 16, v81
	v_and_b32_e32 v57, 0xffff0000, v81
	v_lshl_add_u64 v[50:51], s[4:5], 0, v[50:51]
	v_pk_add_f32 v[48:49], v[52:53], v[48:49]
	v_pk_add_f32 v[44:45], v[44:45], v[56:57]
	v_pk_add_f32 v[42:43], v[42:43], v[54:55]
	v_lshl_add_u64 v[50:51], v[50:51], 0, v[122:123]
	global_store_dwordx4 v[50:51], v[46:49], off
	global_store_dwordx4 v[50:51], v[42:45], off offset:16
	s_waitcnt vmcnt(10)
	v_lshlrev_b32_e32 v46, 16, v84
	v_lshlrev_b32_e32 v42, 16, v82
	v_and_b32_e32 v43, 0xffff0000, v82
	v_lshlrev_b32_e32 v44, 16, v83
	v_and_b32_e32 v45, 0xffff0000, v83
	v_and_b32_e32 v47, 0xffff0000, v84
	v_lshlrev_b32_e32 v48, 16, v85
	v_and_b32_e32 v49, 0xffff0000, v85
	v_pk_add_f32 v[40:41], v[40:41], v[44:45]
	v_pk_add_f32 v[38:39], v[38:39], v[42:43]
	v_pk_add_f32 v[30:31], v[30:31], v[46:47]
	v_pk_add_f32 v[32:33], v[32:33], v[48:49]
	global_store_dwordx4 v[50:51], v[38:41], off offset:512
	global_store_dwordx4 v[50:51], v[30:33], off offset:528
	s_waitcnt vmcnt(11)
	v_lshlrev_b32_e32 v38, 16, v88
	v_lshlrev_b32_e32 v30, 16, v86
	v_and_b32_e32 v31, 0xffff0000, v86
	v_pk_add_f32 v[30:31], v[34:35], v[30:31]
	v_lshlrev_b64 v[34:35], 13, v[102:103]
	v_lshlrev_b32_e32 v32, 16, v87
	v_and_b32_e32 v33, 0xffff0000, v87
	v_and_b32_e32 v39, 0xffff0000, v88
	v_lshlrev_b32_e32 v40, 16, v89
	v_and_b32_e32 v41, 0xffff0000, v89
	v_lshl_add_u64 v[34:35], s[4:5], 0, v[34:35]
	v_pk_add_f32 v[32:33], v[36:37], v[32:33]
	v_pk_add_f32 v[28:29], v[28:29], v[40:41]
	v_pk_add_f32 v[26:27], v[26:27], v[38:39]
	v_lshl_add_u64 v[34:35], v[34:35], 0, v[122:123]
	global_store_dwordx4 v[34:35], v[30:33], off
	global_store_dwordx4 v[34:35], v[26:29], off offset:16
	s_waitcnt vmcnt(12)
	v_lshlrev_b32_e32 v30, 16, v92
	v_lshlrev_b32_e32 v26, 16, v90
	v_and_b32_e32 v27, 0xffff0000, v90
	v_lshlrev_b32_e32 v28, 16, v91
	v_and_b32_e32 v29, 0xffff0000, v91
	v_and_b32_e32 v31, 0xffff0000, v92
	v_lshlrev_b32_e32 v32, 16, v93
	v_and_b32_e32 v33, 0xffff0000, v93
	v_pk_add_f32 v[24:25], v[24:25], v[28:29]
	v_pk_add_f32 v[22:23], v[22:23], v[26:27]
	v_pk_add_f32 v[14:15], v[14:15], v[30:31]
	v_pk_add_f32 v[16:17], v[16:17], v[32:33]
	global_store_dwordx4 v[34:35], v[22:25], off offset:512
	global_store_dwordx4 v[34:35], v[14:17], off offset:528
	s_waitcnt vmcnt(13)
	v_lshlrev_b32_e32 v22, 16, v96
	v_lshlrev_b32_e32 v14, 16, v94
	v_and_b32_e32 v15, 0xffff0000, v94
	v_pk_add_f32 v[14:15], v[18:19], v[14:15]
	v_lshlrev_b64 v[18:19], 13, v[104:105]
	v_lshlrev_b32_e32 v16, 16, v95
	v_and_b32_e32 v17, 0xffff0000, v95
	v_and_b32_e32 v23, 0xffff0000, v96
	v_lshlrev_b32_e32 v24, 16, v97
	v_and_b32_e32 v25, 0xffff0000, v97
	v_lshl_add_u64 v[18:19], s[4:5], 0, v[18:19]
	v_pk_add_f32 v[16:17], v[20:21], v[16:17]
	v_pk_add_f32 v[12:13], v[12:13], v[24:25]
	v_pk_add_f32 v[10:11], v[10:11], v[22:23]
	v_lshl_add_u64 v[18:19], v[18:19], 0, v[122:123]
	global_store_dwordx4 v[18:19], v[14:17], off
	global_store_dwordx4 v[18:19], v[10:13], off offset:16
	s_waitcnt vmcnt(14)
	v_lshlrev_b32_e32 v14, 16, v68
	v_lshlrev_b32_e32 v10, 16, v66
	v_and_b32_e32 v11, 0xffff0000, v66
	v_lshlrev_b32_e32 v12, 16, v67
	v_and_b32_e32 v13, 0xffff0000, v67
	v_and_b32_e32 v15, 0xffff0000, v68
	v_lshlrev_b32_e32 v16, 16, v69
	v_and_b32_e32 v17, 0xffff0000, v69
	v_pk_add_f32 v[8:9], v[8:9], v[12:13]
	v_pk_add_f32 v[6:7], v[6:7], v[10:11]
	v_pk_add_f32 v[4:5], v[4:5], v[16:17]
	v_pk_add_f32 v[2:3], v[2:3], v[14:15]
	global_store_dwordx4 v[18:19], v[6:9], off offset:512
	global_store_dwordx4 v[18:19], v[2:5], off offset:528
	s_cbranch_vccnz .LBB0_872
	s_andn2_b64 vcc, exec, s[12:13]
	s_cbranch_vccnz .LBB0_871
	s_branch .LBB0_871
